# more v_cvt_pk_bf16_f32 packing (402 auto sites + ctx attention P/V packs by hand); same RNE rounding
# baseline (speedup 1.0000x reference)
.Ltail92:
	s_add_i32 s0, s1, 2
	v_add_u32_e32 v111, v104, v105
	ds_read_b128 v[136:139], v111 offset:16384
	ds_read_b128 v[140:143], v111 offset:18432
	ds_read_b128 v[144:147], v111 offset:20480
	ds_read_b128 v[148:151], v111 offset:22528
	v_add_u32_e32 v110, v103, v105
	ds_read_b128 v[116:119], v110
	s_add_i32 s1, s1, 4
	ds_read_b128 v[120:123], v110 offset:2048
	s_min_u32 s1, s1, 15
	v_add_u32_e32 v113, v104, v114
	s_lshl_b32 s92, s1, 7
	ds_read_b128 v[124:127], v110 offset:4096
	v_add_u32_e32 v112, v103, v114
	ds_read_b128 v[194:197], v113 offset:16384
	ds_read_b128 v[198:201], v113 offset:18432
	ds_read_b128 v[202:205], v113 offset:20480
	ds_read_b128 v[206:209], v113 offset:22528
	v_lshl_add_u64 v[164:165], v[98:99], 0, s[92:93]
	ds_read_b128 v[132:135], v110 offset:6144
	ds_read_b128 v[152:155], v112
	ds_read_b128 v[156:159], v112 offset:2048
	ds_read_b128 v[160:163], v112 offset:4096
	ds_read_b128 v[190:193], v112 offset:6144
	s_waitcnt lgkmcnt(11)
	v_mfma_f32_16x16x32_bf16 v[92:95], v[136:139], v[116:119], v[92:95]
	v_mfma_f32_16x16x32_bf16 v[88:91], v[140:143], v[116:119], v[88:91]
	v_mfma_f32_16x16x32_bf16 v[52:55], v[144:147], v[116:119], v[52:55]
	v_mfma_f32_16x16x32_bf16 v[48:51], v[148:151], v[116:119], v[48:51]
	s_waitcnt vmcnt(7)
	ds_write_b128 v109, v[56:59] offset:32768
	v_add_co_u32_e32 v56, vcc, s11, v164
	s_waitcnt lgkmcnt(11)
	v_mfma_f32_16x16x32_bf16 v[44:47], v[136:139], v[120:123], v[44:47]
	v_addc_co_u32_e32 v57, vcc, 0, v165, vcc
	v_mfma_f32_16x16x32_bf16 v[40:43], v[140:143], v[120:123], v[40:43]
	v_mfma_f32_16x16x32_bf16 v[36:39], v[144:147], v[120:123], v[36:39]
	v_mfma_f32_16x16x32_bf16 v[32:35], v[148:151], v[120:123], v[32:35]
	v_add_co_u32_e32 v56, vcc, s33, v164
	s_waitcnt vmcnt(6)
	ds_write_b128 v109, v[60:63] offset:36864
	s_nop 0
	v_addc_co_u32_e32 v57, vcc, 0, v165, vcc
	s_waitcnt lgkmcnt(11)
	v_mfma_f32_16x16x32_bf16 v[28:31], v[136:139], v[124:127], v[28:31]
	v_mfma_f32_16x16x32_bf16 v[24:27], v[140:143], v[124:127], v[24:27]
	v_mfma_f32_16x16x32_bf16 v[20:23], v[144:147], v[124:127], v[20:23]
	v_mfma_f32_16x16x32_bf16 v[16:19], v[148:151], v[124:127], v[16:19]
	v_add_co_u32_e32 v56, vcc, s59, v164
	s_waitcnt vmcnt(5)
	ds_write_b128 v109, v[64:67] offset:40960
	s_nop 0
	v_addc_co_u32_e32 v57, vcc, 0, v165, vcc
	v_lshl_add_u64 v[64:65], v[100:101], 0, s[92:93]
	v_add_co_u32_e32 v66, vcc, s11, v64
	s_waitcnt lgkmcnt(7)
	v_mfma_f32_16x16x32_bf16 v[12:15], v[136:139], v[132:135], v[12:15]
	v_addc_co_u32_e32 v67, vcc, 0, v65, vcc
	v_mfma_f32_16x16x32_bf16 v[8:11], v[140:143], v[132:135], v[8:11]
	v_mfma_f32_16x16x32_bf16 v[4:7], v[144:147], v[132:135], v[4:7]
	v_mfma_f32_16x16x32_bf16 v[0:3], v[148:151], v[132:135], v[0:3]
	s_waitcnt vmcnt(4)
	ds_write_b128 v109, v[72:75] offset:45056
	s_waitcnt lgkmcnt(7)
	v_mfma_f32_16x16x32_bf16 v[56:59], v[194:197], v[152:155], v[92:95]
	v_mfma_f32_16x16x32_bf16 v[60:63], v[198:201], v[152:155], v[88:91]
	v_mfma_f32_16x16x32_bf16 v[52:55], v[202:205], v[152:155], v[52:55]
	v_mfma_f32_16x16x32_bf16 v[48:51], v[206:209], v[152:155], v[48:51]
	s_waitcnt vmcnt(3)
	ds_write_b128 v109, v[68:71] offset:49152
	s_waitcnt lgkmcnt(7)
	v_mfma_f32_16x16x32_bf16 v[44:47], v[194:197], v[156:159], v[44:47]
	v_mfma_f32_16x16x32_bf16 v[40:43], v[198:201], v[156:159], v[40:43]
	v_mfma_f32_16x16x32_bf16 v[36:39], v[202:205], v[156:159], v[36:39]
	v_mfma_f32_16x16x32_bf16 v[32:35], v[206:209], v[156:159], v[32:35]
	v_add_co_u32_e32 v66, vcc, s33, v64
	s_waitcnt vmcnt(2)
	ds_write_b128 v109, v[76:79] offset:53248
	v_addc_co_u32_e32 v67, vcc, 0, v65, vcc
	v_add_co_u32_e32 v64, vcc, s59, v64
	s_waitcnt lgkmcnt(7)
	v_mfma_f32_16x16x32_bf16 v[28:31], v[194:197], v[160:163], v[28:31]
	v_addc_co_u32_e32 v65, vcc, 0, v65, vcc
	v_mfma_f32_16x16x32_bf16 v[24:27], v[198:201], v[160:163], v[24:27]
	v_mfma_f32_16x16x32_bf16 v[20:23], v[202:205], v[160:163], v[20:23]
	v_mfma_f32_16x16x32_bf16 v[16:19], v[206:209], v[160:163], v[16:19]
	s_waitcnt vmcnt(1)
	ds_write_b128 v109, v[80:83] offset:57344
	s_waitcnt lgkmcnt(7)
	v_mfma_f32_16x16x32_bf16 v[12:15], v[194:197], v[190:193], v[12:15]
	v_mfma_f32_16x16x32_bf16 v[8:11], v[198:201], v[190:193], v[8:11]
	v_mfma_f32_16x16x32_bf16 v[4:7], v[202:205], v[190:193], v[4:7]
	v_mfma_f32_16x16x32_bf16 v[0:3], v[206:209], v[190:193], v[0:3]
	s_waitcnt vmcnt(0)
	ds_write_b128 v109, v[84:87] offset:61440
	s_waitcnt lgkmcnt(0)
	s_barrier
	ds_read_b128 v[84:87], v111 offset:51200
	ds_read_b128 v[80:83], v111 offset:49152
	ds_read_b128 v[88:91], v111 offset:53248
	ds_read_b128 v[92:95], v111 offset:55296
	ds_read_b128 v[64:67], v110 offset:32768
	s_min_u32 s1, s0, 12
	s_lshl_b32 s92, s1, 7
	ds_read_b128 v[68:71], v110 offset:34816
	v_lshl_add_u64 v[164:165], v[98:99], 0, s[92:93]
	ds_read_b128 v[72:75], v110 offset:36864
	ds_read_b128 v[76:79], v110 offset:38912
	ds_read_b128 v[152:155], v112 offset:32768
	ds_read_b128 v[156:159], v112 offset:34816
	ds_read_b128 v[160:163], v112 offset:36864
	ds_read_b128 v[190:193], v112 offset:38912
	ds_read_b128 v[194:197], v113 offset:49152
	ds_read_b128 v[198:201], v113 offset:51200
	ds_read_b128 v[202:205], v113 offset:53248
	ds_read_b128 v[206:209], v113 offset:55296
	s_waitcnt lgkmcnt(11)
	v_mfma_f32_16x16x32_bf16 v[214:217], v[84:87], v[64:67], v[60:63]
	v_mfma_f32_16x16x32_bf16 v[210:213], v[80:83], v[64:67], v[56:59]
	s_nop 1
	v_add_co_u32_e32 v60, vcc, s11, v164
	s_nop 1
	v_addc_co_u32_e32 v61, vcc, 0, v165, vcc
	v_mfma_f32_16x16x32_bf16 v[52:55], v[88:91], v[64:67], v[52:55]
	v_mfma_f32_16x16x32_bf16 v[48:51], v[92:95], v[64:67], v[48:51]
	v_add_co_u32_e32 v64, vcc, s33, v164
	s_nop 0
	v_addc_co_u32_e32 v65, vcc, 0, v165, vcc
	s_waitcnt lgkmcnt(10)
	v_mfma_f32_16x16x32_bf16 v[44:47], v[80:83], v[68:71], v[44:47]
	v_mfma_f32_16x16x32_bf16 v[40:43], v[84:87], v[68:71], v[40:43]
	v_mfma_f32_16x16x32_bf16 v[36:39], v[88:91], v[68:71], v[36:39]
	v_mfma_f32_16x16x32_bf16 v[32:35], v[92:95], v[68:71], v[32:35]
	v_add_co_u32_e32 v68, vcc, s59, v164
	s_waitcnt lgkmcnt(9)
	v_mfma_f32_16x16x32_bf16 v[28:31], v[80:83], v[72:75], v[28:31]
	v_addc_co_u32_e32 v69, vcc, 0, v165, vcc
	v_mfma_f32_16x16x32_bf16 v[24:27], v[84:87], v[72:75], v[24:27]
	v_mfma_f32_16x16x32_bf16 v[20:23], v[88:91], v[72:75], v[20:23]
	v_mfma_f32_16x16x32_bf16 v[16:19], v[92:95], v[72:75], v[16:19]
	s_waitcnt lgkmcnt(8)
	v_mfma_f32_16x16x32_bf16 v[8:11], v[84:87], v[76:79], v[8:11]
	v_lshl_add_u64 v[84:85], v[100:101], 0, s[92:93]
	v_mfma_f32_16x16x32_bf16 v[12:15], v[80:83], v[76:79], v[12:15]
	v_mfma_f32_16x16x32_bf16 v[4:7], v[88:91], v[76:79], v[4:7]
	v_mfma_f32_16x16x32_bf16 v[0:3], v[92:95], v[76:79], v[0:3]
	v_add_co_u32_e32 v76, vcc, s11, v84
	s_nop 0
	v_addc_co_u32_e32 v77, vcc, 0, v85, vcc
	v_add_co_u32_e32 v80, vcc, s33, v84
	v_addc_co_u32_e32 v81, vcc, 0, v85, vcc
	s_waitcnt lgkmcnt(3)
	v_mfma_f32_16x16x32_bf16 v[92:95], v[194:197], v[152:155], v[210:213]
	s_waitcnt lgkmcnt(2)
	v_mfma_f32_16x16x32_bf16 v[88:91], v[198:201], v[152:155], v[214:217]
	s_waitcnt lgkmcnt(1)
	v_mfma_f32_16x16x32_bf16 v[52:55], v[202:205], v[152:155], v[52:55]
	s_waitcnt lgkmcnt(0)
	v_mfma_f32_16x16x32_bf16 v[48:51], v[206:209], v[152:155], v[48:51]
	v_add_co_u32_e32 v84, vcc, s59, v84
	v_addc_co_u32_e32 v85, vcc, 0, v85, vcc
	v_mfma_f32_16x16x32_bf16 v[44:47], v[194:197], v[156:159], v[44:47]
	v_mfma_f32_16x16x32_bf16 v[40:43], v[198:201], v[156:159], v[40:43]
	v_mfma_f32_16x16x32_bf16 v[36:39], v[202:205], v[156:159], v[36:39]
	v_mfma_f32_16x16x32_bf16 v[32:35], v[206:209], v[156:159], v[32:35]
	v_mfma_f32_16x16x32_bf16 v[28:31], v[194:197], v[160:163], v[28:31]
	v_mfma_f32_16x16x32_bf16 v[24:27], v[198:201], v[160:163], v[24:27]
	v_mfma_f32_16x16x32_bf16 v[20:23], v[202:205], v[160:163], v[20:23]
	v_mfma_f32_16x16x32_bf16 v[16:19], v[206:209], v[160:163], v[16:19]
	v_mfma_f32_16x16x32_bf16 v[12:15], v[194:197], v[190:193], v[12:15]
	v_mfma_f32_16x16x32_bf16 v[8:11], v[198:201], v[190:193], v[8:11]
	v_mfma_f32_16x16x32_bf16 v[4:7], v[202:205], v[190:193], v[4:7]
	v_mfma_f32_16x16x32_bf16 v[0:3], v[206:209], v[190:193], v[0:3]
	s_mov_b32 s1, s0
	s_waitcnt lgkmcnt(0)
	s_barrier
	s_mul_i32 s0, s69, 0x12000
	v_readlane_b32 s16, v250, 25
	s_add_u32 s24, s16, s0
	v_readlane_b32 s0, v251, 5
	v_lshlrev_b32_e32 v114, 6, v102
	v_readlane_b32 s17, v250, 26
	s_waitcnt vmcnt(5)
	v_add_u32_e32 v64, s0, v108
	v_readlane_b32 s0, v251, 6
	v_add_u32_e32 v56, 0xffffe000, v64
	v_or_b32_e32 v62, v64, v107
	v_or_b32_e32 v65, s0, v114
	v_lshrrev_b32_e32 v56, 10, v56
	s_movk_i32 s0, 0x1800
	v_mad_u32_u24 v56, v56, s0, s0
	v_cmp_lt_i32_e32 vcc, s13, v62
	s_addc_u32 s25, s17, 0
	v_lshlrev_b32_e32 v115, 2, v97
	v_cndmask_b32_e32 v56, 0, v56, vcc
	s_add_u32 s40, s24, 0x2000
	v_or_b32_e32 v58, v65, v115
	v_ashrrev_i32_e32 v57, 31, v56
	s_addc_u32 s41, s25, 0
	s_waitcnt vmcnt(4)
	v_lshlrev_b64 v[74:75], 2, v[56:57]
	v_ashrrev_i32_e32 v59, 31, v58
	v_ashrrev_i32_e32 v63, 31, v62
	v_lshl_add_u64 v[56:57], s[40:41], 0, v[74:75]
	v_lshlrev_b64 v[60:61], 2, v[58:59]
	v_readlane_b32 s0, v250, 15
	s_waitcnt vmcnt(1)
	v_lshl_add_u64 v[82:83], v[56:57], 0, v[60:61]
	v_lshlrev_b64 v[56:57], 12, v[62:63]
	v_readlane_b32 s1, v250, 16
	v_readlane_b32 s16, v250, 21
	v_lshlrev_b64 v[78:79], 11, v[62:63]
	v_lshl_add_u64 v[56:57], s[0:1], 0, v[56:57]
	s_waitcnt vmcnt(0)
	v_lshl_add_u64 v[84:85], v[56:57], 0, v[60:61]
	global_load_dwordx4 v[116:119], v[82:83], off
	global_load_dwordx4 v[120:123], v[82:83], off offset:64
	global_load_dwordx4 v[124:127], v[82:83], off offset:128
	global_load_dwordx4 v[132:135], v[82:83], off offset:192
	global_load_dwordx4 v[190:193], v[84:85], off
	global_load_dwordx4 v[194:197], v[84:85], off offset:64
	global_load_dwordx4 v[198:201], v[84:85], off offset:128
	global_load_dwordx4 v[202:205], v[84:85], off offset:192
	v_add_co_u32_e32 v164, vcc, 0x10000, v84
	s_nop 1
	v_addc_co_u32_e32 v165, vcc, 0, v85, vcc
	v_add_co_u32_e32 v222, vcc, 0x20000, v84
	s_nop 1
	v_addc_co_u32_e32 v223, vcc, 0, v85, vcc
	v_add_co_u32_e32 v224, vcc, 0x30000, v84
	s_nop 1
	v_addc_co_u32_e32 v225, vcc, 0, v85, vcc
	global_load_dwordx4 v[206:209], v[164:165], off
	global_load_dwordx4 v[210:213], v[164:165], off offset:64
	global_load_dwordx4 v[214:217], v[164:165], off offset:128
	global_load_dwordx4 v[218:221], v[164:165], off offset:192
	s_lshl_b32 s0, s69, 12
	v_readlane_b32 s68, v250, 41
	v_readlane_b32 s72, v250, 45
	v_readlane_b32 s73, v250, 46
	s_add_u32 s0, s72, s0
	s_addc_u32 s1, s73, 0
	s_add_u32 s42, s24, 0x4000
	s_addc_u32 s43, s25, 0
	v_lshl_add_u64 v[74:75], s[42:43], 0, v[74:75]
	v_lshl_add_u64 v[56:57], s[0:1], 0, v[60:61]
	v_lshl_add_u64 v[86:87], v[74:75], 0, v[60:61]
	v_readlane_b32 s17, v250, 22
	v_readlane_b32 s69, v250, 42
	v_readlane_b32 s69, v254, 49
	v_lshl_add_u64 v[78:79], s[16:17], 0, v[78:79]
	s_mul_i32 s24, s69, 0x140000
	s_add_u32 s24, s86, s24
	v_lshrrev_b32_e32 v65, 6, v65
	s_mov_b32 s16, 0xa000
	s_addc_u32 s25, s87, 0
	s_add_u32 s26, s24, 0xaf1a000
	s_addc_u32 s27, s25, 0
	v_cmp_eq_u32_e64 s[36:37], 0, v97
	v_readlane_b32 s70, v250, 43
	v_readlane_b32 s71, v250, 44
	v_readlane_b32 s74, v250, 47
	v_readlane_b32 s75, v250, 48
	v_readlane_b32 s76, v250, 49
	v_readlane_b32 s77, v250, 50
	v_readlane_b32 s78, v250, 51
	v_readlane_b32 s79, v250, 52
	v_readlane_b32 s80, v250, 53
	v_readlane_b32 s81, v250, 54
	v_readlane_b32 s82, v250, 55
	v_readlane_b32 s83, v250, 56
	s_waitcnt vmcnt(4)
	v_pk_fma_f32 v[68:69], v[94:95], v[118:119], v[192:193]
	v_pk_fma_f32 v[66:67], v[92:93], v[116:117], v[190:191]
	global_store_dwordx4 v[84:85], v[66:69], off
	global_load_dwordx4 v[136:139], v[56:57], off
	global_load_dwordx4 v[140:143], v[56:57], off offset:64
	global_load_dwordx4 v[144:147], v[56:57], off offset:128
	global_load_dwordx4 v[148:151], v[56:57], off offset:192
	global_load_dwordx4 v[152:155], v[86:87], off
	global_load_dwordx4 v[156:159], v[86:87], off offset:64
	global_load_dwordx4 v[160:163], v[86:87], off offset:128
	global_load_dwordx4 v[180:183], v[86:87], off offset:192
	v_lshl_add_u64 v[92:93], v[58:59], 1, v[78:79]
	s_waitcnt vmcnt(0)
	v_pk_mul_f32 v[72:73], v[68:69], v[138:139]
	v_pk_mul_f32 v[70:71], v[66:67], v[136:137]
	s_waitcnt vmcnt(0)
	v_pk_add_f32 v[76:77], v[154:155], 1.0 op_sel_hi:[1,0]
	v_pk_add_f32 v[74:75], v[152:153], 1.0 op_sel_hi:[1,0]
	v_pk_mul_f32 v[72:73], v[72:73], v[76:77]
	v_pk_mul_f32 v[70:71], v[70:71], v[74:75]
	v_and_b32_sdwa v77, v71, v170 dst_sel:DWORD dst_unused:UNUSED_PAD src0_sel:WORD_1 src1_sel:DWORD
	v_and_b32_sdwa v75, v70, v170 dst_sel:DWORD dst_unused:UNUSED_PAD src0_sel:WORD_1 src1_sel:DWORD
	v_add3_u32 v71, v71, v77, s56
	v_add3_u32 v70, v70, v75, s56
	v_and_b32_e32 v74, 0xffff0000, v71
	v_cvt_pk_bf16_f32 v71, v72, v73
	v_or_b32_sdwa v70, v74, v70 dst_sel:DWORD dst_unused:UNUSED_PAD src0_sel:DWORD src1_sel:WORD_1
	global_store_dwordx2 v[92:93], v[70:71], off
	s_nop 0
	s_waitcnt vmcnt(0)
	v_pk_fma_f32 v[72:73], v[90:91], v[122:123], v[196:197]
	v_pk_fma_f32 v[70:71], v[88:89], v[120:121], v[194:195]
	global_store_dwordx4 v[84:85], v[70:73], off offset:64
	v_pk_mul_f32 v[76:77], v[72:73], v[142:143]
	v_pk_mul_f32 v[74:75], v[70:71], v[140:141]
	v_pk_add_f32 v[80:81], v[158:159], 1.0 op_sel_hi:[1,0]
	v_pk_add_f32 v[78:79], v[156:157], 1.0 op_sel_hi:[1,0]
	v_pk_mul_f32 v[76:77], v[76:77], v[80:81]
	v_pk_mul_f32 v[74:75], v[74:75], v[78:79]
	v_and_b32_sdwa v81, v75, v170 dst_sel:DWORD dst_unused:UNUSED_PAD src0_sel:WORD_1 src1_sel:DWORD
	v_and_b32_sdwa v79, v74, v170 dst_sel:DWORD dst_unused:UNUSED_PAD src0_sel:WORD_1 src1_sel:DWORD
	v_add3_u32 v75, v75, v81, s56
	v_add3_u32 v74, v74, v79, s56
	v_and_b32_e32 v78, 0xffff0000, v75
	v_cvt_pk_bf16_f32 v75, v76, v77
	v_or_b32_sdwa v74, v78, v74 dst_sel:DWORD dst_unused:UNUSED_PAD src0_sel:DWORD src1_sel:WORD_1
	global_store_dwordx2 v[92:93], v[74:75], off offset:32
	s_nop 0
	v_pk_fma_f32 v[54:55], v[54:55], v[126:127], v[200:201]
	v_pk_fma_f32 v[52:53], v[52:53], v[124:125], v[198:199]
	global_store_dwordx4 v[84:85], v[52:55], off offset:128
	v_pk_mul_f32 v[76:77], v[54:55], v[146:147]
	v_pk_mul_f32 v[74:75], v[52:53], v[144:145]
	v_pk_add_f32 v[80:81], v[162:163], 1.0 op_sel_hi:[1,0]
	v_pk_add_f32 v[78:79], v[160:161], 1.0 op_sel_hi:[1,0]
	v_pk_mul_f32 v[76:77], v[76:77], v[80:81]
	v_pk_mul_f32 v[74:75], v[74:75], v[78:79]
	v_and_b32_sdwa v81, v75, v170 dst_sel:DWORD dst_unused:UNUSED_PAD src0_sel:WORD_1 src1_sel:DWORD
	v_and_b32_sdwa v79, v74, v170 dst_sel:DWORD dst_unused:UNUSED_PAD src0_sel:WORD_1 src1_sel:DWORD
	v_add3_u32 v75, v75, v81, s56
	v_add3_u32 v74, v74, v79, s56
	v_and_b32_e32 v78, 0xffff0000, v75
	v_cvt_pk_bf16_f32 v75, v76, v77
	v_or_b32_sdwa v74, v78, v74 dst_sel:DWORD dst_unused:UNUSED_PAD src0_sel:DWORD src1_sel:WORD_1
	global_store_dwordx2 v[92:93], v[74:75], off offset:64
	s_nop 0
	v_pk_fma_f32 v[76:77], v[50:51], v[134:135], v[204:205]
	v_pk_fma_f32 v[74:75], v[48:49], v[132:133], v[202:203]
	global_store_dwordx4 v[84:85], v[74:77], off offset:192
	s_nop 0
	v_mbcnt_lo_u32_b32 v48, -1, 0
	v_mbcnt_hi_u32_b32 v48, -1, v48
	v_and_b32_e32 v50, 64, v48
	v_xor_b32_e32 v49, 16, v48
	v_add_u32_e32 v50, 64, v50
	v_xor_b32_e32 v51, 32, v48
	v_cmp_lt_i32_e32 vcc, v49, v50
	s_nop 1
	v_cndmask_b32_e32 v49, v48, v49, vcc
	v_cmp_lt_i32_e32 vcc, v51, v50
	v_lshlrev_b32_e32 v105, 2, v49
	s_nop 0
	v_cndmask_b32_e32 v50, v48, v51, vcc
	v_lshlrev_b32_e32 v104, 2, v50
	v_mul_f32_e32 v50, v67, v67
	v_mul_f32_e32 v51, v71, v71
	v_fmac_f32_e32 v50, v66, v66
	v_fmac_f32_e32 v51, v70, v70
	v_fmac_f32_e32 v50, v68, v68
	v_fmac_f32_e32 v51, v72, v72
	v_fmac_f32_e32 v50, v69, v69
	v_fmac_f32_e32 v51, v73, v73
	v_add_f32_e32 v50, v50, v51
	v_mul_f32_e32 v51, v53, v53
	v_fmac_f32_e32 v51, v52, v52
	v_fmac_f32_e32 v51, v54, v54
	v_fmac_f32_e32 v51, v55, v55
	v_add_f32_e32 v50, v50, v51
	v_mul_f32_e32 v51, v75, v75
	v_fmac_f32_e32 v51, v74, v74
	v_fmac_f32_e32 v51, v76, v76
	v_fmac_f32_e32 v51, v77, v77
	v_add_f32_e32 v50, v50, v51
	ds_bpermute_b32 v51, v105, v50
	v_mul_lo_u32 v48, v65, s16
	v_ashrrev_i32_e32 v49, 31, v48
	v_lshl_add_u64 v[48:49], s[26:27], 0, v[48:49]
	v_lshl_add_u64 v[48:49], v[62:63], 2, v[48:49]
	s_waitcnt lgkmcnt(0)
	v_add_f32_e32 v50, v50, v51
	ds_bpermute_b32 v51, v104, v50
	v_pk_mul_f32 v[52:53], v[76:77], v[150:151]
	v_pk_mul_f32 v[54:55], v[74:75], v[148:149]
	v_pk_add_f32 v[66:67], v[182:183], 1.0 op_sel_hi:[1,0]
	v_pk_add_f32 v[68:69], v[180:181], 1.0 op_sel_hi:[1,0]
	v_pk_mul_f32 v[52:53], v[52:53], v[66:67]
	v_pk_mul_f32 v[54:55], v[54:55], v[68:69]
	v_cvt_pk_bf16_f32 v53, v52, v53
	v_cvt_pk_bf16_f32 v52, v54, v55
	global_store_dwordx2 v[92:93], v[52:53], off offset:96
	s_and_saveexec_b64 s[24:25], s[36:37]
	s_cbranch_execz .LBB0_95
	s_waitcnt lgkmcnt(0)
	v_add_f32_e32 v50, v50, v51
	global_store_dword v[48:49], v50, off
.LBB0_95:
	s_or_b64 exec, exec, s[24:25]
	v_add_u32_e32 v50, 0xffffe010, v64
	v_or_b32_e32 v54, 16, v62
	v_lshrrev_b32_e32 v50, 10, v50
	s_movk_i32 s5, 0x1800
	s_movk_i32 s13, 0x1fff
	v_mad_u32_u24 v50, v50, s5, s5
	v_cmp_lt_i32_e32 vcc, s13, v54
	v_ashrrev_i32_e32 v55, 31, v54
	v_readlane_b32 s16, v250, 15
	v_cndmask_b32_e32 v50, 0, v50, vcc
	s_waitcnt lgkmcnt(0)
	v_ashrrev_i32_e32 v51, 31, v50
	v_lshlrev_b64 v[70:71], 2, v[50:51]
	v_lshl_add_u64 v[50:51], s[40:41], 0, v[70:71]
	v_lshl_add_u64 v[72:73], v[50:51], 0, v[60:61]
	v_lshlrev_b64 v[50:51], 12, v[54:55]
	v_readlane_b32 s17, v250, 16
	v_lshl_add_u64 v[70:71], s[42:43], 0, v[70:71]
	v_lshl_add_u64 v[70:71], v[70:71], 0, v[60:61]
	v_lshl_add_u64 v[50:51], s[16:17], 0, v[50:51]
	v_lshl_add_u64 v[74:75], v[50:51], 0, v[60:61]
	v_readlane_b32 s16, v250, 21
	v_lshlrev_b64 v[54:55], 11, v[54:55]
	v_readlane_b32 s17, v250, 22
	global_load_dwordx4 v[190:193], v[222:223], off
	global_load_dwordx4 v[194:197], v[222:223], off offset:64
	global_load_dwordx4 v[198:201], v[222:223], off offset:128
	global_load_dwordx4 v[202:205], v[222:223], off offset:192
	s_waitcnt vmcnt(20)
	v_pk_fma_f32 v[46:47], v[46:47], v[118:119], v[208:209]
	v_pk_fma_f32 v[44:45], v[44:45], v[116:117], v[206:207]
	global_store_dwordx4 v[74:75], v[44:47], off
	v_lshl_add_u64 v[54:55], s[16:17], 0, v[54:55]
	v_lshl_add_u64 v[54:55], v[58:59], 1, v[54:55]
	v_pk_mul_f32 v[52:53], v[46:47], v[138:139]
	v_pk_mul_f32 v[50:51], v[44:45], v[136:137]
	v_pk_add_f32 v[68:69], v[154:155], 1.0 op_sel_hi:[1,0]
	v_pk_add_f32 v[66:67], v[152:153], 1.0 op_sel_hi:[1,0]
	v_pk_mul_f32 v[52:53], v[52:53], v[68:69]
	v_pk_mul_f32 v[50:51], v[50:51], v[66:67]
	v_and_b32_sdwa v67, v51, v170 dst_sel:DWORD dst_unused:UNUSED_PAD src0_sel:WORD_1 src1_sel:DWORD
	v_and_b32_sdwa v65, v50, v170 dst_sel:DWORD dst_unused:UNUSED_PAD src0_sel:WORD_1 src1_sel:DWORD
	v_add3_u32 v51, v51, v67, s56
	v_add3_u32 v50, v50, v65, s56
	v_and_b32_e32 v63, 0xffff0000, v51
	v_cvt_pk_bf16_f32 v51, v52, v53
	v_or_b32_sdwa v50, v63, v50 dst_sel:DWORD dst_unused:UNUSED_PAD src0_sel:DWORD src1_sel:WORD_1
	global_store_dwordx2 v[54:55], v[50:51], off
	s_nop 0
	v_pk_fma_f32 v[42:43], v[42:43], v[122:123], v[212:213]
	v_pk_fma_f32 v[40:41], v[40:41], v[120:121], v[210:211]
	global_store_dwordx4 v[74:75], v[40:43], off offset:64
	v_pk_mul_f32 v[52:53], v[42:43], v[142:143]
	v_pk_mul_f32 v[50:51], v[40:41], v[140:141]
	v_pk_add_f32 v[68:69], v[158:159], 1.0 op_sel_hi:[1,0]
	v_pk_add_f32 v[66:67], v[156:157], 1.0 op_sel_hi:[1,0]
	v_pk_mul_f32 v[52:53], v[52:53], v[68:69]
	v_pk_mul_f32 v[50:51], v[50:51], v[66:67]
	v_and_b32_sdwa v67, v51, v170 dst_sel:DWORD dst_unused:UNUSED_PAD src0_sel:WORD_1 src1_sel:DWORD
	v_and_b32_sdwa v65, v50, v170 dst_sel:DWORD dst_unused:UNUSED_PAD src0_sel:WORD_1 src1_sel:DWORD
	v_add3_u32 v51, v51, v67, s56
	v_add3_u32 v50, v50, v65, s56
	v_and_b32_e32 v63, 0xffff0000, v51
	v_cvt_pk_bf16_f32 v51, v52, v53
	v_or_b32_sdwa v50, v63, v50 dst_sel:DWORD dst_unused:UNUSED_PAD src0_sel:DWORD src1_sel:WORD_1
	global_store_dwordx2 v[54:55], v[50:51], off offset:32
	s_nop 0
	v_pk_fma_f32 v[38:39], v[38:39], v[126:127], v[216:217]
	v_pk_fma_f32 v[36:37], v[36:37], v[124:125], v[214:215]
	global_store_dwordx4 v[74:75], v[36:39], off offset:128
	v_pk_mul_f32 v[52:53], v[38:39], v[146:147]
	v_pk_mul_f32 v[50:51], v[36:37], v[144:145]
	v_pk_add_f32 v[68:69], v[162:163], 1.0 op_sel_hi:[1,0]
	v_pk_add_f32 v[66:67], v[160:161], 1.0 op_sel_hi:[1,0]
	v_pk_mul_f32 v[52:53], v[52:53], v[68:69]
	v_pk_mul_f32 v[50:51], v[50:51], v[66:67]
	v_and_b32_sdwa v67, v51, v170 dst_sel:DWORD dst_unused:UNUSED_PAD src0_sel:WORD_1 src1_sel:DWORD
	v_and_b32_sdwa v65, v50, v170 dst_sel:DWORD dst_unused:UNUSED_PAD src0_sel:WORD_1 src1_sel:DWORD
	v_add3_u32 v51, v51, v67, s56
	v_add3_u32 v50, v50, v65, s56
	v_and_b32_e32 v63, 0xffff0000, v51
	v_cvt_pk_bf16_f32 v51, v52, v53
	v_or_b32_sdwa v50, v63, v50 dst_sel:DWORD dst_unused:UNUSED_PAD src0_sel:DWORD src1_sel:WORD_1
	global_store_dwordx2 v[54:55], v[50:51], off offset:64
	s_nop 0
	v_pk_fma_f32 v[52:53], v[34:35], v[134:135], v[220:221]
	v_pk_fma_f32 v[50:51], v[32:33], v[132:133], v[218:219]
	global_store_dwordx4 v[74:75], v[50:53], off offset:192
	s_nop 0
	v_mul_f32_e32 v32, v45, v45
	v_mul_f32_e32 v33, v41, v41
	v_fmac_f32_e32 v32, v44, v44
	v_fmac_f32_e32 v33, v40, v40
	v_fmac_f32_e32 v32, v46, v46
	v_fmac_f32_e32 v33, v42, v42
	v_fmac_f32_e32 v32, v47, v47
	v_fmac_f32_e32 v33, v43, v43
	v_add_f32_e32 v32, v32, v33
	v_mul_f32_e32 v33, v37, v37
	v_fmac_f32_e32 v33, v36, v36
	v_fmac_f32_e32 v33, v38, v38
	v_fmac_f32_e32 v33, v39, v39
	v_add_f32_e32 v32, v32, v33
	v_mul_f32_e32 v33, v51, v51
	v_fmac_f32_e32 v33, v50, v50
	v_fmac_f32_e32 v33, v52, v52
	v_fmac_f32_e32 v33, v53, v53
	v_add_f32_e32 v32, v32, v33
	ds_bpermute_b32 v33, v105, v32
	s_waitcnt lgkmcnt(0)
	v_add_f32_e32 v32, v32, v33
	ds_bpermute_b32 v33, v104, v32
	v_pk_mul_f32 v[34:35], v[52:53], v[150:151]
	v_pk_mul_f32 v[36:37], v[50:51], v[148:149]
	v_pk_add_f32 v[38:39], v[182:183], 1.0 op_sel_hi:[1,0]
	v_pk_add_f32 v[40:41], v[180:181], 1.0 op_sel_hi:[1,0]
	v_pk_mul_f32 v[34:35], v[34:35], v[38:39]
	v_pk_mul_f32 v[36:37], v[36:37], v[40:41]
	v_cvt_pk_bf16_f32 v35, v34, v35
	v_cvt_pk_bf16_f32 v34, v36, v37
	global_store_dwordx2 v[54:55], v[34:35], off offset:96
	s_and_saveexec_b64 s[24:25], s[36:37]
	s_cbranch_execz .LBB0_97
	s_waitcnt lgkmcnt(0)
	v_add_f32_e32 v32, v32, v33
	global_store_dword v[48:49], v32, off offset:64
.LBB0_97:
	s_or_b64 exec, exec, s[24:25]
	v_add_u32_e32 v32, 0xffffe020, v64
	v_or_b32_e32 v40, 32, v62
	v_lshrrev_b32_e32 v32, 10, v32
	v_mad_u32_u24 v32, v32, s5, s5
	v_cmp_lt_i32_e32 vcc, s13, v40
	v_ashrrev_i32_e32 v41, 31, v40
	v_readlane_b32 s16, v250, 15
	v_cndmask_b32_e32 v32, 0, v32, vcc
	s_waitcnt lgkmcnt(0)
	v_ashrrev_i32_e32 v33, 31, v32
	v_lshlrev_b64 v[42:43], 2, v[32:33]
	v_lshl_add_u64 v[32:33], s[40:41], 0, v[42:43]
	v_lshl_add_u64 v[44:45], v[32:33], 0, v[60:61]
	v_lshlrev_b64 v[32:33], 12, v[40:41]
	v_readlane_b32 s17, v250, 16
	v_lshl_add_u64 v[42:43], s[42:43], 0, v[42:43]
	v_lshl_add_u64 v[42:43], v[42:43], 0, v[60:61]
	v_lshl_add_u64 v[32:33], s[16:17], 0, v[32:33]
	v_lshl_add_u64 v[46:47], v[32:33], 0, v[60:61]
	v_readlane_b32 s16, v250, 21
	v_lshlrev_b64 v[40:41], 11, v[40:41]
	v_readlane_b32 s17, v250, 22
	global_load_dwordx4 v[206:209], v[224:225], off
	global_load_dwordx4 v[210:213], v[224:225], off offset:64
	global_load_dwordx4 v[214:217], v[224:225], off offset:128
	global_load_dwordx4 v[218:221], v[224:225], off offset:192
	s_waitcnt vmcnt(12)
	v_pk_fma_f32 v[30:31], v[30:31], v[118:119], v[192:193]
	v_pk_fma_f32 v[28:29], v[28:29], v[116:117], v[190:191]
	global_store_dwordx4 v[46:47], v[28:31], off
	v_lshl_add_u64 v[40:41], s[16:17], 0, v[40:41]
	v_lshl_add_u64 v[50:51], v[58:59], 1, v[40:41]
	v_pk_mul_f32 v[34:35], v[30:31], v[138:139]
	v_pk_mul_f32 v[32:33], v[28:29], v[136:137]
	v_pk_add_f32 v[38:39], v[154:155], 1.0 op_sel_hi:[1,0]
	v_pk_add_f32 v[36:37], v[152:153], 1.0 op_sel_hi:[1,0]
	v_pk_mul_f32 v[34:35], v[34:35], v[38:39]
	v_pk_mul_f32 v[32:33], v[32:33], v[36:37]
	v_and_b32_sdwa v39, v33, v170 dst_sel:DWORD dst_unused:UNUSED_PAD src0_sel:WORD_1 src1_sel:DWORD
	v_and_b32_sdwa v37, v32, v170 dst_sel:DWORD dst_unused:UNUSED_PAD src0_sel:WORD_1 src1_sel:DWORD
	v_add3_u32 v33, v33, v39, s56
	v_add3_u32 v32, v32, v37, s56
	v_and_b32_e32 v36, 0xffff0000, v33
	v_cvt_pk_bf16_f32 v33, v34, v35
	v_or_b32_sdwa v32, v36, v32 dst_sel:DWORD dst_unused:UNUSED_PAD src0_sel:DWORD src1_sel:WORD_1
	global_store_dwordx2 v[50:51], v[32:33], off
	s_nop 0
	v_pk_fma_f32 v[26:27], v[26:27], v[122:123], v[196:197]
	v_pk_fma_f32 v[24:25], v[24:25], v[120:121], v[194:195]
	global_store_dwordx4 v[46:47], v[24:27], off offset:64
	v_pk_mul_f32 v[34:35], v[26:27], v[142:143]
	v_pk_mul_f32 v[32:33], v[24:25], v[140:141]
	v_pk_add_f32 v[38:39], v[158:159], 1.0 op_sel_hi:[1,0]
	v_pk_add_f32 v[36:37], v[156:157], 1.0 op_sel_hi:[1,0]
	v_pk_mul_f32 v[34:35], v[34:35], v[38:39]
	v_pk_mul_f32 v[32:33], v[32:33], v[36:37]
	v_and_b32_sdwa v39, v33, v170 dst_sel:DWORD dst_unused:UNUSED_PAD src0_sel:WORD_1 src1_sel:DWORD
	v_and_b32_sdwa v37, v32, v170 dst_sel:DWORD dst_unused:UNUSED_PAD src0_sel:WORD_1 src1_sel:DWORD
	v_add3_u32 v33, v33, v39, s56
	v_add3_u32 v32, v32, v37, s56
	v_and_b32_e32 v36, 0xffff0000, v33
	v_cvt_pk_bf16_f32 v33, v34, v35
	v_or_b32_sdwa v32, v36, v32 dst_sel:DWORD dst_unused:UNUSED_PAD src0_sel:DWORD src1_sel:WORD_1
	global_store_dwordx2 v[50:51], v[32:33], off offset:32
	s_nop 0
	v_pk_fma_f32 v[22:23], v[22:23], v[126:127], v[200:201]
	v_pk_fma_f32 v[20:21], v[20:21], v[124:125], v[198:199]
	global_store_dwordx4 v[46:47], v[20:23], off offset:128
	v_pk_mul_f32 v[34:35], v[22:23], v[146:147]
	v_pk_mul_f32 v[32:33], v[20:21], v[144:145]
	v_pk_add_f32 v[38:39], v[162:163], 1.0 op_sel_hi:[1,0]
	v_pk_add_f32 v[36:37], v[160:161], 1.0 op_sel_hi:[1,0]
	v_pk_mul_f32 v[34:35], v[34:35], v[38:39]
	v_pk_mul_f32 v[32:33], v[32:33], v[36:37]
	v_and_b32_sdwa v39, v33, v170 dst_sel:DWORD dst_unused:UNUSED_PAD src0_sel:WORD_1 src1_sel:DWORD
	v_and_b32_sdwa v37, v32, v170 dst_sel:DWORD dst_unused:UNUSED_PAD src0_sel:WORD_1 src1_sel:DWORD
	v_add3_u32 v33, v33, v39, s56
	v_add3_u32 v32, v32, v37, s56
	v_and_b32_e32 v36, 0xffff0000, v33
	v_cvt_pk_bf16_f32 v33, v34, v35
	v_or_b32_sdwa v32, v36, v32 dst_sel:DWORD dst_unused:UNUSED_PAD src0_sel:DWORD src1_sel:WORD_1
	global_store_dwordx2 v[50:51], v[32:33], off offset:64
	s_nop 0
	v_pk_fma_f32 v[34:35], v[18:19], v[134:135], v[204:205]
	v_pk_fma_f32 v[32:33], v[16:17], v[132:133], v[202:203]
	global_store_dwordx4 v[46:47], v[32:35], off offset:192
	s_nop 0
	v_mul_f32_e32 v16, v29, v29
	v_mul_f32_e32 v17, v25, v25
	v_fmac_f32_e32 v16, v28, v28
	v_fmac_f32_e32 v17, v24, v24
	v_fmac_f32_e32 v16, v30, v30
	v_fmac_f32_e32 v17, v26, v26
	v_fmac_f32_e32 v16, v31, v31
	v_fmac_f32_e32 v17, v27, v27
	v_add_f32_e32 v16, v16, v17
	v_mul_f32_e32 v17, v21, v21
	v_fmac_f32_e32 v17, v20, v20
	v_fmac_f32_e32 v17, v22, v22
	v_fmac_f32_e32 v17, v23, v23
	v_add_f32_e32 v16, v16, v17
	v_mul_f32_e32 v17, v33, v33
	v_fmac_f32_e32 v17, v32, v32
	v_fmac_f32_e32 v17, v34, v34
	v_fmac_f32_e32 v17, v35, v35
	v_add_f32_e32 v16, v16, v17
	ds_bpermute_b32 v17, v105, v16
	s_waitcnt lgkmcnt(0)
	v_add_f32_e32 v16, v16, v17
	ds_bpermute_b32 v17, v104, v16
	v_pk_mul_f32 v[18:19], v[34:35], v[150:151]
	v_pk_mul_f32 v[20:21], v[32:33], v[148:149]
	v_pk_add_f32 v[22:23], v[182:183], 1.0 op_sel_hi:[1,0]
	v_pk_add_f32 v[24:25], v[180:181], 1.0 op_sel_hi:[1,0]
	v_pk_mul_f32 v[18:19], v[18:19], v[22:23]
	v_pk_mul_f32 v[20:21], v[20:21], v[24:25]
	v_cvt_pk_bf16_f32 v19, v18, v19
	v_cvt_pk_bf16_f32 v18, v20, v21
	global_store_dwordx2 v[50:51], v[18:19], off offset:96
	s_and_saveexec_b64 s[24:25], s[36:37]
	s_movk_i32 s8, 0x400
	s_mov_b32 s5, 0xffff0000
	s_mov_b32 s9, 0x12000
	s_movk_i32 s89, 0xff
	s_mov_b64 s[78:79], s[50:51]
	s_cbranch_execz .LBB0_99
	s_waitcnt lgkmcnt(0)
	v_add_f32_e32 v16, v16, v17
	global_store_dword v[48:49], v16, off offset:128
.LBB0_99:
	s_or_b64 exec, exec, s[24:25]
	v_add_u32_e32 v16, 0xffffe030, v64
	v_or_b32_e32 v24, 48, v62
	v_lshrrev_b32_e32 v16, 10, v16
	s_movk_i32 s16, 0x1800
	v_mad_u32_u24 v16, v16, s16, s16
	v_cmp_lt_i32_e32 vcc, s13, v24
	v_ashrrev_i32_e32 v25, 31, v24
	v_readlane_b32 s16, v250, 15
	v_cndmask_b32_e32 v16, 0, v16, vcc
	s_waitcnt lgkmcnt(0)
	v_ashrrev_i32_e32 v17, 31, v16
	v_lshlrev_b64 v[26:27], 2, v[16:17]
	v_lshl_add_u64 v[16:17], s[40:41], 0, v[26:27]
	v_lshl_add_u64 v[28:29], v[16:17], 0, v[60:61]
	v_lshlrev_b64 v[16:17], 12, v[24:25]
	v_readlane_b32 s17, v250, 16
	v_lshl_add_u64 v[26:27], s[42:43], 0, v[26:27]
	v_lshl_add_u64 v[26:27], v[26:27], 0, v[60:61]
	v_lshl_add_u64 v[16:17], s[16:17], 0, v[16:17]
	v_lshl_add_u64 v[30:31], v[16:17], 0, v[60:61]
	v_readlane_b32 s16, v250, 21
	v_lshlrev_b64 v[24:25], 11, v[24:25]
	v_readlane_b32 s17, v250, 22
	s_waitcnt vmcnt(8)
	v_pk_fma_f32 v[14:15], v[14:15], v[118:119], v[208:209]
	v_pk_fma_f32 v[12:13], v[12:13], v[116:117], v[206:207]
	global_store_dwordx4 v[30:31], v[12:15], off
	v_lshl_add_u64 v[24:25], s[16:17], 0, v[24:25]
	v_lshl_add_u64 v[32:33], v[58:59], 1, v[24:25]
	v_pk_mul_f32 v[18:19], v[14:15], v[138:139]
	v_pk_mul_f32 v[16:17], v[12:13], v[136:137]
	v_pk_add_f32 v[22:23], v[154:155], 1.0 op_sel_hi:[1,0]
	v_pk_add_f32 v[20:21], v[152:153], 1.0 op_sel_hi:[1,0]
	v_pk_mul_f32 v[18:19], v[18:19], v[22:23]
	v_pk_mul_f32 v[16:17], v[16:17], v[20:21]
	v_and_b32_sdwa v23, v17, v170 dst_sel:DWORD dst_unused:UNUSED_PAD src0_sel:WORD_1 src1_sel:DWORD
	v_and_b32_sdwa v21, v16, v170 dst_sel:DWORD dst_unused:UNUSED_PAD src0_sel:WORD_1 src1_sel:DWORD
	v_add3_u32 v17, v17, v23, s56
	v_add3_u32 v16, v16, v21, s56
	v_and_b32_e32 v20, 0xffff0000, v17
	v_cvt_pk_bf16_f32 v17, v18, v19
	v_or_b32_sdwa v16, v20, v16 dst_sel:DWORD dst_unused:UNUSED_PAD src0_sel:DWORD src1_sel:WORD_1
	global_store_dwordx2 v[32:33], v[16:17], off
	s_nop 0
	v_pk_fma_f32 v[10:11], v[10:11], v[122:123], v[212:213]
	v_pk_fma_f32 v[8:9], v[8:9], v[120:121], v[210:211]
	global_store_dwordx4 v[30:31], v[8:11], off offset:64
	v_pk_mul_f32 v[18:19], v[10:11], v[142:143]
	v_pk_mul_f32 v[16:17], v[8:9], v[140:141]
	v_pk_add_f32 v[22:23], v[158:159], 1.0 op_sel_hi:[1,0]
	v_pk_add_f32 v[20:21], v[156:157], 1.0 op_sel_hi:[1,0]
	v_pk_mul_f32 v[18:19], v[18:19], v[22:23]
	v_pk_mul_f32 v[16:17], v[16:17], v[20:21]
	v_and_b32_sdwa v23, v17, v170 dst_sel:DWORD dst_unused:UNUSED_PAD src0_sel:WORD_1 src1_sel:DWORD
	v_and_b32_sdwa v21, v16, v170 dst_sel:DWORD dst_unused:UNUSED_PAD src0_sel:WORD_1 src1_sel:DWORD
	v_add3_u32 v17, v17, v23, s56
	v_add3_u32 v16, v16, v21, s56
	v_and_b32_e32 v20, 0xffff0000, v17
	v_cvt_pk_bf16_f32 v17, v18, v19
	v_or_b32_sdwa v16, v20, v16 dst_sel:DWORD dst_unused:UNUSED_PAD src0_sel:DWORD src1_sel:WORD_1
	global_store_dwordx2 v[32:33], v[16:17], off offset:32
	s_nop 0
	v_pk_fma_f32 v[6:7], v[6:7], v[126:127], v[216:217]
	v_pk_fma_f32 v[4:5], v[4:5], v[124:125], v[214:215]
	global_store_dwordx4 v[30:31], v[4:7], off offset:128
	v_pk_mul_f32 v[18:19], v[6:7], v[146:147]
	v_pk_mul_f32 v[16:17], v[4:5], v[144:145]
	v_pk_add_f32 v[22:23], v[162:163], 1.0 op_sel_hi:[1,0]
	v_pk_add_f32 v[20:21], v[160:161], 1.0 op_sel_hi:[1,0]
	v_pk_mul_f32 v[18:19], v[18:19], v[22:23]
	v_pk_mul_f32 v[16:17], v[16:17], v[20:21]
	v_and_b32_sdwa v23, v17, v170 dst_sel:DWORD dst_unused:UNUSED_PAD src0_sel:WORD_1 src1_sel:DWORD
	v_and_b32_sdwa v21, v16, v170 dst_sel:DWORD dst_unused:UNUSED_PAD src0_sel:WORD_1 src1_sel:DWORD
	v_add3_u32 v17, v17, v23, s56
	v_add3_u32 v16, v16, v21, s56
	v_and_b32_e32 v20, 0xffff0000, v17
	v_cvt_pk_bf16_f32 v17, v18, v19
	v_or_b32_sdwa v16, v20, v16 dst_sel:DWORD dst_unused:UNUSED_PAD src0_sel:DWORD src1_sel:WORD_1
	global_store_dwordx2 v[32:33], v[16:17], off offset:64
	s_nop 0
	v_pk_fma_f32 v[18:19], v[2:3], v[134:135], v[220:221]
	v_pk_fma_f32 v[16:17], v[0:1], v[132:133], v[218:219]
	global_store_dwordx4 v[30:31], v[16:19], off offset:192
	s_nop 0
	v_mul_f32_e32 v0, v13, v13
	v_mul_f32_e32 v1, v9, v9
	v_fmac_f32_e32 v0, v12, v12
	v_fmac_f32_e32 v1, v8, v8
	v_fmac_f32_e32 v0, v14, v14
	v_fmac_f32_e32 v1, v10, v10
	v_fmac_f32_e32 v0, v15, v15
	v_fmac_f32_e32 v1, v11, v11
	v_add_f32_e32 v0, v0, v1
	v_mul_f32_e32 v1, v5, v5
	v_fmac_f32_e32 v1, v4, v4
	v_fmac_f32_e32 v1, v6, v6
	v_fmac_f32_e32 v1, v7, v7
	v_add_f32_e32 v0, v0, v1
	v_mul_f32_e32 v1, v17, v17
	v_fmac_f32_e32 v1, v16, v16
	v_fmac_f32_e32 v1, v18, v18
	v_fmac_f32_e32 v1, v19, v19
	v_add_f32_e32 v0, v0, v1
	ds_bpermute_b32 v1, v105, v0
	s_waitcnt lgkmcnt(0)
	v_add_f32_e32 v0, v0, v1
	ds_bpermute_b32 v1, v104, v0
	v_pk_mul_f32 v[2:3], v[18:19], v[150:151]
	v_pk_mul_f32 v[4:5], v[16:17], v[148:149]
	v_pk_add_f32 v[6:7], v[182:183], 1.0 op_sel_hi:[1,0]
	v_pk_add_f32 v[8:9], v[180:181], 1.0 op_sel_hi:[1,0]
	v_pk_mul_f32 v[2:3], v[2:3], v[6:7]
	v_pk_mul_f32 v[4:5], v[4:5], v[8:9]
	v_cvt_pk_bf16_f32 v3, v2, v3
	v_cvt_pk_bf16_f32 v2, v4, v5
	global_store_dwordx2 v[32:33], v[2:3], off offset:96
	s_and_saveexec_b64 s[24:25], s[36:37]
	s_cbranch_execz .LBB0_101
	s_waitcnt lgkmcnt(0)
	v_add_f32_e32 v0, v0, v1
	global_store_dword v[48:49], v0, off offset:192

.Ltail106:
	s_add_i32 s29, s44, 2
	ds_read_b128 v[136:139], v111 offset:16384
	ds_read_b128 v[140:143], v111 offset:18432
	ds_read_b128 v[144:147], v111 offset:20480
	ds_read_b128 v[148:151], v111 offset:22528
	ds_read_b128 v[116:119], v110
	s_add_i32 s44, s44, 4
	ds_read_b128 v[120:123], v110 offset:2048
	s_min_u32 s44, s44, 15
	s_lshl_b32 s92, s44, 7
	ds_read_b128 v[124:127], v110 offset:4096
	ds_read_b128 v[194:197], v113 offset:16384
	ds_read_b128 v[198:201], v113 offset:18432
	ds_read_b128 v[202:205], v113 offset:20480
	ds_read_b128 v[206:209], v113 offset:22528
	v_lshl_add_u64 v[164:165], v[100:101], 0, s[92:93]
	ds_read_b128 v[132:135], v110 offset:6144
	ds_read_b128 v[152:155], v112
	ds_read_b128 v[156:159], v112 offset:2048
	ds_read_b128 v[160:163], v112 offset:4096
	ds_read_b128 v[190:193], v112 offset:6144
	s_waitcnt lgkmcnt(11)
	v_mfma_f32_16x16x32_bf16 v[92:95], v[136:139], v[116:119], v[92:95]
	v_mfma_f32_16x16x32_bf16 v[88:91], v[140:143], v[116:119], v[88:91]
	v_mfma_f32_16x16x32_bf16 v[56:59], v[144:147], v[116:119], v[56:59]
	v_mfma_f32_16x16x32_bf16 v[48:51], v[148:151], v[116:119], v[48:51]
	s_waitcnt vmcnt(7)
	ds_write_b128 v109, v[52:55] offset:32768
	v_add_co_u32_e32 v52, vcc, s11, v164
	s_waitcnt lgkmcnt(11)
	v_mfma_f32_16x16x32_bf16 v[44:47], v[136:139], v[120:123], v[44:47]
	v_addc_co_u32_e32 v53, vcc, 0, v165, vcc
	v_mfma_f32_16x16x32_bf16 v[40:43], v[140:143], v[120:123], v[40:43]
	v_mfma_f32_16x16x32_bf16 v[36:39], v[144:147], v[120:123], v[36:39]
	v_mfma_f32_16x16x32_bf16 v[32:35], v[148:151], v[120:123], v[32:35]
	v_add_co_u32_e32 v52, vcc, s33, v164
	s_waitcnt vmcnt(6)
	ds_write_b128 v109, v[60:63] offset:36864
	s_nop 0
	v_addc_co_u32_e32 v53, vcc, 0, v165, vcc
	s_waitcnt lgkmcnt(11)
	v_mfma_f32_16x16x32_bf16 v[28:31], v[136:139], v[124:127], v[28:31]
	v_mfma_f32_16x16x32_bf16 v[24:27], v[140:143], v[124:127], v[24:27]
	v_mfma_f32_16x16x32_bf16 v[20:23], v[144:147], v[124:127], v[20:23]
	v_mfma_f32_16x16x32_bf16 v[16:19], v[148:151], v[124:127], v[16:19]
	v_add_co_u32_e32 v52, vcc, s59, v164
	s_waitcnt vmcnt(5)
	ds_write_b128 v109, v[64:67] offset:40960
	s_nop 0
	v_addc_co_u32_e32 v53, vcc, 0, v165, vcc
	v_lshl_add_u64 v[64:65], v[102:103], 0, s[92:93]
	v_add_co_u32_e32 v66, vcc, s11, v64
	s_waitcnt lgkmcnt(7)
	v_mfma_f32_16x16x32_bf16 v[12:15], v[136:139], v[132:135], v[12:15]
	v_addc_co_u32_e32 v67, vcc, 0, v65, vcc
	v_mfma_f32_16x16x32_bf16 v[8:11], v[140:143], v[132:135], v[8:11]
	v_mfma_f32_16x16x32_bf16 v[4:7], v[144:147], v[132:135], v[4:7]
	v_mfma_f32_16x16x32_bf16 v[0:3], v[148:151], v[132:135], v[0:3]
	s_waitcnt vmcnt(4)
	ds_write_b128 v109, v[72:75] offset:45056
	s_waitcnt lgkmcnt(7)
	v_mfma_f32_16x16x32_bf16 v[52:55], v[194:197], v[152:155], v[92:95]
	v_mfma_f32_16x16x32_bf16 v[60:63], v[198:201], v[152:155], v[88:91]
	v_mfma_f32_16x16x32_bf16 v[56:59], v[202:205], v[152:155], v[56:59]
	v_mfma_f32_16x16x32_bf16 v[48:51], v[206:209], v[152:155], v[48:51]
	s_waitcnt vmcnt(3)
	ds_write_b128 v109, v[68:71] offset:49152
	s_waitcnt lgkmcnt(7)
	v_mfma_f32_16x16x32_bf16 v[44:47], v[194:197], v[156:159], v[44:47]
	v_mfma_f32_16x16x32_bf16 v[40:43], v[198:201], v[156:159], v[40:43]
	v_mfma_f32_16x16x32_bf16 v[36:39], v[202:205], v[156:159], v[36:39]
	v_mfma_f32_16x16x32_bf16 v[32:35], v[206:209], v[156:159], v[32:35]
	v_add_co_u32_e32 v66, vcc, s33, v64
	s_waitcnt vmcnt(2)
	ds_write_b128 v109, v[76:79] offset:53248
	v_addc_co_u32_e32 v67, vcc, 0, v65, vcc
	v_add_co_u32_e32 v64, vcc, s59, v64
	s_waitcnt lgkmcnt(7)
	v_mfma_f32_16x16x32_bf16 v[28:31], v[194:197], v[160:163], v[28:31]
	v_addc_co_u32_e32 v65, vcc, 0, v65, vcc
	v_mfma_f32_16x16x32_bf16 v[24:27], v[198:201], v[160:163], v[24:27]
	v_mfma_f32_16x16x32_bf16 v[20:23], v[202:205], v[160:163], v[20:23]
	v_mfma_f32_16x16x32_bf16 v[16:19], v[206:209], v[160:163], v[16:19]
	s_waitcnt vmcnt(1)
	ds_write_b128 v109, v[80:83] offset:57344
	s_waitcnt lgkmcnt(7)
	v_mfma_f32_16x16x32_bf16 v[12:15], v[194:197], v[190:193], v[12:15]
	v_mfma_f32_16x16x32_bf16 v[8:11], v[198:201], v[190:193], v[8:11]
	v_mfma_f32_16x16x32_bf16 v[4:7], v[202:205], v[190:193], v[4:7]
	v_mfma_f32_16x16x32_bf16 v[0:3], v[206:209], v[190:193], v[0:3]
	s_waitcnt vmcnt(0)
	ds_write_b128 v109, v[84:87] offset:61440
	s_waitcnt lgkmcnt(0)
	s_barrier
	ds_read_b128 v[84:87], v111 offset:51200
	ds_read_b128 v[80:83], v111 offset:49152
	ds_read_b128 v[88:91], v111 offset:53248
	ds_read_b128 v[92:95], v111 offset:55296
	ds_read_b128 v[64:67], v110 offset:32768
	s_min_u32 s44, s29, 12
	s_lshl_b32 s92, s44, 7
	ds_read_b128 v[68:71], v110 offset:34816
	v_lshl_add_u64 v[164:165], v[100:101], 0, s[92:93]
	ds_read_b128 v[72:75], v110 offset:36864
	ds_read_b128 v[76:79], v110 offset:38912
	ds_read_b128 v[152:155], v112 offset:32768
	ds_read_b128 v[156:159], v112 offset:34816
	ds_read_b128 v[160:163], v112 offset:36864
	ds_read_b128 v[190:193], v112 offset:38912
	ds_read_b128 v[194:197], v113 offset:49152
	ds_read_b128 v[198:201], v113 offset:51200
	ds_read_b128 v[202:205], v113 offset:53248
	ds_read_b128 v[206:209], v113 offset:55296
	s_waitcnt lgkmcnt(11)
	v_mfma_f32_16x16x32_bf16 v[214:217], v[84:87], v[64:67], v[60:63]
	v_mfma_f32_16x16x32_bf16 v[210:213], v[80:83], v[64:67], v[52:55]
	s_nop 1
	v_add_co_u32_e32 v60, vcc, s11, v164
	s_nop 1
	v_addc_co_u32_e32 v61, vcc, 0, v165, vcc
	v_mfma_f32_16x16x32_bf16 v[56:59], v[88:91], v[64:67], v[56:59]
	v_mfma_f32_16x16x32_bf16 v[48:51], v[92:95], v[64:67], v[48:51]
	v_add_co_u32_e32 v64, vcc, s33, v164
	s_nop 0
	v_addc_co_u32_e32 v65, vcc, 0, v165, vcc
	s_waitcnt lgkmcnt(10)
	v_mfma_f32_16x16x32_bf16 v[44:47], v[80:83], v[68:71], v[44:47]
	v_mfma_f32_16x16x32_bf16 v[40:43], v[84:87], v[68:71], v[40:43]
	v_mfma_f32_16x16x32_bf16 v[36:39], v[88:91], v[68:71], v[36:39]
	v_mfma_f32_16x16x32_bf16 v[32:35], v[92:95], v[68:71], v[32:35]
	v_add_co_u32_e32 v68, vcc, s59, v164
	s_waitcnt lgkmcnt(9)
	v_mfma_f32_16x16x32_bf16 v[28:31], v[80:83], v[72:75], v[28:31]
	v_addc_co_u32_e32 v69, vcc, 0, v165, vcc
	v_mfma_f32_16x16x32_bf16 v[24:27], v[84:87], v[72:75], v[24:27]
	v_mfma_f32_16x16x32_bf16 v[20:23], v[88:91], v[72:75], v[20:23]
	v_mfma_f32_16x16x32_bf16 v[16:19], v[92:95], v[72:75], v[16:19]
	s_waitcnt lgkmcnt(8)
	v_mfma_f32_16x16x32_bf16 v[8:11], v[84:87], v[76:79], v[8:11]
	v_lshl_add_u64 v[84:85], v[102:103], 0, s[92:93]
	v_mfma_f32_16x16x32_bf16 v[12:15], v[80:83], v[76:79], v[12:15]
	v_mfma_f32_16x16x32_bf16 v[4:7], v[88:91], v[76:79], v[4:7]
	v_mfma_f32_16x16x32_bf16 v[0:3], v[92:95], v[76:79], v[0:3]
	v_add_co_u32_e32 v76, vcc, s11, v84
	s_nop 0
	v_addc_co_u32_e32 v77, vcc, 0, v85, vcc
	v_add_co_u32_e32 v80, vcc, s33, v84
	v_addc_co_u32_e32 v81, vcc, 0, v85, vcc
	s_waitcnt lgkmcnt(3)
	v_mfma_f32_16x16x32_bf16 v[92:95], v[194:197], v[152:155], v[210:213]
	s_waitcnt lgkmcnt(2)
	v_mfma_f32_16x16x32_bf16 v[88:91], v[198:201], v[152:155], v[214:217]
	s_waitcnt lgkmcnt(1)
	v_mfma_f32_16x16x32_bf16 v[56:59], v[202:205], v[152:155], v[56:59]
	s_waitcnt lgkmcnt(0)
	v_mfma_f32_16x16x32_bf16 v[48:51], v[206:209], v[152:155], v[48:51]
	v_add_co_u32_e32 v84, vcc, s59, v84
	v_addc_co_u32_e32 v85, vcc, 0, v85, vcc
	v_mfma_f32_16x16x32_bf16 v[44:47], v[194:197], v[156:159], v[44:47]
	v_mfma_f32_16x16x32_bf16 v[40:43], v[198:201], v[156:159], v[40:43]
	v_mfma_f32_16x16x32_bf16 v[36:39], v[202:205], v[156:159], v[36:39]
	v_mfma_f32_16x16x32_bf16 v[32:35], v[206:209], v[156:159], v[32:35]
	v_mfma_f32_16x16x32_bf16 v[28:31], v[194:197], v[160:163], v[28:31]
	v_mfma_f32_16x16x32_bf16 v[24:27], v[198:201], v[160:163], v[24:27]
	v_mfma_f32_16x16x32_bf16 v[20:23], v[202:205], v[160:163], v[20:23]
	v_mfma_f32_16x16x32_bf16 v[16:19], v[206:209], v[160:163], v[16:19]
	v_mfma_f32_16x16x32_bf16 v[12:15], v[194:197], v[190:193], v[12:15]
	v_mfma_f32_16x16x32_bf16 v[8:11], v[198:201], v[190:193], v[8:11]
	v_mfma_f32_16x16x32_bf16 v[4:7], v[202:205], v[190:193], v[4:7]
	v_mfma_f32_16x16x32_bf16 v[0:3], v[206:209], v[190:193], v[0:3]
	s_mov_b32 s44, s29
	s_waitcnt lgkmcnt(0)
	s_barrier
	s_waitcnt vmcnt(5)
	v_add_u32_e32 v64, s24, v108
	v_add_u32_e32 v52, 0xffffe000, v64
	v_or_b32_e32 v62, v64, v107
	v_lshrrev_b32_e32 v52, 10, v52
	s_movk_i32 s16, 0x1800
	v_mad_u32_u24 v52, v52, s16, s16
	v_cmp_lt_i32_e32 vcc, s13, v62
	v_or_b32_e32 v65, s25, v114
	v_or_b32_e32 v54, v65, v115
	v_cndmask_b32_e32 v52, 0, v52, vcc
	v_ashrrev_i32_e32 v53, 31, v52
	s_waitcnt vmcnt(4)
	v_lshlrev_b64 v[74:75], 2, v[52:53]
	v_ashrrev_i32_e32 v55, 31, v54
	v_ashrrev_i32_e32 v63, 31, v62
	v_lshl_add_u64 v[52:53], s[40:41], 0, v[74:75]
	v_lshlrev_b64 v[60:61], 2, v[54:55]
	v_readlane_b32 s16, v250, 15
	s_waitcnt vmcnt(1)
	v_lshl_add_u64 v[82:83], v[52:53], 0, v[60:61]
	v_lshlrev_b64 v[52:53], 12, v[62:63]
	v_readlane_b32 s17, v250, 16
	v_lshl_add_u64 v[74:75], s[42:43], 0, v[74:75]
	s_waitcnt vmcnt(0)
	v_lshl_add_u64 v[86:87], v[74:75], 0, v[60:61]
	v_lshl_add_u64 v[52:53], s[16:17], 0, v[52:53]
	v_lshl_add_u64 v[84:85], v[52:53], 0, v[60:61]
	global_load_dwordx4 v[66:69], v[82:83], off
	global_load_dwordx4 v[70:73], v[84:85], off
	v_lshl_add_u64 v[52:53], s[0:1], 0, v[60:61]
	v_readlane_b32 s16, v250, 21
	v_lshlrev_b64 v[78:79], 11, v[62:63]
	v_readlane_b32 s17, v250, 22
	s_waitcnt vmcnt(0)
	v_pk_fma_f32 v[68:69], v[94:95], v[68:69], v[72:73]
	v_pk_fma_f32 v[66:67], v[92:93], v[66:67], v[70:71]
	global_store_dwordx4 v[84:85], v[66:69], off
	global_load_dwordx4 v[70:73], v[52:53], off
	global_load_dwordx4 v[74:77], v[86:87], off
	v_lshl_add_u64 v[78:79], s[16:17], 0, v[78:79]
	v_lshl_add_u64 v[92:93], v[54:55], 1, v[78:79]
	s_mov_b32 s16, 0xa000
	s_waitcnt vmcnt(1)
	v_pk_mul_f32 v[72:73], v[68:69], v[72:73]
	v_pk_mul_f32 v[70:71], v[66:67], v[70:71]
	s_waitcnt vmcnt(0)
	v_pk_add_f32 v[76:77], v[76:77], 1.0 op_sel_hi:[1,0]
	v_pk_add_f32 v[74:75], v[74:75], 1.0 op_sel_hi:[1,0]
	v_pk_mul_f32 v[72:73], v[72:73], v[76:77]
	v_pk_mul_f32 v[70:71], v[70:71], v[74:75]
	v_and_b32_sdwa v77, v71, v170 dst_sel:DWORD dst_unused:UNUSED_PAD src0_sel:WORD_1 src1_sel:DWORD
	v_and_b32_sdwa v75, v70, v170 dst_sel:DWORD dst_unused:UNUSED_PAD src0_sel:WORD_1 src1_sel:DWORD
	v_add3_u32 v71, v71, v77, s56
	v_add3_u32 v70, v70, v75, s56
	v_and_b32_e32 v74, 0xffff0000, v71
	v_cvt_pk_bf16_f32 v71, v72, v73
	v_or_b32_sdwa v70, v74, v70 dst_sel:DWORD dst_unused:UNUSED_PAD src0_sel:DWORD src1_sel:WORD_1
	global_store_dwordx2 v[92:93], v[70:71], off
	global_load_dwordx4 v[70:73], v[82:83], off offset:64
	s_nop 0
	global_load_dwordx4 v[74:77], v[84:85], off offset:64
	s_waitcnt vmcnt(0)
	v_pk_fma_f32 v[72:73], v[90:91], v[72:73], v[76:77]
	v_pk_fma_f32 v[70:71], v[88:89], v[70:71], v[74:75]
	global_store_dwordx4 v[84:85], v[70:73], off offset:64
	global_load_dwordx4 v[74:77], v[52:53], off offset:64
	global_load_dwordx4 v[78:81], v[86:87], off offset:64
	s_waitcnt vmcnt(1)
	v_pk_mul_f32 v[76:77], v[72:73], v[76:77]
	v_pk_mul_f32 v[74:75], v[70:71], v[74:75]
	s_waitcnt vmcnt(0)
	v_pk_add_f32 v[80:81], v[80:81], 1.0 op_sel_hi:[1,0]
	v_pk_add_f32 v[78:79], v[78:79], 1.0 op_sel_hi:[1,0]
	v_pk_mul_f32 v[76:77], v[76:77], v[80:81]
	v_pk_mul_f32 v[74:75], v[74:75], v[78:79]
	v_and_b32_sdwa v81, v75, v170 dst_sel:DWORD dst_unused:UNUSED_PAD src0_sel:WORD_1 src1_sel:DWORD
	v_and_b32_sdwa v79, v74, v170 dst_sel:DWORD dst_unused:UNUSED_PAD src0_sel:WORD_1 src1_sel:DWORD
	v_add3_u32 v75, v75, v81, s56
	v_add3_u32 v74, v74, v79, s56
	v_and_b32_e32 v78, 0xffff0000, v75
	v_cvt_pk_bf16_f32 v75, v76, v77
	v_or_b32_sdwa v74, v78, v74 dst_sel:DWORD dst_unused:UNUSED_PAD src0_sel:DWORD src1_sel:WORD_1
	global_store_dwordx2 v[92:93], v[74:75], off offset:32
	global_load_dwordx4 v[74:77], v[82:83], off offset:128
	s_nop 0
	global_load_dwordx4 v[78:81], v[84:85], off offset:128
	s_waitcnt vmcnt(0)
	v_pk_fma_f32 v[58:59], v[58:59], v[76:77], v[80:81]
	v_pk_fma_f32 v[56:57], v[56:57], v[74:75], v[78:79]
	global_store_dwordx4 v[84:85], v[56:59], off offset:128
	global_load_dwordx4 v[74:77], v[52:53], off offset:128
	global_load_dwordx4 v[78:81], v[86:87], off offset:128
	s_waitcnt vmcnt(1)
	v_pk_mul_f32 v[76:77], v[58:59], v[76:77]
	v_pk_mul_f32 v[74:75], v[56:57], v[74:75]
	s_waitcnt vmcnt(0)
	v_pk_add_f32 v[80:81], v[80:81], 1.0 op_sel_hi:[1,0]
	v_pk_add_f32 v[78:79], v[78:79], 1.0 op_sel_hi:[1,0]
	v_pk_mul_f32 v[76:77], v[76:77], v[80:81]
	v_pk_mul_f32 v[74:75], v[74:75], v[78:79]
	v_and_b32_sdwa v81, v75, v170 dst_sel:DWORD dst_unused:UNUSED_PAD src0_sel:WORD_1 src1_sel:DWORD
	v_and_b32_sdwa v79, v74, v170 dst_sel:DWORD dst_unused:UNUSED_PAD src0_sel:WORD_1 src1_sel:DWORD
	v_add3_u32 v75, v75, v81, s56
	v_add3_u32 v74, v74, v79, s56
	v_and_b32_e32 v78, 0xffff0000, v75
	v_cvt_pk_bf16_f32 v75, v76, v77
	v_or_b32_sdwa v74, v78, v74 dst_sel:DWORD dst_unused:UNUSED_PAD src0_sel:DWORD src1_sel:WORD_1
	global_store_dwordx2 v[92:93], v[74:75], off offset:64
	global_load_dwordx4 v[74:77], v[82:83], off offset:192
	s_nop 0
	global_load_dwordx4 v[78:81], v[84:85], off offset:192
	s_waitcnt vmcnt(0)
	v_pk_fma_f32 v[76:77], v[50:51], v[76:77], v[80:81]
	v_pk_fma_f32 v[74:75], v[48:49], v[74:75], v[78:79]
	global_store_dwordx4 v[84:85], v[74:77], off offset:192
	global_load_dwordx4 v[78:81], v[52:53], off offset:192
	s_nop 0
	global_load_dwordx4 v[82:85], v[86:87], off offset:192
	v_mul_f32_e32 v48, v67, v67
	v_mul_f32_e32 v49, v71, v71
	v_fmac_f32_e32 v48, v66, v66
	v_fmac_f32_e32 v49, v70, v70
	v_fmac_f32_e32 v48, v68, v68
	v_fmac_f32_e32 v49, v72, v72
	v_fmac_f32_e32 v48, v69, v69
	v_fmac_f32_e32 v49, v73, v73
	v_add_f32_e32 v48, v48, v49
	v_mul_f32_e32 v49, v57, v57
	v_fmac_f32_e32 v49, v56, v56
	v_fmac_f32_e32 v49, v58, v58
	v_fmac_f32_e32 v49, v59, v59
	v_add_f32_e32 v48, v48, v49
	v_mul_f32_e32 v49, v75, v75
	v_fmac_f32_e32 v49, v74, v74
	v_fmac_f32_e32 v49, v76, v76
	v_fmac_f32_e32 v49, v77, v77
	v_add_f32_e32 v50, v48, v49
	ds_bpermute_b32 v51, v105, v50
	v_lshrrev_b32_e32 v48, 6, v65
	v_mul_lo_u32 v48, v48, s16
	v_ashrrev_i32_e32 v49, 31, v48
	v_lshl_add_u64 v[48:49], s[26:27], 0, v[48:49]
	s_waitcnt lgkmcnt(0)
	v_add_f32_e32 v50, v50, v51
	ds_bpermute_b32 v51, v104, v50
	v_lshl_add_u64 v[48:49], v[62:63], 2, v[48:49]
	s_waitcnt vmcnt(1)
	v_pk_mul_f32 v[56:57], v[76:77], v[80:81]
	v_pk_mul_f32 v[58:59], v[74:75], v[78:79]
	s_waitcnt vmcnt(0)
	v_pk_add_f32 v[66:67], v[84:85], 1.0 op_sel_hi:[1,0]
	v_pk_add_f32 v[68:69], v[82:83], 1.0 op_sel_hi:[1,0]
	v_pk_mul_f32 v[56:57], v[56:57], v[66:67]
	v_pk_mul_f32 v[58:59], v[58:59], v[68:69]
	v_cvt_pk_bf16_f32 v57, v56, v57
	v_cvt_pk_bf16_f32 v56, v58, v59
	global_store_dwordx2 v[92:93], v[56:57], off offset:96
	s_and_saveexec_b64 s[24:25], s[36:37]
	s_cbranch_execz .LBB0_109
	s_waitcnt lgkmcnt(0)
	v_add_f32_e32 v50, v50, v51
	global_store_dword v[48:49], v50, off
.LBB0_109:
	s_or_b64 exec, exec, s[24:25]
	s_waitcnt lgkmcnt(0)
	v_add_u32_e32 v51, 0xffffe010, v64
	v_or_b32_e32 v50, 16, v62
	v_lshrrev_b32_e32 v51, 10, v51
	s_movk_i32 s16, 0x1800
	v_mad_u32_u24 v51, v51, s16, s16
	v_cmp_lt_i32_e32 vcc, s13, v50
	v_readlane_b32 s16, v250, 15
	v_readlane_b32 s17, v250, 16
	v_cndmask_b32_e32 v56, 0, v51, vcc
	v_ashrrev_i32_e32 v57, 31, v56
	v_lshlrev_b64 v[70:71], 2, v[56:57]
	v_ashrrev_i32_e32 v51, 31, v50
	v_lshl_add_u64 v[56:57], s[40:41], 0, v[70:71]
	v_lshl_add_u64 v[72:73], v[56:57], 0, v[60:61]
	v_lshlrev_b64 v[56:57], 12, v[50:51]
	v_lshl_add_u64 v[56:57], s[16:17], 0, v[56:57]
	v_lshl_add_u64 v[74:75], v[56:57], 0, v[60:61]
	global_load_dwordx4 v[56:59], v[72:73], off
	global_load_dwordx4 v[66:69], v[74:75], off
	v_lshl_add_u64 v[70:71], s[42:43], 0, v[70:71]
	v_lshl_add_u64 v[70:71], v[70:71], 0, v[60:61]
	v_readlane_b32 s16, v250, 21
	v_lshlrev_b64 v[50:51], 11, v[50:51]
	v_readlane_b32 s17, v250, 22
	s_waitcnt vmcnt(0)
	v_pk_fma_f32 v[46:47], v[46:47], v[58:59], v[68:69]
	v_pk_fma_f32 v[44:45], v[44:45], v[56:57], v[66:67]
	global_store_dwordx4 v[74:75], v[44:47], off
	global_load_dwordx4 v[56:59], v[52:53], off
	global_load_dwordx4 v[66:69], v[70:71], off
	v_lshl_add_u64 v[50:51], s[16:17], 0, v[50:51]
	v_lshl_add_u64 v[50:51], v[54:55], 1, v[50:51]
	s_waitcnt vmcnt(1)
	v_pk_mul_f32 v[58:59], v[46:47], v[58:59]
	v_pk_mul_f32 v[56:57], v[44:45], v[56:57]
	s_waitcnt vmcnt(0)
	v_pk_add_f32 v[68:69], v[68:69], 1.0 op_sel_hi:[1,0]
	v_pk_add_f32 v[66:67], v[66:67], 1.0 op_sel_hi:[1,0]
	v_pk_mul_f32 v[58:59], v[58:59], v[68:69]
	v_pk_mul_f32 v[56:57], v[56:57], v[66:67]
	v_and_b32_sdwa v67, v57, v170 dst_sel:DWORD dst_unused:UNUSED_PAD src0_sel:WORD_1 src1_sel:DWORD
	v_and_b32_sdwa v65, v56, v170 dst_sel:DWORD dst_unused:UNUSED_PAD src0_sel:WORD_1 src1_sel:DWORD
	v_add3_u32 v57, v57, v67, s56
	v_add3_u32 v56, v56, v65, s56
	v_and_b32_e32 v63, 0xffff0000, v57
	v_cvt_pk_bf16_f32 v57, v58, v59
	v_or_b32_sdwa v56, v63, v56 dst_sel:DWORD dst_unused:UNUSED_PAD src0_sel:DWORD src1_sel:WORD_1
	global_store_dwordx2 v[50:51], v[56:57], off
	global_load_dwordx4 v[56:59], v[72:73], off offset:64
	s_nop 0
	global_load_dwordx4 v[66:69], v[74:75], off offset:64
	s_waitcnt vmcnt(0)
	v_pk_fma_f32 v[42:43], v[42:43], v[58:59], v[68:69]
	v_pk_fma_f32 v[40:41], v[40:41], v[56:57], v[66:67]
	global_store_dwordx4 v[74:75], v[40:43], off offset:64
	global_load_dwordx4 v[56:59], v[52:53], off offset:64
	global_load_dwordx4 v[66:69], v[70:71], off offset:64
	s_waitcnt vmcnt(1)
	v_pk_mul_f32 v[58:59], v[42:43], v[58:59]
	v_pk_mul_f32 v[56:57], v[40:41], v[56:57]
	s_waitcnt vmcnt(0)
	v_pk_add_f32 v[68:69], v[68:69], 1.0 op_sel_hi:[1,0]
	v_pk_add_f32 v[66:67], v[66:67], 1.0 op_sel_hi:[1,0]
	v_pk_mul_f32 v[58:59], v[58:59], v[68:69]
	v_pk_mul_f32 v[56:57], v[56:57], v[66:67]
	v_and_b32_sdwa v67, v57, v170 dst_sel:DWORD dst_unused:UNUSED_PAD src0_sel:WORD_1 src1_sel:DWORD
	v_and_b32_sdwa v65, v56, v170 dst_sel:DWORD dst_unused:UNUSED_PAD src0_sel:WORD_1 src1_sel:DWORD
	v_add3_u32 v57, v57, v67, s56
	v_add3_u32 v56, v56, v65, s56
	v_and_b32_e32 v63, 0xffff0000, v57
	v_cvt_pk_bf16_f32 v57, v58, v59
	v_or_b32_sdwa v56, v63, v56 dst_sel:DWORD dst_unused:UNUSED_PAD src0_sel:DWORD src1_sel:WORD_1
	global_store_dwordx2 v[50:51], v[56:57], off offset:32
	global_load_dwordx4 v[56:59], v[72:73], off offset:128
	s_nop 0
	global_load_dwordx4 v[66:69], v[74:75], off offset:128
	s_waitcnt vmcnt(0)
	v_pk_fma_f32 v[38:39], v[38:39], v[58:59], v[68:69]
	v_pk_fma_f32 v[36:37], v[36:37], v[56:57], v[66:67]
	global_store_dwordx4 v[74:75], v[36:39], off offset:128
	global_load_dwordx4 v[56:59], v[52:53], off offset:128
	global_load_dwordx4 v[66:69], v[70:71], off offset:128
	s_waitcnt vmcnt(1)
	v_pk_mul_f32 v[58:59], v[38:39], v[58:59]
	v_pk_mul_f32 v[56:57], v[36:37], v[56:57]
	s_waitcnt vmcnt(0)
	v_pk_add_f32 v[68:69], v[68:69], 1.0 op_sel_hi:[1,0]
	v_pk_add_f32 v[66:67], v[66:67], 1.0 op_sel_hi:[1,0]
	v_pk_mul_f32 v[58:59], v[58:59], v[68:69]
	v_pk_mul_f32 v[56:57], v[56:57], v[66:67]
	v_and_b32_sdwa v67, v57, v170 dst_sel:DWORD dst_unused:UNUSED_PAD src0_sel:WORD_1 src1_sel:DWORD
	v_and_b32_sdwa v65, v56, v170 dst_sel:DWORD dst_unused:UNUSED_PAD src0_sel:WORD_1 src1_sel:DWORD
	v_add3_u32 v57, v57, v67, s56
	v_add3_u32 v56, v56, v65, s56
	v_and_b32_e32 v63, 0xffff0000, v57
	v_cvt_pk_bf16_f32 v57, v58, v59
	v_or_b32_sdwa v56, v63, v56 dst_sel:DWORD dst_unused:UNUSED_PAD src0_sel:DWORD src1_sel:WORD_1
	global_store_dwordx2 v[50:51], v[56:57], off offset:64
	global_load_dwordx4 v[56:59], v[72:73], off offset:192
	s_nop 0
	global_load_dwordx4 v[66:69], v[74:75], off offset:192
	s_waitcnt vmcnt(0)
	v_pk_fma_f32 v[58:59], v[34:35], v[58:59], v[68:69]
	v_pk_fma_f32 v[56:57], v[32:33], v[56:57], v[66:67]
	global_store_dwordx4 v[74:75], v[56:59], off offset:192
	global_load_dwordx4 v[66:69], v[52:53], off offset:192
	s_nop 0
	global_load_dwordx4 v[70:73], v[70:71], off offset:192
	v_mul_f32_e32 v32, v45, v45
	v_mul_f32_e32 v33, v41, v41
	v_fmac_f32_e32 v32, v44, v44
	v_fmac_f32_e32 v33, v40, v40
	v_fmac_f32_e32 v32, v46, v46
	v_fmac_f32_e32 v33, v42, v42
	v_fmac_f32_e32 v32, v47, v47
	v_fmac_f32_e32 v33, v43, v43
	v_add_f32_e32 v32, v32, v33
	v_mul_f32_e32 v33, v37, v37
	v_fmac_f32_e32 v33, v36, v36
	v_fmac_f32_e32 v33, v38, v38
	v_fmac_f32_e32 v33, v39, v39
	v_add_f32_e32 v32, v32, v33
	v_mul_f32_e32 v33, v57, v57
	v_fmac_f32_e32 v33, v56, v56
	v_fmac_f32_e32 v33, v58, v58
	v_fmac_f32_e32 v33, v59, v59
	v_add_f32_e32 v32, v32, v33
	ds_bpermute_b32 v33, v105, v32
	s_waitcnt lgkmcnt(0)
	v_add_f32_e32 v32, v32, v33
	ds_bpermute_b32 v33, v104, v32
	s_waitcnt vmcnt(1)
	v_pk_mul_f32 v[34:35], v[58:59], v[68:69]
	v_pk_mul_f32 v[36:37], v[56:57], v[66:67]
	s_waitcnt vmcnt(0)
	v_pk_add_f32 v[38:39], v[72:73], 1.0 op_sel_hi:[1,0]
	v_pk_add_f32 v[40:41], v[70:71], 1.0 op_sel_hi:[1,0]
	v_pk_mul_f32 v[34:35], v[34:35], v[38:39]
	v_pk_mul_f32 v[36:37], v[36:37], v[40:41]
	v_cvt_pk_bf16_f32 v35, v34, v35
	v_cvt_pk_bf16_f32 v34, v36, v37
	global_store_dwordx2 v[50:51], v[34:35], off offset:96
	s_and_saveexec_b64 s[24:25], s[36:37]
	s_cbranch_execz .LBB0_111
	s_waitcnt lgkmcnt(0)
	v_add_f32_e32 v32, v32, v33
	global_store_dword v[48:49], v32, off offset:64
.LBB0_111:
	s_or_b64 exec, exec, s[24:25]
	v_add_u32_e32 v32, 0xffffe020, v64
	v_or_b32_e32 v40, 32, v62
	v_lshrrev_b32_e32 v32, 10, v32
	s_movk_i32 s16, 0x1800
	v_mad_u32_u24 v32, v32, s16, s16
	v_cmp_lt_i32_e32 vcc, s13, v40
	v_ashrrev_i32_e32 v41, 31, v40
	v_readlane_b32 s16, v250, 15
	v_cndmask_b32_e32 v32, 0, v32, vcc
	s_waitcnt lgkmcnt(0)
	v_ashrrev_i32_e32 v33, 31, v32
	v_lshlrev_b64 v[42:43], 2, v[32:33]
	v_lshl_add_u64 v[32:33], s[40:41], 0, v[42:43]
	v_lshl_add_u64 v[44:45], v[32:33], 0, v[60:61]
	v_lshlrev_b64 v[32:33], 12, v[40:41]
	v_readlane_b32 s17, v250, 16
	v_lshl_add_u64 v[42:43], s[42:43], 0, v[42:43]
	v_lshl_add_u64 v[42:43], v[42:43], 0, v[60:61]
	v_lshl_add_u64 v[32:33], s[16:17], 0, v[32:33]
	v_lshl_add_u64 v[46:47], v[32:33], 0, v[60:61]
	global_load_dwordx4 v[32:35], v[44:45], off
	global_load_dwordx4 v[36:39], v[46:47], off
	v_readlane_b32 s16, v250, 21
	v_lshlrev_b64 v[40:41], 11, v[40:41]
	v_readlane_b32 s17, v250, 22
	s_waitcnt vmcnt(0)
	v_pk_fma_f32 v[30:31], v[30:31], v[34:35], v[38:39]
	v_pk_fma_f32 v[28:29], v[28:29], v[32:33], v[36:37]
	global_store_dwordx4 v[46:47], v[28:31], off
	global_load_dwordx4 v[32:35], v[52:53], off
	global_load_dwordx4 v[36:39], v[42:43], off
	v_lshl_add_u64 v[40:41], s[16:17], 0, v[40:41]
	v_lshl_add_u64 v[50:51], v[54:55], 1, v[40:41]
	s_waitcnt vmcnt(1)
	v_pk_mul_f32 v[34:35], v[30:31], v[34:35]
	v_pk_mul_f32 v[32:33], v[28:29], v[32:33]
	s_waitcnt vmcnt(0)
	v_pk_add_f32 v[38:39], v[38:39], 1.0 op_sel_hi:[1,0]
	v_pk_add_f32 v[36:37], v[36:37], 1.0 op_sel_hi:[1,0]
	v_pk_mul_f32 v[34:35], v[34:35], v[38:39]
	v_pk_mul_f32 v[32:33], v[32:33], v[36:37]
	v_and_b32_sdwa v39, v33, v170 dst_sel:DWORD dst_unused:UNUSED_PAD src0_sel:WORD_1 src1_sel:DWORD
	v_and_b32_sdwa v37, v32, v170 dst_sel:DWORD dst_unused:UNUSED_PAD src0_sel:WORD_1 src1_sel:DWORD
	v_add3_u32 v33, v33, v39, s56
	v_add3_u32 v32, v32, v37, s56
	v_and_b32_e32 v36, 0xffff0000, v33
	v_cvt_pk_bf16_f32 v33, v34, v35
	v_or_b32_sdwa v32, v36, v32 dst_sel:DWORD dst_unused:UNUSED_PAD src0_sel:DWORD src1_sel:WORD_1
	global_store_dwordx2 v[50:51], v[32:33], off
	global_load_dwordx4 v[32:35], v[44:45], off offset:64
	s_nop 0
	global_load_dwordx4 v[36:39], v[46:47], off offset:64
	s_waitcnt vmcnt(0)
	v_pk_fma_f32 v[26:27], v[26:27], v[34:35], v[38:39]
	v_pk_fma_f32 v[24:25], v[24:25], v[32:33], v[36:37]
	global_store_dwordx4 v[46:47], v[24:27], off offset:64
	global_load_dwordx4 v[32:35], v[52:53], off offset:64
	global_load_dwordx4 v[36:39], v[42:43], off offset:64
	s_waitcnt vmcnt(1)
	v_pk_mul_f32 v[34:35], v[26:27], v[34:35]
	v_pk_mul_f32 v[32:33], v[24:25], v[32:33]
	s_waitcnt vmcnt(0)
	v_pk_add_f32 v[38:39], v[38:39], 1.0 op_sel_hi:[1,0]
	v_pk_add_f32 v[36:37], v[36:37], 1.0 op_sel_hi:[1,0]
	v_pk_mul_f32 v[34:35], v[34:35], v[38:39]
	v_pk_mul_f32 v[32:33], v[32:33], v[36:37]
	v_and_b32_sdwa v39, v33, v170 dst_sel:DWORD dst_unused:UNUSED_PAD src0_sel:WORD_1 src1_sel:DWORD
	v_and_b32_sdwa v37, v32, v170 dst_sel:DWORD dst_unused:UNUSED_PAD src0_sel:WORD_1 src1_sel:DWORD
	v_add3_u32 v33, v33, v39, s56
	v_add3_u32 v32, v32, v37, s56
	v_and_b32_e32 v36, 0xffff0000, v33
	v_cvt_pk_bf16_f32 v33, v34, v35
	v_or_b32_sdwa v32, v36, v32 dst_sel:DWORD dst_unused:UNUSED_PAD src0_sel:DWORD src1_sel:WORD_1
	global_store_dwordx2 v[50:51], v[32:33], off offset:32
	global_load_dwordx4 v[32:35], v[44:45], off offset:128
	s_nop 0
	global_load_dwordx4 v[36:39], v[46:47], off offset:128
	s_waitcnt vmcnt(0)
	v_pk_fma_f32 v[22:23], v[22:23], v[34:35], v[38:39]
	v_pk_fma_f32 v[20:21], v[20:21], v[32:33], v[36:37]
	global_store_dwordx4 v[46:47], v[20:23], off offset:128
	global_load_dwordx4 v[32:35], v[52:53], off offset:128
	global_load_dwordx4 v[36:39], v[42:43], off offset:128
	s_waitcnt vmcnt(1)
	v_pk_mul_f32 v[34:35], v[22:23], v[34:35]
	v_pk_mul_f32 v[32:33], v[20:21], v[32:33]
	s_waitcnt vmcnt(0)
	v_pk_add_f32 v[38:39], v[38:39], 1.0 op_sel_hi:[1,0]
	v_pk_add_f32 v[36:37], v[36:37], 1.0 op_sel_hi:[1,0]
	v_pk_mul_f32 v[34:35], v[34:35], v[38:39]
	v_pk_mul_f32 v[32:33], v[32:33], v[36:37]
	v_and_b32_sdwa v39, v33, v170 dst_sel:DWORD dst_unused:UNUSED_PAD src0_sel:WORD_1 src1_sel:DWORD
	v_and_b32_sdwa v37, v32, v170 dst_sel:DWORD dst_unused:UNUSED_PAD src0_sel:WORD_1 src1_sel:DWORD
	v_add3_u32 v33, v33, v39, s56
	v_add3_u32 v32, v32, v37, s56
	v_and_b32_e32 v36, 0xffff0000, v33
	v_cvt_pk_bf16_f32 v33, v34, v35
	v_or_b32_sdwa v32, v36, v32 dst_sel:DWORD dst_unused:UNUSED_PAD src0_sel:DWORD src1_sel:WORD_1
	global_store_dwordx2 v[50:51], v[32:33], off offset:64
	global_load_dwordx4 v[32:35], v[44:45], off offset:192
	s_nop 0
	global_load_dwordx4 v[36:39], v[46:47], off offset:192
	s_waitcnt vmcnt(0)
	v_pk_fma_f32 v[34:35], v[18:19], v[34:35], v[38:39]
	v_pk_fma_f32 v[32:33], v[16:17], v[32:33], v[36:37]
	global_store_dwordx4 v[46:47], v[32:35], off offset:192
	global_load_dwordx4 v[36:39], v[52:53], off offset:192
	s_nop 0
	global_load_dwordx4 v[40:43], v[42:43], off offset:192
	v_mul_f32_e32 v16, v29, v29
	v_mul_f32_e32 v17, v25, v25
	v_fmac_f32_e32 v16, v28, v28
	v_fmac_f32_e32 v17, v24, v24
	v_fmac_f32_e32 v16, v30, v30
	v_fmac_f32_e32 v17, v26, v26
	v_fmac_f32_e32 v16, v31, v31
	v_fmac_f32_e32 v17, v27, v27
	v_add_f32_e32 v16, v16, v17
	v_mul_f32_e32 v17, v21, v21
	v_fmac_f32_e32 v17, v20, v20
	v_fmac_f32_e32 v17, v22, v22
	v_fmac_f32_e32 v17, v23, v23
	v_add_f32_e32 v16, v16, v17
	v_mul_f32_e32 v17, v33, v33
	v_fmac_f32_e32 v17, v32, v32
	v_fmac_f32_e32 v17, v34, v34
	v_fmac_f32_e32 v17, v35, v35
	v_add_f32_e32 v16, v16, v17
	ds_bpermute_b32 v17, v105, v16
	s_waitcnt lgkmcnt(0)
	v_add_f32_e32 v16, v16, v17
	ds_bpermute_b32 v17, v104, v16
	s_waitcnt vmcnt(1)
	v_pk_mul_f32 v[18:19], v[34:35], v[38:39]
	v_pk_mul_f32 v[20:21], v[32:33], v[36:37]
	s_waitcnt vmcnt(0)
	v_pk_add_f32 v[22:23], v[42:43], 1.0 op_sel_hi:[1,0]
	v_pk_add_f32 v[24:25], v[40:41], 1.0 op_sel_hi:[1,0]
	v_pk_mul_f32 v[18:19], v[18:19], v[22:23]
	v_pk_mul_f32 v[20:21], v[20:21], v[24:25]
	v_cvt_pk_bf16_f32 v19, v18, v19
	v_cvt_pk_bf16_f32 v18, v20, v21
	global_store_dwordx2 v[50:51], v[18:19], off offset:96
	s_and_saveexec_b64 s[24:25], s[36:37]
	s_movk_i32 s89, 0xff
	s_cbranch_execz .LBB0_113
	s_waitcnt lgkmcnt(0)
	v_add_f32_e32 v16, v16, v17
	global_store_dword v[48:49], v16, off offset:128
.LBB0_113:
	s_or_b64 exec, exec, s[24:25]
	v_add_u32_e32 v16, 0xffffe030, v64
	v_or_b32_e32 v24, 48, v62
	v_lshrrev_b32_e32 v16, 10, v16
	s_movk_i32 s16, 0x1800
	v_mad_u32_u24 v16, v16, s16, s16
	v_cmp_lt_i32_e32 vcc, s13, v24
	v_ashrrev_i32_e32 v25, 31, v24
	v_readlane_b32 s16, v250, 15
	v_cndmask_b32_e32 v16, 0, v16, vcc
	s_waitcnt lgkmcnt(0)
	v_ashrrev_i32_e32 v17, 31, v16
	v_lshlrev_b64 v[26:27], 2, v[16:17]
	v_lshl_add_u64 v[16:17], s[40:41], 0, v[26:27]
	v_lshl_add_u64 v[28:29], v[16:17], 0, v[60:61]
	v_lshlrev_b64 v[16:17], 12, v[24:25]
	v_readlane_b32 s17, v250, 16
	v_lshl_add_u64 v[26:27], s[42:43], 0, v[26:27]
	v_lshl_add_u64 v[26:27], v[26:27], 0, v[60:61]
	v_lshl_add_u64 v[16:17], s[16:17], 0, v[16:17]
	v_lshl_add_u64 v[30:31], v[16:17], 0, v[60:61]
	global_load_dwordx4 v[16:19], v[28:29], off
	global_load_dwordx4 v[20:23], v[30:31], off
	v_readlane_b32 s16, v250, 21
	v_lshlrev_b64 v[24:25], 11, v[24:25]
	v_readlane_b32 s17, v250, 22
	s_waitcnt vmcnt(0)
	v_pk_fma_f32 v[14:15], v[14:15], v[18:19], v[22:23]
	v_pk_fma_f32 v[12:13], v[12:13], v[16:17], v[20:21]
	global_store_dwordx4 v[30:31], v[12:15], off
	global_load_dwordx4 v[16:19], v[52:53], off
	global_load_dwordx4 v[20:23], v[26:27], off
	v_lshl_add_u64 v[24:25], s[16:17], 0, v[24:25]
	v_lshl_add_u64 v[32:33], v[54:55], 1, v[24:25]
	s_waitcnt vmcnt(1)
	v_pk_mul_f32 v[18:19], v[14:15], v[18:19]
	v_pk_mul_f32 v[16:17], v[12:13], v[16:17]
	s_waitcnt vmcnt(0)
	v_pk_add_f32 v[22:23], v[22:23], 1.0 op_sel_hi:[1,0]
	v_pk_add_f32 v[20:21], v[20:21], 1.0 op_sel_hi:[1,0]
	v_pk_mul_f32 v[18:19], v[18:19], v[22:23]
	v_pk_mul_f32 v[16:17], v[16:17], v[20:21]
	v_and_b32_sdwa v23, v17, v170 dst_sel:DWORD dst_unused:UNUSED_PAD src0_sel:WORD_1 src1_sel:DWORD
	v_and_b32_sdwa v21, v16, v170 dst_sel:DWORD dst_unused:UNUSED_PAD src0_sel:WORD_1 src1_sel:DWORD
	v_add3_u32 v17, v17, v23, s56
	v_add3_u32 v16, v16, v21, s56
	v_and_b32_e32 v20, 0xffff0000, v17
	v_cvt_pk_bf16_f32 v17, v18, v19
	v_or_b32_sdwa v16, v20, v16 dst_sel:DWORD dst_unused:UNUSED_PAD src0_sel:DWORD src1_sel:WORD_1
	global_store_dwordx2 v[32:33], v[16:17], off
	global_load_dwordx4 v[16:19], v[28:29], off offset:64
	s_nop 0
	global_load_dwordx4 v[20:23], v[30:31], off offset:64
	s_waitcnt vmcnt(0)
	v_pk_fma_f32 v[10:11], v[10:11], v[18:19], v[22:23]
	v_pk_fma_f32 v[8:9], v[8:9], v[16:17], v[20:21]
	global_store_dwordx4 v[30:31], v[8:11], off offset:64
	global_load_dwordx4 v[16:19], v[52:53], off offset:64
	global_load_dwordx4 v[20:23], v[26:27], off offset:64
	s_waitcnt vmcnt(1)
	v_pk_mul_f32 v[18:19], v[10:11], v[18:19]
	v_pk_mul_f32 v[16:17], v[8:9], v[16:17]
	s_waitcnt vmcnt(0)
	v_pk_add_f32 v[22:23], v[22:23], 1.0 op_sel_hi:[1,0]
	v_pk_add_f32 v[20:21], v[20:21], 1.0 op_sel_hi:[1,0]
	v_pk_mul_f32 v[18:19], v[18:19], v[22:23]
	v_pk_mul_f32 v[16:17], v[16:17], v[20:21]
	v_and_b32_sdwa v23, v17, v170 dst_sel:DWORD dst_unused:UNUSED_PAD src0_sel:WORD_1 src1_sel:DWORD
	v_and_b32_sdwa v21, v16, v170 dst_sel:DWORD dst_unused:UNUSED_PAD src0_sel:WORD_1 src1_sel:DWORD
	v_add3_u32 v17, v17, v23, s56
	v_add3_u32 v16, v16, v21, s56
	v_and_b32_e32 v20, 0xffff0000, v17
	v_cvt_pk_bf16_f32 v17, v18, v19
	v_or_b32_sdwa v16, v20, v16 dst_sel:DWORD dst_unused:UNUSED_PAD src0_sel:DWORD src1_sel:WORD_1
	global_store_dwordx2 v[32:33], v[16:17], off offset:32
	global_load_dwordx4 v[16:19], v[28:29], off offset:128
	s_nop 0
	global_load_dwordx4 v[20:23], v[30:31], off offset:128
	s_waitcnt vmcnt(0)
	v_pk_fma_f32 v[6:7], v[6:7], v[18:19], v[22:23]
	v_pk_fma_f32 v[4:5], v[4:5], v[16:17], v[20:21]
	global_store_dwordx4 v[30:31], v[4:7], off offset:128
	global_load_dwordx4 v[16:19], v[52:53], off offset:128
	global_load_dwordx4 v[20:23], v[26:27], off offset:128
	s_waitcnt vmcnt(1)
	v_pk_mul_f32 v[18:19], v[6:7], v[18:19]
	v_pk_mul_f32 v[16:17], v[4:5], v[16:17]
	s_waitcnt vmcnt(0)
	v_pk_add_f32 v[22:23], v[22:23], 1.0 op_sel_hi:[1,0]
	v_pk_add_f32 v[20:21], v[20:21], 1.0 op_sel_hi:[1,0]
	v_pk_mul_f32 v[18:19], v[18:19], v[22:23]
	v_pk_mul_f32 v[16:17], v[16:17], v[20:21]
	v_and_b32_sdwa v23, v17, v170 dst_sel:DWORD dst_unused:UNUSED_PAD src0_sel:WORD_1 src1_sel:DWORD
	v_and_b32_sdwa v21, v16, v170 dst_sel:DWORD dst_unused:UNUSED_PAD src0_sel:WORD_1 src1_sel:DWORD
	v_add3_u32 v17, v17, v23, s56
	v_add3_u32 v16, v16, v21, s56
	v_and_b32_e32 v20, 0xffff0000, v17
	v_cvt_pk_bf16_f32 v17, v18, v19
	v_or_b32_sdwa v16, v20, v16 dst_sel:DWORD dst_unused:UNUSED_PAD src0_sel:DWORD src1_sel:WORD_1
	global_store_dwordx2 v[32:33], v[16:17], off offset:64
	global_load_dwordx4 v[16:19], v[28:29], off offset:192
	s_nop 0
	global_load_dwordx4 v[20:23], v[30:31], off offset:192
	s_waitcnt vmcnt(0)
	v_pk_fma_f32 v[18:19], v[2:3], v[18:19], v[22:23]
	v_pk_fma_f32 v[16:17], v[0:1], v[16:17], v[20:21]
	global_store_dwordx4 v[30:31], v[16:19], off offset:192
	global_load_dwordx4 v[20:23], v[52:53], off offset:192
	s_nop 0
	global_load_dwordx4 v[24:27], v[26:27], off offset:192
	v_mul_f32_e32 v0, v13, v13
	v_mul_f32_e32 v1, v9, v9
	v_fmac_f32_e32 v0, v12, v12
	v_fmac_f32_e32 v1, v8, v8
	v_fmac_f32_e32 v0, v14, v14
	v_fmac_f32_e32 v1, v10, v10
	v_fmac_f32_e32 v0, v15, v15
	v_fmac_f32_e32 v1, v11, v11
	v_add_f32_e32 v0, v0, v1
	v_mul_f32_e32 v1, v5, v5
	v_fmac_f32_e32 v1, v4, v4
	v_fmac_f32_e32 v1, v6, v6
	v_fmac_f32_e32 v1, v7, v7
	v_add_f32_e32 v0, v0, v1
	v_mul_f32_e32 v1, v17, v17
	v_fmac_f32_e32 v1, v16, v16
	v_fmac_f32_e32 v1, v18, v18
	v_fmac_f32_e32 v1, v19, v19
	v_add_f32_e32 v0, v0, v1
	ds_bpermute_b32 v1, v105, v0
	s_waitcnt lgkmcnt(0)
	v_add_f32_e32 v0, v0, v1
	ds_bpermute_b32 v1, v104, v0
	s_waitcnt vmcnt(1)
	v_pk_mul_f32 v[2:3], v[18:19], v[22:23]
	v_pk_mul_f32 v[4:5], v[16:17], v[20:21]
	s_waitcnt vmcnt(0)
	v_pk_add_f32 v[6:7], v[26:27], 1.0 op_sel_hi:[1,0]
	v_pk_add_f32 v[8:9], v[24:25], 1.0 op_sel_hi:[1,0]
	v_pk_mul_f32 v[2:3], v[2:3], v[6:7]
	v_pk_mul_f32 v[4:5], v[4:5], v[8:9]
	v_cvt_pk_bf16_f32 v3, v2, v3
	v_cvt_pk_bf16_f32 v2, v4, v5
	global_store_dwordx2 v[32:33], v[2:3], off offset:96
	s_and_saveexec_b64 s[24:25], s[36:37]
	s_cbranch_execz .LBB0_104
	s_waitcnt lgkmcnt(0)
	v_add_f32_e32 v0, v0, v1
	global_store_dword v[48:49], v0, off offset:192
	s_branch .LBB0_104

.LBB0_122:
	s_or_b64 exec, exec, s[2:3]
	v_add_u32_e32 v13, 0xffffe010, v18
	s_waitcnt lgkmcnt(0)
	v_lshl_add_u64 v[14:15], s[0:1], 0, v[128:129]
	v_or_b32_e32 v12, 16, v12
	v_lshrrev_b32_e32 v13, 10, v13
	s_movk_i32 s0, 0x1800
	v_mad_u32_u24 v13, v13, s0, s0
	v_cmp_lt_i32_e64 s[0:1], s13, v12
	s_nop 1
	v_cndmask_b32_e64 v18, 0, v13, s[0:1]
	v_ashrrev_i32_e32 v19, 31, v18
	v_lshlrev_b64 v[34:35], 2, v[18:19]
	v_ashrrev_i32_e32 v13, 31, v12
	v_lshl_add_u64 v[18:19], s[40:41], 0, v[34:35]
	v_readlane_b32 s0, v250, 15
	v_lshl_add_u64 v[20:21], v[18:19], 0, v[128:129]
	v_lshlrev_b64 v[18:19], 12, v[12:13]
	v_readlane_b32 s1, v250, 16
	s_nop 0
	v_lshl_add_u64 v[18:19], s[0:1], 0, v[18:19]
	v_lshl_add_u64 v[18:19], v[18:19], 0, v[128:129]
	v_readlane_b32 s0, v250, 21
	v_readlane_b32 s1, v250, 22
	s_waitcnt vmcnt(16)
	v_pk_fma_f32 v[28:29], v[38:39], v[74:75], v[212:213]
	v_pk_fma_f32 v[26:27], v[36:37], v[72:73], v[210:211]
	v_lshl_add_u64 v[22:23], s[42:43], 0, v[34:35]
	global_store_dwordx4 v[18:19], v[26:29], off
	v_lshl_add_u64 v[22:23], v[22:23], 0, v[128:129]
	v_mul_f32_e32 v38, v27, v27
	v_fmac_f32_e32 v38, v26, v26
	v_fmac_f32_e32 v38, v28, v28
	v_fmac_f32_e32 v38, v29, v29
	v_pk_mul_f32 v[24:25], v[28:29], v[142:143]
	v_pk_add_f32 v[28:29], v[158:159], 1.0 op_sel_hi:[1,0]
	v_pk_mul_f32 v[26:27], v[26:27], v[140:141]
	v_pk_add_f32 v[30:31], v[156:157], 1.0 op_sel_hi:[1,0]
	v_pk_mul_f32 v[24:25], v[24:25], v[28:29]
	v_lshlrev_b64 v[28:29], 11, v[12:13]
	v_pk_mul_f32 v[26:27], v[26:27], v[30:31]
	v_lshl_add_u64 v[28:29], s[0:1], 0, v[28:29]
	v_lshl_add_u64 v[16:17], v[28:29], 0, v[16:17]
	v_cvt_pk_bf16_f32 v25, v24, v25
	v_cvt_pk_bf16_f32 v24, v26, v27
	global_store_dwordx2 v[16:17], v[24:25], off
	s_nop 0
	v_pk_fma_f32 v[8:9], v[8:9], v[80:81], v[214:215]
	s_nop 0
	v_mul_f32_e32 v24, v9, v9
	v_pk_fma_f32 v[10:11], v[10:11], v[82:83], v[216:217]
	v_fmac_f32_e32 v24, v8, v8
	v_fmac_f32_e32 v24, v10, v10
	global_store_dwordx4 v[18:19], v[8:11], off offset:64
	v_fmac_f32_e32 v24, v11, v11
	v_add_f32_e32 v32, v38, v24
	v_pk_mul_f32 v[10:11], v[10:11], v[146:147]
	v_pk_mul_f32 v[8:9], v[8:9], v[144:145]
	v_pk_add_f32 v[24:25], v[162:163], 1.0 op_sel_hi:[1,0]
	v_pk_add_f32 v[26:27], v[160:161], 1.0 op_sel_hi:[1,0]
	v_pk_mul_f32 v[10:11], v[10:11], v[24:25]
	v_pk_mul_f32 v[8:9], v[8:9], v[26:27]
	v_and_b32_sdwa v25, v8, v170 dst_sel:DWORD dst_unused:UNUSED_PAD src0_sel:WORD_1 src1_sel:DWORD
	v_add3_u32 v8, v8, v25, s56
	v_and_b32_sdwa v25, v9, v170 dst_sel:DWORD dst_unused:UNUSED_PAD src0_sel:WORD_1 src1_sel:DWORD
	v_add3_u32 v9, v9, v25, s56
	v_and_b32_e32 v24, 0xffff0000, v9
	v_cvt_pk_bf16_f32 v9, v10, v11
	v_or_b32_sdwa v8, v24, v8 dst_sel:DWORD dst_unused:UNUSED_PAD src0_sel:DWORD src1_sel:WORD_1
	global_store_dwordx2 v[16:17], v[8:9], off offset:32
	s_nop 0
	v_pk_fma_f32 v[4:5], v[4:5], v[88:89], v[218:219]
	s_nop 0
	v_mul_f32_e32 v8, v5, v5
	v_pk_fma_f32 v[6:7], v[6:7], v[90:91], v[220:221]
	v_fmac_f32_e32 v8, v4, v4
	v_fmac_f32_e32 v8, v6, v6
	global_store_dwordx4 v[18:19], v[4:7], off offset:128
	v_fmac_f32_e32 v8, v7, v7
	v_add_f32_e32 v28, v32, v8
	v_pk_mul_f32 v[6:7], v[6:7], v[150:151]
	v_pk_mul_f32 v[4:5], v[4:5], v[148:149]
	v_pk_add_f32 v[8:9], v[182:183], 1.0 op_sel_hi:[1,0]
	v_pk_add_f32 v[10:11], v[180:181], 1.0 op_sel_hi:[1,0]
	v_pk_mul_f32 v[6:7], v[6:7], v[8:9]
	v_pk_mul_f32 v[4:5], v[4:5], v[10:11]
	v_and_b32_sdwa v9, v4, v170 dst_sel:DWORD dst_unused:UNUSED_PAD src0_sel:WORD_1 src1_sel:DWORD
	v_add3_u32 v4, v4, v9, s56
	v_and_b32_sdwa v9, v5, v170 dst_sel:DWORD dst_unused:UNUSED_PAD src0_sel:WORD_1 src1_sel:DWORD
	v_add3_u32 v5, v5, v9, s56
	v_and_b32_e32 v8, 0xffff0000, v5
	v_cvt_pk_bf16_f32 v5, v6, v7
	v_or_b32_sdwa v4, v8, v4 dst_sel:DWORD dst_unused:UNUSED_PAD src0_sel:DWORD src1_sel:WORD_1
	global_store_dwordx2 v[16:17], v[4:5], off offset:64
	s_nop 0
	v_pk_fma_f32 v[0:1], v[0:1], v[136:137], v[222:223]
	s_nop 0
	v_mul_f32_e32 v4, v1, v1
	v_pk_fma_f32 v[2:3], v[2:3], v[138:139], v[224:225]
	v_fmac_f32_e32 v4, v0, v0
	v_fmac_f32_e32 v4, v2, v2
	global_store_dwordx4 v[18:19], v[0:3], off offset:192
	v_fmac_f32_e32 v4, v3, v3
	v_add_f32_e32 v18, v28, v4
	v_pk_mul_f32 v[2:3], v[2:3], v[154:155]
	v_pk_mul_f32 v[0:1], v[0:1], v[152:153]
	v_pk_add_f32 v[4:5], v[192:193], 1.0 op_sel_hi:[1,0]
	v_pk_add_f32 v[6:7], v[190:191], 1.0 op_sel_hi:[1,0]
	v_pk_mul_f32 v[2:3], v[2:3], v[4:5]
	v_pk_mul_f32 v[0:1], v[0:1], v[6:7]
	v_and_b32_sdwa v5, v0, v170 dst_sel:DWORD dst_unused:UNUSED_PAD src0_sel:WORD_1 src1_sel:DWORD
	v_add3_u32 v0, v0, v5, s56
	v_and_b32_sdwa v5, v1, v170 dst_sel:DWORD dst_unused:UNUSED_PAD src0_sel:WORD_1 src1_sel:DWORD
	v_add3_u32 v1, v1, v5, s56
	v_and_b32_e32 v4, 0xffff0000, v1
	v_cvt_pk_bf16_f32 v1, v2, v3
	v_or_b32_sdwa v0, v4, v0 dst_sel:DWORD dst_unused:UNUSED_PAD src0_sel:DWORD src1_sel:WORD_1
	global_store_dwordx2 v[16:17], v[0:1], off offset:96
	ds_bpermute_b32 v0, v105, v18
	s_waitcnt lgkmcnt(0)
	v_add_f32_e32 v0, v18, v0
	ds_bpermute_b32 v1, v104, v0
	s_and_saveexec_b64 s[0:1], vcc
	s_movk_i32 s89, 0xff
	s_cbranch_execz .LBB0_124
	v_readlane_b32 s2, v253, 20
	s_add_u32 s2, s26, s2
	s_addc_u32 s3, s27, 0
	v_lshl_add_u64 v[2:3], v[12:13], 2, s[2:3]
	s_waitcnt lgkmcnt(0)
	v_add_f32_e32 v0, v0, v1
	global_store_dword v[2:3], v0, off

.LBB0_139:
	v_add_u32_e32 v160, v140, v141
	v_add_u32_e32 v143, v139, v141
	ds_read_b128 v[96:99], v160 offset:16384
	ds_read_b128 v[100:103], v160 offset:18432
	ds_read_b128 v[104:107], v143
	ds_read_b128 v[108:111], v143 offset:2048
	ds_read_b128 v[112:115], v160 offset:20480
	ds_read_b128 v[116:119], v160 offset:22528
	s_waitcnt lgkmcnt(3)
	v_mfma_f32_16x16x32_bf16 v[92:95], v[96:99], v[104:107], v[92:95]
	s_add_i32 s29, s28, 2
	s_cmp_lt_u32 s28, 6
	s_cselect_b64 s[0:1], -1, 0
	v_mfma_f32_16x16x32_bf16 v[88:91], v[100:103], v[104:107], v[88:91]
	s_and_b64 vcc, s[0:1], exec
	v_add_u32_e32 v161, v139, v142
	v_add_u32_e32 v162, v140, v142
	s_waitcnt lgkmcnt(1)
	v_mfma_f32_16x16x32_bf16 v[84:87], v[112:115], v[104:107], v[84:87]
	s_cselect_b32 s92, s27, 0x380
	s_addk_i32 s27, 0x100
	s_waitcnt lgkmcnt(0)
	v_mfma_f32_16x16x32_bf16 v[80:83], v[116:119], v[104:107], v[80:83]
	v_mfma_f32_16x16x32_bf16 v[76:79], v[96:99], v[108:111], v[76:79]
	v_mfma_f32_16x16x32_bf16 v[72:75], v[100:103], v[108:111], v[72:75]
	v_mfma_f32_16x16x32_bf16 v[52:55], v[112:115], v[108:111], v[52:55]
	v_mfma_f32_16x16x32_bf16 v[36:39], v[116:119], v[108:111], v[36:39]
	ds_read_b128 v[104:107], v143 offset:4096
	ds_read_b128 v[108:111], v143 offset:6144
	s_waitcnt lgkmcnt(1)
	v_mfma_f32_16x16x32_bf16 v[32:35], v[96:99], v[104:107], v[32:35]
	v_mfma_f32_16x16x32_bf16 v[24:27], v[100:103], v[104:107], v[24:27]
	v_mfma_f32_16x16x32_bf16 v[20:23], v[112:115], v[104:107], v[20:23]
	v_mfma_f32_16x16x32_bf16 v[16:19], v[116:119], v[104:107], v[16:19]
	s_waitcnt lgkmcnt(0)
	v_mfma_f32_16x16x32_bf16 v[8:11], v[96:99], v[108:111], v[8:11]
	v_mfma_f32_16x16x32_bf16 v[4:7], v[100:103], v[108:111], v[4:7]
	ds_read_b128 v[96:99], v161
	ds_read_b128 v[100:103], v161 offset:2048
	ds_read_b128 v[120:123], v162 offset:16384
	ds_read_b128 v[104:107], v161 offset:4096
	ds_read_b128 v[144:147], v161 offset:6144
	ds_read_b128 v[148:151], v162 offset:18432
	ds_read_b128 v[152:155], v162 offset:20480
	ds_read_b128 v[156:159], v162 offset:22528
	s_waitcnt vmcnt(6)
	ds_write_b128 v138, v[40:43] offset:32768
	s_waitcnt vmcnt(5)
	ds_write_b128 v138, v[44:47] offset:36864
	s_waitcnt vmcnt(4)
	ds_write_b128 v138, v[48:51] offset:40960
	s_waitcnt vmcnt(3)
	ds_write_b128 v138, v[60:63] offset:45056
	ds_write_b128 v138, v[28:31] offset:49152
	s_waitcnt vmcnt(2)
	ds_write_b128 v138, v[56:59] offset:53248
	s_waitcnt vmcnt(1)
	ds_write_b128 v138, v[64:67] offset:57344
	v_lshl_add_u64 v[64:65], v[132:133], 0, s[92:93]
	s_waitcnt vmcnt(0)
	ds_write_b128 v138, v[68:71] offset:61440
	v_add_co_u32_e64 v68, s[0:1], s16, v64
	s_waitcnt lgkmcnt(13)
	v_mfma_f32_16x16x32_bf16 v[40:43], v[120:123], v[96:99], v[92:95]
	v_addc_co_u32_e64 v69, s[0:1], 0, v65, s[0:1]
	v_add_co_u32_e64 v70, s[0:1], s11, v64
	s_waitcnt lgkmcnt(10)
	v_mfma_f32_16x16x32_bf16 v[44:47], v[148:151], v[96:99], v[88:91]
	v_addc_co_u32_e64 v71, s[0:1], 0, v65, s[0:1]
	v_lshl_add_u64 v[66:67], v[134:135], 0, s[92:93]
	s_waitcnt lgkmcnt(9)
	v_mfma_f32_16x16x32_bf16 v[28:31], v[152:155], v[96:99], v[84:87]
	s_waitcnt lgkmcnt(8)
	v_mfma_f32_16x16x32_bf16 v[48:51], v[156:159], v[96:99], v[80:83]
	global_load_dwordx4 v[96:99], v[64:65], off
	v_add_co_u32_e64 v64, s[0:1], s60, v64
	v_mfma_f32_16x16x32_bf16 v[60:63], v[148:151], v[100:103], v[72:75]
	s_nop 0
	v_addc_co_u32_e64 v65, s[0:1], 0, v65, s[0:1]
	s_nop 0
	v_add_co_u32_e64 v72, s[0:1], s16, v66
	v_mfma_f32_16x16x32_bf16 v[56:59], v[120:123], v[100:103], v[76:79]
	s_nop 0
	v_addc_co_u32_e64 v73, s[0:1], 0, v67, s[0:1]
	v_add_co_u32_e64 v74, s[0:1], s11, v66
	v_mfma_f32_16x16x32_bf16 v[52:55], v[152:155], v[100:103], v[52:55]
	s_nop 0
	v_addc_co_u32_e64 v75, s[0:1], 0, v67, s[0:1]
	v_mfma_f32_16x16x32_bf16 v[36:39], v[156:159], v[100:103], v[36:39]
	global_load_dwordx4 v[100:103], v[66:67], off
	v_add_co_u32_e64 v66, s[0:1], s60, v66
	v_mfma_f32_16x16x32_bf16 v[0:3], v[112:115], v[108:111], v[0:3]
	s_nop 0
	v_addc_co_u32_e64 v67, s[0:1], 0, v67, s[0:1]
	s_min_u32 s0, s28, 4
	v_mfma_f32_16x16x32_bf16 v[12:15], v[116:119], v[108:111], v[12:15]
	s_lshl_b32 s92, s0, 7
	s_mov_b32 s28, s29
	v_mfma_f32_16x16x32_bf16 v[32:35], v[120:123], v[104:107], v[32:35]
	v_mfma_f32_16x16x32_bf16 v[24:27], v[148:151], v[104:107], v[24:27]
	v_mfma_f32_16x16x32_bf16 v[20:23], v[152:155], v[104:107], v[20:23]
	v_mfma_f32_16x16x32_bf16 v[16:19], v[156:159], v[104:107], v[16:19]
	global_load_dwordx4 v[104:107], v[68:69], off
	global_load_dwordx4 v[108:111], v[70:71], off
	global_load_dwordx4 v[112:115], v[64:65], off
	v_mfma_f32_16x16x32_bf16 v[8:11], v[120:123], v[144:147], v[8:11]
	global_load_dwordx4 v[116:119], v[72:73], off
	global_load_dwordx4 v[120:123], v[74:75], off
	global_load_dwordx4 v[124:127], v[66:67], off
	s_waitcnt lgkmcnt(0)
	s_barrier
	ds_read_b128 v[64:67], v160 offset:49152
	ds_read_b128 v[68:71], v160 offset:51200
	ds_read_b128 v[72:75], v143 offset:32768
	ds_read_b128 v[76:79], v143 offset:34816
	ds_read_b128 v[80:83], v160 offset:53248
	ds_read_b128 v[84:87], v160 offset:55296
	s_waitcnt lgkmcnt(3)
	v_mfma_f32_16x16x32_bf16 v[40:43], v[64:67], v[72:75], v[40:43]
	v_mfma_f32_16x16x32_bf16 v[44:47], v[68:71], v[72:75], v[44:47]
	s_waitcnt lgkmcnt(1)
	v_mfma_f32_16x16x32_bf16 v[28:31], v[80:83], v[72:75], v[28:31]
	s_waitcnt lgkmcnt(0)
	v_mfma_f32_16x16x32_bf16 v[48:51], v[84:87], v[72:75], v[48:51]
	v_mfma_f32_16x16x32_bf16 v[56:59], v[64:67], v[76:79], v[56:59]
	v_mfma_f32_16x16x32_bf16 v[60:63], v[68:71], v[76:79], v[60:63]
	v_mfma_f32_16x16x32_bf16 v[52:55], v[80:83], v[76:79], v[52:55]
	v_mfma_f32_16x16x32_bf16 v[36:39], v[84:87], v[76:79], v[36:39]
	ds_read_b128 v[72:75], v143 offset:36864
	ds_read_b128 v[76:79], v143 offset:38912
	v_mfma_f32_16x16x32_bf16 v[4:7], v[148:151], v[144:147], v[4:7]
	v_mfma_f32_16x16x32_bf16 v[0:3], v[152:155], v[144:147], v[0:3]
	v_mfma_f32_16x16x32_bf16 v[12:15], v[156:159], v[144:147], v[12:15]
	s_waitcnt lgkmcnt(1)
	v_mfma_f32_16x16x32_bf16 v[32:35], v[64:67], v[72:75], v[32:35]
	v_mfma_f32_16x16x32_bf16 v[24:27], v[68:71], v[72:75], v[24:27]
	v_mfma_f32_16x16x32_bf16 v[20:23], v[80:83], v[72:75], v[20:23]
	v_mfma_f32_16x16x32_bf16 v[16:19], v[84:87], v[72:75], v[16:19]
	s_waitcnt lgkmcnt(0)
	v_mfma_f32_16x16x32_bf16 v[8:11], v[64:67], v[76:79], v[8:11]
	v_mfma_f32_16x16x32_bf16 v[4:7], v[68:71], v[76:79], v[4:7]
	ds_read_b128 v[64:67], v162 offset:49152
	ds_read_b128 v[68:71], v162 offset:51200
	ds_read_b128 v[72:75], v161 offset:32768
	ds_read_b128 v[144:147], v161 offset:34816
	ds_read_b128 v[152:155], v162 offset:55296
	ds_read_b128 v[148:151], v162 offset:53248
	s_waitcnt lgkmcnt(3)
	v_mfma_f32_16x16x32_bf16 v[88:91], v[68:71], v[72:75], v[44:47]
	s_nop 2
	v_lshl_add_u64 v[44:45], v[132:133], 0, s[92:93]
	v_mfma_f32_16x16x32_bf16 v[0:3], v[80:83], v[76:79], v[0:3]
	v_lshl_add_u64 v[46:47], v[134:135], 0, s[92:93]
	s_waitcnt lgkmcnt(1)
	v_mfma_f32_16x16x32_bf16 v[80:83], v[152:155], v[72:75], v[48:51]
	s_nop 2
	v_add_co_u32_e64 v48, s[0:1], s16, v44
	v_mfma_f32_16x16x32_bf16 v[12:15], v[84:87], v[76:79], v[12:15]
	s_nop 0
	v_addc_co_u32_e64 v49, s[0:1], 0, v45, s[0:1]
	v_add_co_u32_e64 v50, s[0:1], s11, v44
	v_mfma_f32_16x16x32_bf16 v[76:79], v[64:67], v[144:147], v[56:59]
	s_nop 0
	v_addc_co_u32_e64 v51, s[0:1], 0, v45, s[0:1]
	s_nop 0
	v_add_co_u32_e64 v56, s[0:1], s60, v44
	v_mfma_f32_16x16x32_bf16 v[92:95], v[64:67], v[72:75], v[40:43]
	s_nop 0
	v_addc_co_u32_e64 v57, s[0:1], 0, v45, s[0:1]
	v_add_co_u32_e64 v58, s[0:1], s16, v46
	s_waitcnt lgkmcnt(0)
	v_mfma_f32_16x16x32_bf16 v[84:87], v[148:151], v[72:75], v[28:31]
	ds_read_b128 v[40:43], v161 offset:36864
	v_addc_co_u32_e64 v59, s[0:1], 0, v47, s[0:1]
	v_mfma_f32_16x16x32_bf16 v[72:75], v[68:71], v[144:147], v[60:63]
	v_add_co_u32_e64 v156, s[0:1], s11, v46
	global_load_dwordx4 v[28:31], v[46:47], off offset:384
	v_mfma_f32_16x16x32_bf16 v[52:55], v[148:151], v[144:147], v[52:55]
	v_addc_co_u32_e64 v157, s[0:1], 0, v47, s[0:1]
	v_add_co_u32_e64 v158, s[0:1], s60, v46
	v_mfma_f32_16x16x32_bf16 v[36:39], v[152:155], v[144:147], v[36:39]
	ds_read_b128 v[144:147], v161 offset:38912
	v_addc_co_u32_e64 v159, s[0:1], 0, v47, s[0:1]
	s_waitcnt lgkmcnt(1)
	v_mfma_f32_16x16x32_bf16 v[32:35], v[64:67], v[40:43], v[32:35]
	v_mfma_f32_16x16x32_bf16 v[24:27], v[68:71], v[40:43], v[24:27]
	v_mfma_f32_16x16x32_bf16 v[20:23], v[148:151], v[40:43], v[20:23]
	v_mfma_f32_16x16x32_bf16 v[16:19], v[152:155], v[40:43], v[16:19]
	global_load_dwordx4 v[40:43], v[44:45], off offset:384
	s_nop 0
	global_load_dwordx4 v[44:47], v[48:49], off offset:384
	s_nop 0
	global_load_dwordx4 v[48:51], v[50:51], off offset:384
	s_waitcnt lgkmcnt(0)
	v_mfma_f32_16x16x32_bf16 v[8:11], v[64:67], v[144:147], v[8:11]
	global_load_dwordx4 v[60:63], v[56:57], off offset:384
	s_nop 0
	global_load_dwordx4 v[56:59], v[58:59], off offset:384
	s_nop 0
	global_load_dwordx4 v[64:67], v[156:157], off offset:384
	v_mfma_f32_16x16x32_bf16 v[4:7], v[68:71], v[144:147], v[4:7]
	global_load_dwordx4 v[68:71], v[158:159], off offset:384
	s_waitcnt vmcnt(15)
	ds_write_b128 v138, v[96:99]
	s_waitcnt vmcnt(14)
	ds_write_b128 v138, v[100:103] offset:16384
	s_waitcnt vmcnt(13)
	ds_write_b128 v138, v[104:107] offset:4096
	s_waitcnt vmcnt(12)
	ds_write_b128 v138, v[108:111] offset:8192
	s_waitcnt vmcnt(11)
	ds_write_b128 v138, v[112:115] offset:12288
	s_waitcnt vmcnt(10)
	ds_write_b128 v138, v[116:119] offset:20480
	s_waitcnt vmcnt(9)
	ds_write_b128 v138, v[120:123] offset:24576
	s_waitcnt vmcnt(8)
	ds_write_b128 v138, v[124:127] offset:28672
	s_waitcnt lgkmcnt(0)
	v_mfma_f32_16x16x32_bf16 v[0:3], v[148:151], v[144:147], v[0:3]
	s_barrier
	v_mfma_f32_16x16x32_bf16 v[12:15], v[152:155], v[144:147], v[12:15]
	s_cbranch_vccnz .LBB0_139
	s_lshl_b32 s0, s2, 8
	s_waitcnt vmcnt(7)
	v_or_b32_e32 v28, s26, v136
	v_lshlrev_b32_e32 v29, 6, v137
	v_lshlrev_b32_e32 v30, 2, v128
	v_add3_u32 v28, v28, v130, s0
	s_waitcnt vmcnt(6)
	v_or3_b32 v40, v29, v30, s3
	v_ashrrev_i32_e32 v29, 31, v28
	v_readlane_b32 s0, v251, 20
	v_and_b32_sdwa v41, v95, v170 dst_sel:DWORD dst_unused:UNUSED_PAD src0_sel:WORD_1 src1_sel:DWORD
	v_and_b32_sdwa v42, v93, v170 dst_sel:DWORD dst_unused:UNUSED_PAD src0_sel:WORD_1 src1_sel:DWORD
	v_lshlrev_b64 v[30:31], 11, v[28:29]
	v_readlane_b32 s1, v251, 21
	v_lshlrev_b32_e32 v128, 1, v40
	v_and_b32_sdwa v29, v94, v170 dst_sel:DWORD dst_unused:UNUSED_PAD src0_sel:WORD_1 src1_sel:DWORD
	v_and_b32_sdwa v40, v92, v170 dst_sel:DWORD dst_unused:UNUSED_PAD src0_sel:WORD_1 src1_sel:DWORD
	v_add3_u32 v41, v95, v41, s56
	v_add3_u32 v42, v93, v42, s56
	v_lshl_add_u64 v[30:31], s[0:1], 0, v[30:31]
	v_add3_u32 v40, v92, v40, s56
	v_add3_u32 v29, v94, v29, s56
	v_and_b32_e32 v41, 0xffff0000, v41
	v_and_b32_e32 v42, 0xffff0000, v42
	v_lshl_add_u64 v[30:31], v[30:31], 0, v[128:129]
	v_or_b32_sdwa v41, v41, v29 dst_sel:DWORD dst_unused:UNUSED_PAD src0_sel:DWORD src1_sel:WORD_1
	v_or_b32_sdwa v40, v42, v40 dst_sel:DWORD dst_unused:UNUSED_PAD src0_sel:DWORD src1_sel:WORD_1
	global_store_dwordx2 v[30:31], v[40:41], off
	v_cvt_pk_bf16_f32 v41, v90, v91
	v_cvt_pk_bf16_f32 v40, v88, v89
	global_store_dwordx2 v[30:31], v[40:41], off offset:32
	v_cvt_pk_bf16_f32 v41, v86, v87
	v_cvt_pk_bf16_f32 v40, v84, v85
	global_store_dwordx2 v[30:31], v[40:41], off offset:64
	v_cvt_pk_bf16_f32 v41, v82, v83
	v_cvt_pk_bf16_f32 v40, v80, v81
	global_store_dwordx2 v[30:31], v[40:41], off offset:96
	v_add_u32_e32 v30, 16, v28
	v_ashrrev_i32_e32 v31, 31, v30
	v_lshlrev_b64 v[30:31], 11, v[30:31]
	v_lshl_add_u64 v[30:31], s[0:1], 0, v[30:31]
	v_lshl_add_u64 v[30:31], v[30:31], 0, v[128:129]
	v_cvt_pk_bf16_f32 v41, v78, v79
	v_cvt_pk_bf16_f32 v40, v76, v77
	global_store_dwordx2 v[30:31], v[40:41], off
	v_cvt_pk_bf16_f32 v41, v74, v75
	v_cvt_pk_bf16_f32 v40, v72, v73
	global_store_dwordx2 v[30:31], v[40:41], off offset:32
	v_cvt_pk_bf16_f32 v41, v54, v55
	v_cvt_pk_bf16_f32 v40, v52, v53
	global_store_dwordx2 v[30:31], v[40:41], off offset:64
	v_and_b32_sdwa v29, v38, v170 dst_sel:DWORD dst_unused:UNUSED_PAD src0_sel:WORD_1 src1_sel:DWORD
	v_and_b32_sdwa v40, v36, v170 dst_sel:DWORD dst_unused:UNUSED_PAD src0_sel:WORD_1 src1_sel:DWORD
	v_add3_u32 v36, v36, v40, s56
	v_add3_u32 v29, v38, v29, s56
	v_and_b32_sdwa v38, v39, v170 dst_sel:DWORD dst_unused:UNUSED_PAD src0_sel:WORD_1 src1_sel:DWORD
	v_and_b32_sdwa v40, v37, v170 dst_sel:DWORD dst_unused:UNUSED_PAD src0_sel:WORD_1 src1_sel:DWORD
	v_add3_u32 v38, v39, v38, s56
	v_add3_u32 v37, v37, v40, s56
	v_and_b32_e32 v38, 0xffff0000, v38
	v_and_b32_e32 v39, 0xffff0000, v37
	v_or_b32_sdwa v37, v38, v29 dst_sel:DWORD dst_unused:UNUSED_PAD src0_sel:DWORD src1_sel:WORD_1
	v_or_b32_sdwa v36, v39, v36 dst_sel:DWORD dst_unused:UNUSED_PAD src0_sel:DWORD src1_sel:WORD_1
	global_store_dwordx2 v[30:31], v[36:37], off offset:96
	v_add_u32_e32 v30, 32, v28
	v_and_b32_sdwa v29, v34, v170 dst_sel:DWORD dst_unused:UNUSED_PAD src0_sel:WORD_1 src1_sel:DWORD
	v_and_b32_sdwa v36, v32, v170 dst_sel:DWORD dst_unused:UNUSED_PAD src0_sel:WORD_1 src1_sel:DWORD
	v_ashrrev_i32_e32 v31, 31, v30
	v_add3_u32 v32, v32, v36, s56
	v_add3_u32 v29, v34, v29, s56
	v_and_b32_sdwa v34, v35, v170 dst_sel:DWORD dst_unused:UNUSED_PAD src0_sel:WORD_1 src1_sel:DWORD
	v_and_b32_sdwa v36, v33, v170 dst_sel:DWORD dst_unused:UNUSED_PAD src0_sel:WORD_1 src1_sel:DWORD
	v_lshlrev_b64 v[30:31], 11, v[30:31]
	v_add3_u32 v34, v35, v34, s56
	v_add3_u32 v33, v33, v36, s56
	v_lshl_add_u64 v[30:31], s[0:1], 0, v[30:31]
	v_and_b32_e32 v34, 0xffff0000, v34
	v_and_b32_e32 v35, 0xffff0000, v33
	v_lshl_add_u64 v[30:31], v[30:31], 0, v[128:129]
	v_or_b32_sdwa v33, v34, v29 dst_sel:DWORD dst_unused:UNUSED_PAD src0_sel:DWORD src1_sel:WORD_1
	v_or_b32_sdwa v32, v35, v32 dst_sel:DWORD dst_unused:UNUSED_PAD src0_sel:DWORD src1_sel:WORD_1
	global_store_dwordx2 v[30:31], v[32:33], off
	v_and_b32_sdwa v32, v24, v170 dst_sel:DWORD dst_unused:UNUSED_PAD src0_sel:WORD_1 src1_sel:DWORD
	v_add3_u32 v24, v24, v32, s56
	v_and_b32_sdwa v32, v25, v170 dst_sel:DWORD dst_unused:UNUSED_PAD src0_sel:WORD_1 src1_sel:DWORD
	v_add3_u32 v25, v25, v32, s56
	v_and_b32_e32 v29, 0xffff0000, v25
	v_cvt_pk_bf16_f32 v25, v26, v27
	v_or_b32_sdwa v24, v29, v24 dst_sel:DWORD dst_unused:UNUSED_PAD src0_sel:DWORD src1_sel:WORD_1
	global_store_dwordx2 v[30:31], v[24:25], off offset:32
	v_and_b32_sdwa v25, v20, v170 dst_sel:DWORD dst_unused:UNUSED_PAD src0_sel:WORD_1 src1_sel:DWORD
	v_add3_u32 v20, v20, v25, s56
	v_and_b32_sdwa v25, v21, v170 dst_sel:DWORD dst_unused:UNUSED_PAD src0_sel:WORD_1 src1_sel:DWORD
	v_add3_u32 v21, v21, v25, s56
	v_and_b32_e32 v24, 0xffff0000, v21
	v_cvt_pk_bf16_f32 v21, v22, v23
	v_or_b32_sdwa v20, v24, v20 dst_sel:DWORD dst_unused:UNUSED_PAD src0_sel:DWORD src1_sel:WORD_1
	global_store_dwordx2 v[30:31], v[20:21], off offset:64
	v_and_b32_sdwa v21, v16, v170 dst_sel:DWORD dst_unused:UNUSED_PAD src0_sel:WORD_1 src1_sel:DWORD
	v_add3_u32 v16, v16, v21, s56
	v_and_b32_sdwa v21, v17, v170 dst_sel:DWORD dst_unused:UNUSED_PAD src0_sel:WORD_1 src1_sel:DWORD
	v_add3_u32 v17, v17, v21, s56
	v_and_b32_e32 v20, 0xffff0000, v17
	v_cvt_pk_bf16_f32 v17, v18, v19
	v_or_b32_sdwa v16, v20, v16 dst_sel:DWORD dst_unused:UNUSED_PAD src0_sel:DWORD src1_sel:WORD_1
	global_store_dwordx2 v[30:31], v[16:17], off offset:96
	v_add_u32_e32 v16, 48, v28
	v_and_b32_sdwa v19, v8, v170 dst_sel:DWORD dst_unused:UNUSED_PAD src0_sel:WORD_1 src1_sel:DWORD
	v_ashrrev_i32_e32 v17, 31, v16
	v_add3_u32 v8, v8, v19, s56
	v_and_b32_sdwa v19, v9, v170 dst_sel:DWORD dst_unused:UNUSED_PAD src0_sel:WORD_1 src1_sel:DWORD
	v_lshlrev_b64 v[16:17], 11, v[16:17]
	v_add3_u32 v9, v9, v19, s56
	v_lshl_add_u64 v[16:17], s[0:1], 0, v[16:17]
	v_and_b32_e32 v18, 0xffff0000, v9
	v_lshl_add_u64 v[16:17], v[16:17], 0, v[128:129]
	v_cvt_pk_bf16_f32 v9, v10, v11
	v_or_b32_sdwa v8, v18, v8 dst_sel:DWORD dst_unused:UNUSED_PAD src0_sel:DWORD src1_sel:WORD_1
	global_store_dwordx2 v[16:17], v[8:9], off
	v_and_b32_sdwa v9, v4, v170 dst_sel:DWORD dst_unused:UNUSED_PAD src0_sel:WORD_1 src1_sel:DWORD
	v_add3_u32 v4, v4, v9, s56
	v_and_b32_sdwa v9, v5, v170 dst_sel:DWORD dst_unused:UNUSED_PAD src0_sel:WORD_1 src1_sel:DWORD
	v_add3_u32 v5, v5, v9, s56
	v_and_b32_e32 v8, 0xffff0000, v5
	v_cvt_pk_bf16_f32 v5, v6, v7
	v_or_b32_sdwa v4, v8, v4 dst_sel:DWORD dst_unused:UNUSED_PAD src0_sel:DWORD src1_sel:WORD_1
	global_store_dwordx2 v[16:17], v[4:5], off offset:32
	v_and_b32_sdwa v5, v0, v170 dst_sel:DWORD dst_unused:UNUSED_PAD src0_sel:WORD_1 src1_sel:DWORD
	v_add3_u32 v0, v0, v5, s56
	v_and_b32_sdwa v5, v1, v170 dst_sel:DWORD dst_unused:UNUSED_PAD src0_sel:WORD_1 src1_sel:DWORD
	v_add3_u32 v1, v1, v5, s56
	v_and_b32_e32 v4, 0xffff0000, v1
	v_cvt_pk_bf16_f32 v1, v2, v3
	v_or_b32_sdwa v0, v4, v0 dst_sel:DWORD dst_unused:UNUSED_PAD src0_sel:DWORD src1_sel:WORD_1
	global_store_dwordx2 v[16:17], v[0:1], off offset:64
	v_cvt_pk_bf16_f32 v1, v14, v15
	v_cvt_pk_bf16_f32 v0, v12, v13
	global_store_dwordx2 v[16:17], v[0:1], off offset:96
	s_mov_b64 s[0:1], 0
	s_movk_i32 s89, 0xff

.LBB0_143:
	s_add_i32 s29, s28, 2
	v_add_u32_e32 v117, v87, v88
	v_add_u32_e32 v116, v91, v88
	ds_read_b128 v[56:59], v117 offset:16384
	ds_read_b128 v[60:63], v116
	ds_read_b128 v[64:67], v117 offset:18432
	ds_read_b128 v[68:71], v116 offset:2048
	s_cmp_lt_u32 s28, 30
	s_cselect_b64 s[0:1], -1, 0
	s_and_b64 vcc, s[0:1], exec
	v_add_u32_e32 v118, v91, v89
	v_add_u32_e32 v119, v87, v89
	s_cselect_b32 s92, s27, 0xf80
	ds_read_b128 v[72:75], v117 offset:20480
	ds_read_b128 v[76:79], v117 offset:22528
	ds_read_b128 v[92:95], v118
	ds_read_b128 v[96:99], v118 offset:2048
	ds_read_b128 v[100:103], v119 offset:16384
	ds_read_b128 v[104:107], v119 offset:18432
	ds_read_b128 v[108:111], v119 offset:20480
	ds_read_b128 v[112:115], v119 offset:22528
	s_waitcnt vmcnt(5)
	ds_write_b128 v90, v[4:7] offset:32768
	s_waitcnt vmcnt(3)
	ds_write_b128 v90, v[32:35] offset:36864
	v_lshl_add_u64 v[32:33], v[80:81], 0, s[92:93]
	s_waitcnt lgkmcnt(12)
	v_mfma_f32_16x16x32_bf16 v[44:47], v[56:59], v[60:63], v[44:47]
	s_waitcnt vmcnt(2)
	ds_write_b128 v90, v[28:31] offset:40960
	s_waitcnt vmcnt(1)
	ds_write_b128 v90, v[24:27] offset:45056
	s_waitcnt vmcnt(1)
	ds_write_b128 v90, v[16:19] offset:49152
	v_lshl_add_u64 v[34:35], v[82:83], 0, s[92:93]
	s_waitcnt vmcnt(0)
	ds_write_b128 v90, v[20:23] offset:53248
	s_waitcnt lgkmcnt(14)
	v_mfma_f32_16x16x32_bf16 v[4:7], v[56:59], v[68:71], v[36:39]
	global_load_dwordx4 v[56:59], v[34:35], off
	s_addk_i32 s27, 0x100
	s_nop 0
	v_add_co_u32_e64 v36, s[0:1], s33, v32
	v_mfma_f32_16x16x32_bf16 v[52:55], v[64:67], v[60:63], v[52:55]
	s_nop 0
	v_addc_co_u32_e64 v37, s[0:1], 0, v33, s[0:1]
	v_add_co_u32_e64 v38, s[0:1], s7, v32
	s_waitcnt lgkmcnt(13)
	v_mfma_f32_16x16x32_bf16 v[48:51], v[72:75], v[60:63], v[48:51]
	v_addc_co_u32_e64 v39, s[0:1], 0, v33, s[0:1]
	s_waitcnt lgkmcnt(12)
	v_mfma_f32_16x16x32_bf16 v[40:43], v[76:79], v[60:63], v[40:43]
	s_waitcnt lgkmcnt(9)
	v_mfma_f32_16x16x32_bf16 v[16:19], v[100:103], v[92:95], v[44:47]
	s_nop 2
	v_add_co_u32_e64 v44, s[0:1], s90, v32
	v_mfma_f32_16x16x32_bf16 v[8:11], v[64:67], v[68:71], v[8:11]
	s_nop 0
	v_addc_co_u32_e64 v45, s[0:1], 0, v33, s[0:1]
	v_add_co_u32_e64 v34, s[0:1], s33, v34
	v_mfma_f32_16x16x32_bf16 v[0:3], v[72:75], v[68:71], v[0:3]
	s_nop 0
	v_addc_co_u32_e64 v35, s[0:1], 0, v35, s[0:1]
	global_load_dwordx4 v[64:67], v[32:33], off
	global_load_dwordx4 v[60:63], v[36:37], off
	v_mfma_f32_16x16x32_bf16 v[12:15], v[76:79], v[68:71], v[12:15]
	global_load_dwordx4 v[68:71], v[38:39], off
	global_load_dwordx4 v[72:75], v[44:45], off
	global_load_dwordx4 v[76:79], v[34:35], off
	s_waitcnt lgkmcnt(0)
	s_barrier
	v_mfma_f32_16x16x32_bf16 v[20:23], v[104:107], v[92:95], v[52:55]
	ds_read_b128 v[32:35], v117 offset:49152
	ds_read_b128 v[36:39], v117 offset:51200
	s_min_u32 s0, s28, 28
	v_mfma_f32_16x16x32_bf16 v[24:27], v[108:111], v[92:95], v[48:51]
	s_lshl_b32 s92, s0, 7
	s_mov_b32 s28, s29
	v_mfma_f32_16x16x32_bf16 v[28:31], v[112:115], v[92:95], v[40:43]
	s_nop 2
	ds_read_b128 v[40:43], v116 offset:32768
	ds_read_b128 v[44:47], v116 offset:34816
	ds_read_b128 v[48:51], v117 offset:53248
	ds_read_b128 v[52:55], v117 offset:55296
	v_mfma_f32_16x16x32_bf16 v[8:11], v[104:107], v[96:99], v[8:11]
	v_mfma_f32_16x16x32_bf16 v[4:7], v[100:103], v[96:99], v[4:7]
	v_mfma_f32_16x16x32_bf16 v[0:3], v[108:111], v[96:99], v[0:3]
	v_lshl_add_u64 v[108:109], v[80:81], 0, s[92:93]
	v_lshl_add_u64 v[110:111], v[82:83], 0, s[92:93]
	s_waitcnt lgkmcnt(3)
	v_mfma_f32_16x16x32_bf16 v[16:19], v[32:35], v[40:43], v[16:19]
	v_mfma_f32_16x16x32_bf16 v[20:23], v[36:39], v[40:43], v[20:23]
	s_waitcnt lgkmcnt(1)
	v_mfma_f32_16x16x32_bf16 v[24:27], v[48:51], v[40:43], v[24:27]
	s_waitcnt lgkmcnt(0)
	v_mfma_f32_16x16x32_bf16 v[28:31], v[52:55], v[40:43], v[28:31]
	v_mfma_f32_16x16x32_bf16 v[8:11], v[36:39], v[44:47], v[8:11]
	ds_read_b128 v[36:39], v119 offset:49152
	ds_read_b128 v[40:43], v118 offset:32768
	ds_read_b128 v[92:95], v119 offset:51200
	v_mfma_f32_16x16x32_bf16 v[12:15], v[112:115], v[96:99], v[12:15]
	v_add_co_u32_e64 v112, s[0:1], s33, v108
	v_mfma_f32_16x16x32_bf16 v[32:35], v[32:35], v[44:47], v[4:7]
	s_nop 0
	v_addc_co_u32_e64 v113, s[0:1], 0, v109, s[0:1]
	s_nop 0
	global_load_dwordx4 v[4:7], v[108:109], off offset:384
	ds_read_b128 v[96:99], v118 offset:34816
	ds_read_b128 v[100:103], v119 offset:53248
	ds_read_b128 v[104:107], v119 offset:55296
	v_mfma_f32_16x16x32_bf16 v[12:15], v[52:55], v[44:47], v[12:15]
	s_waitcnt lgkmcnt(3)
	v_mfma_f32_16x16x32_bf16 v[52:55], v[92:95], v[40:43], v[20:23]
	s_nop 2
	v_add_co_u32_e64 v20, s[0:1], s7, v108
	v_mfma_f32_16x16x32_bf16 v[0:3], v[48:51], v[44:47], v[0:3]
	s_nop 0
	v_addc_co_u32_e64 v21, s[0:1], 0, v109, s[0:1]
	v_add_co_u32_e64 v22, s[0:1], s90, v108
	v_mfma_f32_16x16x32_bf16 v[44:47], v[36:39], v[40:43], v[16:19]
	s_nop 0
	v_addc_co_u32_e64 v23, s[0:1], 0, v109, s[0:1]
	v_add_co_u32_e64 v108, s[0:1], s33, v110
	s_waitcnt lgkmcnt(1)
	v_mfma_f32_16x16x32_bf16 v[48:51], v[100:103], v[40:43], v[24:27]
	global_load_dwordx4 v[16:19], v[110:111], off offset:384
	v_addc_co_u32_e64 v109, s[0:1], 0, v111, s[0:1]
	s_waitcnt lgkmcnt(0)
	v_mfma_f32_16x16x32_bf16 v[40:43], v[104:107], v[40:43], v[28:31]
	v_mfma_f32_16x16x32_bf16 v[36:39], v[36:39], v[96:99], v[32:35]
	s_nop 2
	global_load_dwordx4 v[32:35], v[112:113], off offset:384
	global_load_dwordx4 v[28:31], v[20:21], off offset:384
	global_load_dwordx4 v[24:27], v[22:23], off offset:384
	s_nop 0
	global_load_dwordx4 v[20:23], v[108:109], off offset:384
	v_mfma_f32_16x16x32_bf16 v[8:11], v[92:95], v[96:99], v[8:11]
	s_waitcnt vmcnt(10)
	ds_write_b128 v90, v[64:67]
	ds_write_b128 v90, v[56:59] offset:16384
	s_waitcnt vmcnt(9)
	ds_write_b128 v90, v[60:63] offset:4096
	s_waitcnt vmcnt(8)
	ds_write_b128 v90, v[68:71] offset:8192
	s_waitcnt vmcnt(7)
	ds_write_b128 v90, v[72:75] offset:12288
	s_waitcnt vmcnt(6)
	ds_write_b128 v90, v[76:79] offset:20480
	s_waitcnt lgkmcnt(0)
	s_barrier
	v_mfma_f32_16x16x32_bf16 v[0:3], v[100:103], v[96:99], v[0:3]
	v_mfma_f32_16x16x32_bf16 v[12:15], v[104:107], v[96:99], v[12:15]
	s_cbranch_vccnz .LBB0_143
	s_lshl_b32 s0, s2, 10
	s_waitcnt vmcnt(5)
	v_or_b32_e32 v4, s26, v85
	s_waitcnt vmcnt(4)
	v_add3_u32 v16, v4, v86, s0
	v_add_u32_e32 v4, 0x2000, v16
	v_ashrrev_i32_e32 v5, 31, v4
	v_readlane_b32 s16, v251, 20
	v_lshlrev_b64 v[4:5], 11, v[4:5]
	v_readlane_b32 s17, v251, 21
	s_lshl_b32 s0, s3, 1
	v_lshl_add_u64 v[4:5], s[16:17], 0, v[4:5]
	v_lshl_or_b32 v128, v84, 3, s0
	v_lshl_add_u64 v[4:5], v[4:5], 0, v[128:129]
	v_cvt_pk_bf16_f32 v7, v46, v47
	v_cvt_pk_bf16_f32 v6, v44, v45
	global_store_dwordx2 v[4:5], v[6:7], off
	v_cvt_pk_bf16_f32 v7, v54, v55
	v_cvt_pk_bf16_f32 v6, v52, v53
	global_store_dwordx2 v[4:5], v[6:7], off offset:32
	v_cvt_pk_bf16_f32 v7, v50, v51
	v_cvt_pk_bf16_f32 v6, v48, v49
	global_store_dwordx2 v[4:5], v[6:7], off offset:64
	v_cvt_pk_bf16_f32 v7, v42, v43
	v_cvt_pk_bf16_f32 v6, v40, v41
	global_store_dwordx2 v[4:5], v[6:7], off offset:96
	v_add_u32_e32 v4, 0x2010, v16
	v_ashrrev_i32_e32 v5, 31, v4
	v_lshlrev_b64 v[4:5], 11, v[4:5]
	v_lshl_add_u64 v[4:5], s[16:17], 0, v[4:5]
	v_lshl_add_u64 v[4:5], v[4:5], 0, v[128:129]
	v_cvt_pk_bf16_f32 v7, v38, v39
	v_cvt_pk_bf16_f32 v6, v36, v37
	global_store_dwordx2 v[4:5], v[6:7], off
	v_and_b32_sdwa v6, v10, v170 dst_sel:DWORD dst_unused:UNUSED_PAD src0_sel:WORD_1 src1_sel:DWORD
	v_and_b32_sdwa v7, v8, v170 dst_sel:DWORD dst_unused:UNUSED_PAD src0_sel:WORD_1 src1_sel:DWORD
	v_add3_u32 v8, v8, v7, s56
	v_add3_u32 v6, v10, v6, s56
	v_and_b32_sdwa v7, v11, v170 dst_sel:DWORD dst_unused:UNUSED_PAD src0_sel:WORD_1 src1_sel:DWORD
	v_and_b32_sdwa v10, v9, v170 dst_sel:DWORD dst_unused:UNUSED_PAD src0_sel:WORD_1 src1_sel:DWORD
	v_add3_u32 v7, v11, v7, s56
	v_add3_u32 v9, v9, v10, s56
	v_and_b32_e32 v7, 0xffff0000, v7
	v_and_b32_e32 v9, 0xffff0000, v9
	v_or_b32_sdwa v7, v7, v6 dst_sel:DWORD dst_unused:UNUSED_PAD src0_sel:DWORD src1_sel:WORD_1
	v_or_b32_sdwa v6, v9, v8 dst_sel:DWORD dst_unused:UNUSED_PAD src0_sel:DWORD src1_sel:WORD_1
	global_store_dwordx2 v[4:5], v[6:7], off offset:32
	v_and_b32_sdwa v7, v0, v170 dst_sel:DWORD dst_unused:UNUSED_PAD src0_sel:WORD_1 src1_sel:DWORD
	v_add3_u32 v0, v0, v7, s56
	v_and_b32_sdwa v7, v1, v170 dst_sel:DWORD dst_unused:UNUSED_PAD src0_sel:WORD_1 src1_sel:DWORD
	v_add3_u32 v1, v1, v7, s56
	v_and_b32_e32 v6, 0xffff0000, v1
	v_cvt_pk_bf16_f32 v1, v2, v3
	v_or_b32_sdwa v0, v6, v0 dst_sel:DWORD dst_unused:UNUSED_PAD src0_sel:DWORD src1_sel:WORD_1
	global_store_dwordx2 v[4:5], v[0:1], off offset:64
	v_cvt_pk_bf16_f32 v1, v14, v15
	v_cvt_pk_bf16_f32 v0, v12, v13
	s_movk_i32 s89, 0xff
	global_store_dwordx2 v[4:5], v[0:1], off offset:96

.LBB0_163:
	s_or_b64 exec, exec, s[0:1]
	s_mov_b64 s[0:1], src_shared_base
	s_add_i32 s0, 0, 0x11fe0
	s_cmp_lg_u32 s0, -1
	s_cselect_b32 s0, s0, 0
	s_cselect_b32 s1, s1, 0
	v_mov_b32_e32 v0, s0
	v_mov_b32_e32 v1, s1
	s_waitcnt lgkmcnt(0)
	s_barrier
	flat_load_dword v8, v[0:1] sc0 sc1
	s_waitcnt vmcnt(0)
	s_movk_i32 s0, 0x880
	s_waitcnt lgkmcnt(0)
	v_cmp_gt_i32_e32 vcc, s0, v8
	s_mov_b64 s[0:1], -1
	s_and_saveexec_b64 s[26:27], vcc
	s_cbranch_execz .LBB0_158
	s_movk_i32 s0, 0x1ff
	v_cmp_lt_i32_e32 vcc, s0, v8
	s_and_saveexec_b64 s[0:1], vcc
	s_xor_b64 s[48:49], exec, s[0:1]
	s_cbranch_execz .LBB0_197
	s_movk_i32 s0, 0x5ff
	v_cmp_lt_u32_e32 vcc, s0, v8
	s_and_saveexec_b64 s[0:1], vcc
	s_xor_b64 s[2:3], exec, s[0:1]
	s_cbranch_execz .LBB0_167
	s_movk_i32 s0, 0x67f
	v_cmp_lt_u32_e32 vcc, s0, v8
	v_mov_b32_e32 v0, 0xfffffa00
	v_mov_b32_e32 v1, 0xfffff980
	v_cndmask_b32_e32 v0, v0, v1, vcc
	v_cndmask_b32_e64 v2, 4, 2, vcc
	v_cndmask_b32_e64 v1, 6, 4, vcc
	v_cndmask_b32_e64 v3, 3, 1, vcc
	v_add_u32_e32 v0, v0, v8
	v_lshrrev_b32_e32 v2, v2, v8
	v_lshrrev_b32_e32 v128, v1, v0
	v_lshrrev_b32_e32 v3, v3, v8
	v_mov_b32_e32 v0, 0x2000
	v_lshlrev_b32_e32 v2, 7, v2
	v_lshl_add_u32 v0, v128, 10, v0
	v_lshlrev_b32_e32 v1, 8, v128
	v_and_b32_e32 v130, 0x180, v2
	v_lshlrev_b32_e32 v2, 7, v3
	v_mov_b32_e32 v104, v166
	v_cndmask_b32_e64 v4, 7, 1, vcc
	v_cndmask_b32_e32 v0, v0, v1, vcc
	s_barrier
	v_mov_b32_e32 v1, v129
	v_readlane_b32 s0, v251, 32
	v_and_b32_e32 v132, 0x80, v2
	v_and_b32_e32 v4, v4, v8
	v_ashrrev_i32_e32 v6, 3, v104
	v_lshlrev_b64 v[0:1], 10, v[0:1]
	v_readlane_b32 s1, v251, 33
	v_add_u32_e32 v2, v6, v132
	v_lshlrev_b32_e32 v133, 7, v4
	v_lshl_add_u64 v[0:1], s[0:1], 0, v[0:1]
	v_ashrrev_i32_e32 v3, 31, v2
	v_readlane_b32 s0, v250, 37
	v_lshlrev_b64 v[34:35], 20, v[128:129]
	v_lshlrev_b64 v[32:33], 18, v[128:129]
	v_lshlrev_b32_e32 v128, 1, v130
	v_lshlrev_b64 v[2:3], 8, v[2:3]
	v_readlane_b32 s1, v250, 38
	v_lshlrev_b32_e32 v7, 4, v104
	v_add_u32_e32 v4, v6, v133
	v_lshl_add_u64 v[0:1], v[0:1], 0, v[128:129]
	v_lshl_add_u64 v[2:3], s[0:1], 0, v[2:3]
	v_and_b32_e32 v128, 0x70, v7
	v_ashrrev_i32_e32 v5, 31, v4
	v_lshl_add_u64 v[2:3], v[2:3], 0, v[128:129]
	v_lshlrev_b64 v[4:5], 10, v[4:5]
	s_movk_i32 s0, 0x2000
	v_lshl_add_u64 v[0:1], v[0:1], 0, v[4:5]
	v_add_co_u32_e64 v4, s[0:1], s0, v2
	global_load_dwordx4 v[12:15], v[2:3], off
	s_nop 0
	v_addc_co_u32_e64 v5, s[0:1], 0, v3, s[0:1]
	s_movk_i32 s0, 0x4000
	s_nop 0
	v_add_co_u32_e64 v8, s[0:1], s0, v2
	global_load_dwordx4 v[16:19], v[4:5], off
	s_nop 0
	v_addc_co_u32_e64 v9, s[0:1], 0, v3, s[0:1]
	global_load_dwordx4 v[20:23], v[8:9], off
	v_add_co_u32_e64 v50, s[0:1], s58, v2
	v_lshl_add_u64 v[48:49], v[0:1], 0, v[128:129]
	s_nop 0
	v_addc_co_u32_e64 v51, s[0:1], 0, v3, s[0:1]
	global_load_dwordx4 v[24:27], v[50:51], off
	global_load_dwordx4 v[28:31], v[48:49], off
	s_mov_b32 s0, 0x8000
	v_add_co_u32_e64 v52, s[0:1], s0, v48
	v_ashrrev_i32_e32 v0, 1, v104
	s_nop 0
	v_addc_co_u32_e64 v53, s[0:1], 0, v49, s[0:1]
	v_add_co_u32_e64 v54, s[0:1], s11, v48
	global_load_dwordx4 v[36:39], v[52:53], off
	s_nop 0
	v_addc_co_u32_e64 v55, s[0:1], 0, v49, s[0:1]
	global_load_dwordx4 v[40:43], v[54:55], off
	v_add_co_u32_e64 v56, s[0:1], s60, v48
	v_and_b32_e32 v134, 15, v104
	s_nop 0
	v_addc_co_u32_e64 v57, s[0:1], 0, v49, s[0:1]
	global_load_dwordx4 v[44:47], v[56:57], off
	v_and_b32_e32 v135, 0xffffffc0, v0
	v_lshlrev_b32_e32 v0, 7, v6
	v_xor_b32_e32 v1, v7, v104
	s_movk_i32 s0, 0x70
	v_bfe_u32 v128, v104, 6, 1
	v_lshlrev_b32_e32 v6, 7, v134
	v_and_or_b32 v0, v1, s0, v0
	v_lshl_or_b32 v59, v128, 13, v6
	v_add_u32_e32 v136, 0, v0
	global_load_dwordx4 v[0:3], v[2:3], off offset:128
	s_nop 0
	global_load_dwordx4 v[4:7], v[4:5], off offset:128
	s_nop 0
	global_load_dwordx4 v[8:11], v[8:9], off offset:128
	s_waitcnt vmcnt(10)
	ds_write_b128 v136, v[12:15]
	s_waitcnt vmcnt(9)
	ds_write_b128 v136, v[16:19] offset:4096
	s_waitcnt vmcnt(8)
	ds_write_b128 v136, v[20:23] offset:8192
	global_load_dwordx4 v[12:15], v[50:51], off offset:128
	global_load_dwordx4 v[16:19], v[48:49], off offset:128
	global_load_dwordx4 v[20:23], v[52:53], off offset:128
	v_lshrrev_b32_e32 v58, 4, v104
	v_bfe_u32 v105, v104, 1, 3
	v_add_u32_e32 v106, 0, v59
	s_waitcnt vmcnt(10)
	ds_write_b128 v136, v[24:27] offset:12288
	global_load_dwordx4 v[24:27], v[54:55], off offset:128
	s_waitcnt vmcnt(10)
	ds_write_b128 v136, v[28:31] offset:16384
	global_load_dwordx4 v[28:31], v[56:57], off offset:128
	v_bfe_u32 v137, v104, 4, 2
	v_bitop3_b32 v104, v137, v105, 4 bitop3:0x36
	v_lshlrev_b32_e32 v109, 4, v104
	v_add_u32_e32 v122, v106, v109
	s_mov_b64 s[0:1], 0x800000
	v_lshl_add_u64 v[34:35], v[34:35], 0, s[0:1]
	s_waitcnt vmcnt(10)
	ds_write_b128 v136, v[36:39] offset:20480
	v_bitop3_b32 v36, v58, v105, 3 bitop3:0x6c
	v_readlane_b32 s0, v251, 26
	s_waitcnt vmcnt(9)
	ds_write_b128 v136, v[40:43] offset:24576
	v_lshlrev_b32_e32 v40, 4, v36
	v_add_u32_e32 v120, v106, v40
	v_or_b32_e32 v41, v135, v134
	v_lshl_add_u32 v108, v41, 7, 0
	v_add_u32_e32 v121, v108, v40
	s_waitcnt vmcnt(8)
	ds_write_b128 v136, v[44:47] offset:28672
	s_waitcnt lgkmcnt(0)
	s_barrier
	ds_read_b128 v[36:39], v120 offset:16384
	ds_read_b128 v[48:51], v120 offset:18432
	ds_read_b128 v[56:59], v120 offset:20480
	ds_read_b128 v[64:67], v120 offset:22528
	ds_read_b128 v[40:43], v121
	ds_read_b128 v[68:71], v121 offset:2048
	ds_read_b128 v[84:87], v121 offset:4096
	ds_read_b128 v[100:103], v121 offset:6144
	ds_read_b128 v[104:107], v122 offset:16384
	v_add_u32_e32 v124, v108, v109
	ds_read_b128 v[108:111], v122 offset:18432
	ds_read_b128 v[112:115], v122 offset:20480
	ds_read_b128 v[116:119], v122 offset:22528
	s_waitcnt lgkmcnt(7)
	v_mfma_f32_16x16x32_bf16 v[44:47], v[36:39], v[40:43], 0
	v_cndmask_b32_e32 v33, v35, v33, vcc
	v_cndmask_b32_e32 v32, v34, v32, vcc
	v_readlane_b32 s1, v251, 27
	v_mfma_f32_16x16x32_bf16 v[52:55], v[48:51], v[40:43], 0
	s_nop 0
	v_lshl_add_u64 v[32:33], v[32:33], 1, s[0:1]
	s_movk_i32 s0, 0x4f
	v_mfma_f32_16x16x32_bf16 v[60:63], v[56:59], v[40:43], 0
	v_mfma_f32_16x16x32_bf16 v[40:43], v[64:67], v[40:43], 0
	s_waitcnt lgkmcnt(6)
	v_mfma_f32_16x16x32_bf16 v[72:75], v[36:39], v[68:71], 0
	v_mfma_f32_16x16x32_bf16 v[76:79], v[48:51], v[68:71], 0
	v_mfma_f32_16x16x32_bf16 v[80:83], v[56:59], v[68:71], 0
	v_mfma_f32_16x16x32_bf16 v[68:71], v[64:67], v[68:71], 0
	s_waitcnt lgkmcnt(5)
	v_mfma_f32_16x16x32_bf16 v[88:91], v[36:39], v[84:87], 0
	v_mfma_f32_16x16x32_bf16 v[92:95], v[48:51], v[84:87], 0
	v_mfma_f32_16x16x32_bf16 v[96:99], v[56:59], v[84:87], 0
	v_mfma_f32_16x16x32_bf16 v[84:87], v[64:67], v[84:87], 0
	s_waitcnt lgkmcnt(4)
	v_mfma_f32_16x16x32_bf16 v[36:39], v[36:39], v[100:103], 0
	v_mfma_f32_16x16x32_bf16 v[48:51], v[48:51], v[100:103], 0
	v_mfma_f32_16x16x32_bf16 v[56:59], v[56:59], v[100:103], 0
	v_mfma_f32_16x16x32_bf16 v[64:67], v[64:67], v[100:103], 0
	ds_read_b128 v[100:103], v124
	s_waitcnt lgkmcnt(0)
	v_mfma_f32_16x16x32_bf16 v[44:47], v[104:107], v[100:103], v[44:47]
	v_mfma_f32_16x16x32_bf16 v[52:55], v[108:111], v[100:103], v[52:55]
	v_mfma_f32_16x16x32_bf16 v[60:63], v[112:115], v[100:103], v[60:63]
	v_mfma_f32_16x16x32_bf16 v[40:43], v[116:119], v[100:103], v[40:43]
	ds_read_b128 v[100:103], v124 offset:2048
	s_waitcnt lgkmcnt(0)
	v_mfma_f32_16x16x32_bf16 v[72:75], v[104:107], v[100:103], v[72:75]
	v_mfma_f32_16x16x32_bf16 v[76:79], v[108:111], v[100:103], v[76:79]
	v_mfma_f32_16x16x32_bf16 v[80:83], v[112:115], v[100:103], v[80:83]
	v_mfma_f32_16x16x32_bf16 v[68:71], v[116:119], v[100:103], v[68:71]
	ds_read_b128 v[100:103], v124 offset:4096
	s_waitcnt lgkmcnt(0)
	v_mfma_f32_16x16x32_bf16 v[88:91], v[104:107], v[100:103], v[88:91]
	v_mfma_f32_16x16x32_bf16 v[92:95], v[108:111], v[100:103], v[92:95]
	v_mfma_f32_16x16x32_bf16 v[96:99], v[112:115], v[100:103], v[96:99]
	v_mfma_f32_16x16x32_bf16 v[84:87], v[116:119], v[100:103], v[84:87]
	ds_read_b128 v[100:103], v124 offset:6144
	s_waitcnt vmcnt(7)
	ds_write_b128 v136, v[0:3] offset:32768
	s_waitcnt vmcnt(6)
	ds_write_b128 v136, v[4:7] offset:36864
	s_waitcnt vmcnt(5)
	ds_write_b128 v136, v[8:11] offset:40960
	s_waitcnt vmcnt(4)
	ds_write_b128 v136, v[12:15] offset:45056
	s_waitcnt vmcnt(3)
	ds_write_b128 v136, v[16:19] offset:49152
	s_waitcnt vmcnt(2)
	ds_write_b128 v136, v[20:23] offset:53248
	s_waitcnt vmcnt(1)
	ds_write_b128 v136, v[24:27] offset:57344
	s_waitcnt vmcnt(0)
	ds_write_b128 v136, v[28:31] offset:61440
	s_waitcnt lgkmcnt(0)
	v_mfma_f32_16x16x32_bf16 v[36:39], v[104:107], v[100:103], v[36:39]
	s_barrier
	ds_read_b128 v[104:107], v120 offset:49152
	v_mfma_f32_16x16x32_bf16 v[48:51], v[108:111], v[100:103], v[48:51]
	ds_read_b128 v[108:111], v120 offset:51200
	v_mfma_f32_16x16x32_bf16 v[56:59], v[112:115], v[100:103], v[56:59]
	ds_read_b128 v[112:115], v120 offset:53248
	v_mfma_f32_16x16x32_bf16 v[64:67], v[116:119], v[100:103], v[64:67]
	ds_read_b128 v[116:119], v120 offset:55296
	ds_read_b128 v[100:103], v121 offset:32768
	s_waitcnt lgkmcnt(0)
	v_mfma_f32_16x16x32_bf16 v[44:47], v[104:107], v[100:103], v[44:47]
	v_mfma_f32_16x16x32_bf16 v[52:55], v[108:111], v[100:103], v[52:55]
	v_mfma_f32_16x16x32_bf16 v[60:63], v[112:115], v[100:103], v[60:63]
	v_mfma_f32_16x16x32_bf16 v[40:43], v[116:119], v[100:103], v[40:43]
	ds_read_b128 v[100:103], v121 offset:34816
	s_waitcnt lgkmcnt(0)
	v_mfma_f32_16x16x32_bf16 v[72:75], v[104:107], v[100:103], v[72:75]
	v_mfma_f32_16x16x32_bf16 v[76:79], v[108:111], v[100:103], v[76:79]
	v_mfma_f32_16x16x32_bf16 v[80:83], v[112:115], v[100:103], v[80:83]
	v_mfma_f32_16x16x32_bf16 v[68:71], v[116:119], v[100:103], v[68:71]
	ds_read_b128 v[100:103], v121 offset:36864
	s_waitcnt lgkmcnt(0)
	v_mfma_f32_16x16x32_bf16 v[88:91], v[104:107], v[100:103], v[88:91]
	v_mfma_f32_16x16x32_bf16 v[92:95], v[108:111], v[100:103], v[92:95]
	v_mfma_f32_16x16x32_bf16 v[96:99], v[112:115], v[100:103], v[96:99]
	v_mfma_f32_16x16x32_bf16 v[84:87], v[116:119], v[100:103], v[84:87]
	ds_read_b128 v[100:103], v121 offset:38912
	s_waitcnt lgkmcnt(0)
	v_mfma_f32_16x16x32_bf16 v[36:39], v[104:107], v[100:103], v[36:39]
	ds_read_b128 v[104:107], v122 offset:49152
	v_mfma_f32_16x16x32_bf16 v[48:51], v[108:111], v[100:103], v[48:51]
	ds_read_b128 v[108:111], v122 offset:51200
	v_mfma_f32_16x16x32_bf16 v[56:59], v[112:115], v[100:103], v[56:59]
	ds_read_b128 v[112:115], v122 offset:53248
	v_mfma_f32_16x16x32_bf16 v[64:67], v[116:119], v[100:103], v[64:67]
	ds_read_b128 v[116:119], v122 offset:55296
	ds_read_b128 v[100:103], v124 offset:32768
	s_waitcnt lgkmcnt(0)
	v_mfma_f32_16x16x32_bf16 v[44:47], v[104:107], v[100:103], v[44:47]
	v_mfma_f32_16x16x32_bf16 v[52:55], v[108:111], v[100:103], v[52:55]
	v_mfma_f32_16x16x32_bf16 v[60:63], v[112:115], v[100:103], v[60:63]
	v_mfma_f32_16x16x32_bf16 v[40:43], v[116:119], v[100:103], v[40:43]
	ds_read_b128 v[100:103], v124 offset:34816
	ds_read_b128 v[120:123], v124 offset:36864
	ds_read_b128 v[124:127], v124 offset:38912
	ds_write_b128 v136, v[0:3]
	v_or_b32_e32 v0, v134, v132
	v_add_u32_e32 v0, v0, v135
	ds_write_b128 v136, v[4:7] offset:4096
	ds_write_b128 v136, v[8:11] offset:8192
	ds_write_b128 v136, v[12:15] offset:12288
	ds_write_b128 v136, v[16:19] offset:16384
	ds_write_b128 v136, v[20:23] offset:20480
	ds_write_b128 v136, v[24:27] offset:24576
	s_waitcnt lgkmcnt(8)
	v_mfma_f32_16x16x32_bf16 v[20:23], v[116:119], v[120:123], v[84:87]
	v_lshlrev_b32_e32 v1, 6, v128
	v_lshlrev_b32_e32 v2, 2, v137
	ds_write_b128 v136, v[28:31] offset:28672
	v_and_or_b32 v85, v0, s0, v130
	v_cndmask_b32_e64 v86, 11, 9, vcc
	v_or3_b32 v84, v1, v2, v133
	v_lshlrev_b32_e32 v1, v86, v85
	v_lshlrev_b32_e32 v128, 1, v1
	v_ashrrev_i32_e32 v0, 7, v0
	v_cndmask_b32_e64 v1, 10, 8, vcc
	s_waitcnt lgkmcnt(8)
	v_mfma_f32_16x16x32_bf16 v[24:27], v[104:107], v[124:127], v[36:39]
	v_lshl_add_u64 v[34:35], v[32:33], 0, v[128:129]
	v_lshlrev_b32_e32 v128, 1, v84
	s_waitcnt lgkmcnt(0)
	v_lshlrev_b32_e32 v36, v1, v0
	v_and_b32_sdwa v38, v46, v170 dst_sel:DWORD dst_unused:UNUSED_PAD src0_sel:WORD_1 src1_sel:DWORD
	v_and_b32_sdwa v39, v44, v170 dst_sel:DWORD dst_unused:UNUSED_PAD src0_sel:WORD_1 src1_sel:DWORD
	v_ashrrev_i32_e32 v37, 31, v36
	v_add3_u32 v44, v44, v39, s56
	v_add3_u32 v38, v46, v38, s56
	v_and_b32_sdwa v39, v47, v170 dst_sel:DWORD dst_unused:UNUSED_PAD src0_sel:WORD_1 src1_sel:DWORD
	v_and_b32_sdwa v46, v45, v170 dst_sel:DWORD dst_unused:UNUSED_PAD src0_sel:WORD_1 src1_sel:DWORD
	v_lshlrev_b64 v[36:37], 1, v[36:37]
	v_add3_u32 v39, v47, v39, s56
	v_add3_u32 v45, v45, v46, s56
	v_lshl_add_u64 v[34:35], v[34:35], 0, v[36:37]
	v_and_b32_e32 v39, 0xffff0000, v39
	v_and_b32_e32 v45, 0xffff0000, v45
	v_lshl_add_u64 v[34:35], v[34:35], 0, v[128:129]
	v_or_b32_sdwa v39, v39, v38 dst_sel:DWORD dst_unused:UNUSED_PAD src0_sel:DWORD src1_sel:WORD_1
	v_or_b32_sdwa v38, v45, v44 dst_sel:DWORD dst_unused:UNUSED_PAD src0_sel:DWORD src1_sel:WORD_1
	s_barrier
	global_store_dwordx2 v[34:35], v[38:39], off
	v_cvt_pk_bf16_f32 v39, v54, v55
	v_cvt_pk_bf16_f32 v38, v52, v53
	global_store_dwordx2 v[34:35], v[38:39], off offset:32
	v_cvt_pk_bf16_f32 v39, v62, v63
	v_cvt_pk_bf16_f32 v38, v60, v61
	global_store_dwordx2 v[34:35], v[38:39], off offset:64
	v_and_b32_sdwa v38, v42, v170 dst_sel:DWORD dst_unused:UNUSED_PAD src0_sel:WORD_1 src1_sel:DWORD
	v_and_b32_sdwa v39, v40, v170 dst_sel:DWORD dst_unused:UNUSED_PAD src0_sel:WORD_1 src1_sel:DWORD
	v_add3_u32 v40, v40, v39, s56
	v_add3_u32 v38, v42, v38, s56
	v_and_b32_sdwa v39, v43, v170 dst_sel:DWORD dst_unused:UNUSED_PAD src0_sel:WORD_1 src1_sel:DWORD
	v_and_b32_sdwa v42, v41, v170 dst_sel:DWORD dst_unused:UNUSED_PAD src0_sel:WORD_1 src1_sel:DWORD
	v_mfma_f32_16x16x32_bf16 v[72:75], v[104:107], v[100:103], v[72:75]
	v_add3_u32 v39, v43, v39, s56
	v_add3_u32 v41, v41, v42, s56
	v_and_b32_e32 v39, 0xffff0000, v39
	v_and_b32_e32 v41, 0xffff0000, v41
	v_or_b32_sdwa v39, v39, v38 dst_sel:DWORD dst_unused:UNUSED_PAD src0_sel:DWORD src1_sel:WORD_1
	v_or_b32_sdwa v38, v41, v40 dst_sel:DWORD dst_unused:UNUSED_PAD src0_sel:DWORD src1_sel:WORD_1
	global_store_dwordx2 v[34:35], v[38:39], off offset:96
	v_or_b32_e32 v34, 16, v85
	v_lshlrev_b32_e32 v34, v86, v34
	v_mfma_f32_16x16x32_bf16 v[76:79], v[108:111], v[100:103], v[76:79]
	v_lshlrev_b32_e32 v34, 1, v34
	v_mov_b32_e32 v35, v129
	v_lshl_add_u64 v[34:35], v[32:33], 0, v[34:35]
	v_lshl_add_u64 v[34:35], v[34:35], 0, v[36:37]
	v_lshl_add_u64 v[34:35], v[34:35], 0, v[128:129]
	v_cvt_pk_bf16_f32 v39, v74, v75
	v_cvt_pk_bf16_f32 v38, v72, v73
	global_store_dwordx2 v[34:35], v[38:39], off
	v_mfma_f32_16x16x32_bf16 v[80:83], v[112:115], v[100:103], v[80:83]
	v_cvt_pk_bf16_f32 v39, v78, v79
	v_cvt_pk_bf16_f32 v38, v76, v77
	global_store_dwordx2 v[34:35], v[38:39], off offset:32
	v_mfma_f32_16x16x32_bf16 v[68:71], v[116:119], v[100:103], v[68:71]
	v_cvt_pk_bf16_f32 v39, v82, v83
	v_cvt_pk_bf16_f32 v38, v80, v81
	global_store_dwordx2 v[34:35], v[38:39], off offset:64
	v_mfma_f32_16x16x32_bf16 v[8:11], v[104:107], v[120:123], v[88:91]
	v_cvt_pk_bf16_f32 v39, v70, v71
	v_cvt_pk_bf16_f32 v38, v68, v69
	global_store_dwordx2 v[34:35], v[38:39], off offset:96
	v_or_b32_e32 v34, 32, v85
	v_lshlrev_b32_e32 v34, v86, v34
	v_and_b32_sdwa v39, v8, v170 dst_sel:DWORD dst_unused:UNUSED_PAD src0_sel:WORD_1 src1_sel:DWORD
	v_mfma_f32_16x16x32_bf16 v[12:15], v[108:111], v[120:123], v[92:95]
	v_lshlrev_b32_e32 v34, 1, v34
	v_mov_b32_e32 v35, v129
	v_add3_u32 v8, v8, v39, s56
	v_and_b32_sdwa v39, v9, v170 dst_sel:DWORD dst_unused:UNUSED_PAD src0_sel:WORD_1 src1_sel:DWORD
	v_lshl_add_u64 v[34:35], v[32:33], 0, v[34:35]
	v_add3_u32 v9, v9, v39, s56
	v_lshl_add_u64 v[34:35], v[34:35], 0, v[36:37]
	v_and_b32_e32 v38, 0xffff0000, v9
	v_lshl_add_u64 v[34:35], v[34:35], 0, v[128:129]
	v_cvt_pk_bf16_f32 v9, v10, v11
	v_or_b32_sdwa v8, v38, v8 dst_sel:DWORD dst_unused:UNUSED_PAD src0_sel:DWORD src1_sel:WORD_1
	global_store_dwordx2 v[34:35], v[8:9], off
	v_mfma_f32_16x16x32_bf16 v[16:19], v[112:115], v[120:123], v[96:99]
	v_cvt_pk_bf16_f32 v9, v14, v15
	v_cvt_pk_bf16_f32 v8, v12, v13
	global_store_dwordx2 v[34:35], v[8:9], off offset:32
	v_cvt_pk_bf16_f32 v9, v18, v19
	v_cvt_pk_bf16_f32 v8, v16, v17
	global_store_dwordx2 v[34:35], v[8:9], off offset:64
	v_cvt_pk_bf16_f32 v9, v22, v23
	v_cvt_pk_bf16_f32 v8, v20, v21
	global_store_dwordx2 v[34:35], v[8:9], off offset:96
	v_or_b32_e32 v8, 48, v85
	v_lshlrev_b32_e32 v8, v86, v8
	v_mfma_f32_16x16x32_bf16 v[28:31], v[108:111], v[124:127], v[48:51]
	v_lshlrev_b32_e32 v8, 1, v8
	v_mov_b32_e32 v9, v129
	v_lshl_add_u64 v[8:9], v[32:33], 0, v[8:9]
	v_lshl_add_u64 v[8:9], v[8:9], 0, v[36:37]
	v_lshl_add_u64 v[8:9], v[8:9], 0, v[128:129]
	v_cvt_pk_bf16_f32 v11, v26, v27
	v_cvt_pk_bf16_f32 v10, v24, v25
	global_store_dwordx2 v[8:9], v[10:11], off
	v_mfma_f32_16x16x32_bf16 v[4:7], v[112:115], v[124:127], v[56:59]
	v_cvt_pk_bf16_f32 v11, v30, v31
	v_cvt_pk_bf16_f32 v10, v28, v29
	global_store_dwordx2 v[8:9], v[10:11], off offset:32
	v_and_b32_sdwa v11, v4, v170 dst_sel:DWORD dst_unused:UNUSED_PAD src0_sel:WORD_1 src1_sel:DWORD
	v_mfma_f32_16x16x32_bf16 v[0:3], v[116:119], v[124:127], v[64:67]
	v_add3_u32 v4, v4, v11, s56
	v_and_b32_sdwa v11, v5, v170 dst_sel:DWORD dst_unused:UNUSED_PAD src0_sel:WORD_1 src1_sel:DWORD
	v_add3_u32 v5, v5, v11, s56
	v_and_b32_e32 v10, 0xffff0000, v5
	v_cvt_pk_bf16_f32 v5, v6, v7
	v_or_b32_sdwa v4, v10, v4 dst_sel:DWORD dst_unused:UNUSED_PAD src0_sel:DWORD src1_sel:WORD_1
	global_store_dwordx2 v[8:9], v[4:5], off offset:64
	v_bfe_u32 v4, v0, 16, 1
	v_add3_u32 v0, v0, v4, s56
	v_bfe_u32 v4, v1, 16, 1
	v_lshrrev_b32_e32 v0, 16, v0
	v_add3_u32 v1, v1, v4, s56
	v_and_or_b32 v4, v1, s5, v0
	v_bfe_u32 v0, v2, 16, 1
	v_add3_u32 v0, v2, v0, s56
	v_bfe_u32 v1, v3, 16, 1
	v_lshrrev_b32_e32 v0, 16, v0
	v_add3_u32 v1, v3, v1, s56
	s_mov_b64 s[0:1], 0x60
	v_and_or_b32 v2, v1, s5, v0
	v_lshl_add_u64 v[0:1], v[8:9], 0, s[0:1]
	global_store_dword v[8:9], v4, off offset:96

.LBB0_228:
	v_add_u32_e32 v32, s0, v18
	ds_read_b128 v[10:13], v32 offset:256
	ds_read_b128 v[28:31], v32
	v_add_u32_e32 v16, s0, v19
	ds_read_b128 v[24:27], v16
	s_addk_i32 s0, 0x80
	s_cmpk_lg_i32 s0, 0x900
	s_waitcnt lgkmcnt(0)
	v_mfma_f32_16x16x32_bf16 v[4:7], v[10:13], v[24:27], v[4:7]
	v_mfma_f32_16x16x32_bf16 v[0:3], v[28:31], v[24:27], v[0:3]
	ds_read_b128 v[10:13], v32 offset:320
	ds_read_b128 v[24:27], v32 offset:64
	ds_read_b128 v[28:31], v16 offset:64
	s_waitcnt lgkmcnt(0)
	v_mfma_f32_16x16x32_bf16 v[4:7], v[10:13], v[28:31], v[4:7]
	v_mfma_f32_16x16x32_bf16 v[0:3], v[24:27], v[28:31], v[0:3]
	s_cbranch_scc1 .LBB0_228
	global_load_dword v18, v[14:15], off offset:2048
	v_mov_b64_e32 v[10:11], s[86:87]
	s_movk_i32 s0, 0x5000
	v_mad_i64_i32 v[10:11], s[0:1], v8, s0, v[10:11]
	v_lshlrev_b32_e32 v128, 11, v17
	v_lshl_add_u64 v[10:11], v[10:11], 0, v[128:129]
	v_lshlrev_b32_e32 v128, 2, v9
	v_or_b32_e32 v8, v23, v128
	v_lshl_add_u32 v14, v8, 1, v22
	v_ashrrev_i32_e32 v9, 31, v20
	v_sub_co_u32_e32 v8, vcc, v20, v21
	v_mov_b32_e32 v25, v6
	s_nop 0
	v_subbrev_co_u32_e32 v9, vcc, 0, v9, vcc
	v_lshl_add_u64 v[8:9], v[8:9], 0, v[128:129]
	v_lshl_add_u64 v[8:9], v[8:9], 1, v[10:11]
	ds_read2_b64 v[10:13], v14 offset0:32 offset1:64
	v_add_u32_e32 v14, 0x2800, v14
	ds_read2_b64 v[14:17], v14 offset0:40 offset1:72
	v_mov_b32_e32 v6, v5
	v_mov_b32_e32 v24, v4
	s_waitcnt lgkmcnt(1)
	v_lshlrev_b32_e32 v21, 16, v11
	v_lshlrev_b32_e32 v20, 16, v10
	v_and_b32_e32 v11, 0xffff0000, v11
	v_and_b32_e32 v10, 0xffff0000, v10
	s_waitcnt lgkmcnt(0)
	v_lshlrev_b32_e32 v23, 16, v15
	v_lshlrev_b32_e32 v22, 16, v14
	v_and_b32_e32 v15, 0xffff0000, v15
	v_and_b32_e32 v14, 0xffff0000, v14
	s_mov_b64 s[0:1], 0x9a7e000
	v_lshl_add_u64 v[8:9], v[8:9], 0, s[0:1]
	s_mov_b64 s[0:1], 0x1e0
	s_waitcnt vmcnt(0)
	v_pk_fma_f32 v[4:5], v[18:19], v[10:11], v[6:7] op_sel_hi:[0,1,1]
	v_pk_fma_f32 v[20:21], v[18:19], v[20:21], v[24:25] op_sel_hi:[0,1,1]
	v_pk_mul_f32 v[4:5], v[4:5], v[14:15]
	v_pk_mul_f32 v[20:21], v[20:21], v[22:23]
	v_lshlrev_b32_e32 v10, 16, v12
	v_cvt_pk_bf16_f32 v5, v21, v5
	v_cvt_pk_bf16_f32 v4, v20, v4
	v_and_b32_e32 v11, 0xffff0000, v12
	v_lshlrev_b32_e32 v12, 16, v16
	v_fma_f32 v0, v18, v10, v0
	global_store_dwordx2 v[8:9], v[4:5], off offset:224
	v_lshlrev_b32_e32 v4, 16, v13
	v_and_b32_e32 v5, 0xffff0000, v13
	v_and_b32_e32 v13, 0xffff0000, v16
	v_mul_f32_e32 v0, v0, v12
	v_fma_f32 v1, v18, v11, v1
	v_mul_f32_e32 v1, v1, v13
	v_bfe_u32 v10, v0, 16, 1
	v_add3_u32 v0, v0, v10, s56
	v_bfe_u32 v10, v1, 16, 1
	v_lshrrev_b32_e32 v0, 16, v0
	v_add3_u32 v1, v1, v10, s56
	v_lshlrev_b32_e32 v6, 16, v17
	v_and_b32_e32 v7, 0xffff0000, v17
	v_and_or_b32 v10, v1, s5, v0
	v_pk_fma_f32 v[0:1], v[18:19], v[4:5], v[2:3] op_sel_hi:[0,1,1]
	v_pk_mul_f32 v[0:1], v[0:1], v[6:7]
	global_store_dword v[8:9], v10, off offset:480
	v_and_b32_sdwa v3, v0, v170 dst_sel:DWORD dst_unused:UNUSED_PAD src0_sel:WORD_1 src1_sel:DWORD
	v_and_b32_sdwa v2, v1, v170 dst_sel:DWORD dst_unused:UNUSED_PAD src0_sel:WORD_1 src1_sel:DWORD
	v_add3_u32 v0, v0, v3, s56
	v_add3_u32 v1, v1, v2, s56
	v_lshrrev_b32_e32 v0, 16, v0
	v_and_or_b32 v2, v1, s5, v0
	v_lshl_add_u64 v[0:1], v[8:9], 0, s[0:1]
	s_branch .LBB0_157

.Ltail236:
	s_add_i32 s24, s25, 2
	v_add_u32_e32 v111, v104, v105
	ds_read_b128 v[136:139], v111 offset:16384
	ds_read_b128 v[140:143], v111 offset:18432
	ds_read_b128 v[144:147], v111 offset:20480
	ds_read_b128 v[148:151], v111 offset:22528
	v_add_u32_e32 v110, v103, v105
	ds_read_b128 v[116:119], v110
	s_add_i32 s25, s25, 4
	ds_read_b128 v[120:123], v110 offset:2048
	s_min_u32 s25, s25, 63
	v_add_u32_e32 v113, v104, v114
	s_lshl_b32 s92, s25, 7
	ds_read_b128 v[124:127], v110 offset:4096
	v_add_u32_e32 v112, v103, v114
	ds_read_b128 v[194:197], v113 offset:16384
	ds_read_b128 v[198:201], v113 offset:18432
	ds_read_b128 v[202:205], v113 offset:20480
	ds_read_b128 v[206:209], v113 offset:22528
	v_lshl_add_u64 v[164:165], v[98:99], 0, s[92:93]
	ds_read_b128 v[132:135], v110 offset:6144
	ds_read_b128 v[152:155], v112
	ds_read_b128 v[156:159], v112 offset:2048
	ds_read_b128 v[160:163], v112 offset:4096
	ds_read_b128 v[190:193], v112 offset:6144
	s_waitcnt lgkmcnt(11)
	v_mfma_f32_16x16x32_bf16 v[92:95], v[136:139], v[116:119], v[92:95]
	v_mfma_f32_16x16x32_bf16 v[56:59], v[140:143], v[116:119], v[56:59]
	v_mfma_f32_16x16x32_bf16 v[52:55], v[144:147], v[116:119], v[52:55]
	v_mfma_f32_16x16x32_bf16 v[48:51], v[148:151], v[116:119], v[48:51]
	s_waitcnt vmcnt(7)
	ds_write_b128 v109, v[60:63] offset:32768
	v_add_co_u32_e32 v60, vcc, s7, v164
	s_waitcnt lgkmcnt(11)
	v_mfma_f32_16x16x32_bf16 v[44:47], v[136:139], v[120:123], v[44:47]
	v_addc_co_u32_e32 v61, vcc, 0, v165, vcc
	v_mfma_f32_16x16x32_bf16 v[40:43], v[140:143], v[120:123], v[40:43]
	v_mfma_f32_16x16x32_bf16 v[36:39], v[144:147], v[120:123], v[36:39]
	v_mfma_f32_16x16x32_bf16 v[32:35], v[148:151], v[120:123], v[32:35]
	v_add_co_u32_e32 v60, vcc, s52, v164
	s_waitcnt vmcnt(6)
	ds_write_b128 v109, v[64:67] offset:36864
	s_nop 0
	v_addc_co_u32_e32 v61, vcc, 0, v165, vcc
	s_waitcnt lgkmcnt(11)
	v_mfma_f32_16x16x32_bf16 v[28:31], v[136:139], v[124:127], v[28:31]
	v_lshl_add_u64 v[64:65], v[100:101], 0, s[92:93]
	v_mfma_f32_16x16x32_bf16 v[24:27], v[140:143], v[124:127], v[24:27]
	v_mfma_f32_16x16x32_bf16 v[20:23], v[144:147], v[124:127], v[20:23]
	v_mfma_f32_16x16x32_bf16 v[16:19], v[148:151], v[124:127], v[16:19]
	v_add_co_u32_e32 v60, vcc, s34, v164
	s_waitcnt vmcnt(5)
	ds_write_b128 v109, v[68:71] offset:40960
	s_nop 0
	v_addc_co_u32_e32 v61, vcc, 0, v165, vcc
	v_add_co_u32_e32 v66, vcc, s7, v64
	s_waitcnt lgkmcnt(7)
	v_mfma_f32_16x16x32_bf16 v[12:15], v[136:139], v[132:135], v[12:15]
	v_addc_co_u32_e32 v67, vcc, 0, v65, vcc
	v_mfma_f32_16x16x32_bf16 v[8:11], v[140:143], v[132:135], v[8:11]
	v_mfma_f32_16x16x32_bf16 v[4:7], v[144:147], v[132:135], v[4:7]
	v_mfma_f32_16x16x32_bf16 v[0:3], v[148:151], v[132:135], v[0:3]
	s_waitcnt vmcnt(4)
	ds_write_b128 v109, v[76:79] offset:45056
	s_waitcnt lgkmcnt(7)
	v_mfma_f32_16x16x32_bf16 v[60:63], v[194:197], v[152:155], v[92:95]
	v_mfma_f32_16x16x32_bf16 v[56:59], v[198:201], v[152:155], v[56:59]
	v_mfma_f32_16x16x32_bf16 v[52:55], v[202:205], v[152:155], v[52:55]
	v_mfma_f32_16x16x32_bf16 v[48:51], v[206:209], v[152:155], v[48:51]
	s_waitcnt vmcnt(3)
	ds_write_b128 v109, v[72:75] offset:49152
	s_waitcnt lgkmcnt(7)
	v_mfma_f32_16x16x32_bf16 v[44:47], v[194:197], v[156:159], v[44:47]
	v_mfma_f32_16x16x32_bf16 v[40:43], v[198:201], v[156:159], v[40:43]
	v_mfma_f32_16x16x32_bf16 v[36:39], v[202:205], v[156:159], v[36:39]
	v_mfma_f32_16x16x32_bf16 v[32:35], v[206:209], v[156:159], v[32:35]
	v_add_co_u32_e32 v66, vcc, s52, v64
	s_waitcnt vmcnt(2)
	ds_write_b128 v109, v[80:83] offset:53248
	v_addc_co_u32_e32 v67, vcc, 0, v65, vcc
	v_add_co_u32_e32 v64, vcc, s34, v64
	s_waitcnt lgkmcnt(7)
	v_mfma_f32_16x16x32_bf16 v[28:31], v[194:197], v[160:163], v[28:31]
	v_addc_co_u32_e32 v65, vcc, 0, v65, vcc
	v_mfma_f32_16x16x32_bf16 v[24:27], v[198:201], v[160:163], v[24:27]
	v_mfma_f32_16x16x32_bf16 v[20:23], v[202:205], v[160:163], v[20:23]
	v_mfma_f32_16x16x32_bf16 v[16:19], v[206:209], v[160:163], v[16:19]
	s_waitcnt vmcnt(1)
	ds_write_b128 v109, v[84:87] offset:57344
	s_waitcnt lgkmcnt(7)
	v_mfma_f32_16x16x32_bf16 v[12:15], v[194:197], v[190:193], v[12:15]
	v_mfma_f32_16x16x32_bf16 v[8:11], v[198:201], v[190:193], v[8:11]
	v_mfma_f32_16x16x32_bf16 v[4:7], v[202:205], v[190:193], v[4:7]
	v_mfma_f32_16x16x32_bf16 v[0:3], v[206:209], v[190:193], v[0:3]
	s_waitcnt vmcnt(0)
	ds_write_b128 v109, v[88:91] offset:61440
	s_waitcnt lgkmcnt(0)
	s_barrier
	ds_read_b128 v[80:83], v111 offset:49152
	ds_read_b128 v[84:87], v111 offset:51200
	ds_read_b128 v[88:91], v111 offset:53248
	ds_read_b128 v[92:95], v111 offset:55296
	ds_read_b128 v[64:67], v110 offset:32768
	ds_read_b128 v[68:71], v110 offset:34816
	s_min_u32 s25, s24, 60
	s_lshl_b32 s92, s25, 7
	ds_read_b128 v[72:75], v110 offset:36864
	v_lshl_add_u64 v[164:165], v[98:99], 0, s[92:93]
	ds_read_b128 v[76:79], v110 offset:38912
	ds_read_b128 v[152:155], v112 offset:32768
	ds_read_b128 v[156:159], v112 offset:34816
	ds_read_b128 v[160:163], v112 offset:36864
	ds_read_b128 v[190:193], v112 offset:38912
	ds_read_b128 v[194:197], v113 offset:49152
	ds_read_b128 v[198:201], v113 offset:51200
	ds_read_b128 v[202:205], v113 offset:53248
	ds_read_b128 v[206:209], v113 offset:55296
	s_waitcnt lgkmcnt(11)
	v_mfma_f32_16x16x32_bf16 v[210:213], v[80:83], v[64:67], v[60:63]
	v_mfma_f32_16x16x32_bf16 v[56:59], v[84:87], v[64:67], v[56:59]
	v_mfma_f32_16x16x32_bf16 v[52:55], v[88:91], v[64:67], v[52:55]
	v_mfma_f32_16x16x32_bf16 v[48:51], v[92:95], v[64:67], v[48:51]
	v_add_co_u32_e32 v64, vcc, s7, v164
	s_nop 0
	v_addc_co_u32_e32 v65, vcc, 0, v165, vcc
	s_waitcnt lgkmcnt(10)
	v_mfma_f32_16x16x32_bf16 v[44:47], v[80:83], v[68:71], v[44:47]
	v_mfma_f32_16x16x32_bf16 v[40:43], v[84:87], v[68:71], v[40:43]
	v_mfma_f32_16x16x32_bf16 v[36:39], v[88:91], v[68:71], v[36:39]
	v_mfma_f32_16x16x32_bf16 v[32:35], v[92:95], v[68:71], v[32:35]
	v_add_co_u32_e32 v68, vcc, s52, v164
	s_nop 0
	v_addc_co_u32_e32 v69, vcc, 0, v165, vcc
	s_waitcnt lgkmcnt(9)
	v_mfma_f32_16x16x32_bf16 v[28:31], v[80:83], v[72:75], v[28:31]
	v_mfma_f32_16x16x32_bf16 v[24:27], v[84:87], v[72:75], v[24:27]
	v_mfma_f32_16x16x32_bf16 v[20:23], v[88:91], v[72:75], v[20:23]
	v_mfma_f32_16x16x32_bf16 v[16:19], v[92:95], v[72:75], v[16:19]
	v_add_co_u32_e32 v72, vcc, s34, v164
	s_waitcnt lgkmcnt(8)
	v_mfma_f32_16x16x32_bf16 v[4:7], v[88:91], v[76:79], v[4:7]
	v_addc_co_u32_e32 v73, vcc, 0, v165, vcc
	v_lshl_add_u64 v[88:89], v[100:101], 0, s[92:93]
	v_mfma_f32_16x16x32_bf16 v[12:15], v[80:83], v[76:79], v[12:15]
	v_add_co_u32_e32 v80, vcc, s7, v88
	v_mfma_f32_16x16x32_bf16 v[8:11], v[84:87], v[76:79], v[8:11]
	s_nop 0
	v_addc_co_u32_e32 v81, vcc, 0, v89, vcc
	v_add_co_u32_e32 v84, vcc, s52, v88
	v_mfma_f32_16x16x32_bf16 v[0:3], v[92:95], v[76:79], v[0:3]
	s_nop 0
	v_addc_co_u32_e32 v85, vcc, 0, v89, vcc
	s_waitcnt lgkmcnt(3)
	v_mfma_f32_16x16x32_bf16 v[92:95], v[194:197], v[152:155], v[210:213]
	s_waitcnt lgkmcnt(2)
	v_mfma_f32_16x16x32_bf16 v[56:59], v[198:201], v[152:155], v[56:59]
	s_waitcnt lgkmcnt(1)
	v_mfma_f32_16x16x32_bf16 v[52:55], v[202:205], v[152:155], v[52:55]
	s_waitcnt lgkmcnt(0)
	v_mfma_f32_16x16x32_bf16 v[48:51], v[206:209], v[152:155], v[48:51]
	v_add_co_u32_e32 v88, vcc, s34, v88
	v_addc_co_u32_e32 v89, vcc, 0, v89, vcc
	v_mfma_f32_16x16x32_bf16 v[44:47], v[194:197], v[156:159], v[44:47]
	v_mfma_f32_16x16x32_bf16 v[40:43], v[198:201], v[156:159], v[40:43]
	v_mfma_f32_16x16x32_bf16 v[36:39], v[202:205], v[156:159], v[36:39]
	v_mfma_f32_16x16x32_bf16 v[32:35], v[206:209], v[156:159], v[32:35]
	v_mfma_f32_16x16x32_bf16 v[28:31], v[194:197], v[160:163], v[28:31]
	v_mfma_f32_16x16x32_bf16 v[24:27], v[198:201], v[160:163], v[24:27]
	v_mfma_f32_16x16x32_bf16 v[20:23], v[202:205], v[160:163], v[20:23]
	v_mfma_f32_16x16x32_bf16 v[16:19], v[206:209], v[160:163], v[16:19]
	v_mfma_f32_16x16x32_bf16 v[12:15], v[194:197], v[190:193], v[12:15]
	v_mfma_f32_16x16x32_bf16 v[8:11], v[198:201], v[190:193], v[8:11]
	v_mfma_f32_16x16x32_bf16 v[4:7], v[202:205], v[190:193], v[4:7]
	v_mfma_f32_16x16x32_bf16 v[0:3], v[206:209], v[190:193], v[0:3]
	s_mov_b32 s25, s24
	s_waitcnt lgkmcnt(0)
	s_barrier
	s_add_i32 s26, s69, 1
	v_readlane_b32 s16, v251, 5
	s_and_b64 s[24:25], s[8:9], exec
	s_mul_i32 s25, s69, 0x12000
	s_waitcnt vmcnt(2)
	v_add_u32_e32 v80, s16, v108
	v_readlane_b32 s28, v250, 25
	v_add_u32_e32 v60, 0xffffe000, v80
	s_cselect_b32 s24, 3, s26
	v_readlane_b32 s29, v250, 26
	s_add_u32 s25, s28, s25
	v_or_b32_e32 v70, v80, v107
	v_lshlrev_b32_e32 v114, 6, v102
	v_readlane_b32 s16, v251, 6
	v_lshrrev_b32_e32 v60, 10, v60
	s_movk_i32 s5, 0x1800
	s_addc_u32 s26, s29, 0
	v_or_b32_e32 v81, s16, v114
	v_lshlrev_b32_e32 v115, 2, v97
	v_mad_u32_u24 v60, v60, s5, s5
	v_cmp_lt_i32_e32 vcc, s13, v70
	s_add_u32 s40, s25, 0x5000
	v_or_b32_e32 v64, v81, v115
	v_cndmask_b32_e32 v76, 0, v60, vcc
	s_addc_u32 s41, s26, 0
	v_ashrrev_i32_e32 v77, 31, v76
	v_ashrrev_i32_e32 v65, 31, v64
	v_ashrrev_i32_e32 v71, 31, v70
	v_lshl_add_u64 v[60:61], v[76:77], 2, s[40:41]
	v_lshlrev_b64 v[66:67], 2, v[64:65]
	v_readlane_b32 s16, v250, 15
	v_lshl_add_u64 v[74:75], v[60:61], 0, v[66:67]
	v_lshlrev_b64 v[60:61], 12, v[70:71]
	v_readlane_b32 s17, v250, 16
	v_readlane_b32 s68, v250, 41
	s_mul_i32 s25, s24, 0x12000
	v_lshl_add_u64 v[60:61], s[16:17], 0, v[60:61]
	v_lshl_add_u64 v[72:73], v[60:61], 0, v[66:67]
	global_load_dwordx4 v[116:119], v[74:75], off
	global_load_dwordx4 v[120:123], v[74:75], off offset:64
	global_load_dwordx4 v[124:127], v[74:75], off offset:128
	global_load_dwordx4 v[132:135], v[74:75], off offset:192
	global_load_dwordx4 v[190:193], v[72:73], off
	global_load_dwordx4 v[194:197], v[72:73], off offset:64
	global_load_dwordx4 v[198:201], v[72:73], off offset:128
	global_load_dwordx4 v[202:205], v[72:73], off offset:192
	v_add_co_u32_e32 v164, vcc, 0x10000, v72
	s_nop 1
	v_addc_co_u32_e32 v165, vcc, 0, v73, vcc
	v_add_co_u32_e32 v222, vcc, 0x20000, v72
	s_nop 1
	v_addc_co_u32_e32 v223, vcc, 0, v73, vcc
	v_add_co_u32_e32 v224, vcc, 0x30000, v72
	s_nop 1
	v_addc_co_u32_e32 v225, vcc, 0, v73, vcc
	global_load_dwordx4 v[206:209], v[164:165], off
	global_load_dwordx4 v[210:213], v[164:165], off offset:64
	global_load_dwordx4 v[214:217], v[164:165], off offset:128
	global_load_dwordx4 v[218:221], v[164:165], off offset:192
	s_lshl_b32 s24, s24, 12
	v_readlane_b32 s70, v250, 43
	v_readlane_b32 s71, v250, 44
	s_add_u32 s26, s70, s24
	s_addc_u32 s27, s71, 0
	s_add_u32 s24, s28, s25
	s_addc_u32 s25, s29, 0
	s_add_u32 s42, s24, 0x1000
	v_cndmask_b32_e64 v68, 0, 1, s[2:3]
	s_addc_u32 s43, s25, 0
	s_andn2_b64 vcc, exec, s[2:3]
	v_readlane_b32 s2, v250, 21
	s_waitcnt vmcnt(3)
	v_lshlrev_b64 v[86:87], 10, v[70:71]
	v_readlane_b32 s3, v250, 22
	v_cmp_ne_u32_e64 s[36:37], 1, v68
	v_lshl_add_u64 v[68:69], s[26:27], 0, v[66:67]
	v_lshl_add_u64 v[78:79], v[76:77], 2, s[42:43]
	v_lshl_add_u64 v[76:77], v[86:87], 1, s[2:3]
	v_readlane_b32 s69, v250, 42
	v_readlane_b32 s72, v250, 45
	v_readlane_b32 s73, v250, 46
	v_readlane_b32 s74, v250, 47
	v_readlane_b32 s75, v250, 48
	v_readlane_b32 s76, v250, 49
	v_readlane_b32 s77, v250, 50
	v_readlane_b32 s78, v250, 51
	v_readlane_b32 s79, v250, 52
	v_readlane_b32 s80, v250, 53
	v_readlane_b32 s81, v250, 54
	v_readlane_b32 s82, v250, 55
	v_readlane_b32 s83, v250, 56
	s_waitcnt vmcnt(4)
	v_pk_fma_f32 v[62:63], v[94:95], v[118:119], v[192:193]
	v_pk_fma_f32 v[60:61], v[92:93], v[116:117], v[190:191]
	global_store_dwordx4 v[72:73], v[60:63], off
	s_cbranch_vccnz .LBB0_239
	v_lshl_add_u64 v[86:87], v[78:79], 0, v[66:67]
	global_load_dwordx4 v[136:139], v[68:69], off
	global_load_dwordx4 v[140:143], v[68:69], off offset:64
	global_load_dwordx4 v[144:147], v[68:69], off offset:128
	global_load_dwordx4 v[148:151], v[68:69], off offset:192
	s_waitcnt vmcnt(0)
	v_pk_mul_f32 v[84:85], v[62:63], v[138:139]
	global_load_dwordx4 v[152:155], v[86:87], off
	global_load_dwordx4 v[156:159], v[86:87], off offset:64
	global_load_dwordx4 v[160:163], v[86:87], off offset:128
	global_load_dwordx4 v[180:183], v[86:87], off offset:192
	v_pk_mul_f32 v[82:83], v[60:61], v[136:137]
	s_waitcnt vmcnt(0)
	v_pk_add_f32 v[88:89], v[154:155], 1.0 op_sel_hi:[1,0]
	v_pk_add_f32 v[86:87], v[152:153], 1.0 op_sel_hi:[1,0]
	v_pk_mul_f32 v[84:85], v[84:85], v[88:89]
	v_pk_mul_f32 v[82:83], v[82:83], v[86:87]
	v_and_b32_sdwa v89, v82, v170 dst_sel:DWORD dst_unused:UNUSED_PAD src0_sel:WORD_1 src1_sel:DWORD
	v_add3_u32 v82, v82, v89, s56
	v_and_b32_sdwa v89, v83, v170 dst_sel:DWORD dst_unused:UNUSED_PAD src0_sel:WORD_1 src1_sel:DWORD
	v_add3_u32 v83, v83, v89, s56
	v_and_b32_e32 v88, 0xffff0000, v83
	v_lshl_add_u64 v[86:87], v[64:65], 1, v[76:77]
	v_cvt_pk_bf16_f32 v83, v84, v85
	v_or_b32_sdwa v82, v88, v82 dst_sel:DWORD dst_unused:UNUSED_PAD src0_sel:DWORD src1_sel:WORD_1
	global_store_dwordx2 v[86:87], v[82:83], off
.LBB0_239:
	s_nop 0
	s_and_b64 vcc, exec, s[36:37]
	s_waitcnt vmcnt(0)
	v_pk_fma_f32 v[58:59], v[58:59], v[122:123], v[196:197]
	v_pk_fma_f32 v[56:57], v[56:57], v[120:121], v[194:195]
	global_store_dwordx4 v[72:73], v[56:59], off offset:64
	s_cbranch_vccnz .LBB0_241
	v_lshl_add_u64 v[86:87], v[78:79], 0, v[66:67]
	v_pk_mul_f32 v[84:85], v[58:59], v[142:143]
	v_pk_mul_f32 v[82:83], v[56:57], v[140:141]
	v_pk_add_f32 v[88:89], v[158:159], 1.0 op_sel_hi:[1,0]
	v_pk_add_f32 v[86:87], v[156:157], 1.0 op_sel_hi:[1,0]
	v_pk_mul_f32 v[84:85], v[84:85], v[88:89]
	v_pk_mul_f32 v[82:83], v[82:83], v[86:87]
	v_and_b32_sdwa v89, v82, v170 dst_sel:DWORD dst_unused:UNUSED_PAD src0_sel:WORD_1 src1_sel:DWORD
	v_add3_u32 v82, v82, v89, s56
	v_and_b32_sdwa v89, v83, v170 dst_sel:DWORD dst_unused:UNUSED_PAD src0_sel:WORD_1 src1_sel:DWORD
	v_add3_u32 v83, v83, v89, s56
	v_and_b32_e32 v88, 0xffff0000, v83
	v_lshl_add_u64 v[86:87], v[64:65], 1, v[76:77]
	v_cvt_pk_bf16_f32 v83, v84, v85
	v_or_b32_sdwa v82, v88, v82 dst_sel:DWORD dst_unused:UNUSED_PAD src0_sel:DWORD src1_sel:WORD_1
	global_store_dwordx2 v[86:87], v[82:83], off offset:32
.LBB0_241:
	s_nop 0
	s_and_b64 vcc, exec, s[36:37]
	s_movk_i32 s8, 0x400
	s_movk_i32 s13, 0x1fff
	s_mov_b32 s5, 0xffff0000
	s_mov_b32 s9, 0x12000
	s_movk_i32 s89, 0xff
	v_readlane_b32 s69, v254, 49
	v_pk_fma_f32 v[54:55], v[54:55], v[126:127], v[200:201]
	v_pk_fma_f32 v[52:53], v[52:53], v[124:125], v[198:199]
	global_store_dwordx4 v[72:73], v[52:55], off offset:128
	s_cbranch_vccnz .LBB0_243
	v_lshl_add_u64 v[86:87], v[78:79], 0, v[66:67]
	v_pk_mul_f32 v[84:85], v[54:55], v[146:147]
	v_pk_mul_f32 v[82:83], v[52:53], v[144:145]
	v_pk_add_f32 v[88:89], v[162:163], 1.0 op_sel_hi:[1,0]
	v_pk_add_f32 v[86:87], v[160:161], 1.0 op_sel_hi:[1,0]
	v_pk_mul_f32 v[84:85], v[84:85], v[88:89]
	v_pk_mul_f32 v[82:83], v[82:83], v[86:87]
	v_and_b32_sdwa v89, v82, v170 dst_sel:DWORD dst_unused:UNUSED_PAD src0_sel:WORD_1 src1_sel:DWORD
	v_add3_u32 v82, v82, v89, s56
	v_and_b32_sdwa v89, v83, v170 dst_sel:DWORD dst_unused:UNUSED_PAD src0_sel:WORD_1 src1_sel:DWORD
	v_add3_u32 v83, v83, v89, s56
	v_and_b32_e32 v88, 0xffff0000, v83
	v_lshl_add_u64 v[86:87], v[64:65], 1, v[76:77]
	v_cvt_pk_bf16_f32 v83, v84, v85
	v_or_b32_sdwa v82, v88, v82 dst_sel:DWORD dst_unused:UNUSED_PAD src0_sel:DWORD src1_sel:WORD_1
	global_store_dwordx2 v[86:87], v[82:83], off offset:64
.LBB0_243:
	s_nop 0
	s_and_b64 vcc, exec, s[36:37]
	v_pk_fma_f32 v[50:51], v[50:51], v[134:135], v[204:205]
	v_pk_fma_f32 v[48:49], v[48:49], v[132:133], v[202:203]
	global_store_dwordx4 v[72:73], v[48:51], off offset:192
	s_cbranch_vccnz .LBB0_245
	v_lshl_add_u64 v[78:79], v[78:79], 0, v[66:67]
	v_lshl_add_u64 v[76:77], v[64:65], 1, v[76:77]
	v_pk_mul_f32 v[74:75], v[50:51], v[150:151]
	v_pk_mul_f32 v[72:73], v[48:49], v[148:149]
	v_pk_add_f32 v[78:79], v[182:183], 1.0 op_sel_hi:[1,0]
	v_pk_add_f32 v[82:83], v[180:181], 1.0 op_sel_hi:[1,0]
	v_pk_mul_f32 v[74:75], v[74:75], v[78:79]
	v_pk_mul_f32 v[72:73], v[72:73], v[82:83]
	v_and_b32_sdwa v83, v73, v170 dst_sel:DWORD dst_unused:UNUSED_PAD src0_sel:WORD_1 src1_sel:DWORD
	v_and_b32_sdwa v79, v72, v170 dst_sel:DWORD dst_unused:UNUSED_PAD src0_sel:WORD_1 src1_sel:DWORD
	v_add3_u32 v73, v73, v83, s56
	v_add3_u32 v72, v72, v79, s56
	v_and_b32_e32 v78, 0xffff0000, v73
	v_cvt_pk_bf16_f32 v73, v74, v75
	v_or_b32_sdwa v72, v78, v72 dst_sel:DWORD dst_unused:UNUSED_PAD src0_sel:DWORD src1_sel:WORD_1
	global_store_dwordx2 v[76:77], v[72:73], off offset:96

.LBB0_247:
	s_or_b64 exec, exec, s[2:3]
	v_add_u32_e32 v50, 0xffffe010, v80
	v_or_b32_e32 v52, 16, v70
	v_lshrrev_b32_e32 v50, 10, v50
	s_movk_i32 s2, 0x1800
	v_mad_u32_u24 v50, v50, s2, s2
	v_cmp_lt_i32_e32 vcc, s13, v52
	v_ashrrev_i32_e32 v53, 31, v52
	v_readlane_b32 s2, v250, 15
	v_cndmask_b32_e32 v56, 0, v50, vcc
	v_ashrrev_i32_e32 v57, 31, v56
	s_waitcnt lgkmcnt(0)
	v_lshl_add_u64 v[50:51], v[56:57], 2, s[40:41]
	v_lshl_add_u64 v[54:55], v[50:51], 0, v[66:67]
	v_lshlrev_b64 v[50:51], 12, v[52:53]
	v_readlane_b32 s3, v250, 16
	v_lshlrev_b64 v[52:53], 10, v[52:53]
	s_and_b64 vcc, exec, s[36:37]
	v_lshl_add_u64 v[50:51], s[2:3], 0, v[50:51]
	v_lshl_add_u64 v[50:51], v[50:51], 0, v[66:67]
	v_readlane_b32 s2, v250, 21
	v_readlane_b32 s3, v250, 22
	v_lshl_add_u64 v[56:57], v[56:57], 2, s[42:43]
	global_load_dwordx4 v[190:193], v[222:223], off
	global_load_dwordx4 v[194:197], v[222:223], off offset:64
	global_load_dwordx4 v[198:201], v[222:223], off offset:128
	global_load_dwordx4 v[202:205], v[222:223], off offset:192
	s_waitcnt vmcnt(8)
	v_pk_fma_f32 v[46:47], v[46:47], v[118:119], v[208:209]
	v_pk_fma_f32 v[44:45], v[44:45], v[116:117], v[206:207]
	v_lshl_add_u64 v[52:53], v[52:53], 1, s[2:3]
	global_store_dwordx4 v[50:51], v[44:47], off
	s_cbranch_vccnz .LBB0_249
	v_lshl_add_u64 v[62:63], v[56:57], 0, v[66:67]
	v_pk_mul_f32 v[60:61], v[46:47], v[138:139]
	v_pk_mul_f32 v[58:59], v[44:45], v[136:137]
	v_pk_add_f32 v[62:63], v[154:155], 1.0 op_sel_hi:[1,0]
	v_pk_add_f32 v[72:73], v[152:153], 1.0 op_sel_hi:[1,0]
	v_pk_mul_f32 v[60:61], v[60:61], v[62:63]
	v_pk_mul_f32 v[58:59], v[58:59], v[72:73]
	v_and_b32_sdwa v72, v58, v170 dst_sel:DWORD dst_unused:UNUSED_PAD src0_sel:WORD_1 src1_sel:DWORD
	v_add3_u32 v58, v58, v72, s56
	v_and_b32_sdwa v72, v59, v170 dst_sel:DWORD dst_unused:UNUSED_PAD src0_sel:WORD_1 src1_sel:DWORD
	v_add3_u32 v59, v59, v72, s56
	v_and_b32_e32 v71, 0xffff0000, v59
	v_lshl_add_u64 v[62:63], v[64:65], 1, v[52:53]
	v_cvt_pk_bf16_f32 v59, v60, v61
	v_or_b32_sdwa v58, v71, v58 dst_sel:DWORD dst_unused:UNUSED_PAD src0_sel:DWORD src1_sel:WORD_1
	global_store_dwordx2 v[62:63], v[58:59], off
.LBB0_249:
	s_nop 0
	s_and_b64 vcc, exec, s[36:37]
	v_pk_fma_f32 v[42:43], v[42:43], v[122:123], v[212:213]
	v_pk_fma_f32 v[40:41], v[40:41], v[120:121], v[210:211]
	global_store_dwordx4 v[50:51], v[40:43], off offset:64
	s_cbranch_vccnz .LBB0_251
	v_lshl_add_u64 v[62:63], v[56:57], 0, v[66:67]
	v_pk_mul_f32 v[60:61], v[42:43], v[142:143]
	v_pk_mul_f32 v[58:59], v[40:41], v[140:141]
	v_pk_add_f32 v[62:63], v[158:159], 1.0 op_sel_hi:[1,0]
	v_pk_add_f32 v[72:73], v[156:157], 1.0 op_sel_hi:[1,0]
	v_pk_mul_f32 v[60:61], v[60:61], v[62:63]
	v_pk_mul_f32 v[58:59], v[58:59], v[72:73]
	v_and_b32_sdwa v72, v58, v170 dst_sel:DWORD dst_unused:UNUSED_PAD src0_sel:WORD_1 src1_sel:DWORD
	v_add3_u32 v58, v58, v72, s56
	v_and_b32_sdwa v72, v59, v170 dst_sel:DWORD dst_unused:UNUSED_PAD src0_sel:WORD_1 src1_sel:DWORD
	v_add3_u32 v59, v59, v72, s56
	v_and_b32_e32 v71, 0xffff0000, v59
	v_lshl_add_u64 v[62:63], v[64:65], 1, v[52:53]
	v_cvt_pk_bf16_f32 v59, v60, v61
	v_or_b32_sdwa v58, v71, v58 dst_sel:DWORD dst_unused:UNUSED_PAD src0_sel:DWORD src1_sel:WORD_1
	global_store_dwordx2 v[62:63], v[58:59], off offset:32
.LBB0_251:
	s_nop 0
	s_and_b64 vcc, exec, s[36:37]
	v_pk_fma_f32 v[38:39], v[38:39], v[126:127], v[216:217]
	v_pk_fma_f32 v[36:37], v[36:37], v[124:125], v[214:215]
	global_store_dwordx4 v[50:51], v[36:39], off offset:128
	s_cbranch_vccnz .LBB0_253
	v_lshl_add_u64 v[62:63], v[56:57], 0, v[66:67]
	v_pk_mul_f32 v[60:61], v[38:39], v[146:147]
	v_pk_mul_f32 v[58:59], v[36:37], v[144:145]
	v_pk_add_f32 v[62:63], v[162:163], 1.0 op_sel_hi:[1,0]
	v_pk_add_f32 v[72:73], v[160:161], 1.0 op_sel_hi:[1,0]
	v_pk_mul_f32 v[60:61], v[60:61], v[62:63]
	v_pk_mul_f32 v[58:59], v[58:59], v[72:73]
	v_and_b32_sdwa v72, v58, v170 dst_sel:DWORD dst_unused:UNUSED_PAD src0_sel:WORD_1 src1_sel:DWORD
	v_add3_u32 v58, v58, v72, s56
	v_and_b32_sdwa v72, v59, v170 dst_sel:DWORD dst_unused:UNUSED_PAD src0_sel:WORD_1 src1_sel:DWORD
	v_add3_u32 v59, v59, v72, s56
	v_and_b32_e32 v71, 0xffff0000, v59
	v_lshl_add_u64 v[62:63], v[64:65], 1, v[52:53]
	v_cvt_pk_bf16_f32 v59, v60, v61
	v_or_b32_sdwa v58, v71, v58 dst_sel:DWORD dst_unused:UNUSED_PAD src0_sel:DWORD src1_sel:WORD_1
	global_store_dwordx2 v[62:63], v[58:59], off offset:64

.LBB0_257:
	s_or_b64 exec, exec, s[2:3]
	v_add_u32_e32 v32, 0xffffe020, v80
	v_or_b32_e32 v34, 32, v70
	v_lshrrev_b32_e32 v32, 10, v32
	s_movk_i32 s2, 0x1800
	v_mad_u32_u24 v32, v32, s2, s2
	v_cmp_lt_i32_e32 vcc, s13, v34
	v_ashrrev_i32_e32 v35, 31, v34
	v_readlane_b32 s2, v250, 15
	v_cndmask_b32_e32 v38, 0, v32, vcc
	v_ashrrev_i32_e32 v39, 31, v38
	s_waitcnt lgkmcnt(0)
	v_lshl_add_u64 v[32:33], v[38:39], 2, s[40:41]
	v_lshl_add_u64 v[36:37], v[32:33], 0, v[66:67]
	v_lshlrev_b64 v[32:33], 12, v[34:35]
	v_readlane_b32 s3, v250, 16
	v_lshlrev_b64 v[34:35], 10, v[34:35]
	s_and_b64 vcc, exec, s[36:37]
	v_lshl_add_u64 v[32:33], s[2:3], 0, v[32:33]
	v_lshl_add_u64 v[32:33], v[32:33], 0, v[66:67]
	v_readlane_b32 s2, v250, 21
	v_readlane_b32 s3, v250, 22
	v_lshl_add_u64 v[38:39], v[38:39], 2, s[42:43]
	global_load_dwordx4 v[206:209], v[224:225], off
	global_load_dwordx4 v[210:213], v[224:225], off offset:64
	global_load_dwordx4 v[214:217], v[224:225], off offset:128
	global_load_dwordx4 v[218:221], v[224:225], off offset:192
	s_waitcnt vmcnt(8)
	v_pk_fma_f32 v[30:31], v[30:31], v[118:119], v[192:193]
	v_pk_fma_f32 v[28:29], v[28:29], v[116:117], v[190:191]
	v_lshl_add_u64 v[34:35], v[34:35], 1, s[2:3]
	global_store_dwordx4 v[32:33], v[28:31], off
	s_cbranch_vccnz .LBB0_259
	v_lshl_add_u64 v[44:45], v[38:39], 0, v[66:67]
	v_pk_mul_f32 v[42:43], v[30:31], v[138:139]
	v_pk_mul_f32 v[40:41], v[28:29], v[136:137]
	v_pk_add_f32 v[46:47], v[154:155], 1.0 op_sel_hi:[1,0]
	v_pk_add_f32 v[44:45], v[152:153], 1.0 op_sel_hi:[1,0]
	v_pk_mul_f32 v[42:43], v[42:43], v[46:47]
	v_pk_mul_f32 v[40:41], v[40:41], v[44:45]
	v_and_b32_sdwa v47, v40, v170 dst_sel:DWORD dst_unused:UNUSED_PAD src0_sel:WORD_1 src1_sel:DWORD
	v_add3_u32 v40, v40, v47, s56
	v_and_b32_sdwa v47, v41, v170 dst_sel:DWORD dst_unused:UNUSED_PAD src0_sel:WORD_1 src1_sel:DWORD
	v_add3_u32 v41, v41, v47, s56
	v_and_b32_e32 v46, 0xffff0000, v41
	v_lshl_add_u64 v[44:45], v[64:65], 1, v[34:35]
	v_cvt_pk_bf16_f32 v41, v42, v43
	v_or_b32_sdwa v40, v46, v40 dst_sel:DWORD dst_unused:UNUSED_PAD src0_sel:DWORD src1_sel:WORD_1
	global_store_dwordx2 v[44:45], v[40:41], off
.LBB0_259:
	s_nop 0
	s_and_b64 vcc, exec, s[36:37]
	v_pk_fma_f32 v[26:27], v[26:27], v[122:123], v[196:197]
	v_pk_fma_f32 v[24:25], v[24:25], v[120:121], v[194:195]
	global_store_dwordx4 v[32:33], v[24:27], off offset:64
	s_cbranch_vccnz .LBB0_261
	v_lshl_add_u64 v[44:45], v[38:39], 0, v[66:67]
	v_pk_mul_f32 v[42:43], v[26:27], v[142:143]
	v_pk_mul_f32 v[40:41], v[24:25], v[140:141]
	v_pk_add_f32 v[46:47], v[158:159], 1.0 op_sel_hi:[1,0]
	v_pk_add_f32 v[44:45], v[156:157], 1.0 op_sel_hi:[1,0]
	v_pk_mul_f32 v[42:43], v[42:43], v[46:47]
	v_pk_mul_f32 v[40:41], v[40:41], v[44:45]
	v_and_b32_sdwa v47, v40, v170 dst_sel:DWORD dst_unused:UNUSED_PAD src0_sel:WORD_1 src1_sel:DWORD
	v_add3_u32 v40, v40, v47, s56
	v_and_b32_sdwa v47, v41, v170 dst_sel:DWORD dst_unused:UNUSED_PAD src0_sel:WORD_1 src1_sel:DWORD
	v_add3_u32 v41, v41, v47, s56
	v_and_b32_e32 v46, 0xffff0000, v41
	v_lshl_add_u64 v[44:45], v[64:65], 1, v[34:35]
	v_cvt_pk_bf16_f32 v41, v42, v43
	v_or_b32_sdwa v40, v46, v40 dst_sel:DWORD dst_unused:UNUSED_PAD src0_sel:DWORD src1_sel:WORD_1
	global_store_dwordx2 v[44:45], v[40:41], off offset:32
.LBB0_261:
	s_nop 0
	s_and_b64 vcc, exec, s[36:37]
	v_pk_fma_f32 v[22:23], v[22:23], v[126:127], v[200:201]
	v_pk_fma_f32 v[20:21], v[20:21], v[124:125], v[198:199]
	global_store_dwordx4 v[32:33], v[20:23], off offset:128
	s_cbranch_vccnz .LBB0_263
	v_lshl_add_u64 v[44:45], v[38:39], 0, v[66:67]
	v_pk_mul_f32 v[42:43], v[22:23], v[146:147]
	v_pk_mul_f32 v[40:41], v[20:21], v[144:145]
	v_pk_add_f32 v[46:47], v[162:163], 1.0 op_sel_hi:[1,0]
	v_pk_add_f32 v[44:45], v[160:161], 1.0 op_sel_hi:[1,0]
	v_pk_mul_f32 v[42:43], v[42:43], v[46:47]
	v_pk_mul_f32 v[40:41], v[40:41], v[44:45]
	v_and_b32_sdwa v47, v40, v170 dst_sel:DWORD dst_unused:UNUSED_PAD src0_sel:WORD_1 src1_sel:DWORD
	v_add3_u32 v40, v40, v47, s56
	v_and_b32_sdwa v47, v41, v170 dst_sel:DWORD dst_unused:UNUSED_PAD src0_sel:WORD_1 src1_sel:DWORD
	v_add3_u32 v41, v41, v47, s56
	v_and_b32_e32 v46, 0xffff0000, v41
	v_lshl_add_u64 v[44:45], v[64:65], 1, v[34:35]
	v_cvt_pk_bf16_f32 v41, v42, v43
	v_or_b32_sdwa v40, v46, v40 dst_sel:DWORD dst_unused:UNUSED_PAD src0_sel:DWORD src1_sel:WORD_1
	global_store_dwordx2 v[44:45], v[40:41], off offset:64

.LBB0_267:
	s_or_b64 exec, exec, s[2:3]
	v_add_u32_e32 v16, 0xffffe030, v80
	v_or_b32_e32 v18, 48, v70
	v_lshrrev_b32_e32 v16, 10, v16
	s_movk_i32 s2, 0x1800
	v_mad_u32_u24 v16, v16, s2, s2
	v_cmp_lt_i32_e32 vcc, s13, v18
	v_ashrrev_i32_e32 v19, 31, v18
	v_readlane_b32 s2, v250, 15
	v_cndmask_b32_e32 v22, 0, v16, vcc
	v_ashrrev_i32_e32 v23, 31, v22
	s_waitcnt lgkmcnt(0)
	v_lshl_add_u64 v[16:17], v[22:23], 2, s[40:41]
	v_lshl_add_u64 v[20:21], v[16:17], 0, v[66:67]
	v_lshlrev_b64 v[16:17], 12, v[18:19]
	v_readlane_b32 s3, v250, 16
	v_lshlrev_b64 v[18:19], 10, v[18:19]
	s_and_b64 vcc, exec, s[36:37]
	v_lshl_add_u64 v[16:17], s[2:3], 0, v[16:17]
	v_lshl_add_u64 v[16:17], v[16:17], 0, v[66:67]
	v_readlane_b32 s2, v250, 21
	v_readlane_b32 s3, v250, 22
	v_lshl_add_u64 v[22:23], v[22:23], 2, s[42:43]
	s_waitcnt vmcnt(4)
	v_pk_fma_f32 v[14:15], v[14:15], v[118:119], v[208:209]
	v_pk_fma_f32 v[12:13], v[12:13], v[116:117], v[206:207]
	v_lshl_add_u64 v[18:19], v[18:19], 1, s[2:3]
	global_store_dwordx4 v[16:17], v[12:15], off
	s_cbranch_vccnz .LBB0_269
	v_lshl_add_u64 v[28:29], v[22:23], 0, v[66:67]
	v_pk_mul_f32 v[26:27], v[14:15], v[138:139]
	v_pk_mul_f32 v[24:25], v[12:13], v[136:137]
	v_pk_add_f32 v[30:31], v[154:155], 1.0 op_sel_hi:[1,0]
	v_pk_add_f32 v[28:29], v[152:153], 1.0 op_sel_hi:[1,0]
	v_pk_mul_f32 v[26:27], v[26:27], v[30:31]
	v_pk_mul_f32 v[24:25], v[24:25], v[28:29]
	v_and_b32_sdwa v31, v24, v170 dst_sel:DWORD dst_unused:UNUSED_PAD src0_sel:WORD_1 src1_sel:DWORD
	v_add3_u32 v24, v24, v31, s56
	v_and_b32_sdwa v31, v25, v170 dst_sel:DWORD dst_unused:UNUSED_PAD src0_sel:WORD_1 src1_sel:DWORD
	v_add3_u32 v25, v25, v31, s56
	v_and_b32_e32 v30, 0xffff0000, v25
	v_lshl_add_u64 v[28:29], v[64:65], 1, v[18:19]
	v_cvt_pk_bf16_f32 v25, v26, v27
	v_or_b32_sdwa v24, v30, v24 dst_sel:DWORD dst_unused:UNUSED_PAD src0_sel:DWORD src1_sel:WORD_1
	global_store_dwordx2 v[28:29], v[24:25], off
.LBB0_269:
	s_nop 0
	s_and_b64 vcc, exec, s[36:37]
	v_pk_fma_f32 v[10:11], v[10:11], v[122:123], v[212:213]
	v_pk_fma_f32 v[8:9], v[8:9], v[120:121], v[210:211]
	global_store_dwordx4 v[16:17], v[8:11], off offset:64
	s_cbranch_vccnz .LBB0_271
	v_lshl_add_u64 v[28:29], v[22:23], 0, v[66:67]
	v_pk_mul_f32 v[26:27], v[10:11], v[142:143]
	v_pk_mul_f32 v[24:25], v[8:9], v[140:141]
	v_pk_add_f32 v[30:31], v[158:159], 1.0 op_sel_hi:[1,0]
	v_pk_add_f32 v[28:29], v[156:157], 1.0 op_sel_hi:[1,0]
	v_pk_mul_f32 v[26:27], v[26:27], v[30:31]
	v_pk_mul_f32 v[24:25], v[24:25], v[28:29]
	v_and_b32_sdwa v31, v24, v170 dst_sel:DWORD dst_unused:UNUSED_PAD src0_sel:WORD_1 src1_sel:DWORD
	v_add3_u32 v24, v24, v31, s56
	v_and_b32_sdwa v31, v25, v170 dst_sel:DWORD dst_unused:UNUSED_PAD src0_sel:WORD_1 src1_sel:DWORD
	v_add3_u32 v25, v25, v31, s56
	v_and_b32_e32 v30, 0xffff0000, v25
	v_lshl_add_u64 v[28:29], v[64:65], 1, v[18:19]
	v_cvt_pk_bf16_f32 v25, v26, v27
	v_or_b32_sdwa v24, v30, v24 dst_sel:DWORD dst_unused:UNUSED_PAD src0_sel:DWORD src1_sel:WORD_1
	global_store_dwordx2 v[28:29], v[24:25], off offset:32
.LBB0_271:
	s_nop 0
	s_and_b64 vcc, exec, s[36:37]
	v_pk_fma_f32 v[6:7], v[6:7], v[126:127], v[216:217]
	v_pk_fma_f32 v[4:5], v[4:5], v[124:125], v[214:215]
	global_store_dwordx4 v[16:17], v[4:7], off offset:128
	s_cbranch_vccnz .LBB0_273
	v_lshl_add_u64 v[28:29], v[22:23], 0, v[66:67]
	v_pk_mul_f32 v[26:27], v[6:7], v[146:147]
	v_pk_mul_f32 v[24:25], v[4:5], v[144:145]
	v_pk_add_f32 v[30:31], v[162:163], 1.0 op_sel_hi:[1,0]
	v_pk_add_f32 v[28:29], v[160:161], 1.0 op_sel_hi:[1,0]
	v_pk_mul_f32 v[26:27], v[26:27], v[30:31]
	v_pk_mul_f32 v[24:25], v[24:25], v[28:29]
	v_and_b32_sdwa v31, v24, v170 dst_sel:DWORD dst_unused:UNUSED_PAD src0_sel:WORD_1 src1_sel:DWORD
	v_add3_u32 v24, v24, v31, s56
	v_and_b32_sdwa v31, v25, v170 dst_sel:DWORD dst_unused:UNUSED_PAD src0_sel:WORD_1 src1_sel:DWORD
	v_add3_u32 v25, v25, v31, s56
	v_and_b32_e32 v30, 0xffff0000, v25
	v_lshl_add_u64 v[28:29], v[64:65], 1, v[18:19]
	v_cvt_pk_bf16_f32 v25, v26, v27
	v_or_b32_sdwa v24, v30, v24 dst_sel:DWORD dst_unused:UNUSED_PAD src0_sel:DWORD src1_sel:WORD_1
	global_store_dwordx2 v[28:29], v[24:25], off offset:64

.Ltail282:
	s_add_i32 s25, s28, 2
	ds_read_b128 v[136:139], v111 offset:16384
	ds_read_b128 v[140:143], v111 offset:18432
	ds_read_b128 v[144:147], v111 offset:20480
	ds_read_b128 v[148:151], v111 offset:22528
	ds_read_b128 v[116:119], v110
	s_add_i32 s28, s28, 4
	ds_read_b128 v[120:123], v110 offset:2048
	s_min_u32 s28, s28, 63
	s_lshl_b32 s92, s28, 7
	ds_read_b128 v[124:127], v110 offset:4096
	ds_read_b128 v[194:197], v113 offset:16384
	ds_read_b128 v[198:201], v113 offset:18432
	ds_read_b128 v[202:205], v113 offset:20480
	ds_read_b128 v[206:209], v113 offset:22528
	v_lshl_add_u64 v[164:165], v[100:101], 0, s[92:93]
	ds_read_b128 v[132:135], v110 offset:6144
	ds_read_b128 v[152:155], v112
	ds_read_b128 v[156:159], v112 offset:2048
	ds_read_b128 v[160:163], v112 offset:4096
	ds_read_b128 v[190:193], v112 offset:6144
	s_waitcnt lgkmcnt(11)
	v_mfma_f32_16x16x32_bf16 v[92:95], v[136:139], v[116:119], v[92:95]
	v_mfma_f32_16x16x32_bf16 v[56:59], v[140:143], v[116:119], v[56:59]
	v_mfma_f32_16x16x32_bf16 v[52:55], v[144:147], v[116:119], v[52:55]
	v_mfma_f32_16x16x32_bf16 v[48:51], v[148:151], v[116:119], v[48:51]
	s_waitcnt vmcnt(7)
	ds_write_b128 v109, v[60:63] offset:32768
	v_add_co_u32_e32 v60, vcc, s7, v164
	s_waitcnt lgkmcnt(11)
	v_mfma_f32_16x16x32_bf16 v[44:47], v[136:139], v[120:123], v[44:47]
	v_addc_co_u32_e32 v61, vcc, 0, v165, vcc
	v_mfma_f32_16x16x32_bf16 v[40:43], v[140:143], v[120:123], v[40:43]
	v_mfma_f32_16x16x32_bf16 v[36:39], v[144:147], v[120:123], v[36:39]
	v_mfma_f32_16x16x32_bf16 v[32:35], v[148:151], v[120:123], v[32:35]
	v_add_co_u32_e32 v60, vcc, s52, v164
	s_waitcnt vmcnt(6)
	ds_write_b128 v109, v[64:67] offset:36864
	s_nop 0
	v_addc_co_u32_e32 v61, vcc, 0, v165, vcc
	s_waitcnt lgkmcnt(11)
	v_mfma_f32_16x16x32_bf16 v[28:31], v[136:139], v[124:127], v[28:31]
	v_lshl_add_u64 v[64:65], v[102:103], 0, s[92:93]
	v_mfma_f32_16x16x32_bf16 v[24:27], v[140:143], v[124:127], v[24:27]
	v_mfma_f32_16x16x32_bf16 v[20:23], v[144:147], v[124:127], v[20:23]
	v_mfma_f32_16x16x32_bf16 v[16:19], v[148:151], v[124:127], v[16:19]
	v_add_co_u32_e32 v60, vcc, s34, v164
	s_waitcnt vmcnt(5)
	ds_write_b128 v109, v[68:71] offset:40960
	s_nop 0
	v_addc_co_u32_e32 v61, vcc, 0, v165, vcc
	v_add_co_u32_e32 v66, vcc, s7, v64
	s_waitcnt lgkmcnt(7)
	v_mfma_f32_16x16x32_bf16 v[12:15], v[136:139], v[132:135], v[12:15]
	v_addc_co_u32_e32 v67, vcc, 0, v65, vcc
	v_mfma_f32_16x16x32_bf16 v[8:11], v[140:143], v[132:135], v[8:11]
	v_mfma_f32_16x16x32_bf16 v[4:7], v[144:147], v[132:135], v[4:7]
	v_mfma_f32_16x16x32_bf16 v[0:3], v[148:151], v[132:135], v[0:3]
	s_waitcnt vmcnt(4)
	ds_write_b128 v109, v[76:79] offset:45056
	s_waitcnt lgkmcnt(7)
	v_mfma_f32_16x16x32_bf16 v[60:63], v[194:197], v[152:155], v[92:95]
	v_mfma_f32_16x16x32_bf16 v[56:59], v[198:201], v[152:155], v[56:59]
	v_mfma_f32_16x16x32_bf16 v[52:55], v[202:205], v[152:155], v[52:55]
	v_mfma_f32_16x16x32_bf16 v[48:51], v[206:209], v[152:155], v[48:51]
	s_waitcnt vmcnt(3)
	ds_write_b128 v109, v[72:75] offset:49152
	s_waitcnt lgkmcnt(7)
	v_mfma_f32_16x16x32_bf16 v[44:47], v[194:197], v[156:159], v[44:47]
	v_mfma_f32_16x16x32_bf16 v[40:43], v[198:201], v[156:159], v[40:43]
	v_mfma_f32_16x16x32_bf16 v[36:39], v[202:205], v[156:159], v[36:39]
	v_mfma_f32_16x16x32_bf16 v[32:35], v[206:209], v[156:159], v[32:35]
	v_add_co_u32_e32 v66, vcc, s52, v64
	s_waitcnt vmcnt(2)
	ds_write_b128 v109, v[80:83] offset:53248
	v_addc_co_u32_e32 v67, vcc, 0, v65, vcc
	v_add_co_u32_e32 v64, vcc, s34, v64
	s_waitcnt lgkmcnt(7)
	v_mfma_f32_16x16x32_bf16 v[28:31], v[194:197], v[160:163], v[28:31]
	v_addc_co_u32_e32 v65, vcc, 0, v65, vcc
	v_mfma_f32_16x16x32_bf16 v[24:27], v[198:201], v[160:163], v[24:27]
	v_mfma_f32_16x16x32_bf16 v[20:23], v[202:205], v[160:163], v[20:23]
	v_mfma_f32_16x16x32_bf16 v[16:19], v[206:209], v[160:163], v[16:19]
	s_waitcnt vmcnt(1)
	ds_write_b128 v109, v[84:87] offset:57344
	s_waitcnt lgkmcnt(7)
	v_mfma_f32_16x16x32_bf16 v[12:15], v[194:197], v[190:193], v[12:15]
	v_mfma_f32_16x16x32_bf16 v[8:11], v[198:201], v[190:193], v[8:11]
	v_mfma_f32_16x16x32_bf16 v[4:7], v[202:205], v[190:193], v[4:7]
	v_mfma_f32_16x16x32_bf16 v[0:3], v[206:209], v[190:193], v[0:3]
	s_waitcnt vmcnt(0)
	ds_write_b128 v109, v[88:91] offset:61440
	s_waitcnt lgkmcnt(0)
	s_barrier
	ds_read_b128 v[80:83], v111 offset:49152
	ds_read_b128 v[84:87], v111 offset:51200
	ds_read_b128 v[88:91], v111 offset:53248
	ds_read_b128 v[92:95], v111 offset:55296
	ds_read_b128 v[64:67], v110 offset:32768
	ds_read_b128 v[68:71], v110 offset:34816
	s_min_u32 s28, s25, 60
	s_lshl_b32 s92, s28, 7
	ds_read_b128 v[72:75], v110 offset:36864
	v_lshl_add_u64 v[164:165], v[100:101], 0, s[92:93]
	ds_read_b128 v[76:79], v110 offset:38912
	ds_read_b128 v[152:155], v112 offset:32768
	ds_read_b128 v[156:159], v112 offset:34816
	ds_read_b128 v[160:163], v112 offset:36864
	ds_read_b128 v[190:193], v112 offset:38912
	ds_read_b128 v[194:197], v113 offset:49152
	ds_read_b128 v[198:201], v113 offset:51200
	ds_read_b128 v[202:205], v113 offset:53248
	ds_read_b128 v[206:209], v113 offset:55296
	s_waitcnt lgkmcnt(11)
	v_mfma_f32_16x16x32_bf16 v[210:213], v[80:83], v[64:67], v[60:63]
	v_mfma_f32_16x16x32_bf16 v[56:59], v[84:87], v[64:67], v[56:59]
	v_mfma_f32_16x16x32_bf16 v[52:55], v[88:91], v[64:67], v[52:55]
	v_mfma_f32_16x16x32_bf16 v[48:51], v[92:95], v[64:67], v[48:51]
	v_add_co_u32_e32 v64, vcc, s7, v164
	s_nop 0
	v_addc_co_u32_e32 v65, vcc, 0, v165, vcc
	s_waitcnt lgkmcnt(10)
	v_mfma_f32_16x16x32_bf16 v[44:47], v[80:83], v[68:71], v[44:47]
	v_mfma_f32_16x16x32_bf16 v[40:43], v[84:87], v[68:71], v[40:43]
	v_mfma_f32_16x16x32_bf16 v[36:39], v[88:91], v[68:71], v[36:39]
	v_mfma_f32_16x16x32_bf16 v[32:35], v[92:95], v[68:71], v[32:35]
	v_add_co_u32_e32 v68, vcc, s52, v164
	s_nop 0
	v_addc_co_u32_e32 v69, vcc, 0, v165, vcc
	s_waitcnt lgkmcnt(9)
	v_mfma_f32_16x16x32_bf16 v[28:31], v[80:83], v[72:75], v[28:31]
	v_mfma_f32_16x16x32_bf16 v[24:27], v[84:87], v[72:75], v[24:27]
	v_mfma_f32_16x16x32_bf16 v[20:23], v[88:91], v[72:75], v[20:23]
	v_mfma_f32_16x16x32_bf16 v[16:19], v[92:95], v[72:75], v[16:19]
	v_add_co_u32_e32 v72, vcc, s34, v164
	s_waitcnt lgkmcnt(8)
	v_mfma_f32_16x16x32_bf16 v[4:7], v[88:91], v[76:79], v[4:7]
	v_addc_co_u32_e32 v73, vcc, 0, v165, vcc
	v_lshl_add_u64 v[88:89], v[102:103], 0, s[92:93]
	v_mfma_f32_16x16x32_bf16 v[12:15], v[80:83], v[76:79], v[12:15]
	v_add_co_u32_e32 v80, vcc, s7, v88
	v_mfma_f32_16x16x32_bf16 v[8:11], v[84:87], v[76:79], v[8:11]
	s_nop 0
	v_addc_co_u32_e32 v81, vcc, 0, v89, vcc
	v_add_co_u32_e32 v84, vcc, s52, v88
	v_mfma_f32_16x16x32_bf16 v[0:3], v[92:95], v[76:79], v[0:3]
	s_nop 0
	v_addc_co_u32_e32 v85, vcc, 0, v89, vcc
	s_waitcnt lgkmcnt(3)
	v_mfma_f32_16x16x32_bf16 v[92:95], v[194:197], v[152:155], v[210:213]
	s_waitcnt lgkmcnt(2)
	v_mfma_f32_16x16x32_bf16 v[56:59], v[198:201], v[152:155], v[56:59]
	s_waitcnt lgkmcnt(1)
	v_mfma_f32_16x16x32_bf16 v[52:55], v[202:205], v[152:155], v[52:55]
	s_waitcnt lgkmcnt(0)
	v_mfma_f32_16x16x32_bf16 v[48:51], v[206:209], v[152:155], v[48:51]
	v_add_co_u32_e32 v88, vcc, s34, v88
	v_addc_co_u32_e32 v89, vcc, 0, v89, vcc
	v_mfma_f32_16x16x32_bf16 v[44:47], v[194:197], v[156:159], v[44:47]
	v_mfma_f32_16x16x32_bf16 v[40:43], v[198:201], v[156:159], v[40:43]
	v_mfma_f32_16x16x32_bf16 v[36:39], v[202:205], v[156:159], v[36:39]
	v_mfma_f32_16x16x32_bf16 v[32:35], v[206:209], v[156:159], v[32:35]
	v_mfma_f32_16x16x32_bf16 v[28:31], v[194:197], v[160:163], v[28:31]
	v_mfma_f32_16x16x32_bf16 v[24:27], v[198:201], v[160:163], v[24:27]
	v_mfma_f32_16x16x32_bf16 v[20:23], v[202:205], v[160:163], v[20:23]
	v_mfma_f32_16x16x32_bf16 v[16:19], v[206:209], v[160:163], v[16:19]
	v_mfma_f32_16x16x32_bf16 v[12:15], v[194:197], v[190:193], v[12:15]
	v_mfma_f32_16x16x32_bf16 v[8:11], v[198:201], v[190:193], v[8:11]
	v_mfma_f32_16x16x32_bf16 v[4:7], v[202:205], v[190:193], v[4:7]
	v_mfma_f32_16x16x32_bf16 v[0:3], v[206:209], v[190:193], v[0:3]
	s_mov_b32 s28, s25
	s_waitcnt lgkmcnt(0)
	s_barrier
	s_waitcnt vmcnt(2)
	v_add_u32_e32 v80, s2, v108
	v_add_u32_e32 v60, 0xffffe000, v80
	v_or_b32_e32 v70, v80, v107
	v_lshrrev_b32_e32 v60, 10, v60
	s_movk_i32 s2, 0x1800
	v_or_b32_e32 v81, s3, v114
	v_mad_u32_u24 v60, v60, s2, s2
	v_cmp_lt_i32_e32 vcc, s13, v70
	v_or_b32_e32 v64, v81, v115
	v_ashrrev_i32_e32 v71, 31, v70
	v_cndmask_b32_e32 v82, 0, v60, vcc
	v_readlane_b32 s2, v250, 15
	v_ashrrev_i32_e32 v83, 31, v82
	v_ashrrev_i32_e32 v65, 31, v64
	v_lshlrev_b64 v[68:69], 12, v[70:71]
	v_readlane_b32 s3, v250, 16
	v_lshl_add_u64 v[60:61], v[82:83], 2, s[40:41]
	v_lshlrev_b64 v[66:67], 2, v[64:65]
	v_lshl_add_u64 v[68:69], s[2:3], 0, v[68:69]
	v_lshl_add_u64 v[74:75], v[60:61], 0, v[66:67]
	v_lshl_add_u64 v[72:73], v[68:69], 0, v[66:67]
	global_load_dwordx4 v[60:63], v[74:75], off
	global_load_dwordx4 v[76:79], v[72:73], off
	v_readlane_b32 s2, v250, 21
	s_waitcnt vmcnt(3)
	v_lshlrev_b64 v[84:85], 10, v[70:71]
	v_readlane_b32 s3, v250, 22
	s_and_b64 vcc, exec, s[36:37]
	v_lshl_add_u64 v[68:69], s[26:27], 0, v[66:67]
	s_waitcnt vmcnt(0)
	v_pk_fma_f32 v[62:63], v[94:95], v[62:63], v[78:79]
	v_pk_fma_f32 v[60:61], v[92:93], v[60:61], v[76:77]
	v_lshl_add_u64 v[76:77], v[82:83], 2, s[42:43]
	v_lshl_add_u64 v[78:79], v[84:85], 1, s[2:3]
	global_store_dwordx4 v[72:73], v[60:63], off
	s_cbranch_vccnz .LBB0_285
	v_lshl_add_u64 v[86:87], v[76:77], 0, v[66:67]
	global_load_dwordx4 v[82:85], v[68:69], off
	s_waitcnt vmcnt(0)
	v_pk_mul_f32 v[84:85], v[62:63], v[84:85]
	global_load_dwordx4 v[86:89], v[86:87], off
	v_pk_mul_f32 v[82:83], v[60:61], v[82:83]
	s_waitcnt vmcnt(0)
	v_pk_add_f32 v[88:89], v[88:89], 1.0 op_sel_hi:[1,0]
	v_pk_add_f32 v[86:87], v[86:87], 1.0 op_sel_hi:[1,0]
	v_pk_mul_f32 v[84:85], v[84:85], v[88:89]
	v_pk_mul_f32 v[82:83], v[82:83], v[86:87]
	v_and_b32_sdwa v89, v82, v170 dst_sel:DWORD dst_unused:UNUSED_PAD src0_sel:WORD_1 src1_sel:DWORD
	v_add3_u32 v82, v82, v89, s56
	v_and_b32_sdwa v89, v83, v170 dst_sel:DWORD dst_unused:UNUSED_PAD src0_sel:WORD_1 src1_sel:DWORD
	v_add3_u32 v83, v83, v89, s56
	v_and_b32_e32 v88, 0xffff0000, v83
	v_lshl_add_u64 v[86:87], v[64:65], 1, v[78:79]
	v_cvt_pk_bf16_f32 v83, v84, v85
	v_or_b32_sdwa v82, v88, v82 dst_sel:DWORD dst_unused:UNUSED_PAD src0_sel:DWORD src1_sel:WORD_1
	global_store_dwordx2 v[86:87], v[82:83], off
.LBB0_285:
	global_load_dwordx4 v[82:85], v[74:75], off offset:64
	s_nop 0
	global_load_dwordx4 v[86:89], v[72:73], off offset:64
	s_and_b64 vcc, exec, s[36:37]
	s_waitcnt vmcnt(0)
	v_pk_fma_f32 v[58:59], v[58:59], v[84:85], v[88:89]
	v_pk_fma_f32 v[56:57], v[56:57], v[82:83], v[86:87]
	global_store_dwordx4 v[72:73], v[56:59], off offset:64
	s_cbranch_vccnz .LBB0_287
	v_lshl_add_u64 v[86:87], v[76:77], 0, v[66:67]
	global_load_dwordx4 v[82:85], v[68:69], off offset:64
	s_waitcnt vmcnt(0)
	v_pk_mul_f32 v[84:85], v[58:59], v[84:85]
	global_load_dwordx4 v[86:89], v[86:87], off offset:64
	v_pk_mul_f32 v[82:83], v[56:57], v[82:83]
	s_waitcnt vmcnt(0)
	v_pk_add_f32 v[88:89], v[88:89], 1.0 op_sel_hi:[1,0]
	v_pk_add_f32 v[86:87], v[86:87], 1.0 op_sel_hi:[1,0]
	v_pk_mul_f32 v[84:85], v[84:85], v[88:89]
	v_pk_mul_f32 v[82:83], v[82:83], v[86:87]
	v_and_b32_sdwa v89, v82, v170 dst_sel:DWORD dst_unused:UNUSED_PAD src0_sel:WORD_1 src1_sel:DWORD
	v_add3_u32 v82, v82, v89, s56
	v_and_b32_sdwa v89, v83, v170 dst_sel:DWORD dst_unused:UNUSED_PAD src0_sel:WORD_1 src1_sel:DWORD
	v_add3_u32 v83, v83, v89, s56
	v_and_b32_e32 v88, 0xffff0000, v83
	v_lshl_add_u64 v[86:87], v[64:65], 1, v[78:79]
	v_cvt_pk_bf16_f32 v83, v84, v85
	v_or_b32_sdwa v82, v88, v82 dst_sel:DWORD dst_unused:UNUSED_PAD src0_sel:DWORD src1_sel:WORD_1
	global_store_dwordx2 v[86:87], v[82:83], off offset:32
.LBB0_287:
	global_load_dwordx4 v[82:85], v[74:75], off offset:128
	s_nop 0
	global_load_dwordx4 v[86:89], v[72:73], off offset:128
	s_and_b64 vcc, exec, s[36:37]
	s_waitcnt vmcnt(0)
	v_pk_fma_f32 v[54:55], v[54:55], v[84:85], v[88:89]
	v_pk_fma_f32 v[52:53], v[52:53], v[82:83], v[86:87]
	global_store_dwordx4 v[72:73], v[52:55], off offset:128
	s_cbranch_vccnz .LBB0_289
	v_lshl_add_u64 v[86:87], v[76:77], 0, v[66:67]
	global_load_dwordx4 v[82:85], v[68:69], off offset:128
	s_waitcnt vmcnt(0)
	v_pk_mul_f32 v[84:85], v[54:55], v[84:85]
	global_load_dwordx4 v[86:89], v[86:87], off offset:128
	v_pk_mul_f32 v[82:83], v[52:53], v[82:83]
	s_waitcnt vmcnt(0)
	v_pk_add_f32 v[88:89], v[88:89], 1.0 op_sel_hi:[1,0]
	v_pk_add_f32 v[86:87], v[86:87], 1.0 op_sel_hi:[1,0]
	v_pk_mul_f32 v[84:85], v[84:85], v[88:89]
	v_pk_mul_f32 v[82:83], v[82:83], v[86:87]
	v_and_b32_sdwa v89, v82, v170 dst_sel:DWORD dst_unused:UNUSED_PAD src0_sel:WORD_1 src1_sel:DWORD
	v_add3_u32 v82, v82, v89, s56
	v_and_b32_sdwa v89, v83, v170 dst_sel:DWORD dst_unused:UNUSED_PAD src0_sel:WORD_1 src1_sel:DWORD
	v_add3_u32 v83, v83, v89, s56
	v_and_b32_e32 v88, 0xffff0000, v83
	v_lshl_add_u64 v[86:87], v[64:65], 1, v[78:79]
	v_cvt_pk_bf16_f32 v83, v84, v85
	v_or_b32_sdwa v82, v88, v82 dst_sel:DWORD dst_unused:UNUSED_PAD src0_sel:DWORD src1_sel:WORD_1
	global_store_dwordx2 v[86:87], v[82:83], off offset:64
.LBB0_289:
	global_load_dwordx4 v[82:85], v[74:75], off offset:192
	s_nop 0
	global_load_dwordx4 v[86:89], v[72:73], off offset:192
	s_and_b64 vcc, exec, s[36:37]
	s_movk_i32 s89, 0xff
	s_waitcnt vmcnt(0)
	v_pk_fma_f32 v[50:51], v[50:51], v[84:85], v[88:89]
	v_pk_fma_f32 v[48:49], v[48:49], v[82:83], v[86:87]
	global_store_dwordx4 v[72:73], v[48:51], off offset:192
	s_cbranch_vccnz .LBB0_291
	v_lshl_add_u64 v[76:77], v[76:77], 0, v[66:67]
	global_load_dwordx4 v[72:75], v[68:69], off offset:192
	global_load_dwordx4 v[82:85], v[76:77], off offset:192
	v_lshl_add_u64 v[76:77], v[64:65], 1, v[78:79]
	s_waitcnt vmcnt(1)
	v_pk_mul_f32 v[74:75], v[50:51], v[74:75]
	v_pk_mul_f32 v[72:73], v[48:49], v[72:73]
	s_waitcnt vmcnt(0)
	v_pk_add_f32 v[78:79], v[84:85], 1.0 op_sel_hi:[1,0]
	v_pk_add_f32 v[82:83], v[82:83], 1.0 op_sel_hi:[1,0]
	v_pk_mul_f32 v[74:75], v[74:75], v[78:79]
	v_pk_mul_f32 v[72:73], v[72:73], v[82:83]
	v_and_b32_sdwa v83, v73, v170 dst_sel:DWORD dst_unused:UNUSED_PAD src0_sel:WORD_1 src1_sel:DWORD
	v_and_b32_sdwa v79, v72, v170 dst_sel:DWORD dst_unused:UNUSED_PAD src0_sel:WORD_1 src1_sel:DWORD
	v_add3_u32 v73, v73, v83, s56
	v_add3_u32 v72, v72, v79, s56
	v_and_b32_e32 v78, 0xffff0000, v73
	v_cvt_pk_bf16_f32 v73, v74, v75
	v_or_b32_sdwa v72, v78, v72 dst_sel:DWORD dst_unused:UNUSED_PAD src0_sel:DWORD src1_sel:WORD_1
	global_store_dwordx2 v[76:77], v[72:73], off offset:96

.LBB0_293:
	s_or_b64 exec, exec, s[2:3]
	v_add_u32_e32 v50, 0xffffe010, v80
	v_or_b32_e32 v52, 16, v70
	v_lshrrev_b32_e32 v50, 10, v50
	s_movk_i32 s2, 0x1800
	v_mad_u32_u24 v50, v50, s2, s2
	v_cmp_lt_i32_e32 vcc, s13, v52
	v_ashrrev_i32_e32 v53, 31, v52
	v_readlane_b32 s2, v250, 15
	v_cndmask_b32_e32 v56, 0, v50, vcc
	v_ashrrev_i32_e32 v57, 31, v56
	s_waitcnt lgkmcnt(0)
	v_lshl_add_u64 v[50:51], v[56:57], 2, s[40:41]
	v_lshl_add_u64 v[54:55], v[50:51], 0, v[66:67]
	v_lshlrev_b64 v[50:51], 12, v[52:53]
	v_readlane_b32 s3, v250, 16
	v_lshlrev_b64 v[52:53], 10, v[52:53]
	s_and_b64 vcc, exec, s[36:37]
	v_lshl_add_u64 v[50:51], s[2:3], 0, v[50:51]
	v_lshl_add_u64 v[50:51], v[50:51], 0, v[66:67]
	global_load_dwordx4 v[58:61], v[54:55], off
	global_load_dwordx4 v[72:75], v[50:51], off
	v_readlane_b32 s2, v250, 21
	v_readlane_b32 s3, v250, 22
	v_lshl_add_u64 v[56:57], v[56:57], 2, s[42:43]
	s_waitcnt vmcnt(0)
	v_pk_fma_f32 v[46:47], v[46:47], v[60:61], v[74:75]
	v_pk_fma_f32 v[44:45], v[44:45], v[58:59], v[72:73]
	v_lshl_add_u64 v[52:53], v[52:53], 1, s[2:3]
	global_store_dwordx4 v[50:51], v[44:47], off
	s_cbranch_vccnz .LBB0_295
	v_lshl_add_u64 v[62:63], v[56:57], 0, v[66:67]
	global_load_dwordx4 v[58:61], v[68:69], off
	global_load_dwordx4 v[72:75], v[62:63], off
	s_waitcnt vmcnt(1)
	v_pk_mul_f32 v[60:61], v[46:47], v[60:61]
	v_pk_mul_f32 v[58:59], v[44:45], v[58:59]
	s_waitcnt vmcnt(0)
	v_pk_add_f32 v[62:63], v[74:75], 1.0 op_sel_hi:[1,0]
	v_pk_add_f32 v[72:73], v[72:73], 1.0 op_sel_hi:[1,0]
	v_pk_mul_f32 v[60:61], v[60:61], v[62:63]
	v_pk_mul_f32 v[58:59], v[58:59], v[72:73]
	v_and_b32_sdwa v72, v58, v170 dst_sel:DWORD dst_unused:UNUSED_PAD src0_sel:WORD_1 src1_sel:DWORD
	v_add3_u32 v58, v58, v72, s56
	v_and_b32_sdwa v72, v59, v170 dst_sel:DWORD dst_unused:UNUSED_PAD src0_sel:WORD_1 src1_sel:DWORD
	v_add3_u32 v59, v59, v72, s56
	v_and_b32_e32 v71, 0xffff0000, v59
	v_lshl_add_u64 v[62:63], v[64:65], 1, v[52:53]
	v_cvt_pk_bf16_f32 v59, v60, v61
	v_or_b32_sdwa v58, v71, v58 dst_sel:DWORD dst_unused:UNUSED_PAD src0_sel:DWORD src1_sel:WORD_1
	global_store_dwordx2 v[62:63], v[58:59], off
.LBB0_295:
	global_load_dwordx4 v[58:61], v[54:55], off offset:64
	s_nop 0
	global_load_dwordx4 v[72:75], v[50:51], off offset:64
	s_and_b64 vcc, exec, s[36:37]
	s_waitcnt vmcnt(0)
	v_pk_fma_f32 v[42:43], v[42:43], v[60:61], v[74:75]
	v_pk_fma_f32 v[40:41], v[40:41], v[58:59], v[72:73]
	global_store_dwordx4 v[50:51], v[40:43], off offset:64
	s_cbranch_vccnz .LBB0_297
	v_lshl_add_u64 v[62:63], v[56:57], 0, v[66:67]
	global_load_dwordx4 v[58:61], v[68:69], off offset:64
	global_load_dwordx4 v[72:75], v[62:63], off offset:64
	s_waitcnt vmcnt(1)
	v_pk_mul_f32 v[60:61], v[42:43], v[60:61]
	v_pk_mul_f32 v[58:59], v[40:41], v[58:59]
	s_waitcnt vmcnt(0)
	v_pk_add_f32 v[62:63], v[74:75], 1.0 op_sel_hi:[1,0]
	v_pk_add_f32 v[72:73], v[72:73], 1.0 op_sel_hi:[1,0]
	v_pk_mul_f32 v[60:61], v[60:61], v[62:63]
	v_pk_mul_f32 v[58:59], v[58:59], v[72:73]
	v_and_b32_sdwa v72, v58, v170 dst_sel:DWORD dst_unused:UNUSED_PAD src0_sel:WORD_1 src1_sel:DWORD
	v_add3_u32 v58, v58, v72, s56
	v_and_b32_sdwa v72, v59, v170 dst_sel:DWORD dst_unused:UNUSED_PAD src0_sel:WORD_1 src1_sel:DWORD
	v_add3_u32 v59, v59, v72, s56
	v_and_b32_e32 v71, 0xffff0000, v59
	v_lshl_add_u64 v[62:63], v[64:65], 1, v[52:53]
	v_cvt_pk_bf16_f32 v59, v60, v61
	v_or_b32_sdwa v58, v71, v58 dst_sel:DWORD dst_unused:UNUSED_PAD src0_sel:DWORD src1_sel:WORD_1
	global_store_dwordx2 v[62:63], v[58:59], off offset:32
.LBB0_297:
	global_load_dwordx4 v[58:61], v[54:55], off offset:128
	s_nop 0
	global_load_dwordx4 v[72:75], v[50:51], off offset:128
	s_and_b64 vcc, exec, s[36:37]
	s_waitcnt vmcnt(0)
	v_pk_fma_f32 v[38:39], v[38:39], v[60:61], v[74:75]
	v_pk_fma_f32 v[36:37], v[36:37], v[58:59], v[72:73]
	global_store_dwordx4 v[50:51], v[36:39], off offset:128
	s_cbranch_vccnz .LBB0_299
	v_lshl_add_u64 v[62:63], v[56:57], 0, v[66:67]
	global_load_dwordx4 v[58:61], v[68:69], off offset:128
	global_load_dwordx4 v[72:75], v[62:63], off offset:128
	s_waitcnt vmcnt(1)
	v_pk_mul_f32 v[60:61], v[38:39], v[60:61]
	v_pk_mul_f32 v[58:59], v[36:37], v[58:59]
	s_waitcnt vmcnt(0)
	v_pk_add_f32 v[62:63], v[74:75], 1.0 op_sel_hi:[1,0]
	v_pk_add_f32 v[72:73], v[72:73], 1.0 op_sel_hi:[1,0]
	v_pk_mul_f32 v[60:61], v[60:61], v[62:63]
	v_pk_mul_f32 v[58:59], v[58:59], v[72:73]
	v_and_b32_sdwa v72, v58, v170 dst_sel:DWORD dst_unused:UNUSED_PAD src0_sel:WORD_1 src1_sel:DWORD
	v_add3_u32 v58, v58, v72, s56
	v_and_b32_sdwa v72, v59, v170 dst_sel:DWORD dst_unused:UNUSED_PAD src0_sel:WORD_1 src1_sel:DWORD
	v_add3_u32 v59, v59, v72, s56
	v_and_b32_e32 v71, 0xffff0000, v59
	v_lshl_add_u64 v[62:63], v[64:65], 1, v[52:53]
	v_cvt_pk_bf16_f32 v59, v60, v61
	v_or_b32_sdwa v58, v71, v58 dst_sel:DWORD dst_unused:UNUSED_PAD src0_sel:DWORD src1_sel:WORD_1
	global_store_dwordx2 v[62:63], v[58:59], off offset:64

.LBB0_303:
	s_or_b64 exec, exec, s[2:3]
	v_add_u32_e32 v32, 0xffffe020, v80
	v_or_b32_e32 v34, 32, v70
	v_lshrrev_b32_e32 v32, 10, v32
	s_movk_i32 s2, 0x1800
	v_mad_u32_u24 v32, v32, s2, s2
	v_cmp_lt_i32_e32 vcc, s13, v34
	v_ashrrev_i32_e32 v35, 31, v34
	v_readlane_b32 s2, v250, 15
	v_cndmask_b32_e32 v38, 0, v32, vcc
	v_ashrrev_i32_e32 v39, 31, v38
	s_waitcnt lgkmcnt(0)
	v_lshl_add_u64 v[32:33], v[38:39], 2, s[40:41]
	v_lshl_add_u64 v[36:37], v[32:33], 0, v[66:67]
	v_lshlrev_b64 v[32:33], 12, v[34:35]
	v_readlane_b32 s3, v250, 16
	v_lshlrev_b64 v[34:35], 10, v[34:35]
	s_and_b64 vcc, exec, s[36:37]
	v_lshl_add_u64 v[32:33], s[2:3], 0, v[32:33]
	v_lshl_add_u64 v[32:33], v[32:33], 0, v[66:67]
	global_load_dwordx4 v[40:43], v[36:37], off
	global_load_dwordx4 v[44:47], v[32:33], off
	v_readlane_b32 s2, v250, 21
	v_readlane_b32 s3, v250, 22
	v_lshl_add_u64 v[38:39], v[38:39], 2, s[42:43]
	s_waitcnt vmcnt(0)
	v_pk_fma_f32 v[30:31], v[30:31], v[42:43], v[46:47]
	v_pk_fma_f32 v[28:29], v[28:29], v[40:41], v[44:45]
	v_lshl_add_u64 v[34:35], v[34:35], 1, s[2:3]
	global_store_dwordx4 v[32:33], v[28:31], off
	s_cbranch_vccnz .LBB0_305
	v_lshl_add_u64 v[44:45], v[38:39], 0, v[66:67]
	global_load_dwordx4 v[40:43], v[68:69], off
	s_waitcnt vmcnt(0)
	v_pk_mul_f32 v[42:43], v[30:31], v[42:43]
	global_load_dwordx4 v[44:47], v[44:45], off
	v_pk_mul_f32 v[40:41], v[28:29], v[40:41]
	s_waitcnt vmcnt(0)
	v_pk_add_f32 v[46:47], v[46:47], 1.0 op_sel_hi:[1,0]
	v_pk_add_f32 v[44:45], v[44:45], 1.0 op_sel_hi:[1,0]
	v_pk_mul_f32 v[42:43], v[42:43], v[46:47]
	v_pk_mul_f32 v[40:41], v[40:41], v[44:45]
	v_and_b32_sdwa v47, v40, v170 dst_sel:DWORD dst_unused:UNUSED_PAD src0_sel:WORD_1 src1_sel:DWORD
	v_add3_u32 v40, v40, v47, s56
	v_and_b32_sdwa v47, v41, v170 dst_sel:DWORD dst_unused:UNUSED_PAD src0_sel:WORD_1 src1_sel:DWORD
	v_add3_u32 v41, v41, v47, s56
	v_and_b32_e32 v46, 0xffff0000, v41
	v_lshl_add_u64 v[44:45], v[64:65], 1, v[34:35]
	v_cvt_pk_bf16_f32 v41, v42, v43
	v_or_b32_sdwa v40, v46, v40 dst_sel:DWORD dst_unused:UNUSED_PAD src0_sel:DWORD src1_sel:WORD_1
	global_store_dwordx2 v[44:45], v[40:41], off
.LBB0_305:
	global_load_dwordx4 v[40:43], v[36:37], off offset:64
	s_nop 0
	global_load_dwordx4 v[44:47], v[32:33], off offset:64
	s_and_b64 vcc, exec, s[36:37]
	s_waitcnt vmcnt(0)
	v_pk_fma_f32 v[26:27], v[26:27], v[42:43], v[46:47]
	v_pk_fma_f32 v[24:25], v[24:25], v[40:41], v[44:45]
	global_store_dwordx4 v[32:33], v[24:27], off offset:64
	s_cbranch_vccnz .LBB0_307
	v_lshl_add_u64 v[44:45], v[38:39], 0, v[66:67]
	global_load_dwordx4 v[40:43], v[68:69], off offset:64
	s_waitcnt vmcnt(0)
	v_pk_mul_f32 v[42:43], v[26:27], v[42:43]
	global_load_dwordx4 v[44:47], v[44:45], off offset:64
	v_pk_mul_f32 v[40:41], v[24:25], v[40:41]
	s_waitcnt vmcnt(0)
	v_pk_add_f32 v[46:47], v[46:47], 1.0 op_sel_hi:[1,0]
	v_pk_add_f32 v[44:45], v[44:45], 1.0 op_sel_hi:[1,0]
	v_pk_mul_f32 v[42:43], v[42:43], v[46:47]
	v_pk_mul_f32 v[40:41], v[40:41], v[44:45]
	v_and_b32_sdwa v47, v40, v170 dst_sel:DWORD dst_unused:UNUSED_PAD src0_sel:WORD_1 src1_sel:DWORD
	v_add3_u32 v40, v40, v47, s56
	v_and_b32_sdwa v47, v41, v170 dst_sel:DWORD dst_unused:UNUSED_PAD src0_sel:WORD_1 src1_sel:DWORD
	v_add3_u32 v41, v41, v47, s56
	v_and_b32_e32 v46, 0xffff0000, v41
	v_lshl_add_u64 v[44:45], v[64:65], 1, v[34:35]
	v_cvt_pk_bf16_f32 v41, v42, v43
	v_or_b32_sdwa v40, v46, v40 dst_sel:DWORD dst_unused:UNUSED_PAD src0_sel:DWORD src1_sel:WORD_1
	global_store_dwordx2 v[44:45], v[40:41], off offset:32
.LBB0_307:
	global_load_dwordx4 v[40:43], v[36:37], off offset:128
	s_nop 0
	global_load_dwordx4 v[44:47], v[32:33], off offset:128
	s_and_b64 vcc, exec, s[36:37]
	s_waitcnt vmcnt(0)
	v_pk_fma_f32 v[22:23], v[22:23], v[42:43], v[46:47]
	v_pk_fma_f32 v[20:21], v[20:21], v[40:41], v[44:45]
	global_store_dwordx4 v[32:33], v[20:23], off offset:128
	s_cbranch_vccnz .LBB0_309
	v_lshl_add_u64 v[44:45], v[38:39], 0, v[66:67]
	global_load_dwordx4 v[40:43], v[68:69], off offset:128
	s_waitcnt vmcnt(0)
	v_pk_mul_f32 v[42:43], v[22:23], v[42:43]
	global_load_dwordx4 v[44:47], v[44:45], off offset:128
	v_pk_mul_f32 v[40:41], v[20:21], v[40:41]
	s_waitcnt vmcnt(0)
	v_pk_add_f32 v[46:47], v[46:47], 1.0 op_sel_hi:[1,0]
	v_pk_add_f32 v[44:45], v[44:45], 1.0 op_sel_hi:[1,0]
	v_pk_mul_f32 v[42:43], v[42:43], v[46:47]
	v_pk_mul_f32 v[40:41], v[40:41], v[44:45]
	v_and_b32_sdwa v47, v40, v170 dst_sel:DWORD dst_unused:UNUSED_PAD src0_sel:WORD_1 src1_sel:DWORD
	v_add3_u32 v40, v40, v47, s56
	v_and_b32_sdwa v47, v41, v170 dst_sel:DWORD dst_unused:UNUSED_PAD src0_sel:WORD_1 src1_sel:DWORD
	v_add3_u32 v41, v41, v47, s56
	v_and_b32_e32 v46, 0xffff0000, v41
	v_lshl_add_u64 v[44:45], v[64:65], 1, v[34:35]
	v_cvt_pk_bf16_f32 v41, v42, v43
	v_or_b32_sdwa v40, v46, v40 dst_sel:DWORD dst_unused:UNUSED_PAD src0_sel:DWORD src1_sel:WORD_1
	global_store_dwordx2 v[44:45], v[40:41], off offset:64

.LBB0_313:
	s_or_b64 exec, exec, s[2:3]
	v_add_u32_e32 v16, 0xffffe030, v80
	v_or_b32_e32 v18, 48, v70
	v_lshrrev_b32_e32 v16, 10, v16
	s_movk_i32 s2, 0x1800
	v_mad_u32_u24 v16, v16, s2, s2
	v_cmp_lt_i32_e32 vcc, s13, v18
	v_ashrrev_i32_e32 v19, 31, v18
	v_readlane_b32 s2, v250, 15
	v_cndmask_b32_e32 v22, 0, v16, vcc
	v_ashrrev_i32_e32 v23, 31, v22
	s_waitcnt lgkmcnt(0)
	v_lshl_add_u64 v[16:17], v[22:23], 2, s[40:41]
	v_lshl_add_u64 v[20:21], v[16:17], 0, v[66:67]
	v_lshlrev_b64 v[16:17], 12, v[18:19]
	v_readlane_b32 s3, v250, 16
	v_lshlrev_b64 v[18:19], 10, v[18:19]
	s_and_b64 vcc, exec, s[36:37]
	v_lshl_add_u64 v[16:17], s[2:3], 0, v[16:17]
	v_lshl_add_u64 v[16:17], v[16:17], 0, v[66:67]
	global_load_dwordx4 v[24:27], v[20:21], off
	global_load_dwordx4 v[28:31], v[16:17], off
	v_readlane_b32 s2, v250, 21
	v_readlane_b32 s3, v250, 22
	v_lshl_add_u64 v[22:23], v[22:23], 2, s[42:43]
	s_waitcnt vmcnt(0)
	v_pk_fma_f32 v[14:15], v[14:15], v[26:27], v[30:31]
	v_pk_fma_f32 v[12:13], v[12:13], v[24:25], v[28:29]
	v_lshl_add_u64 v[18:19], v[18:19], 1, s[2:3]
	global_store_dwordx4 v[16:17], v[12:15], off
	s_cbranch_vccnz .LBB0_315
	v_lshl_add_u64 v[28:29], v[22:23], 0, v[66:67]
	global_load_dwordx4 v[24:27], v[68:69], off
	s_waitcnt vmcnt(0)
	v_pk_mul_f32 v[26:27], v[14:15], v[26:27]
	global_load_dwordx4 v[28:31], v[28:29], off
	v_pk_mul_f32 v[24:25], v[12:13], v[24:25]
	s_waitcnt vmcnt(0)
	v_pk_add_f32 v[30:31], v[30:31], 1.0 op_sel_hi:[1,0]
	v_pk_add_f32 v[28:29], v[28:29], 1.0 op_sel_hi:[1,0]
	v_pk_mul_f32 v[26:27], v[26:27], v[30:31]
	v_pk_mul_f32 v[24:25], v[24:25], v[28:29]
	v_and_b32_sdwa v31, v24, v170 dst_sel:DWORD dst_unused:UNUSED_PAD src0_sel:WORD_1 src1_sel:DWORD
	v_add3_u32 v24, v24, v31, s56
	v_and_b32_sdwa v31, v25, v170 dst_sel:DWORD dst_unused:UNUSED_PAD src0_sel:WORD_1 src1_sel:DWORD
	v_add3_u32 v25, v25, v31, s56
	v_and_b32_e32 v30, 0xffff0000, v25
	v_lshl_add_u64 v[28:29], v[64:65], 1, v[18:19]
	v_cvt_pk_bf16_f32 v25, v26, v27
	v_or_b32_sdwa v24, v30, v24 dst_sel:DWORD dst_unused:UNUSED_PAD src0_sel:DWORD src1_sel:WORD_1
	global_store_dwordx2 v[28:29], v[24:25], off
.LBB0_315:
	global_load_dwordx4 v[24:27], v[20:21], off offset:64
	s_nop 0
	global_load_dwordx4 v[28:31], v[16:17], off offset:64
	s_and_b64 vcc, exec, s[36:37]
	s_waitcnt vmcnt(0)
	v_pk_fma_f32 v[10:11], v[10:11], v[26:27], v[30:31]
	v_pk_fma_f32 v[8:9], v[8:9], v[24:25], v[28:29]
	global_store_dwordx4 v[16:17], v[8:11], off offset:64
	s_cbranch_vccnz .LBB0_317
	v_lshl_add_u64 v[28:29], v[22:23], 0, v[66:67]
	global_load_dwordx4 v[24:27], v[68:69], off offset:64
	s_waitcnt vmcnt(0)
	v_pk_mul_f32 v[26:27], v[10:11], v[26:27]
	global_load_dwordx4 v[28:31], v[28:29], off offset:64
	v_pk_mul_f32 v[24:25], v[8:9], v[24:25]
	s_waitcnt vmcnt(0)
	v_pk_add_f32 v[30:31], v[30:31], 1.0 op_sel_hi:[1,0]
	v_pk_add_f32 v[28:29], v[28:29], 1.0 op_sel_hi:[1,0]
	v_pk_mul_f32 v[26:27], v[26:27], v[30:31]
	v_pk_mul_f32 v[24:25], v[24:25], v[28:29]
	v_and_b32_sdwa v31, v24, v170 dst_sel:DWORD dst_unused:UNUSED_PAD src0_sel:WORD_1 src1_sel:DWORD
	v_add3_u32 v24, v24, v31, s56
	v_and_b32_sdwa v31, v25, v170 dst_sel:DWORD dst_unused:UNUSED_PAD src0_sel:WORD_1 src1_sel:DWORD
	v_add3_u32 v25, v25, v31, s56
	v_and_b32_e32 v30, 0xffff0000, v25
	v_lshl_add_u64 v[28:29], v[64:65], 1, v[18:19]
	v_cvt_pk_bf16_f32 v25, v26, v27
	v_or_b32_sdwa v24, v30, v24 dst_sel:DWORD dst_unused:UNUSED_PAD src0_sel:DWORD src1_sel:WORD_1
	global_store_dwordx2 v[28:29], v[24:25], off offset:32
.LBB0_317:
	global_load_dwordx4 v[24:27], v[20:21], off offset:128
	s_nop 0
	global_load_dwordx4 v[28:31], v[16:17], off offset:128
	s_and_b64 vcc, exec, s[36:37]
	s_waitcnt vmcnt(0)
	v_pk_fma_f32 v[6:7], v[6:7], v[26:27], v[30:31]
	v_pk_fma_f32 v[4:5], v[4:5], v[24:25], v[28:29]
	global_store_dwordx4 v[16:17], v[4:7], off offset:128
	s_cbranch_vccnz .LBB0_319
	v_lshl_add_u64 v[28:29], v[22:23], 0, v[66:67]
	global_load_dwordx4 v[24:27], v[68:69], off offset:128
	s_waitcnt vmcnt(0)
	v_pk_mul_f32 v[26:27], v[6:7], v[26:27]
	global_load_dwordx4 v[28:31], v[28:29], off offset:128
	v_pk_mul_f32 v[24:25], v[4:5], v[24:25]
	s_waitcnt vmcnt(0)
	v_pk_add_f32 v[30:31], v[30:31], 1.0 op_sel_hi:[1,0]
	v_pk_add_f32 v[28:29], v[28:29], 1.0 op_sel_hi:[1,0]
	v_pk_mul_f32 v[26:27], v[26:27], v[30:31]
	v_pk_mul_f32 v[24:25], v[24:25], v[28:29]
	v_and_b32_sdwa v31, v24, v170 dst_sel:DWORD dst_unused:UNUSED_PAD src0_sel:WORD_1 src1_sel:DWORD
	v_add3_u32 v24, v24, v31, s56
	v_and_b32_sdwa v31, v25, v170 dst_sel:DWORD dst_unused:UNUSED_PAD src0_sel:WORD_1 src1_sel:DWORD
	v_add3_u32 v25, v25, v31, s56
	v_and_b32_e32 v30, 0xffff0000, v25
	v_lshl_add_u64 v[28:29], v[64:65], 1, v[18:19]
	v_cvt_pk_bf16_f32 v25, v26, v27
	v_or_b32_sdwa v24, v30, v24 dst_sel:DWORD dst_unused:UNUSED_PAD src0_sel:DWORD src1_sel:WORD_1
	global_store_dwordx2 v[28:29], v[24:25], off offset:64

.Ltail327:
	s_add_i32 s0, s1, 2
	v_add_u32_e32 v127, v89, v90
	ds_read_b128 v[100:103], v127 offset:16384
	ds_read_b128 v[106:109], v127 offset:18432
	ds_read_b128 v[110:113], v127 offset:20480
	ds_read_b128 v[114:117], v127 offset:22528
	v_add_u32_e32 v126, v88, v90
	ds_read_b128 v[92:95], v126
	ds_read_b128 v[96:99], v126 offset:2048
	s_add_i32 s1, s1, 4
	s_min_u32 s1, s1, 63
	v_add_u32_e32 v128, v88, v91
	v_add_u32_e32 v130, v89, v91
	s_lshl_b32 s92, s1, 7
	ds_read_b128 v[118:121], v130 offset:18432
	ds_read_b128 v[122:125], v130 offset:20480
	ds_read_b128 v[132:135], v130 offset:22528
	s_waitcnt lgkmcnt(4)
	v_mfma_f32_16x16x32_bf16 v[76:79], v[100:103], v[92:95], v[76:79]
	v_lshl_add_u64 v[48:49], v[80:81], 0, s[92:93]
	v_add_co_u32_e32 v50, vcc, s7, v48
	v_mfma_f32_16x16x32_bf16 v[56:59], v[106:109], v[92:95], v[56:59]
	s_nop 0
	v_addc_co_u32_e32 v51, vcc, 0, v49, vcc
	v_mfma_f32_16x16x32_bf16 v[44:47], v[110:113], v[92:95], v[44:47]
	v_mfma_f32_16x16x32_bf16 v[24:27], v[114:117], v[92:95], v[24:27]
	s_waitcnt lgkmcnt(3)
	v_mfma_f32_16x16x32_bf16 v[92:95], v[100:103], v[96:99], v[12:15]
	s_nop 2
	ds_read_b128 v[12:15], v128
	v_mfma_f32_16x16x32_bf16 v[100:103], v[106:109], v[96:99], v[8:11]
	v_mfma_f32_16x16x32_bf16 v[106:109], v[110:113], v[96:99], v[4:7]
	ds_read_b128 v[110:113], v128 offset:2048
	v_mfma_f32_16x16x32_bf16 v[96:99], v[114:117], v[96:99], v[0:3]
	ds_read_b128 v[114:117], v130 offset:16384
	s_waitcnt vmcnt(0)
	ds_write_b128 v87, v[16:19] offset:53248
	v_add_co_u32_e32 v50, vcc, s52, v48
	s_waitcnt vmcnt(1)
	ds_write_b128 v87, v[20:23] offset:49152
	s_nop 0
	v_addc_co_u32_e32 v51, vcc, 0, v49, vcc
	v_add_co_u32_e32 v48, vcc, s34, v48
	s_nop 0
	v_addc_co_u32_e32 v49, vcc, 0, v49, vcc
	s_waitcnt vmcnt(2)
	ds_write_b128 v87, v[28:31] offset:45056
	v_lshl_add_u64 v[48:49], v[82:83], 0, s[92:93]
	s_waitcnt vmcnt(5)
	ds_write_b128 v87, v[36:39] offset:32768
	s_waitcnt lgkmcnt(4)
	v_mfma_f32_16x16x32_bf16 v[0:3], v[114:117], v[12:15], v[76:79]
	v_mfma_f32_16x16x32_bf16 v[4:7], v[118:121], v[12:15], v[56:59]
	v_add_co_u32_e32 v48, vcc, s7, v48
	s_waitcnt vmcnt(4)
	ds_write_b128 v87, v[40:43] offset:36864
	s_nop 0
	v_addc_co_u32_e32 v49, vcc, 0, v49, vcc
	v_mfma_f32_16x16x32_bf16 v[8:11], v[122:125], v[12:15], v[44:47]
	v_mfma_f32_16x16x32_bf16 v[12:15], v[132:135], v[12:15], v[24:27]
	s_waitcnt vmcnt(3)
	ds_write_b128 v87, v[32:35] offset:40960
	v_mfma_f32_16x16x32_bf16 v[24:27], v[114:117], v[110:113], v[92:95]
	v_mfma_f32_16x16x32_bf16 v[44:47], v[118:121], v[110:113], v[100:103]
	v_mfma_f32_16x16x32_bf16 v[56:59], v[122:125], v[110:113], v[106:109]
	v_mfma_f32_16x16x32_bf16 v[76:79], v[132:135], v[110:113], v[96:99]
	s_waitcnt lgkmcnt(0)
	s_barrier
	ds_read_b128 v[100:103], v127 offset:49152
	ds_read_b128 v[106:109], v127 offset:51200
	ds_read_b128 v[110:113], v127 offset:53248
	ds_read_b128 v[114:117], v127 offset:55296
	ds_read_b128 v[92:95], v126 offset:32768
	ds_read_b128 v[96:99], v126 offset:34816
	s_min_u32 s1, s0, 60
	s_lshl_b32 s92, s1, 7
	ds_read_b128 v[118:121], v130 offset:51200
	ds_read_b128 v[122:125], v130 offset:53248
	ds_read_b128 v[132:135], v130 offset:55296
	s_waitcnt lgkmcnt(4)
	v_mfma_f32_16x16x32_bf16 v[0:3], v[100:103], v[92:95], v[0:3]
	v_lshl_add_u64 v[16:17], v[80:81], 0, s[92:93]
	v_add_co_u32_e32 v18, vcc, s7, v16
	v_mfma_f32_16x16x32_bf16 v[4:7], v[106:109], v[92:95], v[4:7]
	s_nop 0
	v_addc_co_u32_e32 v19, vcc, 0, v17, vcc
	v_mfma_f32_16x16x32_bf16 v[8:11], v[110:113], v[92:95], v[8:11]
	v_mfma_f32_16x16x32_bf16 v[12:15], v[114:117], v[92:95], v[12:15]
	s_waitcnt lgkmcnt(3)
	v_mfma_f32_16x16x32_bf16 v[92:95], v[100:103], v[96:99], v[24:27]
	s_nop 2
	ds_read_b128 v[24:27], v128 offset:32768
	v_mfma_f32_16x16x32_bf16 v[100:103], v[106:109], v[96:99], v[44:47]
	v_mfma_f32_16x16x32_bf16 v[106:109], v[110:113], v[96:99], v[56:59]
	ds_read_b128 v[110:113], v128 offset:34816
	v_mfma_f32_16x16x32_bf16 v[96:99], v[114:117], v[96:99], v[76:79]
	ds_read_b128 v[114:117], v130 offset:49152
	v_add_co_u32_e32 v18, vcc, s52, v16
	s_nop 0
	v_addc_co_u32_e32 v19, vcc, 0, v17, vcc
	v_add_co_u32_e32 v16, vcc, s34, v16
	s_nop 0
	v_addc_co_u32_e32 v17, vcc, 0, v17, vcc
	v_lshl_add_u64 v[16:17], v[82:83], 0, s[92:93]
	s_waitcnt lgkmcnt(0)
	v_mfma_f32_16x16x32_bf16 v[76:79], v[114:117], v[24:27], v[0:3]
	v_mfma_f32_16x16x32_bf16 v[56:59], v[118:121], v[24:27], v[4:7]
	v_add_co_u32_e32 v16, vcc, s7, v16
	s_nop 0
	v_addc_co_u32_e32 v17, vcc, 0, v17, vcc
	v_mfma_f32_16x16x32_bf16 v[44:47], v[122:125], v[24:27], v[8:11]
	v_mfma_f32_16x16x32_bf16 v[24:27], v[132:135], v[24:27], v[12:15]
	v_mfma_f32_16x16x32_bf16 v[12:15], v[114:117], v[110:113], v[92:95]
	v_mfma_f32_16x16x32_bf16 v[8:11], v[118:121], v[110:113], v[100:103]
	v_mfma_f32_16x16x32_bf16 v[4:7], v[122:125], v[110:113], v[106:109]
	v_mfma_f32_16x16x32_bf16 v[0:3], v[132:135], v[110:113], v[96:99]
	s_mov_b32 s1, s0
	s_waitcnt lgkmcnt(0)
	s_barrier
	v_readlane_b32 s0, v251, 18
	s_nop 1
	v_add_u32_e32 v48, s0, v86
	v_readlane_b32 s0, v251, 19
	s_waitcnt vmcnt(0)
	v_add_u32_e32 v16, 0xffffe000, v48
	v_or_b32_e32 v34, v48, v85
	v_lshl_or_b32 v32, v84, 2, s0
	v_lshrrev_b32_e32 v16, 10, v16
	s_movk_i32 s0, 0x1800
	v_mad_u32_u24 v16, v16, s0, s0
	v_cmp_lt_i32_e32 vcc, s13, v34
	v_ashrrev_i32_e32 v35, 31, v34
	v_lshlrev_b32_e32 v128, 2, v32
	v_cndmask_b32_e32 v28, 0, v16, vcc
	v_ashrrev_i32_e32 v29, 31, v28
	v_lshl_add_u64 v[16:17], v[28:29], 2, s[40:41]
	v_readlane_b32 s0, v250, 15
	v_lshl_add_u64 v[40:41], v[16:17], 0, v[128:129]
	v_lshlrev_b64 v[16:17], 12, v[34:35]
	v_readlane_b32 s1, v250, 16
	v_lshlrev_b64 v[30:31], 10, v[34:35]
	s_and_b64 vcc, exec, s[36:37]
	v_lshl_add_u64 v[16:17], s[0:1], 0, v[16:17]
	v_lshl_add_u64 v[38:39], v[16:17], 0, v[128:129]
	global_load_dwordx4 v[60:63], v[40:41], off
	global_load_dwordx4 v[72:75], v[40:41], off offset:64
	global_load_dwordx4 v[80:83], v[40:41], off offset:128
	global_load_dwordx4 v[88:91], v[40:41], off offset:192
	global_load_dwordx4 v[190:193], v[38:39], off
	global_load_dwordx4 v[194:197], v[38:39], off offset:64
	global_load_dwordx4 v[198:201], v[38:39], off offset:128
	global_load_dwordx4 v[202:205], v[38:39], off offset:192
	v_add_co_u32_e32 v54, vcc, 0x10000, v38
	s_nop 1
	v_addc_co_u32_e32 v55, vcc, 0, v39, vcc
	global_load_dwordx4 v[206:209], v[54:55], off
	global_load_dwordx4 v[210:213], v[54:55], off offset:64
	global_load_dwordx4 v[214:217], v[54:55], off offset:128
	global_load_dwordx4 v[218:221], v[54:55], off offset:192
	v_readlane_b32 s0, v250, 21
	v_readlane_b32 s1, v250, 22
	v_lshl_add_u64 v[42:43], v[28:29], 2, s[42:43]
	v_lshlrev_b32_e32 v32, 1, v32
	v_lshl_add_u64 v[36:37], v[30:31], 1, s[0:1]
	s_waitcnt vmcnt(4)
	v_pk_fma_f32 v[18:19], v[78:79], v[62:63], v[192:193]
	v_pk_fma_f32 v[16:17], v[76:77], v[60:61], v[190:191]
	global_store_dwordx4 v[38:39], v[16:19], off
	s_cbranch_vccnz .LBB0_330
	v_lshl_add_u64 v[28:29], v[42:43], 0, v[128:129]
	global_load_dwordx4 v[136:139], v128, s[26:27]
	global_load_dwordx4 v[140:143], v128, s[26:27] offset:64
	global_load_dwordx4 v[144:147], v128, s[26:27] offset:128
	global_load_dwordx4 v[148:151], v128, s[26:27] offset:192
	v_mov_b32_e32 v33, v129
	global_load_dwordx4 v[152:155], v[28:29], off
	global_load_dwordx4 v[156:159], v[28:29], off offset:64
	global_load_dwordx4 v[160:163], v[28:29], off offset:128
	global_load_dwordx4 v[180:183], v[28:29], off offset:192
	s_waitcnt vmcnt(0)
	v_pk_mul_f32 v[22:23], v[18:19], v[138:139]
	v_pk_mul_f32 v[20:21], v[16:17], v[136:137]
	s_waitcnt vmcnt(0)
	v_pk_add_f32 v[30:31], v[154:155], 1.0 op_sel_hi:[1,0]
	v_pk_add_f32 v[28:29], v[152:153], 1.0 op_sel_hi:[1,0]
	v_pk_mul_f32 v[22:23], v[22:23], v[30:31]
	v_pk_mul_f32 v[20:21], v[20:21], v[28:29]
	v_and_b32_sdwa v31, v20, v170 dst_sel:DWORD dst_unused:UNUSED_PAD src0_sel:WORD_1 src1_sel:DWORD
	v_add3_u32 v20, v20, v31, s56
	v_and_b32_sdwa v31, v21, v170 dst_sel:DWORD dst_unused:UNUSED_PAD src0_sel:WORD_1 src1_sel:DWORD
	v_add3_u32 v21, v21, v31, s56
	v_and_b32_e32 v30, 0xffff0000, v21
	v_lshl_add_u64 v[28:29], v[36:37], 0, v[32:33]
	v_cvt_pk_bf16_f32 v21, v22, v23
	v_or_b32_sdwa v20, v30, v20 dst_sel:DWORD dst_unused:UNUSED_PAD src0_sel:DWORD src1_sel:WORD_1
	global_store_dwordx2 v[28:29], v[20:21], off
.LBB0_330:
	s_nop 0
	s_and_b64 vcc, exec, s[36:37]
	s_waitcnt vmcnt(0)
	v_pk_fma_f32 v[22:23], v[58:59], v[74:75], v[196:197]
	v_pk_fma_f32 v[20:21], v[56:57], v[72:73], v[194:195]
	global_store_dwordx4 v[38:39], v[20:23], off offset:64
	s_cbranch_vccnz .LBB0_332
	v_lshl_add_u64 v[50:51], v[42:43], 0, v[128:129]
	v_mov_b32_e32 v33, v129
	v_pk_mul_f32 v[30:31], v[22:23], v[142:143]
	v_pk_mul_f32 v[28:29], v[20:21], v[140:141]
	v_pk_add_f32 v[52:53], v[158:159], 1.0 op_sel_hi:[1,0]
	v_pk_add_f32 v[50:51], v[156:157], 1.0 op_sel_hi:[1,0]
	v_pk_mul_f32 v[30:31], v[30:31], v[52:53]
	v_pk_mul_f32 v[28:29], v[28:29], v[50:51]
	v_lshl_add_u64 v[50:51], v[36:37], 0, v[32:33]
	v_and_b32_sdwa v49, v28, v170 dst_sel:DWORD dst_unused:UNUSED_PAD src0_sel:WORD_1 src1_sel:DWORD
	v_add3_u32 v28, v28, v49, s56
	v_and_b32_sdwa v49, v29, v170 dst_sel:DWORD dst_unused:UNUSED_PAD src0_sel:WORD_1 src1_sel:DWORD
	v_add3_u32 v29, v29, v49, s56
	v_and_b32_e32 v33, 0xffff0000, v29
	v_cvt_pk_bf16_f32 v29, v30, v31
	v_or_b32_sdwa v28, v33, v28 dst_sel:DWORD dst_unused:UNUSED_PAD src0_sel:DWORD src1_sel:WORD_1
	global_store_dwordx2 v[50:51], v[28:29], off offset:32

.LBB0_338:
	s_or_b64 exec, exec, s[2:3]
	s_waitcnt lgkmcnt(0)
	v_add_u32_e32 v17, 0xffffe010, v48
	v_or_b32_e32 v16, 16, v34
	v_lshrrev_b32_e32 v17, 10, v17
	s_movk_i32 s2, 0x1800
	v_mad_u32_u24 v17, v17, s2, s2
	v_cmp_lt_i32_e32 vcc, s13, v16
	v_readlane_b32 s2, v250, 15
	v_readlane_b32 s3, v250, 16
	v_cndmask_b32_e32 v20, 0, v17, vcc
	v_ashrrev_i32_e32 v21, 31, v20
	v_ashrrev_i32_e32 v17, 31, v16
	v_lshl_add_u64 v[18:19], v[20:21], 2, s[40:41]
	v_lshl_add_u64 v[22:23], v[18:19], 0, v[128:129]
	v_lshlrev_b64 v[18:19], 12, v[16:17]
	v_lshl_add_u64 v[18:19], s[2:3], 0, v[18:19]
	v_lshl_add_u64 v[18:19], v[18:19], 0, v[128:129]
	v_readlane_b32 s2, v250, 21
	v_lshlrev_b64 v[30:31], 10, v[16:17]
	v_readlane_b32 s3, v250, 22
	s_and_b64 vcc, exec, s[36:37]
	v_lshl_add_u64 v[24:25], v[20:21], 2, s[42:43]
	v_lshl_add_u64 v[20:21], v[30:31], 1, s[2:3]
	s_waitcnt vmcnt(4)
	v_pk_fma_f32 v[14:15], v[14:15], v[62:63], v[208:209]
	v_pk_fma_f32 v[12:13], v[12:13], v[60:61], v[206:207]
	global_store_dwordx4 v[18:19], v[12:15], off
	s_cbranch_vccnz .LBB0_340
	v_lshl_add_u64 v[30:31], v[24:25], 0, v[128:129]
	v_mov_b32_e32 v33, v129
	v_pk_mul_f32 v[28:29], v[14:15], v[138:139]
	v_pk_mul_f32 v[26:27], v[12:13], v[136:137]
	v_pk_add_f32 v[30:31], v[154:155], 1.0 op_sel_hi:[1,0]
	v_pk_add_f32 v[34:35], v[152:153], 1.0 op_sel_hi:[1,0]
	v_pk_mul_f32 v[28:29], v[28:29], v[30:31]
	v_pk_mul_f32 v[26:27], v[26:27], v[34:35]
	v_lshl_add_u64 v[30:31], v[20:21], 0, v[32:33]
	v_and_b32_sdwa v34, v26, v170 dst_sel:DWORD dst_unused:UNUSED_PAD src0_sel:WORD_1 src1_sel:DWORD
	v_add3_u32 v26, v26, v34, s56
	v_and_b32_sdwa v34, v27, v170 dst_sel:DWORD dst_unused:UNUSED_PAD src0_sel:WORD_1 src1_sel:DWORD
	v_add3_u32 v27, v27, v34, s56
	v_and_b32_e32 v33, 0xffff0000, v27
	v_cvt_pk_bf16_f32 v27, v28, v29
	v_or_b32_sdwa v26, v33, v26 dst_sel:DWORD dst_unused:UNUSED_PAD src0_sel:DWORD src1_sel:WORD_1
	global_store_dwordx2 v[30:31], v[26:27], off
.LBB0_340:
	s_nop 0
	s_and_b64 vcc, exec, s[36:37]
	v_pk_fma_f32 v[10:11], v[10:11], v[74:75], v[212:213]
	v_pk_fma_f32 v[8:9], v[8:9], v[72:73], v[210:211]
	global_store_dwordx4 v[18:19], v[8:11], off offset:64
	s_cbranch_vccnz .LBB0_342
	v_lshl_add_u64 v[30:31], v[24:25], 0, v[128:129]
	v_mov_b32_e32 v33, v129
	v_pk_mul_f32 v[28:29], v[10:11], v[142:143]
	v_pk_mul_f32 v[26:27], v[8:9], v[140:141]
	v_pk_add_f32 v[30:31], v[158:159], 1.0 op_sel_hi:[1,0]
	v_pk_add_f32 v[34:35], v[156:157], 1.0 op_sel_hi:[1,0]
	v_pk_mul_f32 v[28:29], v[28:29], v[30:31]
	v_pk_mul_f32 v[26:27], v[26:27], v[34:35]
	v_lshl_add_u64 v[30:31], v[20:21], 0, v[32:33]
	v_and_b32_sdwa v34, v26, v170 dst_sel:DWORD dst_unused:UNUSED_PAD src0_sel:WORD_1 src1_sel:DWORD
	v_add3_u32 v26, v26, v34, s56
	v_and_b32_sdwa v34, v27, v170 dst_sel:DWORD dst_unused:UNUSED_PAD src0_sel:WORD_1 src1_sel:DWORD
	v_add3_u32 v27, v27, v34, s56
	v_and_b32_e32 v33, 0xffff0000, v27
	v_cvt_pk_bf16_f32 v27, v28, v29
	v_or_b32_sdwa v26, v33, v26 dst_sel:DWORD dst_unused:UNUSED_PAD src0_sel:DWORD src1_sel:WORD_1
	global_store_dwordx2 v[30:31], v[26:27], off offset:32

.LBB0_353:
	s_or_b64 exec, exec, s[28:29]
	v_add_u32_e32 v66, s26, v142
	v_lshlrev_b32_e32 v65, 1, v66
	v_and_b32_e32 v65, 0xfffff800, v65
	v_or_b32_e32 v64, s40, v147
	v_add_u32_e32 v65, 0xffffc800, v65
	v_cmp_lt_i32_e32 vcc, s13, v66
	s_waitcnt lgkmcnt(0)
	s_barrier
	v_cndmask_b32_e32 v128, 0, v65, vcc
	v_ashrrev_i32_e32 v65, 31, v64
	v_lshl_add_u64 v[68:69], v[128:129], 2, s[0:1]
	s_waitcnt vmcnt(6)
	v_lshlrev_b64 v[100:101], 2, v[64:65]
	s_waitcnt vmcnt(3)
	v_lshl_add_u64 v[110:111], v[68:69], 0, v[100:101]
	global_load_dwordx4 v[96:99], v[110:111], off
	s_ashr_i32 s27, s39, 31
	s_lshr_b32 s27, s27, 28
	s_add_i32 s27, s39, s27
	v_ashrrev_i32_e32 v67, 31, v66
	s_ashr_i32 s28, s27, 4
	s_and_b32 s27, s27, -16
	v_readlane_b32 s16, v251, 32
	v_lshlrev_b64 v[66:67], 10, v[66:67]
	v_readlane_b32 s17, v251, 33
	s_sub_i32 s27, s39, s27
	v_lshlrev_b64 v[106:107], 1, v[64:65]
	v_lshl_add_u64 v[64:65], s[16:17], 0, v[66:67]
	s_lshl_b32 s29, s28, 2
	s_ashr_i32 s28, s27, 2
	v_lshl_add_u64 v[114:115], v[64:65], 0, v[106:107]
	v_lshl_add_u32 v64, s28, 7, v130
	v_ashrrev_i32_e32 v65, 31, v64
	v_lshlrev_b64 v[64:65], 11, v[64:65]
	v_lshl_add_u64 v[64:65], v[134:135], 0, v[64:65]
	s_and_b32 s40, s27, 3
	v_add_co_u32_e32 v84, vcc, s11, v64
	s_or_b32 s29, s40, s29
	s_nop 0
	v_addc_co_u32_e32 v85, vcc, 0, v65, vcc
	v_lshl_add_u32 v66, s29, 7, v130
	v_add_co_u32_e32 v72, vcc, s33, v64
	v_ashrrev_i32_e32 v67, 31, v66
	s_nop 0
	v_addc_co_u32_e32 v73, vcc, 0, v65, vcc
	v_lshlrev_b64 v[66:67], 11, v[66:67]
	v_add_co_u32_e32 v74, vcc, s59, v64
	ds_read_b32 v108, v148
	ds_read_b32 v112, v150
	ds_read_b32 v102, v152
	ds_read_b32 v104, v154
	v_lshl_add_u64 v[66:67], v[132:133], 0, v[66:67]
	v_addc_co_u32_e32 v75, vcc, 0, v65, vcc
	v_add_co_u32_e32 v80, vcc, s11, v66
	s_movk_i32 s89, 0xff
	s_nop 0
	v_addc_co_u32_e32 v81, vcc, 0, v67, vcc
	v_add_co_u32_e32 v82, vcc, s33, v66
	s_waitcnt vmcnt(0) lgkmcnt(3)
	v_pk_fma_f32 v[62:63], v[62:63], v[108:109], v[98:99] op_sel_hi:[1,0,1]
	v_pk_fma_f32 v[60:61], v[60:61], v[108:109], v[96:97] op_sel_hi:[1,0,1]
	v_and_b32_sdwa v99, v61, v170 dst_sel:DWORD dst_unused:UNUSED_PAD src0_sel:WORD_1 src1_sel:DWORD
	v_addc_co_u32_e32 v83, vcc, 0, v67, vcc
	v_and_b32_sdwa v97, v60, v170 dst_sel:DWORD dst_unused:UNUSED_PAD src0_sel:WORD_1 src1_sel:DWORD
	v_add3_u32 v61, v61, v99, s56
	v_add_co_u32_e32 v86, vcc, s59, v66
	v_add3_u32 v60, v60, v97, s56
	v_and_b32_e32 v96, 0xffff0000, v61
	v_addc_co_u32_e32 v87, vcc, 0, v67, vcc
	v_cvt_pk_bf16_f32 v61, v62, v63
	v_or_b32_sdwa v60, v96, v60 dst_sel:DWORD dst_unused:UNUSED_PAD src0_sel:DWORD src1_sel:WORD_1
	global_load_dwordx4 v[68:71], v[66:67], off
	global_load_dwordx4 v[76:79], v[64:65], off
	global_load_dwordx4 v[88:91], v[72:73], off
	global_load_dwordx4 v[92:95], v[74:75], off
	s_nop 0
	global_load_dwordx4 v[64:67], v[80:81], off
	global_load_dwordx4 v[72:75], v[82:83], off
	s_nop 0
	global_load_dwordx4 v[80:83], v[86:87], off
	s_nop 0
	global_load_dwordx4 v[84:87], v[84:85], off
	s_nop 0
	global_store_dwordx2 v[114:115], v[60:61], off
	global_load_dwordx4 v[60:63], v[110:111], off offset:64
	s_waitcnt vmcnt(0)
	v_pk_fma_f32 v[58:59], v[58:59], v[108:109], v[62:63] op_sel_hi:[1,0,1]
	v_pk_fma_f32 v[56:57], v[56:57], v[108:109], v[60:61] op_sel_hi:[1,0,1]
	v_and_b32_sdwa v63, v57, v170 dst_sel:DWORD dst_unused:UNUSED_PAD src0_sel:WORD_1 src1_sel:DWORD
	v_and_b32_sdwa v61, v56, v170 dst_sel:DWORD dst_unused:UNUSED_PAD src0_sel:WORD_1 src1_sel:DWORD
	v_add3_u32 v57, v57, v63, s56
	v_add3_u32 v56, v56, v61, s56
	v_and_b32_e32 v60, 0xffff0000, v57
	v_cvt_pk_bf16_f32 v57, v58, v59
	v_or_b32_sdwa v56, v60, v56 dst_sel:DWORD dst_unused:UNUSED_PAD src0_sel:DWORD src1_sel:WORD_1
	global_store_dwordx2 v[114:115], v[56:57], off offset:32
	global_load_dwordx4 v[56:59], v[110:111], off offset:128
	s_waitcnt vmcnt(0)
	v_pk_fma_f32 v[54:55], v[54:55], v[108:109], v[58:59] op_sel_hi:[1,0,1]
	v_pk_fma_f32 v[52:53], v[52:53], v[108:109], v[56:57] op_sel_hi:[1,0,1]
	v_and_b32_sdwa v59, v53, v170 dst_sel:DWORD dst_unused:UNUSED_PAD src0_sel:WORD_1 src1_sel:DWORD
	v_and_b32_sdwa v57, v52, v170 dst_sel:DWORD dst_unused:UNUSED_PAD src0_sel:WORD_1 src1_sel:DWORD
	v_add3_u32 v53, v53, v59, s56
	v_add3_u32 v52, v52, v57, s56
	v_and_b32_e32 v56, 0xffff0000, v53
	v_cvt_pk_bf16_f32 v53, v54, v55
	v_or_b32_sdwa v52, v56, v52 dst_sel:DWORD dst_unused:UNUSED_PAD src0_sel:DWORD src1_sel:WORD_1
	global_store_dwordx2 v[114:115], v[52:53], off offset:64
	global_load_dwordx4 v[52:55], v[110:111], off offset:192
	v_add_u32_e32 v56, s26, v149
	v_lshlrev_b32_e32 v57, 1, v56
	v_and_b32_e32 v57, 0xfffff800, v57
	v_add_u32_e32 v57, 0xffffc800, v57
	v_cmp_lt_i32_e32 vcc, s13, v56
	s_waitcnt vmcnt(0)
	v_pk_fma_f32 v[50:51], v[50:51], v[108:109], v[54:55] op_sel_hi:[1,0,1]
	v_pk_fma_f32 v[48:49], v[48:49], v[108:109], v[52:53] op_sel_hi:[1,0,1]
	v_and_b32_sdwa v55, v49, v170 dst_sel:DWORD dst_unused:UNUSED_PAD src0_sel:WORD_1 src1_sel:DWORD
	v_and_b32_sdwa v53, v48, v170 dst_sel:DWORD dst_unused:UNUSED_PAD src0_sel:WORD_1 src1_sel:DWORD
	v_add3_u32 v49, v49, v55, s56
	v_cndmask_b32_e32 v128, 0, v57, vcc
	v_add3_u32 v48, v48, v53, s56
	v_and_b32_e32 v52, 0xffff0000, v49
	v_lshl_add_u64 v[58:59], v[128:129], 2, s[0:1]
	v_cvt_pk_bf16_f32 v49, v50, v51
	v_or_b32_sdwa v48, v52, v48 dst_sel:DWORD dst_unused:UNUSED_PAD src0_sel:DWORD src1_sel:WORD_1
	v_lshl_add_u64 v[58:59], v[58:59], 0, v[100:101]
	global_store_dwordx2 v[114:115], v[48:49], off offset:96
	global_load_dwordx4 v[48:51], v[58:59], off
	v_ashrrev_i32_e32 v57, 31, v56
	v_lshlrev_b64 v[52:53], 10, v[56:57]
	v_lshl_add_u64 v[52:53], s[16:17], 0, v[52:53]
	v_lshl_add_u64 v[52:53], v[52:53], 0, v[106:107]
	s_waitcnt vmcnt(0) lgkmcnt(2)
	v_pk_fma_f32 v[46:47], v[46:47], v[112:113], v[50:51] op_sel_hi:[1,0,1]
	v_pk_fma_f32 v[44:45], v[44:45], v[112:113], v[48:49] op_sel_hi:[1,0,1]
	v_and_b32_sdwa v51, v45, v170 dst_sel:DWORD dst_unused:UNUSED_PAD src0_sel:WORD_1 src1_sel:DWORD
	v_and_b32_sdwa v49, v44, v170 dst_sel:DWORD dst_unused:UNUSED_PAD src0_sel:WORD_1 src1_sel:DWORD
	v_add3_u32 v45, v45, v51, s56
	v_add3_u32 v44, v44, v49, s56
	v_and_b32_e32 v48, 0xffff0000, v45
	v_cvt_pk_bf16_f32 v45, v46, v47
	v_or_b32_sdwa v44, v48, v44 dst_sel:DWORD dst_unused:UNUSED_PAD src0_sel:DWORD src1_sel:WORD_1
	global_store_dwordx2 v[52:53], v[44:45], off
	global_load_dwordx4 v[44:47], v[58:59], off offset:64
	s_waitcnt vmcnt(0)
	v_pk_fma_f32 v[42:43], v[42:43], v[112:113], v[46:47] op_sel_hi:[1,0,1]
	v_pk_fma_f32 v[40:41], v[40:41], v[112:113], v[44:45] op_sel_hi:[1,0,1]
	v_and_b32_sdwa v47, v41, v170 dst_sel:DWORD dst_unused:UNUSED_PAD src0_sel:WORD_1 src1_sel:DWORD
	v_and_b32_sdwa v45, v40, v170 dst_sel:DWORD dst_unused:UNUSED_PAD src0_sel:WORD_1 src1_sel:DWORD
	v_add3_u32 v41, v41, v47, s56
	v_add3_u32 v40, v40, v45, s56
	v_and_b32_e32 v44, 0xffff0000, v41
	v_cvt_pk_bf16_f32 v41, v42, v43
	v_or_b32_sdwa v40, v44, v40 dst_sel:DWORD dst_unused:UNUSED_PAD src0_sel:DWORD src1_sel:WORD_1
	global_store_dwordx2 v[52:53], v[40:41], off offset:32
	global_load_dwordx4 v[40:43], v[58:59], off offset:128
	s_waitcnt vmcnt(0)
	v_pk_fma_f32 v[38:39], v[38:39], v[112:113], v[42:43] op_sel_hi:[1,0,1]
	v_pk_fma_f32 v[36:37], v[36:37], v[112:113], v[40:41] op_sel_hi:[1,0,1]
	v_and_b32_sdwa v43, v37, v170 dst_sel:DWORD dst_unused:UNUSED_PAD src0_sel:WORD_1 src1_sel:DWORD
	v_and_b32_sdwa v41, v36, v170 dst_sel:DWORD dst_unused:UNUSED_PAD src0_sel:WORD_1 src1_sel:DWORD
	v_add3_u32 v37, v37, v43, s56
	v_add3_u32 v36, v36, v41, s56
	v_and_b32_e32 v40, 0xffff0000, v37
	v_cvt_pk_bf16_f32 v37, v38, v39
	v_or_b32_sdwa v36, v40, v36 dst_sel:DWORD dst_unused:UNUSED_PAD src0_sel:DWORD src1_sel:WORD_1
	global_store_dwordx2 v[52:53], v[36:37], off offset:64
	global_load_dwordx4 v[36:39], v[58:59], off offset:192
	v_add_u32_e32 v40, s26, v151
	v_lshlrev_b32_e32 v41, 1, v40
	v_and_b32_e32 v41, 0xfffff800, v41
	v_add_u32_e32 v41, 0xffffc800, v41
	v_cmp_lt_i32_e32 vcc, s13, v40
	s_waitcnt vmcnt(0)
	v_pk_fma_f32 v[34:35], v[34:35], v[112:113], v[38:39] op_sel_hi:[1,0,1]
	v_pk_fma_f32 v[32:33], v[32:33], v[112:113], v[36:37] op_sel_hi:[1,0,1]
	v_and_b32_sdwa v39, v33, v170 dst_sel:DWORD dst_unused:UNUSED_PAD src0_sel:WORD_1 src1_sel:DWORD
	v_and_b32_sdwa v37, v32, v170 dst_sel:DWORD dst_unused:UNUSED_PAD src0_sel:WORD_1 src1_sel:DWORD
	v_add3_u32 v33, v33, v39, s56
	v_cndmask_b32_e32 v128, 0, v41, vcc
	v_add3_u32 v32, v32, v37, s56
	v_and_b32_e32 v36, 0xffff0000, v33
	v_lshl_add_u64 v[42:43], v[128:129], 2, s[0:1]
	v_cvt_pk_bf16_f32 v33, v34, v35
	v_or_b32_sdwa v32, v36, v32 dst_sel:DWORD dst_unused:UNUSED_PAD src0_sel:DWORD src1_sel:WORD_1
	v_lshl_add_u64 v[42:43], v[42:43], 0, v[100:101]
	global_store_dwordx2 v[52:53], v[32:33], off offset:96
	global_load_dwordx4 v[34:37], v[42:43], off
	v_ashrrev_i32_e32 v41, 31, v40
	v_lshlrev_b64 v[32:33], 10, v[40:41]
	v_lshl_add_u64 v[32:33], s[16:17], 0, v[32:33]
	v_lshl_add_u64 v[32:33], v[32:33], 0, v[106:107]
	s_waitcnt vmcnt(0) lgkmcnt(1)
	v_pk_fma_f32 v[30:31], v[30:31], v[102:103], v[36:37] op_sel_hi:[1,0,1]
	v_pk_fma_f32 v[28:29], v[28:29], v[102:103], v[34:35] op_sel_hi:[1,0,1]
	v_and_b32_sdwa v37, v29, v170 dst_sel:DWORD dst_unused:UNUSED_PAD src0_sel:WORD_1 src1_sel:DWORD
	v_and_b32_sdwa v35, v28, v170 dst_sel:DWORD dst_unused:UNUSED_PAD src0_sel:WORD_1 src1_sel:DWORD
	v_add3_u32 v29, v29, v37, s56
	v_add3_u32 v28, v28, v35, s56
	v_and_b32_e32 v34, 0xffff0000, v29
	v_cvt_pk_bf16_f32 v29, v30, v31
	v_or_b32_sdwa v28, v34, v28 dst_sel:DWORD dst_unused:UNUSED_PAD src0_sel:DWORD src1_sel:WORD_1
	global_store_dwordx2 v[32:33], v[28:29], off
	global_load_dwordx4 v[28:31], v[42:43], off offset:64
	s_waitcnt vmcnt(0)
	v_pk_fma_f32 v[26:27], v[26:27], v[102:103], v[30:31] op_sel_hi:[1,0,1]
	v_pk_fma_f32 v[24:25], v[24:25], v[102:103], v[28:29] op_sel_hi:[1,0,1]
	v_and_b32_sdwa v31, v25, v170 dst_sel:DWORD dst_unused:UNUSED_PAD src0_sel:WORD_1 src1_sel:DWORD
	v_and_b32_sdwa v29, v24, v170 dst_sel:DWORD dst_unused:UNUSED_PAD src0_sel:WORD_1 src1_sel:DWORD
	v_add3_u32 v25, v25, v31, s56
	v_add3_u32 v24, v24, v29, s56
	v_and_b32_e32 v28, 0xffff0000, v25
	v_cvt_pk_bf16_f32 v25, v26, v27
	v_or_b32_sdwa v24, v28, v24 dst_sel:DWORD dst_unused:UNUSED_PAD src0_sel:DWORD src1_sel:WORD_1
	global_store_dwordx2 v[32:33], v[24:25], off offset:32
	global_load_dwordx4 v[24:27], v[42:43], off offset:128
	s_waitcnt vmcnt(0)
	v_pk_fma_f32 v[22:23], v[22:23], v[102:103], v[26:27] op_sel_hi:[1,0,1]
	v_pk_fma_f32 v[20:21], v[20:21], v[102:103], v[24:25] op_sel_hi:[1,0,1]
	v_and_b32_sdwa v27, v21, v170 dst_sel:DWORD dst_unused:UNUSED_PAD src0_sel:WORD_1 src1_sel:DWORD
	v_and_b32_sdwa v25, v20, v170 dst_sel:DWORD dst_unused:UNUSED_PAD src0_sel:WORD_1 src1_sel:DWORD
	v_add3_u32 v21, v21, v27, s56
	v_add3_u32 v20, v20, v25, s56
	v_and_b32_e32 v24, 0xffff0000, v21
	v_cvt_pk_bf16_f32 v21, v22, v23
	v_or_b32_sdwa v20, v24, v20 dst_sel:DWORD dst_unused:UNUSED_PAD src0_sel:DWORD src1_sel:WORD_1
	global_store_dwordx2 v[32:33], v[20:21], off offset:64
	global_load_dwordx4 v[20:23], v[42:43], off offset:192
	v_add_u32_e32 v24, s26, v153
	v_lshlrev_b32_e32 v25, 1, v24
	v_and_b32_e32 v25, 0xfffff800, v25
	v_add_u32_e32 v25, 0xffffc800, v25
	v_cmp_lt_i32_e32 vcc, s13, v24
	s_waitcnt vmcnt(0)
	v_pk_fma_f32 v[18:19], v[18:19], v[102:103], v[22:23] op_sel_hi:[1,0,1]
	v_pk_fma_f32 v[16:17], v[16:17], v[102:103], v[20:21] op_sel_hi:[1,0,1]
	v_and_b32_sdwa v23, v17, v170 dst_sel:DWORD dst_unused:UNUSED_PAD src0_sel:WORD_1 src1_sel:DWORD
	v_and_b32_sdwa v21, v16, v170 dst_sel:DWORD dst_unused:UNUSED_PAD src0_sel:WORD_1 src1_sel:DWORD
	v_add3_u32 v17, v17, v23, s56
	v_cndmask_b32_e32 v128, 0, v25, vcc
	v_add3_u32 v16, v16, v21, s56
	v_and_b32_e32 v20, 0xffff0000, v17
	v_lshl_add_u64 v[26:27], v[128:129], 2, s[0:1]
	v_cvt_pk_bf16_f32 v17, v18, v19
	v_or_b32_sdwa v16, v20, v16 dst_sel:DWORD dst_unused:UNUSED_PAD src0_sel:DWORD src1_sel:WORD_1
	v_lshl_add_u64 v[26:27], v[26:27], 0, v[100:101]
	global_store_dwordx2 v[32:33], v[16:17], off offset:96
	global_load_dwordx4 v[16:19], v[26:27], off
	v_ashrrev_i32_e32 v25, 31, v24
	v_lshlrev_b64 v[20:21], 10, v[24:25]
	v_lshl_add_u64 v[20:21], s[16:17], 0, v[20:21]
	v_lshl_add_u64 v[20:21], v[20:21], 0, v[106:107]
	v_readlane_b32 s16, v253, 12
	s_cmp_lg_u32 s38, s16
	s_waitcnt vmcnt(0) lgkmcnt(0)
	v_pk_fma_f32 v[14:15], v[14:15], v[104:105], v[18:19] op_sel_hi:[1,0,1]
	v_pk_fma_f32 v[12:13], v[12:13], v[104:105], v[16:17] op_sel_hi:[1,0,1]
	v_and_b32_sdwa v19, v13, v170 dst_sel:DWORD dst_unused:UNUSED_PAD src0_sel:WORD_1 src1_sel:DWORD
	v_and_b32_sdwa v17, v12, v170 dst_sel:DWORD dst_unused:UNUSED_PAD src0_sel:WORD_1 src1_sel:DWORD
	v_add3_u32 v13, v13, v19, s56
	v_add3_u32 v12, v12, v17, s56
	v_and_b32_e32 v16, 0xffff0000, v13
	v_cvt_pk_bf16_f32 v13, v14, v15
	v_or_b32_sdwa v12, v16, v12 dst_sel:DWORD dst_unused:UNUSED_PAD src0_sel:DWORD src1_sel:WORD_1
	global_store_dwordx2 v[20:21], v[12:13], off
	global_load_dwordx4 v[12:15], v[26:27], off offset:64
	s_waitcnt vmcnt(0)
	v_pk_fma_f32 v[10:11], v[10:11], v[104:105], v[14:15] op_sel_hi:[1,0,1]
	v_pk_fma_f32 v[8:9], v[8:9], v[104:105], v[12:13] op_sel_hi:[1,0,1]
	v_and_b32_sdwa v15, v9, v170 dst_sel:DWORD dst_unused:UNUSED_PAD src0_sel:WORD_1 src1_sel:DWORD
	v_and_b32_sdwa v13, v8, v170 dst_sel:DWORD dst_unused:UNUSED_PAD src0_sel:WORD_1 src1_sel:DWORD
	v_add3_u32 v9, v9, v15, s56
	v_add3_u32 v8, v8, v13, s56
	v_and_b32_e32 v12, 0xffff0000, v9
	v_cvt_pk_bf16_f32 v9, v10, v11
	v_or_b32_sdwa v8, v12, v8 dst_sel:DWORD dst_unused:UNUSED_PAD src0_sel:DWORD src1_sel:WORD_1
	global_store_dwordx2 v[20:21], v[8:9], off offset:32
	global_load_dwordx4 v[8:11], v[26:27], off offset:128
	s_waitcnt vmcnt(0)
	v_pk_fma_f32 v[6:7], v[6:7], v[104:105], v[10:11] op_sel_hi:[1,0,1]
	v_pk_fma_f32 v[4:5], v[4:5], v[104:105], v[8:9] op_sel_hi:[1,0,1]
	v_and_b32_sdwa v11, v5, v170 dst_sel:DWORD dst_unused:UNUSED_PAD src0_sel:WORD_1 src1_sel:DWORD
	v_and_b32_sdwa v9, v4, v170 dst_sel:DWORD dst_unused:UNUSED_PAD src0_sel:WORD_1 src1_sel:DWORD
	v_add3_u32 v5, v5, v11, s56
	v_add3_u32 v4, v4, v9, s56
	v_and_b32_e32 v8, 0xffff0000, v5
	v_cvt_pk_bf16_f32 v5, v6, v7
	v_or_b32_sdwa v4, v8, v4 dst_sel:DWORD dst_unused:UNUSED_PAD src0_sel:DWORD src1_sel:WORD_1
	global_store_dwordx2 v[20:21], v[4:5], off offset:64
	global_load_dwordx4 v[4:7], v[26:27], off offset:192
	s_waitcnt vmcnt(0)
	v_pk_fma_f32 v[2:3], v[2:3], v[104:105], v[6:7] op_sel_hi:[1,0,1]
	v_pk_fma_f32 v[0:1], v[0:1], v[104:105], v[4:5] op_sel_hi:[1,0,1]
	v_and_b32_sdwa v7, v1, v170 dst_sel:DWORD dst_unused:UNUSED_PAD src0_sel:WORD_1 src1_sel:DWORD
	v_and_b32_sdwa v5, v0, v170 dst_sel:DWORD dst_unused:UNUSED_PAD src0_sel:WORD_1 src1_sel:DWORD
	v_add3_u32 v1, v1, v7, s56
	v_add3_u32 v0, v0, v5, s56
	v_and_b32_e32 v4, 0xffff0000, v1
	v_cvt_pk_bf16_f32 v1, v2, v3
	v_or_b32_sdwa v0, v4, v0 dst_sel:DWORD dst_unused:UNUSED_PAD src0_sel:DWORD src1_sel:WORD_1
	global_store_dwordx2 v[20:21], v[0:1], off offset:96
	s_cbranch_scc0 .LBB0_362

.LBB0_366:
	s_or_b64 exec, exec, s[24:25]
	v_add_u32_e32 v44, s2, v146
	v_lshlrev_b32_e32 v45, 1, v44
	v_and_b32_e32 v45, 0xfffff800, v45
	s_waitcnt vmcnt(3)
	v_or_b32_e32 v108, s39, v147
	v_add_u32_e32 v45, 0xffffc800, v45
	v_cmp_lt_i32_e32 vcc, s13, v44
	v_ashrrev_i32_e32 v109, 31, v108
	v_lshlrev_b64 v[104:105], 2, v[108:109]
	v_cndmask_b32_e32 v128, 0, v45, vcc
	v_lshl_add_u64 v[46:47], v[128:129], 2, s[0:1]
	v_lshl_add_u64 v[110:111], v[46:47], 0, v[104:105]
	s_waitcnt lgkmcnt(0)
	s_barrier
	global_load_dword v112, v[110:111], off offset:2048
	v_readlane_b32 s42, v254, 41
	s_mul_hi_i32 s3, s28, 0x2aaaaaab
	v_readlane_b32 s43, v254, 42
	s_lshr_b32 s39, s3, 31
	s_ashr_i32 s3, s3, 3
	v_mov_b64_e32 v[46:47], s[42:43]
	s_movk_i32 s16, 0x5000
	v_mad_i64_i32 v[46:47], s[24:25], v108, s16, v[46:47]
	s_add_i32 s3, s3, s39
	s_mul_i32 s24, s3, 48
	s_sub_i32 s24, s28, s24
	v_ashrrev_i32_e32 v45, 31, v44
	s_ashr_i32 s39, s24, 2
	v_lshlrev_b64 v[114:115], 1, v[44:45]
	v_lshl_add_u32 v44, s39, 7, v130
	v_ashrrev_i32_e32 v45, 31, v44
	v_lshlrev_b64 v[44:45], 11, v[44:45]
	v_lshl_add_u64 v[48:49], v[134:135], 0, v[44:45]
	s_lshl_b32 s3, s3, 2
	s_and_b32 s25, s24, 3
	v_add_co_u32_e32 v72, vcc, s11, v48
	s_or_b32 s40, s25, s3
	s_nop 0
	v_addc_co_u32_e32 v73, vcc, 0, v49, vcc
	v_lshl_add_u64 v[106:107], v[46:47], 0, v[114:115]
	v_lshl_add_u32 v46, s40, 7, v130
	v_add_co_u32_e32 v52, vcc, s33, v48
	ds_read_b128 v[100:103], v148
	ds_read_b128 v[96:99], v150
	v_ashrrev_i32_e32 v47, 31, v46
	v_addc_co_u32_e32 v53, vcc, 0, v49, vcc
	v_lshlrev_b64 v[46:47], 11, v[46:47]
	v_add_co_u32_e32 v54, vcc, s59, v48
	v_lshl_add_u64 v[44:45], v[132:133], 0, v[46:47]
	s_nop 0
	v_addc_co_u32_e32 v55, vcc, 0, v49, vcc
	v_add_co_u32_e32 v56, vcc, s11, v44
	s_mov_b64 s[24:25], 0x50000
	s_nop 0
	v_addc_co_u32_e32 v57, vcc, 0, v45, vcc
	v_add_co_u32_e32 v58, vcc, s33, v44
	s_cmp_eq_u32 s29, s38
	s_nop 0
	v_addc_co_u32_e32 v59, vcc, 0, v45, vcc
	v_add_co_u32_e32 v60, vcc, s59, v44
	s_movk_i32 s89, 0xff
	s_nop 0
	v_addc_co_u32_e32 v61, vcc, 0, v45, vcc
	global_load_dwordx4 v[44:47], v[44:45], off
	s_nop 0
	global_load_dwordx4 v[48:51], v[48:49], off
	s_nop 0
	global_load_dwordx4 v[68:71], v[52:53], off
	global_load_dwordx4 v[76:79], v[54:55], off
	s_nop 0
	global_load_dwordx4 v[52:55], v[56:57], off
	s_nop 0
	global_load_dwordx4 v[56:59], v[58:59], off
	s_nop 0
	global_load_dwordx4 v[60:63], v[60:61], off
	s_nop 0
	global_load_dwordx4 v[72:75], v[72:73], off
	s_waitcnt vmcnt(8) lgkmcnt(1)
	v_pk_fma_f32 v[92:93], v[92:93], v[100:101], v[112:113] op_sel_hi:[1,1,0]
	v_pk_fma_f32 v[94:95], v[94:95], v[102:103], v[112:113] op_sel_hi:[1,1,0]
	v_and_b32_sdwa v116, v93, v170 dst_sel:DWORD dst_unused:UNUSED_PAD src0_sel:WORD_1 src1_sel:DWORD
	v_and_b32_sdwa v113, v95, v170 dst_sel:DWORD dst_unused:UNUSED_PAD src0_sel:WORD_1 src1_sel:DWORD
	v_and_b32_sdwa v109, v94, v170 dst_sel:DWORD dst_unused:UNUSED_PAD src0_sel:WORD_1 src1_sel:DWORD
	v_and_b32_sdwa v112, v92, v170 dst_sel:DWORD dst_unused:UNUSED_PAD src0_sel:WORD_1 src1_sel:DWORD
	v_add3_u32 v95, v95, v113, s56
	v_add3_u32 v93, v93, v116, s56
	v_add3_u32 v92, v92, v112, s56
	v_add3_u32 v94, v94, v109, s56
	v_and_b32_e32 v95, 0xffff0000, v95
	v_and_b32_e32 v109, 0xffff0000, v93
	v_or_b32_sdwa v93, v95, v94 dst_sel:DWORD dst_unused:UNUSED_PAD src0_sel:DWORD src1_sel:WORD_1
	v_or_b32_sdwa v92, v109, v92 dst_sel:DWORD dst_unused:UNUSED_PAD src0_sel:DWORD src1_sel:WORD_1
	global_store_dwordx2 v[106:107], v[92:93], off
	global_load_dword v94, v[110:111], off offset:2112
	v_mul_lo_u32 v92, v108, s16
	v_ashrrev_i32_e32 v93, 31, v92
	v_lshl_add_u64 v[108:109], s[42:43], 0, v[92:93]
	v_lshl_add_u64 v[92:93], v[108:109], 0, s[24:25]
	v_lshl_add_u64 v[112:113], v[92:93], 0, v[114:115]
	s_mov_b64 s[24:25], 0xa0000
	s_waitcnt vmcnt(0)
	v_pk_fma_f32 v[88:89], v[88:89], v[100:101], v[94:95] op_sel_hi:[1,1,0]
	v_pk_fma_f32 v[90:91], v[90:91], v[102:103], v[94:95] op_sel_hi:[1,1,0]
	v_and_b32_sdwa v117, v89, v170 dst_sel:DWORD dst_unused:UNUSED_PAD src0_sel:WORD_1 src1_sel:DWORD
	v_and_b32_sdwa v116, v91, v170 dst_sel:DWORD dst_unused:UNUSED_PAD src0_sel:WORD_1 src1_sel:DWORD
	v_and_b32_sdwa v94, v90, v170 dst_sel:DWORD dst_unused:UNUSED_PAD src0_sel:WORD_1 src1_sel:DWORD
	v_and_b32_sdwa v95, v88, v170 dst_sel:DWORD dst_unused:UNUSED_PAD src0_sel:WORD_1 src1_sel:DWORD
	v_add3_u32 v91, v91, v116, s56
	v_add3_u32 v89, v89, v117, s56
	v_add3_u32 v88, v88, v95, s56
	v_add3_u32 v90, v90, v94, s56
	v_and_b32_e32 v91, 0xffff0000, v91
	v_and_b32_e32 v94, 0xffff0000, v89
	v_or_b32_sdwa v89, v91, v90 dst_sel:DWORD dst_unused:UNUSED_PAD src0_sel:DWORD src1_sel:WORD_1
	v_or_b32_sdwa v88, v94, v88 dst_sel:DWORD dst_unused:UNUSED_PAD src0_sel:DWORD src1_sel:WORD_1
	global_store_dwordx2 v[112:113], v[88:89], off
	global_load_dword v90, v[110:111], off offset:2176
	v_lshl_add_u64 v[88:89], v[108:109], 0, s[24:25]
	v_lshl_add_u64 v[94:95], v[88:89], 0, v[114:115]
	s_mov_b64 s[24:25], 0xf0000
	s_waitcnt vmcnt(0)
	v_pk_fma_f32 v[84:85], v[84:85], v[100:101], v[90:91] op_sel_hi:[1,1,0]
	v_pk_fma_f32 v[86:87], v[86:87], v[102:103], v[90:91] op_sel_hi:[1,1,0]
	v_and_b32_sdwa v113, v85, v170 dst_sel:DWORD dst_unused:UNUSED_PAD src0_sel:WORD_1 src1_sel:DWORD
	v_and_b32_sdwa v91, v84, v170 dst_sel:DWORD dst_unused:UNUSED_PAD src0_sel:WORD_1 src1_sel:DWORD
	v_add3_u32 v85, v85, v113, s56
	v_add3_u32 v84, v84, v91, s56
	v_and_b32_e32 v90, 0xffff0000, v85
	v_cvt_pk_bf16_f32 v85, v86, v87
	v_or_b32_sdwa v84, v90, v84 dst_sel:DWORD dst_unused:UNUSED_PAD src0_sel:DWORD src1_sel:WORD_1
	global_store_dwordx2 v[94:95], v[84:85], off
	global_load_dword v86, v[110:111], off offset:2240
	v_add_u32_e32 v90, s2, v149
	v_lshlrev_b32_e32 v84, 1, v90
	v_and_b32_e32 v84, 0xfffff800, v84
	v_add_u32_e32 v87, 0xffffc800, v84
	v_cmp_lt_i32_e32 vcc, s13, v90
	v_lshl_add_u64 v[84:85], v[108:109], 0, s[24:25]
	v_lshl_add_u64 v[94:95], v[84:85], 0, v[114:115]
	v_cndmask_b32_e32 v128, 0, v87, vcc
	v_lshl_add_u64 v[108:109], v[128:129], 2, s[0:1]
	v_lshl_add_u64 v[108:109], v[108:109], 0, v[104:105]
	s_waitcnt vmcnt(0)
	v_pk_fma_f32 v[80:81], v[80:81], v[100:101], v[86:87] op_sel_hi:[1,1,0]
	v_pk_fma_f32 v[82:83], v[82:83], v[102:103], v[86:87] op_sel_hi:[1,1,0]
	v_and_b32_sdwa v100, v81, v170 dst_sel:DWORD dst_unused:UNUSED_PAD src0_sel:WORD_1 src1_sel:DWORD
	v_and_b32_sdwa v87, v80, v170 dst_sel:DWORD dst_unused:UNUSED_PAD src0_sel:WORD_1 src1_sel:DWORD
	v_add3_u32 v81, v81, v100, s56
	v_add3_u32 v80, v80, v87, s56
	v_and_b32_e32 v86, 0xffff0000, v81
	v_cvt_pk_bf16_f32 v81, v82, v83
	v_or_b32_sdwa v80, v86, v80 dst_sel:DWORD dst_unused:UNUSED_PAD src0_sel:DWORD src1_sel:WORD_1
	global_store_dwordx2 v[94:95], v[80:81], off
	global_load_dword v80, v[108:109], off offset:2048
	v_ashrrev_i32_e32 v91, 31, v90
	s_waitcnt vmcnt(0) lgkmcnt(0)
	v_pk_fma_f32 v[66:67], v[66:67], v[98:99], v[80:81] op_sel_hi:[1,1,0]
	v_pk_fma_f32 v[64:65], v[64:65], v[96:97], v[80:81] op_sel_hi:[1,1,0]
	v_and_b32_sdwa v83, v65, v170 dst_sel:DWORD dst_unused:UNUSED_PAD src0_sel:WORD_1 src1_sel:DWORD
	v_and_b32_sdwa v81, v64, v170 dst_sel:DWORD dst_unused:UNUSED_PAD src0_sel:WORD_1 src1_sel:DWORD
	v_add3_u32 v65, v65, v83, s56
	v_add3_u32 v64, v64, v81, s56
	v_and_b32_e32 v80, 0xffff0000, v65
	v_cvt_pk_bf16_f32 v65, v66, v67
	v_or_b32_sdwa v64, v80, v64 dst_sel:DWORD dst_unused:UNUSED_PAD src0_sel:DWORD src1_sel:WORD_1
	global_store_dwordx2 v[106:107], v[64:65], off offset:32
	global_load_dword v64, v[108:109], off offset:2112
	v_lshlrev_b64 v[66:67], 1, v[90:91]
	v_lshl_add_u64 v[80:81], v[92:93], 0, v[66:67]
	s_waitcnt vmcnt(0)
	v_pk_fma_f32 v[40:41], v[40:41], v[96:97], v[64:65] op_sel_hi:[1,1,0]
	v_pk_fma_f32 v[42:43], v[42:43], v[98:99], v[64:65] op_sel_hi:[1,1,0]
	v_and_b32_sdwa v83, v41, v170 dst_sel:DWORD dst_unused:UNUSED_PAD src0_sel:WORD_1 src1_sel:DWORD
	v_and_b32_sdwa v65, v40, v170 dst_sel:DWORD dst_unused:UNUSED_PAD src0_sel:WORD_1 src1_sel:DWORD
	v_add3_u32 v41, v41, v83, s56
	v_add3_u32 v40, v40, v65, s56
	v_and_b32_e32 v64, 0xffff0000, v41
	v_cvt_pk_bf16_f32 v41, v42, v43
	v_or_b32_sdwa v40, v64, v40 dst_sel:DWORD dst_unused:UNUSED_PAD src0_sel:DWORD src1_sel:WORD_1
	global_store_dwordx2 v[80:81], v[40:41], off
	global_load_dword v40, v[108:109], off offset:2176
	v_lshl_add_u64 v[42:43], v[88:89], 0, v[66:67]
	s_waitcnt vmcnt(0)
	v_pk_fma_f32 v[36:37], v[36:37], v[96:97], v[40:41] op_sel_hi:[1,1,0]
	v_pk_fma_f32 v[38:39], v[38:39], v[98:99], v[40:41] op_sel_hi:[1,1,0]
	v_and_b32_sdwa v65, v37, v170 dst_sel:DWORD dst_unused:UNUSED_PAD src0_sel:WORD_1 src1_sel:DWORD
	v_and_b32_sdwa v41, v36, v170 dst_sel:DWORD dst_unused:UNUSED_PAD src0_sel:WORD_1 src1_sel:DWORD
	v_add3_u32 v37, v37, v65, s56
	v_add3_u32 v36, v36, v41, s56
	v_and_b32_e32 v40, 0xffff0000, v37
	v_cvt_pk_bf16_f32 v37, v38, v39
	v_or_b32_sdwa v36, v40, v36 dst_sel:DWORD dst_unused:UNUSED_PAD src0_sel:DWORD src1_sel:WORD_1
	global_store_dwordx2 v[42:43], v[36:37], off
	global_load_dword v36, v[108:109], off offset:2240
	v_add_u32_e32 v40, s2, v151
	v_lshlrev_b32_e32 v37, 1, v40
	v_and_b32_e32 v37, 0xfffff800, v37
	v_add_u32_e32 v37, 0xffffc800, v37
	v_cmp_lt_i32_e32 vcc, s13, v40
	v_lshl_add_u64 v[38:39], v[84:85], 0, v[66:67]
	s_waitcnt vmcnt(0)
	v_pk_fma_f32 v[32:33], v[32:33], v[96:97], v[36:37] op_sel_hi:[1,1,0]
	v_pk_fma_f32 v[34:35], v[34:35], v[98:99], v[36:37] op_sel_hi:[1,1,0]
	v_and_b32_sdwa v64, v33, v170 dst_sel:DWORD dst_unused:UNUSED_PAD src0_sel:WORD_1 src1_sel:DWORD
	v_cndmask_b32_e32 v128, 0, v37, vcc
	v_and_b32_sdwa v37, v32, v170 dst_sel:DWORD dst_unused:UNUSED_PAD src0_sel:WORD_1 src1_sel:DWORD
	v_add3_u32 v33, v33, v64, s56
	v_add3_u32 v32, v32, v37, s56
	v_and_b32_e32 v36, 0xffff0000, v33
	v_lshl_add_u64 v[42:43], v[128:129], 2, s[0:1]
	v_cvt_pk_bf16_f32 v33, v34, v35
	v_or_b32_sdwa v32, v36, v32 dst_sel:DWORD dst_unused:UNUSED_PAD src0_sel:DWORD src1_sel:WORD_1
	v_lshl_add_u64 v[42:43], v[42:43], 0, v[104:105]
	global_store_dwordx2 v[38:39], v[32:33], off
	global_load_dword v64, v[42:43], off offset:2048
	ds_read_b128 v[36:39], v152
	ds_read_b128 v[32:35], v154
	s_waitcnt vmcnt(0) lgkmcnt(1)
	v_pk_fma_f32 v[30:31], v[30:31], v[38:39], v[64:65] op_sel_hi:[1,1,0]
	v_pk_fma_f32 v[28:29], v[28:29], v[36:37], v[64:65] op_sel_hi:[1,1,0]
	v_and_b32_sdwa v66, v29, v170 dst_sel:DWORD dst_unused:UNUSED_PAD src0_sel:WORD_1 src1_sel:DWORD
	v_and_b32_sdwa v64, v28, v170 dst_sel:DWORD dst_unused:UNUSED_PAD src0_sel:WORD_1 src1_sel:DWORD
	v_add3_u32 v29, v29, v66, s56
	v_add3_u32 v28, v28, v64, s56
	v_and_b32_e32 v41, 0xffff0000, v29
	v_cvt_pk_bf16_f32 v29, v30, v31
	v_or_b32_sdwa v28, v41, v28 dst_sel:DWORD dst_unused:UNUSED_PAD src0_sel:DWORD src1_sel:WORD_1
	global_store_dwordx2 v[106:107], v[28:29], off offset:64
	global_load_dword v28, v[42:43], off offset:2112
	v_ashrrev_i32_e32 v41, 31, v40
	v_lshlrev_b64 v[30:31], 1, v[40:41]
	v_lshl_add_u64 v[40:41], v[92:93], 0, v[30:31]
	s_waitcnt vmcnt(0)
	v_pk_fma_f32 v[24:25], v[24:25], v[36:37], v[28:29] op_sel_hi:[1,1,0]
	v_pk_fma_f32 v[26:27], v[26:27], v[38:39], v[28:29] op_sel_hi:[1,1,0]
	v_and_b32_sdwa v65, v25, v170 dst_sel:DWORD dst_unused:UNUSED_PAD src0_sel:WORD_1 src1_sel:DWORD
	v_and_b32_sdwa v29, v24, v170 dst_sel:DWORD dst_unused:UNUSED_PAD src0_sel:WORD_1 src1_sel:DWORD
	v_add3_u32 v25, v25, v65, s56
	v_add3_u32 v24, v24, v29, s56
	v_and_b32_e32 v28, 0xffff0000, v25
	v_cvt_pk_bf16_f32 v25, v26, v27
	v_or_b32_sdwa v24, v28, v24 dst_sel:DWORD dst_unused:UNUSED_PAD src0_sel:DWORD src1_sel:WORD_1
	global_store_dwordx2 v[40:41], v[24:25], off
	global_load_dword v24, v[42:43], off offset:2176
	v_lshl_add_u64 v[26:27], v[88:89], 0, v[30:31]
	s_waitcnt vmcnt(0)
	v_pk_fma_f32 v[20:21], v[20:21], v[36:37], v[24:25] op_sel_hi:[1,1,0]
	v_pk_fma_f32 v[22:23], v[22:23], v[38:39], v[24:25] op_sel_hi:[1,1,0]
	v_and_b32_sdwa v29, v21, v170 dst_sel:DWORD dst_unused:UNUSED_PAD src0_sel:WORD_1 src1_sel:DWORD
	v_and_b32_sdwa v25, v20, v170 dst_sel:DWORD dst_unused:UNUSED_PAD src0_sel:WORD_1 src1_sel:DWORD
	v_add3_u32 v21, v21, v29, s56
	v_add3_u32 v20, v20, v25, s56
	v_and_b32_e32 v24, 0xffff0000, v21
	v_cvt_pk_bf16_f32 v21, v22, v23
	v_or_b32_sdwa v20, v24, v20 dst_sel:DWORD dst_unused:UNUSED_PAD src0_sel:DWORD src1_sel:WORD_1
	global_store_dwordx2 v[26:27], v[20:21], off
	global_load_dword v20, v[42:43], off offset:2240
	v_add_u32_e32 v22, s2, v153
	v_lshlrev_b32_e32 v21, 1, v22
	v_and_b32_e32 v21, 0xfffff800, v21
	v_add_u32_e32 v21, 0xffffc800, v21
	v_cmp_lt_i32_e32 vcc, s13, v22
	v_lshl_add_u64 v[24:25], v[84:85], 0, v[30:31]
	s_waitcnt vmcnt(0)
	v_pk_fma_f32 v[16:17], v[16:17], v[36:37], v[20:21] op_sel_hi:[1,1,0]
	v_pk_fma_f32 v[18:19], v[18:19], v[38:39], v[20:21] op_sel_hi:[1,1,0]
	v_and_b32_sdwa v28, v17, v170 dst_sel:DWORD dst_unused:UNUSED_PAD src0_sel:WORD_1 src1_sel:DWORD
	v_cndmask_b32_e32 v128, 0, v21, vcc
	v_and_b32_sdwa v21, v16, v170 dst_sel:DWORD dst_unused:UNUSED_PAD src0_sel:WORD_1 src1_sel:DWORD
	v_add3_u32 v17, v17, v28, s56
	v_add3_u32 v16, v16, v21, s56
	v_and_b32_e32 v20, 0xffff0000, v17
	v_lshl_add_u64 v[26:27], v[128:129], 2, s[0:1]
	v_cvt_pk_bf16_f32 v17, v18, v19
	v_or_b32_sdwa v16, v20, v16 dst_sel:DWORD dst_unused:UNUSED_PAD src0_sel:DWORD src1_sel:WORD_1
	v_lshl_add_u64 v[26:27], v[26:27], 0, v[104:105]
	global_store_dwordx2 v[24:25], v[16:17], off
	global_load_dword v16, v[26:27], off offset:2048
	v_ashrrev_i32_e32 v23, 31, v22
	s_waitcnt vmcnt(0) lgkmcnt(0)
	v_pk_fma_f32 v[14:15], v[14:15], v[34:35], v[16:17] op_sel_hi:[1,1,0]
	v_pk_fma_f32 v[12:13], v[12:13], v[32:33], v[16:17] op_sel_hi:[1,1,0]
	v_and_b32_sdwa v19, v13, v170 dst_sel:DWORD dst_unused:UNUSED_PAD src0_sel:WORD_1 src1_sel:DWORD
	v_and_b32_sdwa v17, v12, v170 dst_sel:DWORD dst_unused:UNUSED_PAD src0_sel:WORD_1 src1_sel:DWORD
	v_add3_u32 v13, v13, v19, s56
	v_add3_u32 v12, v12, v17, s56
	v_and_b32_e32 v16, 0xffff0000, v13
	v_cvt_pk_bf16_f32 v13, v14, v15
	v_or_b32_sdwa v12, v16, v12 dst_sel:DWORD dst_unused:UNUSED_PAD src0_sel:DWORD src1_sel:WORD_1
	global_store_dwordx2 v[106:107], v[12:13], off offset:96
	global_load_dword v12, v[26:27], off offset:2112
	v_lshlrev_b64 v[14:15], 1, v[22:23]
	v_lshl_add_u64 v[16:17], v[92:93], 0, v[14:15]
	s_waitcnt vmcnt(0)
	v_pk_fma_f32 v[8:9], v[8:9], v[32:33], v[12:13] op_sel_hi:[1,1,0]
	v_pk_fma_f32 v[10:11], v[10:11], v[34:35], v[12:13] op_sel_hi:[1,1,0]
	v_and_b32_sdwa v19, v9, v170 dst_sel:DWORD dst_unused:UNUSED_PAD src0_sel:WORD_1 src1_sel:DWORD
	v_and_b32_sdwa v13, v8, v170 dst_sel:DWORD dst_unused:UNUSED_PAD src0_sel:WORD_1 src1_sel:DWORD
	v_add3_u32 v9, v9, v19, s56
	v_add3_u32 v8, v8, v13, s56
	v_and_b32_e32 v12, 0xffff0000, v9
	v_cvt_pk_bf16_f32 v9, v10, v11
	v_or_b32_sdwa v8, v12, v8 dst_sel:DWORD dst_unused:UNUSED_PAD src0_sel:DWORD src1_sel:WORD_1
	global_store_dwordx2 v[16:17], v[8:9], off
	global_load_dword v8, v[26:27], off offset:2176
	v_lshl_add_u64 v[10:11], v[88:89], 0, v[14:15]
	s_waitcnt vmcnt(0)
	v_pk_fma_f32 v[4:5], v[4:5], v[32:33], v[8:9] op_sel_hi:[1,1,0]
	v_pk_fma_f32 v[6:7], v[6:7], v[34:35], v[8:9] op_sel_hi:[1,1,0]
	v_and_b32_sdwa v13, v5, v170 dst_sel:DWORD dst_unused:UNUSED_PAD src0_sel:WORD_1 src1_sel:DWORD
	v_and_b32_sdwa v9, v4, v170 dst_sel:DWORD dst_unused:UNUSED_PAD src0_sel:WORD_1 src1_sel:DWORD
	v_add3_u32 v5, v5, v13, s56
	v_add3_u32 v4, v4, v9, s56
	v_and_b32_e32 v8, 0xffff0000, v5
	v_cvt_pk_bf16_f32 v5, v6, v7
	v_or_b32_sdwa v4, v8, v4 dst_sel:DWORD dst_unused:UNUSED_PAD src0_sel:DWORD src1_sel:WORD_1
	global_store_dwordx2 v[10:11], v[4:5], off
	global_load_dword v4, v[26:27], off offset:2240
	v_lshl_add_u64 v[6:7], v[84:85], 0, v[14:15]
	s_waitcnt vmcnt(0)
	v_pk_fma_f32 v[0:1], v[0:1], v[32:33], v[4:5] op_sel_hi:[1,1,0]
	v_pk_fma_f32 v[2:3], v[2:3], v[34:35], v[4:5] op_sel_hi:[1,1,0]
	v_and_b32_sdwa v9, v1, v170 dst_sel:DWORD dst_unused:UNUSED_PAD src0_sel:WORD_1 src1_sel:DWORD
	v_and_b32_sdwa v5, v0, v170 dst_sel:DWORD dst_unused:UNUSED_PAD src0_sel:WORD_1 src1_sel:DWORD
	v_add3_u32 v1, v1, v9, s56
	v_add3_u32 v0, v0, v5, s56
	v_and_b32_e32 v4, 0xffff0000, v1
	v_cvt_pk_bf16_f32 v1, v2, v3
	v_or_b32_sdwa v0, v4, v0 dst_sel:DWORD dst_unused:UNUSED_PAD src0_sel:DWORD src1_sel:WORD_1
	global_store_dwordx2 v[6:7], v[0:1], off
	s_cbranch_scc1 .LBB0_375

.Ltail392:
	s_add_i32 s0, s1, 2
	v_add_u32_e32 v111, v104, v105
	ds_read_b128 v[136:139], v111 offset:16384
	ds_read_b128 v[140:143], v111 offset:18432
	ds_read_b128 v[144:147], v111 offset:20480
	ds_read_b128 v[148:151], v111 offset:22528
	v_add_u32_e32 v110, v103, v105
	ds_read_b128 v[116:119], v110
	s_add_i32 s1, s1, 4
	ds_read_b128 v[120:123], v110 offset:2048
	s_min_u32 s1, s1, 15
	v_add_u32_e32 v113, v104, v114
	s_lshl_b32 s92, s1, 7
	ds_read_b128 v[124:127], v110 offset:4096
	v_add_u32_e32 v112, v103, v114
	ds_read_b128 v[194:197], v113 offset:16384
	ds_read_b128 v[198:201], v113 offset:18432
	ds_read_b128 v[202:205], v113 offset:20480
	ds_read_b128 v[206:209], v113 offset:22528
	v_lshl_add_u64 v[164:165], v[98:99], 0, s[92:93]
	ds_read_b128 v[132:135], v110 offset:6144
	ds_read_b128 v[152:155], v112
	ds_read_b128 v[156:159], v112 offset:2048
	ds_read_b128 v[160:163], v112 offset:4096
	ds_read_b128 v[190:193], v112 offset:6144
	s_waitcnt lgkmcnt(11)
	v_mfma_f32_16x16x32_bf16 v[92:95], v[136:139], v[116:119], v[92:95]
	v_mfma_f32_16x16x32_bf16 v[88:91], v[140:143], v[116:119], v[88:91]
	v_mfma_f32_16x16x32_bf16 v[52:55], v[144:147], v[116:119], v[52:55]
	v_mfma_f32_16x16x32_bf16 v[48:51], v[148:151], v[116:119], v[48:51]
	s_waitcnt vmcnt(7)
	ds_write_b128 v109, v[56:59] offset:32768
	v_add_co_u32_e32 v56, vcc, s11, v164
	s_waitcnt lgkmcnt(11)
	v_mfma_f32_16x16x32_bf16 v[44:47], v[136:139], v[120:123], v[44:47]
	v_addc_co_u32_e32 v57, vcc, 0, v165, vcc
	v_mfma_f32_16x16x32_bf16 v[40:43], v[140:143], v[120:123], v[40:43]
	v_mfma_f32_16x16x32_bf16 v[36:39], v[144:147], v[120:123], v[36:39]
	v_mfma_f32_16x16x32_bf16 v[32:35], v[148:151], v[120:123], v[32:35]
	v_add_co_u32_e32 v56, vcc, s33, v164
	s_waitcnt vmcnt(6)
	ds_write_b128 v109, v[60:63] offset:36864
	s_nop 0
	v_addc_co_u32_e32 v57, vcc, 0, v165, vcc
	s_waitcnt lgkmcnt(11)
	v_mfma_f32_16x16x32_bf16 v[28:31], v[136:139], v[124:127], v[28:31]
	v_mfma_f32_16x16x32_bf16 v[24:27], v[140:143], v[124:127], v[24:27]
	v_mfma_f32_16x16x32_bf16 v[20:23], v[144:147], v[124:127], v[20:23]
	v_mfma_f32_16x16x32_bf16 v[16:19], v[148:151], v[124:127], v[16:19]
	v_add_co_u32_e32 v56, vcc, s59, v164
	s_waitcnt vmcnt(5)
	ds_write_b128 v109, v[64:67] offset:40960
	s_nop 0
	v_addc_co_u32_e32 v57, vcc, 0, v165, vcc
	v_lshl_add_u64 v[64:65], v[100:101], 0, s[92:93]
	v_add_co_u32_e32 v66, vcc, s11, v64
	s_waitcnt lgkmcnt(7)
	v_mfma_f32_16x16x32_bf16 v[12:15], v[136:139], v[132:135], v[12:15]
	v_addc_co_u32_e32 v67, vcc, 0, v65, vcc
	v_mfma_f32_16x16x32_bf16 v[8:11], v[140:143], v[132:135], v[8:11]
	v_mfma_f32_16x16x32_bf16 v[4:7], v[144:147], v[132:135], v[4:7]
	v_mfma_f32_16x16x32_bf16 v[0:3], v[148:151], v[132:135], v[0:3]
	s_waitcnt vmcnt(4)
	ds_write_b128 v109, v[72:75] offset:45056
	s_waitcnt lgkmcnt(7)
	v_mfma_f32_16x16x32_bf16 v[56:59], v[194:197], v[152:155], v[92:95]
	v_mfma_f32_16x16x32_bf16 v[60:63], v[198:201], v[152:155], v[88:91]
	v_mfma_f32_16x16x32_bf16 v[52:55], v[202:205], v[152:155], v[52:55]
	v_mfma_f32_16x16x32_bf16 v[48:51], v[206:209], v[152:155], v[48:51]
	s_waitcnt vmcnt(3)
	ds_write_b128 v109, v[68:71] offset:49152
	s_waitcnt lgkmcnt(7)
	v_mfma_f32_16x16x32_bf16 v[44:47], v[194:197], v[156:159], v[44:47]
	v_mfma_f32_16x16x32_bf16 v[40:43], v[198:201], v[156:159], v[40:43]
	v_mfma_f32_16x16x32_bf16 v[36:39], v[202:205], v[156:159], v[36:39]
	v_mfma_f32_16x16x32_bf16 v[32:35], v[206:209], v[156:159], v[32:35]
	v_add_co_u32_e32 v66, vcc, s33, v64
	s_waitcnt vmcnt(2)
	ds_write_b128 v109, v[76:79] offset:53248
	v_addc_co_u32_e32 v67, vcc, 0, v65, vcc
	v_add_co_u32_e32 v64, vcc, s59, v64
	s_waitcnt lgkmcnt(7)
	v_mfma_f32_16x16x32_bf16 v[28:31], v[194:197], v[160:163], v[28:31]
	v_addc_co_u32_e32 v65, vcc, 0, v65, vcc
	v_mfma_f32_16x16x32_bf16 v[24:27], v[198:201], v[160:163], v[24:27]
	v_mfma_f32_16x16x32_bf16 v[20:23], v[202:205], v[160:163], v[20:23]
	v_mfma_f32_16x16x32_bf16 v[16:19], v[206:209], v[160:163], v[16:19]
	s_waitcnt vmcnt(1)
	ds_write_b128 v109, v[80:83] offset:57344
	s_waitcnt lgkmcnt(7)
	v_mfma_f32_16x16x32_bf16 v[12:15], v[194:197], v[190:193], v[12:15]
	v_mfma_f32_16x16x32_bf16 v[8:11], v[198:201], v[190:193], v[8:11]
	v_mfma_f32_16x16x32_bf16 v[4:7], v[202:205], v[190:193], v[4:7]
	v_mfma_f32_16x16x32_bf16 v[0:3], v[206:209], v[190:193], v[0:3]
	s_waitcnt vmcnt(0)
	ds_write_b128 v109, v[84:87] offset:61440
	s_waitcnt lgkmcnt(0)
	s_barrier
	ds_read_b128 v[84:87], v111 offset:51200
	ds_read_b128 v[80:83], v111 offset:49152
	ds_read_b128 v[88:91], v111 offset:53248
	ds_read_b128 v[92:95], v111 offset:55296
	ds_read_b128 v[64:67], v110 offset:32768
	s_min_u32 s1, s0, 12
	s_lshl_b32 s92, s1, 7
	ds_read_b128 v[68:71], v110 offset:34816
	v_lshl_add_u64 v[164:165], v[98:99], 0, s[92:93]
	ds_read_b128 v[72:75], v110 offset:36864
	ds_read_b128 v[76:79], v110 offset:38912
	ds_read_b128 v[152:155], v112 offset:32768
	ds_read_b128 v[156:159], v112 offset:34816
	ds_read_b128 v[160:163], v112 offset:36864
	ds_read_b128 v[190:193], v112 offset:38912
	ds_read_b128 v[194:197], v113 offset:49152
	ds_read_b128 v[198:201], v113 offset:51200
	ds_read_b128 v[202:205], v113 offset:53248
	ds_read_b128 v[206:209], v113 offset:55296
	s_waitcnt lgkmcnt(11)
	v_mfma_f32_16x16x32_bf16 v[214:217], v[84:87], v[64:67], v[60:63]
	v_mfma_f32_16x16x32_bf16 v[210:213], v[80:83], v[64:67], v[56:59]
	s_nop 1
	v_add_co_u32_e32 v60, vcc, s11, v164
	s_nop 1
	v_addc_co_u32_e32 v61, vcc, 0, v165, vcc
	v_mfma_f32_16x16x32_bf16 v[52:55], v[88:91], v[64:67], v[52:55]
	v_mfma_f32_16x16x32_bf16 v[48:51], v[92:95], v[64:67], v[48:51]
	v_add_co_u32_e32 v64, vcc, s33, v164
	s_nop 0
	v_addc_co_u32_e32 v65, vcc, 0, v165, vcc
	s_waitcnt lgkmcnt(10)
	v_mfma_f32_16x16x32_bf16 v[44:47], v[80:83], v[68:71], v[44:47]
	v_mfma_f32_16x16x32_bf16 v[40:43], v[84:87], v[68:71], v[40:43]
	v_mfma_f32_16x16x32_bf16 v[36:39], v[88:91], v[68:71], v[36:39]
	v_mfma_f32_16x16x32_bf16 v[32:35], v[92:95], v[68:71], v[32:35]
	v_add_co_u32_e32 v68, vcc, s59, v164
	s_waitcnt lgkmcnt(9)
	v_mfma_f32_16x16x32_bf16 v[28:31], v[80:83], v[72:75], v[28:31]
	v_addc_co_u32_e32 v69, vcc, 0, v165, vcc
	v_mfma_f32_16x16x32_bf16 v[24:27], v[84:87], v[72:75], v[24:27]
	v_mfma_f32_16x16x32_bf16 v[20:23], v[88:91], v[72:75], v[20:23]
	v_mfma_f32_16x16x32_bf16 v[16:19], v[92:95], v[72:75], v[16:19]
	s_waitcnt lgkmcnt(8)
	v_mfma_f32_16x16x32_bf16 v[8:11], v[84:87], v[76:79], v[8:11]
	v_lshl_add_u64 v[84:85], v[100:101], 0, s[92:93]
	v_mfma_f32_16x16x32_bf16 v[12:15], v[80:83], v[76:79], v[12:15]
	v_mfma_f32_16x16x32_bf16 v[4:7], v[88:91], v[76:79], v[4:7]
	v_mfma_f32_16x16x32_bf16 v[0:3], v[92:95], v[76:79], v[0:3]
	v_add_co_u32_e32 v76, vcc, s11, v84
	s_nop 0
	v_addc_co_u32_e32 v77, vcc, 0, v85, vcc
	v_add_co_u32_e32 v80, vcc, s33, v84
	v_addc_co_u32_e32 v81, vcc, 0, v85, vcc
	s_waitcnt lgkmcnt(3)
	v_mfma_f32_16x16x32_bf16 v[92:95], v[194:197], v[152:155], v[210:213]
	s_waitcnt lgkmcnt(2)
	v_mfma_f32_16x16x32_bf16 v[88:91], v[198:201], v[152:155], v[214:217]
	s_waitcnt lgkmcnt(1)
	v_mfma_f32_16x16x32_bf16 v[52:55], v[202:205], v[152:155], v[52:55]
	s_waitcnt lgkmcnt(0)
	v_mfma_f32_16x16x32_bf16 v[48:51], v[206:209], v[152:155], v[48:51]
	v_add_co_u32_e32 v84, vcc, s59, v84
	v_addc_co_u32_e32 v85, vcc, 0, v85, vcc
	v_mfma_f32_16x16x32_bf16 v[44:47], v[194:197], v[156:159], v[44:47]
	v_mfma_f32_16x16x32_bf16 v[40:43], v[198:201], v[156:159], v[40:43]
	v_mfma_f32_16x16x32_bf16 v[36:39], v[202:205], v[156:159], v[36:39]
	v_mfma_f32_16x16x32_bf16 v[32:35], v[206:209], v[156:159], v[32:35]
	v_mfma_f32_16x16x32_bf16 v[28:31], v[194:197], v[160:163], v[28:31]
	v_mfma_f32_16x16x32_bf16 v[24:27], v[198:201], v[160:163], v[24:27]
	v_mfma_f32_16x16x32_bf16 v[20:23], v[202:205], v[160:163], v[20:23]
	v_mfma_f32_16x16x32_bf16 v[16:19], v[206:209], v[160:163], v[16:19]
	v_mfma_f32_16x16x32_bf16 v[12:15], v[194:197], v[190:193], v[12:15]
	v_mfma_f32_16x16x32_bf16 v[8:11], v[198:201], v[190:193], v[8:11]
	v_mfma_f32_16x16x32_bf16 v[4:7], v[202:205], v[190:193], v[4:7]
	v_mfma_f32_16x16x32_bf16 v[0:3], v[206:209], v[190:193], v[0:3]
	s_mov_b32 s1, s0
	s_waitcnt lgkmcnt(0)
	s_barrier
	s_mul_i32 s0, s69, 0x12000
	v_readlane_b32 s16, v250, 25
	s_add_u32 s24, s16, s0
	v_readlane_b32 s0, v251, 5
	v_lshlrev_b32_e32 v114, 6, v102
	v_readlane_b32 s17, v250, 26
	s_waitcnt vmcnt(5)
	v_add_u32_e32 v64, s0, v108
	v_readlane_b32 s0, v251, 6
	v_add_u32_e32 v56, 0xffffe000, v64
	v_or_b32_e32 v62, v64, v107
	v_or_b32_e32 v65, s0, v114
	v_lshrrev_b32_e32 v56, 10, v56
	s_movk_i32 s0, 0x1800
	v_mad_u32_u24 v56, v56, s0, s0
	v_cmp_lt_i32_e32 vcc, s13, v62
	s_addc_u32 s25, s17, 0
	v_lshlrev_b32_e32 v115, 2, v97
	v_cndmask_b32_e32 v56, 0, v56, vcc
	s_add_u32 s40, s24, 0x2000
	v_or_b32_e32 v58, v65, v115
	v_ashrrev_i32_e32 v57, 31, v56
	s_addc_u32 s41, s25, 0
	s_waitcnt vmcnt(4)
	v_lshlrev_b64 v[74:75], 2, v[56:57]
	v_ashrrev_i32_e32 v59, 31, v58
	v_ashrrev_i32_e32 v63, 31, v62
	v_lshl_add_u64 v[56:57], s[40:41], 0, v[74:75]
	v_lshlrev_b64 v[60:61], 2, v[58:59]
	v_readlane_b32 s0, v250, 15
	s_waitcnt vmcnt(1)
	v_lshl_add_u64 v[82:83], v[56:57], 0, v[60:61]
	v_lshlrev_b64 v[56:57], 12, v[62:63]
	v_readlane_b32 s1, v250, 16
	v_readlane_b32 s16, v250, 21
	v_lshlrev_b64 v[78:79], 11, v[62:63]
	v_lshl_add_u64 v[56:57], s[0:1], 0, v[56:57]
	s_waitcnt vmcnt(0)
	v_lshl_add_u64 v[84:85], v[56:57], 0, v[60:61]
	global_load_dwordx4 v[116:119], v[82:83], off
	global_load_dwordx4 v[120:123], v[82:83], off offset:64
	global_load_dwordx4 v[124:127], v[82:83], off offset:128
	global_load_dwordx4 v[132:135], v[82:83], off offset:192
	global_load_dwordx4 v[190:193], v[84:85], off
	global_load_dwordx4 v[194:197], v[84:85], off offset:64
	global_load_dwordx4 v[198:201], v[84:85], off offset:128
	global_load_dwordx4 v[202:205], v[84:85], off offset:192
	v_add_co_u32_e32 v164, vcc, 0x10000, v84
	s_nop 1
	v_addc_co_u32_e32 v165, vcc, 0, v85, vcc
	v_add_co_u32_e32 v222, vcc, 0x20000, v84
	s_nop 1
	v_addc_co_u32_e32 v223, vcc, 0, v85, vcc
	v_add_co_u32_e32 v224, vcc, 0x30000, v84
	s_nop 1
	v_addc_co_u32_e32 v225, vcc, 0, v85, vcc
	global_load_dwordx4 v[206:209], v[164:165], off
	global_load_dwordx4 v[210:213], v[164:165], off offset:64
	global_load_dwordx4 v[214:217], v[164:165], off offset:128
	global_load_dwordx4 v[218:221], v[164:165], off offset:192
	s_lshl_b32 s0, s69, 12
	v_readlane_b32 s68, v250, 41
	v_readlane_b32 s72, v250, 45
	v_readlane_b32 s73, v250, 46
	s_add_u32 s0, s72, s0
	s_addc_u32 s1, s73, 0
	s_add_u32 s42, s24, 0x4000
	s_addc_u32 s43, s25, 0
	v_lshl_add_u64 v[74:75], s[42:43], 0, v[74:75]
	v_lshl_add_u64 v[56:57], s[0:1], 0, v[60:61]
	v_lshl_add_u64 v[86:87], v[74:75], 0, v[60:61]
	v_readlane_b32 s17, v250, 22
	v_readlane_b32 s69, v250, 42
	v_readlane_b32 s69, v254, 49
	v_lshl_add_u64 v[78:79], s[16:17], 0, v[78:79]
	s_mul_i32 s24, s69, 0x140000
	s_add_u32 s24, s86, s24
	v_lshrrev_b32_e32 v65, 6, v65
	s_mov_b32 s16, 0xa000
	s_addc_u32 s25, s87, 0
	s_add_u32 s38, s24, 0xaf1a000
	s_addc_u32 s39, s25, 0
	v_cmp_eq_u32_e64 s[36:37], 0, v97
	v_readlane_b32 s70, v250, 43
	v_readlane_b32 s71, v250, 44
	v_readlane_b32 s74, v250, 47
	v_readlane_b32 s75, v250, 48
	v_readlane_b32 s76, v250, 49
	v_readlane_b32 s77, v250, 50
	v_readlane_b32 s78, v250, 51
	v_readlane_b32 s79, v250, 52
	v_readlane_b32 s80, v250, 53
	v_readlane_b32 s81, v250, 54
	v_readlane_b32 s82, v250, 55
	v_readlane_b32 s83, v250, 56
	s_waitcnt vmcnt(4)
	v_pk_fma_f32 v[68:69], v[94:95], v[118:119], v[192:193]
	v_pk_fma_f32 v[66:67], v[92:93], v[116:117], v[190:191]
	global_store_dwordx4 v[84:85], v[66:69], off
	global_load_dwordx4 v[136:139], v[56:57], off
	global_load_dwordx4 v[140:143], v[56:57], off offset:64
	global_load_dwordx4 v[144:147], v[56:57], off offset:128
	global_load_dwordx4 v[148:151], v[56:57], off offset:192
	global_load_dwordx4 v[152:155], v[86:87], off
	global_load_dwordx4 v[156:159], v[86:87], off offset:64
	global_load_dwordx4 v[160:163], v[86:87], off offset:128
	global_load_dwordx4 v[180:183], v[86:87], off offset:192
	v_lshl_add_u64 v[92:93], v[58:59], 1, v[78:79]
	s_waitcnt vmcnt(0)
	v_pk_mul_f32 v[72:73], v[68:69], v[138:139]
	v_pk_mul_f32 v[70:71], v[66:67], v[136:137]
	s_waitcnt vmcnt(0)
	v_pk_add_f32 v[76:77], v[154:155], 1.0 op_sel_hi:[1,0]
	v_pk_add_f32 v[74:75], v[152:153], 1.0 op_sel_hi:[1,0]
	v_pk_mul_f32 v[72:73], v[72:73], v[76:77]
	v_pk_mul_f32 v[70:71], v[70:71], v[74:75]
	v_and_b32_sdwa v77, v71, v170 dst_sel:DWORD dst_unused:UNUSED_PAD src0_sel:WORD_1 src1_sel:DWORD
	v_and_b32_sdwa v75, v70, v170 dst_sel:DWORD dst_unused:UNUSED_PAD src0_sel:WORD_1 src1_sel:DWORD
	v_add3_u32 v71, v71, v77, s56
	v_add3_u32 v70, v70, v75, s56
	v_and_b32_e32 v74, 0xffff0000, v71
	v_cvt_pk_bf16_f32 v71, v72, v73
	v_or_b32_sdwa v70, v74, v70 dst_sel:DWORD dst_unused:UNUSED_PAD src0_sel:DWORD src1_sel:WORD_1
	global_store_dwordx2 v[92:93], v[70:71], off
	s_nop 0
	s_waitcnt vmcnt(0)
	v_pk_fma_f32 v[72:73], v[90:91], v[122:123], v[196:197]
	v_pk_fma_f32 v[70:71], v[88:89], v[120:121], v[194:195]
	global_store_dwordx4 v[84:85], v[70:73], off offset:64
	v_pk_mul_f32 v[76:77], v[72:73], v[142:143]
	v_pk_mul_f32 v[74:75], v[70:71], v[140:141]
	v_pk_add_f32 v[80:81], v[158:159], 1.0 op_sel_hi:[1,0]
	v_pk_add_f32 v[78:79], v[156:157], 1.0 op_sel_hi:[1,0]
	v_pk_mul_f32 v[76:77], v[76:77], v[80:81]
	v_pk_mul_f32 v[74:75], v[74:75], v[78:79]
	v_and_b32_sdwa v81, v75, v170 dst_sel:DWORD dst_unused:UNUSED_PAD src0_sel:WORD_1 src1_sel:DWORD
	v_and_b32_sdwa v79, v74, v170 dst_sel:DWORD dst_unused:UNUSED_PAD src0_sel:WORD_1 src1_sel:DWORD
	v_add3_u32 v75, v75, v81, s56
	v_add3_u32 v74, v74, v79, s56
	v_and_b32_e32 v78, 0xffff0000, v75
	v_cvt_pk_bf16_f32 v75, v76, v77
	v_or_b32_sdwa v74, v78, v74 dst_sel:DWORD dst_unused:UNUSED_PAD src0_sel:DWORD src1_sel:WORD_1
	global_store_dwordx2 v[92:93], v[74:75], off offset:32
	s_nop 0
	v_pk_fma_f32 v[54:55], v[54:55], v[126:127], v[200:201]
	v_pk_fma_f32 v[52:53], v[52:53], v[124:125], v[198:199]
	global_store_dwordx4 v[84:85], v[52:55], off offset:128
	v_pk_mul_f32 v[76:77], v[54:55], v[146:147]
	v_pk_mul_f32 v[74:75], v[52:53], v[144:145]
	v_pk_add_f32 v[80:81], v[162:163], 1.0 op_sel_hi:[1,0]
	v_pk_add_f32 v[78:79], v[160:161], 1.0 op_sel_hi:[1,0]
	v_pk_mul_f32 v[76:77], v[76:77], v[80:81]
	v_pk_mul_f32 v[74:75], v[74:75], v[78:79]
	v_and_b32_sdwa v81, v75, v170 dst_sel:DWORD dst_unused:UNUSED_PAD src0_sel:WORD_1 src1_sel:DWORD
	v_and_b32_sdwa v79, v74, v170 dst_sel:DWORD dst_unused:UNUSED_PAD src0_sel:WORD_1 src1_sel:DWORD
	v_add3_u32 v75, v75, v81, s56
	v_add3_u32 v74, v74, v79, s56
	v_and_b32_e32 v78, 0xffff0000, v75
	v_cvt_pk_bf16_f32 v75, v76, v77
	v_or_b32_sdwa v74, v78, v74 dst_sel:DWORD dst_unused:UNUSED_PAD src0_sel:DWORD src1_sel:WORD_1
	global_store_dwordx2 v[92:93], v[74:75], off offset:64
	s_nop 0
	v_pk_fma_f32 v[76:77], v[50:51], v[134:135], v[204:205]
	v_pk_fma_f32 v[74:75], v[48:49], v[132:133], v[202:203]
	global_store_dwordx4 v[84:85], v[74:77], off offset:192
	s_nop 0
	v_mbcnt_lo_u32_b32 v48, -1, 0
	v_mbcnt_hi_u32_b32 v48, -1, v48
	v_and_b32_e32 v50, 64, v48
	v_xor_b32_e32 v49, 16, v48
	v_add_u32_e32 v50, 64, v50
	v_xor_b32_e32 v51, 32, v48
	v_cmp_lt_i32_e32 vcc, v49, v50
	s_nop 1
	v_cndmask_b32_e32 v49, v48, v49, vcc
	v_cmp_lt_i32_e32 vcc, v51, v50
	v_lshlrev_b32_e32 v105, 2, v49
	s_nop 0
	v_cndmask_b32_e32 v50, v48, v51, vcc
	v_lshlrev_b32_e32 v104, 2, v50
	v_mul_f32_e32 v50, v67, v67
	v_mul_f32_e32 v51, v71, v71
	v_fmac_f32_e32 v50, v66, v66
	v_fmac_f32_e32 v51, v70, v70
	v_fmac_f32_e32 v50, v68, v68
	v_fmac_f32_e32 v51, v72, v72
	v_fmac_f32_e32 v50, v69, v69
	v_fmac_f32_e32 v51, v73, v73
	v_add_f32_e32 v50, v50, v51
	v_mul_f32_e32 v51, v53, v53
	v_fmac_f32_e32 v51, v52, v52
	v_fmac_f32_e32 v51, v54, v54
	v_fmac_f32_e32 v51, v55, v55
	v_add_f32_e32 v50, v50, v51
	v_mul_f32_e32 v51, v75, v75
	v_fmac_f32_e32 v51, v74, v74
	v_fmac_f32_e32 v51, v76, v76
	v_fmac_f32_e32 v51, v77, v77
	v_add_f32_e32 v50, v50, v51
	ds_bpermute_b32 v51, v105, v50
	v_mul_lo_u32 v48, v65, s16
	v_ashrrev_i32_e32 v49, 31, v48
	v_lshl_add_u64 v[48:49], s[38:39], 0, v[48:49]
	v_lshl_add_u64 v[48:49], v[62:63], 2, v[48:49]
	s_waitcnt lgkmcnt(0)
	v_add_f32_e32 v50, v50, v51
	ds_bpermute_b32 v51, v104, v50
	v_pk_mul_f32 v[52:53], v[76:77], v[150:151]
	v_pk_mul_f32 v[54:55], v[74:75], v[148:149]
	v_pk_add_f32 v[66:67], v[182:183], 1.0 op_sel_hi:[1,0]
	v_pk_add_f32 v[68:69], v[180:181], 1.0 op_sel_hi:[1,0]
	v_pk_mul_f32 v[52:53], v[52:53], v[66:67]
	v_pk_mul_f32 v[54:55], v[54:55], v[68:69]
	v_cvt_pk_bf16_f32 v53, v52, v53
	v_cvt_pk_bf16_f32 v52, v54, v55
	global_store_dwordx2 v[92:93], v[52:53], off offset:96
	s_and_saveexec_b64 s[24:25], s[36:37]
	s_cbranch_execz .LBB0_395
	s_waitcnt lgkmcnt(0)
	v_add_f32_e32 v50, v50, v51
	global_store_dword v[48:49], v50, off

.LBB0_397:
	s_or_b64 exec, exec, s[24:25]
	v_add_u32_e32 v32, 0xffffe020, v64
	v_or_b32_e32 v40, 32, v62
	v_lshrrev_b32_e32 v32, 10, v32
	v_mad_u32_u24 v32, v32, s5, s5
	v_cmp_lt_i32_e32 vcc, s13, v40
	v_ashrrev_i32_e32 v41, 31, v40
	v_readlane_b32 s16, v250, 15
	v_cndmask_b32_e32 v32, 0, v32, vcc
	s_waitcnt lgkmcnt(0)
	v_ashrrev_i32_e32 v33, 31, v32
	v_lshlrev_b64 v[42:43], 2, v[32:33]
	v_lshl_add_u64 v[32:33], s[40:41], 0, v[42:43]
	v_lshl_add_u64 v[44:45], v[32:33], 0, v[60:61]
	v_lshlrev_b64 v[32:33], 12, v[40:41]
	v_readlane_b32 s17, v250, 16
	v_lshl_add_u64 v[42:43], s[42:43], 0, v[42:43]
	v_lshl_add_u64 v[42:43], v[42:43], 0, v[60:61]
	v_lshl_add_u64 v[32:33], s[16:17], 0, v[32:33]
	v_lshl_add_u64 v[46:47], v[32:33], 0, v[60:61]
	v_readlane_b32 s16, v250, 21
	v_lshlrev_b64 v[40:41], 11, v[40:41]
	v_readlane_b32 s17, v250, 22
	global_load_dwordx4 v[206:209], v[224:225], off
	global_load_dwordx4 v[210:213], v[224:225], off offset:64
	global_load_dwordx4 v[214:217], v[224:225], off offset:128
	global_load_dwordx4 v[218:221], v[224:225], off offset:192
	s_waitcnt vmcnt(12)
	v_pk_fma_f32 v[30:31], v[30:31], v[118:119], v[192:193]
	v_pk_fma_f32 v[28:29], v[28:29], v[116:117], v[190:191]
	global_store_dwordx4 v[46:47], v[28:31], off
	v_lshl_add_u64 v[40:41], s[16:17], 0, v[40:41]
	v_lshl_add_u64 v[50:51], v[58:59], 1, v[40:41]
	v_pk_mul_f32 v[34:35], v[30:31], v[138:139]
	v_pk_mul_f32 v[32:33], v[28:29], v[136:137]
	v_pk_add_f32 v[38:39], v[154:155], 1.0 op_sel_hi:[1,0]
	v_pk_add_f32 v[36:37], v[152:153], 1.0 op_sel_hi:[1,0]
	v_pk_mul_f32 v[34:35], v[34:35], v[38:39]
	v_pk_mul_f32 v[32:33], v[32:33], v[36:37]
	v_and_b32_sdwa v39, v33, v170 dst_sel:DWORD dst_unused:UNUSED_PAD src0_sel:WORD_1 src1_sel:DWORD
	v_and_b32_sdwa v37, v32, v170 dst_sel:DWORD dst_unused:UNUSED_PAD src0_sel:WORD_1 src1_sel:DWORD
	v_add3_u32 v33, v33, v39, s56
	v_add3_u32 v32, v32, v37, s56
	v_and_b32_e32 v36, 0xffff0000, v33
	v_cvt_pk_bf16_f32 v33, v34, v35
	v_or_b32_sdwa v32, v36, v32 dst_sel:DWORD dst_unused:UNUSED_PAD src0_sel:DWORD src1_sel:WORD_1
	global_store_dwordx2 v[50:51], v[32:33], off
	s_nop 0
	v_pk_fma_f32 v[26:27], v[26:27], v[122:123], v[196:197]
	v_pk_fma_f32 v[24:25], v[24:25], v[120:121], v[194:195]
	global_store_dwordx4 v[46:47], v[24:27], off offset:64
	v_pk_mul_f32 v[34:35], v[26:27], v[142:143]
	v_pk_mul_f32 v[32:33], v[24:25], v[140:141]
	v_pk_add_f32 v[38:39], v[158:159], 1.0 op_sel_hi:[1,0]
	v_pk_add_f32 v[36:37], v[156:157], 1.0 op_sel_hi:[1,0]
	v_pk_mul_f32 v[34:35], v[34:35], v[38:39]
	v_pk_mul_f32 v[32:33], v[32:33], v[36:37]
	v_and_b32_sdwa v39, v33, v170 dst_sel:DWORD dst_unused:UNUSED_PAD src0_sel:WORD_1 src1_sel:DWORD
	v_and_b32_sdwa v37, v32, v170 dst_sel:DWORD dst_unused:UNUSED_PAD src0_sel:WORD_1 src1_sel:DWORD
	v_add3_u32 v33, v33, v39, s56
	v_add3_u32 v32, v32, v37, s56
	v_and_b32_e32 v36, 0xffff0000, v33
	v_cvt_pk_bf16_f32 v33, v34, v35
	v_or_b32_sdwa v32, v36, v32 dst_sel:DWORD dst_unused:UNUSED_PAD src0_sel:DWORD src1_sel:WORD_1
	global_store_dwordx2 v[50:51], v[32:33], off offset:32
	s_nop 0
	v_pk_fma_f32 v[22:23], v[22:23], v[126:127], v[200:201]
	v_pk_fma_f32 v[20:21], v[20:21], v[124:125], v[198:199]
	global_store_dwordx4 v[46:47], v[20:23], off offset:128
	v_pk_mul_f32 v[34:35], v[22:23], v[146:147]
	v_pk_mul_f32 v[32:33], v[20:21], v[144:145]
	v_pk_add_f32 v[38:39], v[162:163], 1.0 op_sel_hi:[1,0]
	v_pk_add_f32 v[36:37], v[160:161], 1.0 op_sel_hi:[1,0]
	v_pk_mul_f32 v[34:35], v[34:35], v[38:39]
	v_pk_mul_f32 v[32:33], v[32:33], v[36:37]
	v_and_b32_sdwa v39, v33, v170 dst_sel:DWORD dst_unused:UNUSED_PAD src0_sel:WORD_1 src1_sel:DWORD
	v_and_b32_sdwa v37, v32, v170 dst_sel:DWORD dst_unused:UNUSED_PAD src0_sel:WORD_1 src1_sel:DWORD
	v_add3_u32 v33, v33, v39, s56
	v_add3_u32 v32, v32, v37, s56
	v_and_b32_e32 v36, 0xffff0000, v33
	v_cvt_pk_bf16_f32 v33, v34, v35
	v_or_b32_sdwa v32, v36, v32 dst_sel:DWORD dst_unused:UNUSED_PAD src0_sel:DWORD src1_sel:WORD_1
	global_store_dwordx2 v[50:51], v[32:33], off offset:64
	s_nop 0
	v_pk_fma_f32 v[34:35], v[18:19], v[134:135], v[204:205]
	v_pk_fma_f32 v[32:33], v[16:17], v[132:133], v[202:203]
	global_store_dwordx4 v[46:47], v[32:35], off offset:192
	s_nop 0
	v_mul_f32_e32 v16, v29, v29
	v_mul_f32_e32 v17, v25, v25
	v_fmac_f32_e32 v16, v28, v28
	v_fmac_f32_e32 v17, v24, v24
	v_fmac_f32_e32 v16, v30, v30
	v_fmac_f32_e32 v17, v26, v26
	v_fmac_f32_e32 v16, v31, v31
	v_fmac_f32_e32 v17, v27, v27
	v_add_f32_e32 v16, v16, v17
	v_mul_f32_e32 v17, v21, v21
	v_fmac_f32_e32 v17, v20, v20
	v_fmac_f32_e32 v17, v22, v22
	v_fmac_f32_e32 v17, v23, v23
	v_add_f32_e32 v16, v16, v17
	v_mul_f32_e32 v17, v33, v33
	v_fmac_f32_e32 v17, v32, v32
	v_fmac_f32_e32 v17, v34, v34
	v_fmac_f32_e32 v17, v35, v35
	v_add_f32_e32 v16, v16, v17
	ds_bpermute_b32 v17, v105, v16
	s_waitcnt lgkmcnt(0)
	v_add_f32_e32 v16, v16, v17
	ds_bpermute_b32 v17, v104, v16
	v_pk_mul_f32 v[18:19], v[34:35], v[150:151]
	v_pk_mul_f32 v[20:21], v[32:33], v[148:149]
	v_pk_add_f32 v[22:23], v[182:183], 1.0 op_sel_hi:[1,0]
	v_pk_add_f32 v[24:25], v[180:181], 1.0 op_sel_hi:[1,0]
	v_pk_mul_f32 v[18:19], v[18:19], v[22:23]
	v_pk_mul_f32 v[20:21], v[20:21], v[24:25]
	v_cvt_pk_bf16_f32 v19, v18, v19
	v_cvt_pk_bf16_f32 v18, v20, v21
	global_store_dwordx2 v[50:51], v[18:19], off offset:96
	s_and_saveexec_b64 s[24:25], s[36:37]
	s_movk_i32 s8, 0x400
	s_mov_b32 s5, 0xffff0000
	s_mov_b32 s9, 0x12000
	s_movk_i32 s89, 0xff
	s_cbranch_execz .LBB0_399
	s_waitcnt lgkmcnt(0)
	v_add_f32_e32 v16, v16, v17
	global_store_dword v[48:49], v16, off offset:128

.Ltail406:
	s_add_i32 s29, s44, 2
	ds_read_b128 v[136:139], v111 offset:16384
	ds_read_b128 v[140:143], v111 offset:18432
	ds_read_b128 v[144:147], v111 offset:20480
	ds_read_b128 v[148:151], v111 offset:22528
	ds_read_b128 v[116:119], v110
	s_add_i32 s44, s44, 4
	ds_read_b128 v[120:123], v110 offset:2048
	s_min_u32 s44, s44, 15
	s_lshl_b32 s92, s44, 7
	ds_read_b128 v[124:127], v110 offset:4096
	ds_read_b128 v[194:197], v113 offset:16384
	ds_read_b128 v[198:201], v113 offset:18432
	ds_read_b128 v[202:205], v113 offset:20480
	ds_read_b128 v[206:209], v113 offset:22528
	v_lshl_add_u64 v[164:165], v[100:101], 0, s[92:93]
	ds_read_b128 v[132:135], v110 offset:6144
	ds_read_b128 v[152:155], v112
	ds_read_b128 v[156:159], v112 offset:2048
	ds_read_b128 v[160:163], v112 offset:4096
	ds_read_b128 v[190:193], v112 offset:6144
	s_waitcnt lgkmcnt(11)
	v_mfma_f32_16x16x32_bf16 v[92:95], v[136:139], v[116:119], v[92:95]
	v_mfma_f32_16x16x32_bf16 v[88:91], v[140:143], v[116:119], v[88:91]
	v_mfma_f32_16x16x32_bf16 v[56:59], v[144:147], v[116:119], v[56:59]
	v_mfma_f32_16x16x32_bf16 v[48:51], v[148:151], v[116:119], v[48:51]
	s_waitcnt vmcnt(7)
	ds_write_b128 v109, v[52:55] offset:32768
	v_add_co_u32_e32 v52, vcc, s11, v164
	s_waitcnt lgkmcnt(11)
	v_mfma_f32_16x16x32_bf16 v[44:47], v[136:139], v[120:123], v[44:47]
	v_addc_co_u32_e32 v53, vcc, 0, v165, vcc
	v_mfma_f32_16x16x32_bf16 v[40:43], v[140:143], v[120:123], v[40:43]
	v_mfma_f32_16x16x32_bf16 v[36:39], v[144:147], v[120:123], v[36:39]
	v_mfma_f32_16x16x32_bf16 v[32:35], v[148:151], v[120:123], v[32:35]
	v_add_co_u32_e32 v52, vcc, s33, v164
	s_waitcnt vmcnt(6)
	ds_write_b128 v109, v[60:63] offset:36864
	s_nop 0
	v_addc_co_u32_e32 v53, vcc, 0, v165, vcc
	s_waitcnt lgkmcnt(11)
	v_mfma_f32_16x16x32_bf16 v[28:31], v[136:139], v[124:127], v[28:31]
	v_mfma_f32_16x16x32_bf16 v[24:27], v[140:143], v[124:127], v[24:27]
	v_mfma_f32_16x16x32_bf16 v[20:23], v[144:147], v[124:127], v[20:23]
	v_mfma_f32_16x16x32_bf16 v[16:19], v[148:151], v[124:127], v[16:19]
	v_add_co_u32_e32 v52, vcc, s59, v164
	s_waitcnt vmcnt(5)
	ds_write_b128 v109, v[64:67] offset:40960
	s_nop 0
	v_addc_co_u32_e32 v53, vcc, 0, v165, vcc
	v_lshl_add_u64 v[64:65], v[102:103], 0, s[92:93]
	v_add_co_u32_e32 v66, vcc, s11, v64
	s_waitcnt lgkmcnt(7)
	v_mfma_f32_16x16x32_bf16 v[12:15], v[136:139], v[132:135], v[12:15]
	v_addc_co_u32_e32 v67, vcc, 0, v65, vcc
	v_mfma_f32_16x16x32_bf16 v[8:11], v[140:143], v[132:135], v[8:11]
	v_mfma_f32_16x16x32_bf16 v[4:7], v[144:147], v[132:135], v[4:7]
	v_mfma_f32_16x16x32_bf16 v[0:3], v[148:151], v[132:135], v[0:3]
	s_waitcnt vmcnt(4)
	ds_write_b128 v109, v[72:75] offset:45056
	s_waitcnt lgkmcnt(7)
	v_mfma_f32_16x16x32_bf16 v[52:55], v[194:197], v[152:155], v[92:95]
	v_mfma_f32_16x16x32_bf16 v[60:63], v[198:201], v[152:155], v[88:91]
	v_mfma_f32_16x16x32_bf16 v[56:59], v[202:205], v[152:155], v[56:59]
	v_mfma_f32_16x16x32_bf16 v[48:51], v[206:209], v[152:155], v[48:51]
	s_waitcnt vmcnt(3)
	ds_write_b128 v109, v[68:71] offset:49152
	s_waitcnt lgkmcnt(7)
	v_mfma_f32_16x16x32_bf16 v[44:47], v[194:197], v[156:159], v[44:47]
	v_mfma_f32_16x16x32_bf16 v[40:43], v[198:201], v[156:159], v[40:43]
	v_mfma_f32_16x16x32_bf16 v[36:39], v[202:205], v[156:159], v[36:39]
	v_mfma_f32_16x16x32_bf16 v[32:35], v[206:209], v[156:159], v[32:35]
	v_add_co_u32_e32 v66, vcc, s33, v64
	s_waitcnt vmcnt(2)
	ds_write_b128 v109, v[76:79] offset:53248
	v_addc_co_u32_e32 v67, vcc, 0, v65, vcc
	v_add_co_u32_e32 v64, vcc, s59, v64
	s_waitcnt lgkmcnt(7)
	v_mfma_f32_16x16x32_bf16 v[28:31], v[194:197], v[160:163], v[28:31]
	v_addc_co_u32_e32 v65, vcc, 0, v65, vcc
	v_mfma_f32_16x16x32_bf16 v[24:27], v[198:201], v[160:163], v[24:27]
	v_mfma_f32_16x16x32_bf16 v[20:23], v[202:205], v[160:163], v[20:23]
	v_mfma_f32_16x16x32_bf16 v[16:19], v[206:209], v[160:163], v[16:19]
	s_waitcnt vmcnt(1)
	ds_write_b128 v109, v[80:83] offset:57344
	s_waitcnt lgkmcnt(7)
	v_mfma_f32_16x16x32_bf16 v[12:15], v[194:197], v[190:193], v[12:15]
	v_mfma_f32_16x16x32_bf16 v[8:11], v[198:201], v[190:193], v[8:11]
	v_mfma_f32_16x16x32_bf16 v[4:7], v[202:205], v[190:193], v[4:7]
	v_mfma_f32_16x16x32_bf16 v[0:3], v[206:209], v[190:193], v[0:3]
	s_waitcnt vmcnt(0)
	ds_write_b128 v109, v[84:87] offset:61440
	s_waitcnt lgkmcnt(0)
	s_barrier
	ds_read_b128 v[84:87], v111 offset:51200
	ds_read_b128 v[80:83], v111 offset:49152
	ds_read_b128 v[88:91], v111 offset:53248
	ds_read_b128 v[92:95], v111 offset:55296
	ds_read_b128 v[64:67], v110 offset:32768
	s_min_u32 s44, s29, 12
	s_lshl_b32 s92, s44, 7
	ds_read_b128 v[68:71], v110 offset:34816
	v_lshl_add_u64 v[164:165], v[100:101], 0, s[92:93]
	ds_read_b128 v[72:75], v110 offset:36864
	ds_read_b128 v[76:79], v110 offset:38912
	ds_read_b128 v[152:155], v112 offset:32768
	ds_read_b128 v[156:159], v112 offset:34816
	ds_read_b128 v[160:163], v112 offset:36864
	ds_read_b128 v[190:193], v112 offset:38912
	ds_read_b128 v[194:197], v113 offset:49152
	ds_read_b128 v[198:201], v113 offset:51200
	ds_read_b128 v[202:205], v113 offset:53248
	ds_read_b128 v[206:209], v113 offset:55296
	s_waitcnt lgkmcnt(11)
	v_mfma_f32_16x16x32_bf16 v[214:217], v[84:87], v[64:67], v[60:63]
	v_mfma_f32_16x16x32_bf16 v[210:213], v[80:83], v[64:67], v[52:55]
	s_nop 1
	v_add_co_u32_e32 v60, vcc, s11, v164
	s_nop 1
	v_addc_co_u32_e32 v61, vcc, 0, v165, vcc
	v_mfma_f32_16x16x32_bf16 v[56:59], v[88:91], v[64:67], v[56:59]
	v_mfma_f32_16x16x32_bf16 v[48:51], v[92:95], v[64:67], v[48:51]
	v_add_co_u32_e32 v64, vcc, s33, v164
	s_nop 0
	v_addc_co_u32_e32 v65, vcc, 0, v165, vcc
	s_waitcnt lgkmcnt(10)
	v_mfma_f32_16x16x32_bf16 v[44:47], v[80:83], v[68:71], v[44:47]
	v_mfma_f32_16x16x32_bf16 v[40:43], v[84:87], v[68:71], v[40:43]
	v_mfma_f32_16x16x32_bf16 v[36:39], v[88:91], v[68:71], v[36:39]
	v_mfma_f32_16x16x32_bf16 v[32:35], v[92:95], v[68:71], v[32:35]
	v_add_co_u32_e32 v68, vcc, s59, v164
	s_waitcnt lgkmcnt(9)
	v_mfma_f32_16x16x32_bf16 v[28:31], v[80:83], v[72:75], v[28:31]
	v_addc_co_u32_e32 v69, vcc, 0, v165, vcc
	v_mfma_f32_16x16x32_bf16 v[24:27], v[84:87], v[72:75], v[24:27]
	v_mfma_f32_16x16x32_bf16 v[20:23], v[88:91], v[72:75], v[20:23]
	v_mfma_f32_16x16x32_bf16 v[16:19], v[92:95], v[72:75], v[16:19]
	s_waitcnt lgkmcnt(8)
	v_mfma_f32_16x16x32_bf16 v[8:11], v[84:87], v[76:79], v[8:11]
	v_lshl_add_u64 v[84:85], v[102:103], 0, s[92:93]
	v_mfma_f32_16x16x32_bf16 v[12:15], v[80:83], v[76:79], v[12:15]
	v_mfma_f32_16x16x32_bf16 v[4:7], v[88:91], v[76:79], v[4:7]
	v_mfma_f32_16x16x32_bf16 v[0:3], v[92:95], v[76:79], v[0:3]
	v_add_co_u32_e32 v76, vcc, s11, v84
	s_nop 0
	v_addc_co_u32_e32 v77, vcc, 0, v85, vcc
	v_add_co_u32_e32 v80, vcc, s33, v84
	v_addc_co_u32_e32 v81, vcc, 0, v85, vcc
	s_waitcnt lgkmcnt(3)
	v_mfma_f32_16x16x32_bf16 v[92:95], v[194:197], v[152:155], v[210:213]
	s_waitcnt lgkmcnt(2)
	v_mfma_f32_16x16x32_bf16 v[88:91], v[198:201], v[152:155], v[214:217]
	s_waitcnt lgkmcnt(1)
	v_mfma_f32_16x16x32_bf16 v[56:59], v[202:205], v[152:155], v[56:59]
	s_waitcnt lgkmcnt(0)
	v_mfma_f32_16x16x32_bf16 v[48:51], v[206:209], v[152:155], v[48:51]
	v_add_co_u32_e32 v84, vcc, s59, v84
	v_addc_co_u32_e32 v85, vcc, 0, v85, vcc
	v_mfma_f32_16x16x32_bf16 v[44:47], v[194:197], v[156:159], v[44:47]
	v_mfma_f32_16x16x32_bf16 v[40:43], v[198:201], v[156:159], v[40:43]
	v_mfma_f32_16x16x32_bf16 v[36:39], v[202:205], v[156:159], v[36:39]
	v_mfma_f32_16x16x32_bf16 v[32:35], v[206:209], v[156:159], v[32:35]
	v_mfma_f32_16x16x32_bf16 v[28:31], v[194:197], v[160:163], v[28:31]
	v_mfma_f32_16x16x32_bf16 v[24:27], v[198:201], v[160:163], v[24:27]
	v_mfma_f32_16x16x32_bf16 v[20:23], v[202:205], v[160:163], v[20:23]
	v_mfma_f32_16x16x32_bf16 v[16:19], v[206:209], v[160:163], v[16:19]
	v_mfma_f32_16x16x32_bf16 v[12:15], v[194:197], v[190:193], v[12:15]
	v_mfma_f32_16x16x32_bf16 v[8:11], v[198:201], v[190:193], v[8:11]
	v_mfma_f32_16x16x32_bf16 v[4:7], v[202:205], v[190:193], v[4:7]
	v_mfma_f32_16x16x32_bf16 v[0:3], v[206:209], v[190:193], v[0:3]
	s_mov_b32 s44, s29
	s_waitcnt lgkmcnt(0)
	s_barrier
	s_waitcnt vmcnt(5)
	v_add_u32_e32 v64, s24, v108
	v_add_u32_e32 v52, 0xffffe000, v64
	v_or_b32_e32 v62, v64, v107
	v_lshrrev_b32_e32 v52, 10, v52
	s_movk_i32 s16, 0x1800
	v_mad_u32_u24 v52, v52, s16, s16
	v_cmp_lt_i32_e32 vcc, s13, v62
	v_or_b32_e32 v65, s25, v114
	v_or_b32_e32 v54, v65, v115
	v_cndmask_b32_e32 v52, 0, v52, vcc
	v_ashrrev_i32_e32 v53, 31, v52
	s_waitcnt vmcnt(4)
	v_lshlrev_b64 v[74:75], 2, v[52:53]
	v_ashrrev_i32_e32 v55, 31, v54
	v_ashrrev_i32_e32 v63, 31, v62
	v_lshl_add_u64 v[52:53], s[40:41], 0, v[74:75]
	v_lshlrev_b64 v[60:61], 2, v[54:55]
	v_readlane_b32 s16, v250, 15
	s_waitcnt vmcnt(1)
	v_lshl_add_u64 v[82:83], v[52:53], 0, v[60:61]
	v_lshlrev_b64 v[52:53], 12, v[62:63]
	v_readlane_b32 s17, v250, 16
	v_lshl_add_u64 v[74:75], s[42:43], 0, v[74:75]
	s_waitcnt vmcnt(0)
	v_lshl_add_u64 v[86:87], v[74:75], 0, v[60:61]
	v_lshl_add_u64 v[52:53], s[16:17], 0, v[52:53]
	v_lshl_add_u64 v[84:85], v[52:53], 0, v[60:61]
	global_load_dwordx4 v[66:69], v[82:83], off
	global_load_dwordx4 v[70:73], v[84:85], off
	v_lshl_add_u64 v[52:53], s[0:1], 0, v[60:61]
	v_readlane_b32 s16, v250, 21
	v_lshlrev_b64 v[78:79], 11, v[62:63]
	v_readlane_b32 s17, v250, 22
	s_waitcnt vmcnt(0)
	v_pk_fma_f32 v[68:69], v[94:95], v[68:69], v[72:73]
	v_pk_fma_f32 v[66:67], v[92:93], v[66:67], v[70:71]
	global_store_dwordx4 v[84:85], v[66:69], off
	global_load_dwordx4 v[70:73], v[52:53], off
	global_load_dwordx4 v[74:77], v[86:87], off
	v_lshl_add_u64 v[78:79], s[16:17], 0, v[78:79]
	v_lshl_add_u64 v[92:93], v[54:55], 1, v[78:79]
	s_mov_b32 s16, 0xa000
	s_waitcnt vmcnt(1)
	v_pk_mul_f32 v[72:73], v[68:69], v[72:73]
	v_pk_mul_f32 v[70:71], v[66:67], v[70:71]
	s_waitcnt vmcnt(0)
	v_pk_add_f32 v[76:77], v[76:77], 1.0 op_sel_hi:[1,0]
	v_pk_add_f32 v[74:75], v[74:75], 1.0 op_sel_hi:[1,0]
	v_pk_mul_f32 v[72:73], v[72:73], v[76:77]
	v_pk_mul_f32 v[70:71], v[70:71], v[74:75]
	v_and_b32_sdwa v77, v71, v170 dst_sel:DWORD dst_unused:UNUSED_PAD src0_sel:WORD_1 src1_sel:DWORD
	v_and_b32_sdwa v75, v70, v170 dst_sel:DWORD dst_unused:UNUSED_PAD src0_sel:WORD_1 src1_sel:DWORD
	v_add3_u32 v71, v71, v77, s56
	v_add3_u32 v70, v70, v75, s56
	v_and_b32_e32 v74, 0xffff0000, v71
	v_cvt_pk_bf16_f32 v71, v72, v73
	v_or_b32_sdwa v70, v74, v70 dst_sel:DWORD dst_unused:UNUSED_PAD src0_sel:DWORD src1_sel:WORD_1
	global_store_dwordx2 v[92:93], v[70:71], off
	global_load_dwordx4 v[70:73], v[82:83], off offset:64
	s_nop 0
	global_load_dwordx4 v[74:77], v[84:85], off offset:64
	s_waitcnt vmcnt(0)
	v_pk_fma_f32 v[72:73], v[90:91], v[72:73], v[76:77]
	v_pk_fma_f32 v[70:71], v[88:89], v[70:71], v[74:75]
	global_store_dwordx4 v[84:85], v[70:73], off offset:64
	global_load_dwordx4 v[74:77], v[52:53], off offset:64
	global_load_dwordx4 v[78:81], v[86:87], off offset:64
	s_waitcnt vmcnt(1)
	v_pk_mul_f32 v[76:77], v[72:73], v[76:77]
	v_pk_mul_f32 v[74:75], v[70:71], v[74:75]
	s_waitcnt vmcnt(0)
	v_pk_add_f32 v[80:81], v[80:81], 1.0 op_sel_hi:[1,0]
	v_pk_add_f32 v[78:79], v[78:79], 1.0 op_sel_hi:[1,0]
	v_pk_mul_f32 v[76:77], v[76:77], v[80:81]
	v_pk_mul_f32 v[74:75], v[74:75], v[78:79]
	v_and_b32_sdwa v81, v75, v170 dst_sel:DWORD dst_unused:UNUSED_PAD src0_sel:WORD_1 src1_sel:DWORD
	v_and_b32_sdwa v79, v74, v170 dst_sel:DWORD dst_unused:UNUSED_PAD src0_sel:WORD_1 src1_sel:DWORD
	v_add3_u32 v75, v75, v81, s56
	v_add3_u32 v74, v74, v79, s56
	v_and_b32_e32 v78, 0xffff0000, v75
	v_cvt_pk_bf16_f32 v75, v76, v77
	v_or_b32_sdwa v74, v78, v74 dst_sel:DWORD dst_unused:UNUSED_PAD src0_sel:DWORD src1_sel:WORD_1
	global_store_dwordx2 v[92:93], v[74:75], off offset:32
	global_load_dwordx4 v[74:77], v[82:83], off offset:128
	s_nop 0
	global_load_dwordx4 v[78:81], v[84:85], off offset:128
	s_waitcnt vmcnt(0)
	v_pk_fma_f32 v[58:59], v[58:59], v[76:77], v[80:81]
	v_pk_fma_f32 v[56:57], v[56:57], v[74:75], v[78:79]
	global_store_dwordx4 v[84:85], v[56:59], off offset:128
	global_load_dwordx4 v[74:77], v[52:53], off offset:128
	global_load_dwordx4 v[78:81], v[86:87], off offset:128
	s_waitcnt vmcnt(1)
	v_pk_mul_f32 v[76:77], v[58:59], v[76:77]
	v_pk_mul_f32 v[74:75], v[56:57], v[74:75]
	s_waitcnt vmcnt(0)
	v_pk_add_f32 v[80:81], v[80:81], 1.0 op_sel_hi:[1,0]
	v_pk_add_f32 v[78:79], v[78:79], 1.0 op_sel_hi:[1,0]
	v_pk_mul_f32 v[76:77], v[76:77], v[80:81]
	v_pk_mul_f32 v[74:75], v[74:75], v[78:79]
	v_and_b32_sdwa v81, v75, v170 dst_sel:DWORD dst_unused:UNUSED_PAD src0_sel:WORD_1 src1_sel:DWORD
	v_and_b32_sdwa v79, v74, v170 dst_sel:DWORD dst_unused:UNUSED_PAD src0_sel:WORD_1 src1_sel:DWORD
	v_add3_u32 v75, v75, v81, s56
	v_add3_u32 v74, v74, v79, s56
	v_and_b32_e32 v78, 0xffff0000, v75
	v_cvt_pk_bf16_f32 v75, v76, v77
	v_or_b32_sdwa v74, v78, v74 dst_sel:DWORD dst_unused:UNUSED_PAD src0_sel:DWORD src1_sel:WORD_1
	global_store_dwordx2 v[92:93], v[74:75], off offset:64
	global_load_dwordx4 v[74:77], v[82:83], off offset:192
	s_nop 0
	global_load_dwordx4 v[78:81], v[84:85], off offset:192
	s_waitcnt vmcnt(0)
	v_pk_fma_f32 v[76:77], v[50:51], v[76:77], v[80:81]
	v_pk_fma_f32 v[74:75], v[48:49], v[74:75], v[78:79]
	global_store_dwordx4 v[84:85], v[74:77], off offset:192
	global_load_dwordx4 v[78:81], v[52:53], off offset:192
	s_nop 0
	global_load_dwordx4 v[82:85], v[86:87], off offset:192
	v_mul_f32_e32 v48, v67, v67
	v_mul_f32_e32 v49, v71, v71
	v_fmac_f32_e32 v48, v66, v66
	v_fmac_f32_e32 v49, v70, v70
	v_fmac_f32_e32 v48, v68, v68
	v_fmac_f32_e32 v49, v72, v72
	v_fmac_f32_e32 v48, v69, v69
	v_fmac_f32_e32 v49, v73, v73
	v_add_f32_e32 v48, v48, v49
	v_mul_f32_e32 v49, v57, v57
	v_fmac_f32_e32 v49, v56, v56
	v_fmac_f32_e32 v49, v58, v58
	v_fmac_f32_e32 v49, v59, v59
	v_add_f32_e32 v48, v48, v49
	v_mul_f32_e32 v49, v75, v75
	v_fmac_f32_e32 v49, v74, v74
	v_fmac_f32_e32 v49, v76, v76
	v_fmac_f32_e32 v49, v77, v77
	v_add_f32_e32 v50, v48, v49
	ds_bpermute_b32 v51, v105, v50
	v_lshrrev_b32_e32 v48, 6, v65
	v_mul_lo_u32 v48, v48, s16
	v_ashrrev_i32_e32 v49, 31, v48
	v_lshl_add_u64 v[48:49], s[38:39], 0, v[48:49]
	s_waitcnt lgkmcnt(0)
	v_add_f32_e32 v50, v50, v51
	ds_bpermute_b32 v51, v104, v50
	v_lshl_add_u64 v[48:49], v[62:63], 2, v[48:49]
	s_waitcnt vmcnt(1)
	v_pk_mul_f32 v[56:57], v[76:77], v[80:81]
	v_pk_mul_f32 v[58:59], v[74:75], v[78:79]
	s_waitcnt vmcnt(0)
	v_pk_add_f32 v[66:67], v[84:85], 1.0 op_sel_hi:[1,0]
	v_pk_add_f32 v[68:69], v[82:83], 1.0 op_sel_hi:[1,0]
	v_pk_mul_f32 v[56:57], v[56:57], v[66:67]
	v_pk_mul_f32 v[58:59], v[58:59], v[68:69]
	v_cvt_pk_bf16_f32 v57, v56, v57
	v_cvt_pk_bf16_f32 v56, v58, v59
	global_store_dwordx2 v[92:93], v[56:57], off offset:96
	s_and_saveexec_b64 s[24:25], s[36:37]
	s_cbranch_execz .LBB0_409
	s_waitcnt lgkmcnt(0)
	v_add_f32_e32 v50, v50, v51
	global_store_dword v[48:49], v50, off

.LBB0_422:
	s_or_b64 exec, exec, s[2:3]
	v_add_u32_e32 v13, 0xffffe010, v18
	s_waitcnt lgkmcnt(0)
	v_lshl_add_u64 v[14:15], s[0:1], 0, v[128:129]
	v_or_b32_e32 v12, 16, v12
	v_lshrrev_b32_e32 v13, 10, v13
	s_movk_i32 s0, 0x1800
	v_mad_u32_u24 v13, v13, s0, s0
	v_cmp_lt_i32_e64 s[0:1], s13, v12
	s_nop 1
	v_cndmask_b32_e64 v18, 0, v13, s[0:1]
	v_ashrrev_i32_e32 v19, 31, v18
	v_lshlrev_b64 v[34:35], 2, v[18:19]
	v_ashrrev_i32_e32 v13, 31, v12
	v_lshl_add_u64 v[18:19], s[40:41], 0, v[34:35]
	v_readlane_b32 s0, v250, 15
	v_lshl_add_u64 v[20:21], v[18:19], 0, v[128:129]
	v_lshlrev_b64 v[18:19], 12, v[12:13]
	v_readlane_b32 s1, v250, 16
	s_nop 0
	v_lshl_add_u64 v[18:19], s[0:1], 0, v[18:19]
	v_lshl_add_u64 v[18:19], v[18:19], 0, v[128:129]
	v_readlane_b32 s0, v250, 21
	v_readlane_b32 s1, v250, 22
	s_waitcnt vmcnt(16)
	v_pk_fma_f32 v[28:29], v[38:39], v[74:75], v[212:213]
	v_pk_fma_f32 v[26:27], v[36:37], v[72:73], v[210:211]
	v_lshl_add_u64 v[22:23], s[42:43], 0, v[34:35]
	global_store_dwordx4 v[18:19], v[26:29], off
	v_lshl_add_u64 v[22:23], v[22:23], 0, v[128:129]
	v_mul_f32_e32 v38, v27, v27
	v_fmac_f32_e32 v38, v26, v26
	v_fmac_f32_e32 v38, v28, v28
	v_fmac_f32_e32 v38, v29, v29
	v_pk_mul_f32 v[24:25], v[28:29], v[142:143]
	v_pk_add_f32 v[28:29], v[158:159], 1.0 op_sel_hi:[1,0]
	v_pk_mul_f32 v[26:27], v[26:27], v[140:141]
	v_pk_add_f32 v[30:31], v[156:157], 1.0 op_sel_hi:[1,0]
	v_pk_mul_f32 v[24:25], v[24:25], v[28:29]
	v_lshlrev_b64 v[28:29], 11, v[12:13]
	v_pk_mul_f32 v[26:27], v[26:27], v[30:31]
	v_lshl_add_u64 v[28:29], s[0:1], 0, v[28:29]
	v_lshl_add_u64 v[16:17], v[28:29], 0, v[16:17]
	v_cvt_pk_bf16_f32 v25, v24, v25
	v_cvt_pk_bf16_f32 v24, v26, v27
	global_store_dwordx2 v[16:17], v[24:25], off
	s_nop 0
	v_pk_fma_f32 v[8:9], v[8:9], v[80:81], v[214:215]
	s_nop 0
	v_mul_f32_e32 v24, v9, v9
	v_pk_fma_f32 v[10:11], v[10:11], v[82:83], v[216:217]
	v_fmac_f32_e32 v24, v8, v8
	v_fmac_f32_e32 v24, v10, v10
	global_store_dwordx4 v[18:19], v[8:11], off offset:64
	v_fmac_f32_e32 v24, v11, v11
	v_add_f32_e32 v32, v38, v24
	v_pk_mul_f32 v[10:11], v[10:11], v[146:147]
	v_pk_mul_f32 v[8:9], v[8:9], v[144:145]
	v_pk_add_f32 v[24:25], v[162:163], 1.0 op_sel_hi:[1,0]
	v_pk_add_f32 v[26:27], v[160:161], 1.0 op_sel_hi:[1,0]
	v_pk_mul_f32 v[10:11], v[10:11], v[24:25]
	v_pk_mul_f32 v[8:9], v[8:9], v[26:27]
	v_and_b32_sdwa v25, v8, v170 dst_sel:DWORD dst_unused:UNUSED_PAD src0_sel:WORD_1 src1_sel:DWORD
	v_add3_u32 v8, v8, v25, s56
	v_and_b32_sdwa v25, v9, v170 dst_sel:DWORD dst_unused:UNUSED_PAD src0_sel:WORD_1 src1_sel:DWORD
	v_add3_u32 v9, v9, v25, s56
	v_and_b32_e32 v24, 0xffff0000, v9
	v_cvt_pk_bf16_f32 v9, v10, v11
	v_or_b32_sdwa v8, v24, v8 dst_sel:DWORD dst_unused:UNUSED_PAD src0_sel:DWORD src1_sel:WORD_1
	global_store_dwordx2 v[16:17], v[8:9], off offset:32
	s_nop 0
	v_pk_fma_f32 v[4:5], v[4:5], v[88:89], v[218:219]
	s_nop 0
	v_mul_f32_e32 v8, v5, v5
	v_pk_fma_f32 v[6:7], v[6:7], v[90:91], v[220:221]
	v_fmac_f32_e32 v8, v4, v4
	v_fmac_f32_e32 v8, v6, v6
	global_store_dwordx4 v[18:19], v[4:7], off offset:128
	v_fmac_f32_e32 v8, v7, v7
	v_add_f32_e32 v28, v32, v8
	v_pk_mul_f32 v[6:7], v[6:7], v[150:151]
	v_pk_mul_f32 v[4:5], v[4:5], v[148:149]
	v_pk_add_f32 v[8:9], v[182:183], 1.0 op_sel_hi:[1,0]
	v_pk_add_f32 v[10:11], v[180:181], 1.0 op_sel_hi:[1,0]
	v_pk_mul_f32 v[6:7], v[6:7], v[8:9]
	v_pk_mul_f32 v[4:5], v[4:5], v[10:11]
	v_and_b32_sdwa v9, v4, v170 dst_sel:DWORD dst_unused:UNUSED_PAD src0_sel:WORD_1 src1_sel:DWORD
	v_add3_u32 v4, v4, v9, s56
	v_and_b32_sdwa v9, v5, v170 dst_sel:DWORD dst_unused:UNUSED_PAD src0_sel:WORD_1 src1_sel:DWORD
	v_add3_u32 v5, v5, v9, s56
	v_and_b32_e32 v8, 0xffff0000, v5
	v_cvt_pk_bf16_f32 v5, v6, v7
	v_or_b32_sdwa v4, v8, v4 dst_sel:DWORD dst_unused:UNUSED_PAD src0_sel:DWORD src1_sel:WORD_1
	global_store_dwordx2 v[16:17], v[4:5], off offset:64
	s_nop 0
	v_pk_fma_f32 v[0:1], v[0:1], v[136:137], v[222:223]
	s_nop 0
	v_mul_f32_e32 v4, v1, v1
	v_pk_fma_f32 v[2:3], v[2:3], v[138:139], v[224:225]
	v_fmac_f32_e32 v4, v0, v0
	v_fmac_f32_e32 v4, v2, v2
	global_store_dwordx4 v[18:19], v[0:3], off offset:192
	v_fmac_f32_e32 v4, v3, v3
	v_add_f32_e32 v18, v28, v4
	v_pk_mul_f32 v[2:3], v[2:3], v[154:155]
	v_pk_mul_f32 v[0:1], v[0:1], v[152:153]
	v_pk_add_f32 v[4:5], v[192:193], 1.0 op_sel_hi:[1,0]
	v_pk_add_f32 v[6:7], v[190:191], 1.0 op_sel_hi:[1,0]
	v_pk_mul_f32 v[2:3], v[2:3], v[4:5]
	v_pk_mul_f32 v[0:1], v[0:1], v[6:7]
	v_and_b32_sdwa v5, v0, v170 dst_sel:DWORD dst_unused:UNUSED_PAD src0_sel:WORD_1 src1_sel:DWORD
	v_add3_u32 v0, v0, v5, s56
	v_and_b32_sdwa v5, v1, v170 dst_sel:DWORD dst_unused:UNUSED_PAD src0_sel:WORD_1 src1_sel:DWORD
	v_add3_u32 v1, v1, v5, s56
	v_and_b32_e32 v4, 0xffff0000, v1
	v_cvt_pk_bf16_f32 v1, v2, v3
	v_or_b32_sdwa v0, v4, v0 dst_sel:DWORD dst_unused:UNUSED_PAD src0_sel:DWORD src1_sel:WORD_1
	global_store_dwordx2 v[16:17], v[0:1], off offset:96
	ds_bpermute_b32 v0, v105, v18
	s_waitcnt lgkmcnt(0)
	v_add_f32_e32 v0, v18, v0
	ds_bpermute_b32 v1, v104, v0
	s_and_saveexec_b64 s[0:1], vcc
	s_movk_i32 s89, 0xff
	s_cbranch_execz .LBB0_424
	v_readlane_b32 s2, v253, 20
	s_add_u32 s2, s38, s2
	s_addc_u32 s3, s39, 0
	v_lshl_add_u64 v[2:3], v[12:13], 2, s[2:3]
	s_waitcnt lgkmcnt(0)
	v_add_f32_e32 v0, v0, v1
	global_store_dword v[2:3], v0, off

.LBB0_442:
	ds_read_b128 v[82:85], v77
	ds_read_b128 v[86:89], v77 offset:2048
	ds_read_b128 v[94:97], v78
	ds_read_b128 v[102:105], v78 offset:2048
	s_mov_b32 s2, 0x7060302
	s_waitcnt lgkmcnt(3)
	v_mfma_f32_16x16x32_bf16 v[90:93], v[82:85], v[28:31], 0
	s_cmp_lg_u32 s24, 8
	s_waitcnt lgkmcnt(2)
	v_mfma_f32_16x16x32_bf16 v[98:101], v[86:89], v[28:31], 0
	s_waitcnt lgkmcnt(1)
	v_mfma_f32_16x16x32_bf16 v[90:93], v[94:97], v[32:35], v[90:93]
	s_waitcnt lgkmcnt(0)
	v_mfma_f32_16x16x32_bf16 v[98:101], v[102:105], v[32:35], v[98:101]
	v_mfma_f32_16x16x32_bf16 v[82:85], v[82:85], v[36:39], 0
	s_nop 4
	v_max_f32_e32 v59, v91, v91
	v_max_f32_e32 v61, v90, v90
	v_max_f32_e32 v66, v93, v93
	v_max_f32_e32 v67, v92, v92
	v_max_f32_e32 v106, v101, v101
	v_max_f32_e32 v107, v100, v100
	v_max_f32_e32 v59, v61, v59
	v_max_f32_e32 v61, v67, v66
	v_max_f32_e32 v66, v107, v106
	v_max3_f32 v66, v98, v99, v66
	v_max3_f32 v59, v59, v61, v66
	v_mov_b32_e32 v66, v59
	v_mov_b32_e32 v61, v59
	s_nop 1
	v_permlane16_swap_b32_e32 v66, v61
	v_max_f32_e32 v61, v66, v61
	v_mfma_f32_16x16x32_bf16 v[86:89], v[86:89], v[36:39], 0
	v_add_u32_e32 v67, 0x1000, v79
	ds_read2_b64 v[106:109], v67 offset1:4
	s_waitcnt lgkmcnt(1)
	v_max_f32_e32 v61, v61, v61
	v_max_f32_e32 v59, v59, v61
	v_mov_b32_e32 v66, v59
	v_mov_b32_e32 v61, v59
	s_nop 1
	v_permlane32_swap_b32_e32 v66, v61
	v_max_f32_e32 v61, v66, v61
	v_mfma_f32_16x16x32_bf16 v[82:85], v[94:97], v[44:47], v[82:85]
	s_waitcnt lgkmcnt(0)
	v_max3_f32 v59, v81, v59, v61
	v_sub_f32_e32 v61, v81, v59
	v_sub_f32_e32 v81, v91, v59
	v_mul_f32_e32 v81, 0x3fb8aa3b, v81
	v_exp_f32_e32 v110, v81
	v_sub_f32_e32 v81, v93, v59
	v_mul_f32_e32 v81, 0x3fb8aa3b, v81
	v_exp_f32_e32 v114, v81
	v_sub_f32_e32 v81, v98, v59
	v_mul_f32_e32 v81, 0x3fb8aa3b, v81
	v_exp_f32_e32 v116, v81
	v_sub_f32_e32 v81, v99, v59
	v_mul_f32_e32 v81, 0x3fb8aa3b, v81
	v_exp_f32_e32 v118, v81
	v_sub_f32_e32 v81, v101, v59
	v_mul_f32_e32 v81, 0x3fb8aa3b, v81
	v_sub_f32_e32 v66, v90, v59
	v_sub_f32_e32 v90, v92, v59
	v_exp_f32_e32 v120, v81
	v_sub_f32_e32 v81, v100, v59
	v_mul_f32_e32 v66, 0x3fb8aa3b, v66
	v_mul_f32_e32 v90, 0x3fb8aa3b, v90
	v_mul_f32_e32 v81, 0x3fb8aa3b, v81
	v_exp_f32_e32 v66, v66
	v_exp_f32_e32 v112, v90
	v_exp_f32_e32 v122, v81
	v_mfma_f32_16x16x32_bf16 v[86:89], v[102:105], v[44:47], v[86:89]
	v_cvt_pk_bf16_f32 v93, v122, v120
	v_cvt_pk_bf16_f32 v92, v116, v118
	v_cvt_pk_bf16_f32 v91, v112, v114
	v_cvt_pk_bf16_f32 v90, v66, v110
	v_xor_b32_e32 v98, 16, v67
	ds_read2_b64 v[98:101], v98 offset0:128 offset1:132
	v_max_f32_e32 v67, v83, v83
	v_max_f32_e32 v81, v82, v82
	v_max_f32_e32 v67, v81, v67
	v_max_f32_e32 v81, v85, v85
	v_max_f32_e32 v102, v84, v84
	v_max_f32_e32 v81, v102, v81
	v_max_f32_e32 v102, v89, v89
	v_max_f32_e32 v103, v88, v88
	v_max_f32_e32 v102, v103, v102
	v_max3_f32 v102, v86, v87, v102
	v_max3_f32 v67, v67, v81, v102
	v_mov_b32_e32 v103, v67
	v_mov_b32_e32 v81, v67
	s_nop 1
	v_permlane16_swap_b32_e32 v103, v81
	v_max_f32_e32 v81, v103, v81
	v_mul_f32_e32 v61, 0x3fb8aa3b, v61
	v_exp_f32_e32 v124, v61
	v_add_u32_e32 v61, 0x1800, v79
	ds_read2_b64 v[94:97], v61 offset0:4 offset1:0
	v_xor_b32_e32 v102, 16, v61
	ds_read2_b64 v[102:105], v102 offset0:132 offset1:128
	s_waitcnt lgkmcnt(2)
	v_max_f32_e32 v61, v81, v81
	v_max_f32_e32 v61, v67, v61
	v_mov_b32_e32 v81, v61
	v_mov_b32_e32 v67, v61
	s_nop 1
	v_permlane32_swap_b32_e32 v81, v67
	v_max_f32_e32 v67, v81, v67
	v_pk_mul_f32 v[42:43], v[42:43], v[124:125] op_sel_hi:[1,0]
	v_pk_mul_f32 v[40:41], v[40:41], v[124:125] op_sel_hi:[1,0]
	v_pk_mul_f32 v[26:27], v[26:27], v[124:125] op_sel_hi:[1,0]
	v_pk_mul_f32 v[24:25], v[24:25], v[124:125] op_sel_hi:[1,0]
	s_waitcnt lgkmcnt(0)
	v_max3_f32 v61, v80, v61, v67
	v_sub_f32_e32 v81, v83, v61
	v_mul_f32_e32 v81, 0x3fb8aa3b, v81
	v_exp_f32_e32 v111, v81
	v_sub_f32_e32 v81, v84, v61
	v_sub_f32_e32 v67, v80, v61
	v_mul_f32_e32 v81, 0x3fb8aa3b, v81
	v_mul_f32_e32 v80, 0x3fb8aa3b, v67
	v_sub_f32_e32 v67, v82, v61
	v_exp_f32_e32 v113, v81
	v_sub_f32_e32 v81, v85, v61
	v_mul_f32_e32 v67, 0x3fb8aa3b, v67
	v_mul_f32_e32 v81, 0x3fb8aa3b, v81
	v_exp_f32_e32 v67, v67
	v_exp_f32_e32 v115, v81
	v_sub_f32_e32 v81, v86, v61
	v_sub_f32_e32 v82, v87, v61
	v_sub_f32_e32 v83, v88, v61
	v_sub_f32_e32 v84, v89, v61
	v_mul_f32_e32 v81, 0x3fb8aa3b, v81
	v_mul_f32_e32 v82, 0x3fb8aa3b, v82
	v_mul_f32_e32 v83, 0x3fb8aa3b, v83
	v_mul_f32_e32 v84, 0x3fb8aa3b, v84
	v_exp_f32_e32 v121, v84
	v_exp_f32_e32 v123, v83
	v_exp_f32_e32 v119, v82
	v_exp_f32_e32 v117, v81
	v_pk_mul_f32 v[22:23], v[22:23], v[124:125] op_sel_hi:[1,0]
	v_pk_mul_f32 v[20:21], v[20:21], v[124:125] op_sel_hi:[1,0]
	v_pk_mul_f32 v[18:19], v[18:19], v[124:125] op_sel_hi:[1,0]
	v_pk_mul_f32 v[16:17], v[16:17], v[124:125] op_sel_hi:[1,0]
	v_exp_f32_e32 v125, v80
	v_cvt_pk_bf16_f32 v80, v67, v111
	v_pk_add_f32 v[66:67], v[66:67], 0 op_sel_hi:[1,0]
	v_pk_add_f32 v[66:67], v[110:111], v[66:67]
	v_pk_add_f32 v[66:67], v[112:113], v[66:67]
	v_pk_add_f32 v[66:67], v[114:115], v[66:67]
	v_cvt_pk_bf16_f32 v83, v123, v121
	v_cvt_pk_bf16_f32 v82, v117, v119
	v_mov_b32_e32 v84, v125
	v_pk_add_f32 v[66:67], v[116:117], v[66:67]
	v_cvt_pk_bf16_f32 v81, v113, v115
	v_pk_mul_f32 v[14:15], v[14:15], v[84:85] op_sel_hi:[1,0]
	v_pk_mul_f32 v[12:13], v[12:13], v[84:85] op_sel_hi:[1,0]
	v_pk_mul_f32 v[10:11], v[10:11], v[84:85] op_sel_hi:[1,0]
	v_pk_mul_f32 v[8:9], v[8:9], v[84:85] op_sel_hi:[1,0]
	v_pk_mul_f32 v[6:7], v[6:7], v[84:85] op_sel_hi:[1,0]
	v_pk_mul_f32 v[4:5], v[4:5], v[84:85] op_sel_hi:[1,0]
	v_pk_mul_f32 v[2:3], v[2:3], v[84:85] op_sel_hi:[1,0]
	v_pk_mul_f32 v[0:1], v[0:1], v[84:85] op_sel_hi:[1,0]
	v_mfma_f32_16x16x32_bf16 v[40:43], v[106:109], v[90:93], v[40:43]
	v_add_f32_e64 v66, v118, v66
	v_add_f32_e64 v67, v119, v67
	v_pk_add_f32 v[66:67], v[122:123], v[66:67]
	v_mfma_f32_16x16x32_bf16 v[24:27], v[98:101], v[90:93], v[24:27]
	v_add_f32_e64 v66, v120, v66
	v_add_f32_e64 v67, v121, v67
	v_pk_fma_f32 v[50:51], v[50:51], v[124:125], v[66:67]
	v_mfma_f32_16x16x32_bf16 v[20:23], v[94:97], v[90:93], v[20:23]
	v_mfma_f32_16x16x32_bf16 v[16:19], v[102:105], v[90:93], v[16:19]
	v_mfma_f32_16x16x32_bf16 v[12:15], v[106:109], v[80:83], v[12:15]
	v_mfma_f32_16x16x32_bf16 v[8:11], v[98:101], v[80:83], v[8:11]
	v_mfma_f32_16x16x32_bf16 v[4:7], v[94:97], v[80:83], v[4:7]
	v_mfma_f32_16x16x32_bf16 v[0:3], v[102:105], v[80:83], v[0:3]
	v_mov_b32_e32 v81, v59
	v_mov_b32_e32 v80, v61
	s_cbranch_scc0 .LBB0_447
.LBB0_443:
	v_mov_b32_e32 v59, v129
	v_lshl_add_u64 v[62:63], v[62:63], 0, v[58:59]
	v_mov_b32_e32 v61, v129
	v_lshl_add_u64 v[82:83], v[64:65], 0, v[128:129]
	v_lshl_add_u64 v[62:63], v[62:63], 0, v[60:61]
	global_load_dwordx4 v[64:67], v[82:83], off offset:16
	s_nop 0
	global_load_dwordx4 v[82:85], v[82:83], off
	s_nop 0
	global_load_dwordx4 v[86:89], v[62:63], off offset:64
	global_load_dwordx4 v[90:93], v[62:63], off
	s_barrier
	s_mov_b32 s2, s24
	s_add_i32 s24, s24, 1
	s_cmp_lt_u32 s2, 7
	s_cselect_b32 s2, s24, s2
	s_lshl_b32 s3, s2, 5
	s_add_i32 s25, s3, 0xffffff00
	s_cmp_lt_u32 s2, 8
	s_cselect_b32 s3, s3, s25
	s_cmp_gt_u32 s2, 7
	s_waitcnt vmcnt(0)
	v_cvt_pk_bf16_f32 v63, v92, v93
	v_cvt_pk_bf16_f32 v62, v90, v91
	ds_write_b64 v74, v[62:63]
	v_cvt_pk_bf16_f32 v63, v88, v89
	v_cvt_pk_bf16_f32 v62, v86, v87
	v_cvt_pk_bf16_f32 v59, v82, v64
	ds_write_b64 v75, v[62:63]
	ds_write_b16 v76, v59 offset:4096
	ds_write_b16_d16_hi v76, v59 offset:4352
	v_cvt_pk_bf16_f32 v59, v83, v65
	ds_write_b16 v76, v59 offset:4160
	ds_write_b16_d16_hi v76, v59 offset:4416
	v_cvt_pk_bf16_f32 v59, v84, v66
	ds_write_b16 v76, v59 offset:4224
	ds_write_b16_d16_hi v76, v59 offset:4480
	v_cvt_pk_bf16_f32 v59, v85, v67
	ds_write_b16 v76, v59 offset:4288
	v_add_u32_e32 v66, s3, v73
	s_mov_b64 s[2:3], -1
	ds_write_b16_d16_hi v76, v59 offset:4544
	s_waitcnt lgkmcnt(0)
	s_barrier
	s_cbranch_scc0 .LBB0_445
	v_ashrrev_i32_e32 v67, 31, v66
	v_lshl_add_u64 v[62:63], v[66:67], 0, v[54:55]
	v_lshlrev_b64 v[64:65], 9, v[62:63]
	v_readlane_b32 s68, v253, 56
	v_lshl_or_b32 v64, v52, 2, v64
	v_readlane_b32 s74, v253, 62
	v_readlane_b32 s75, v253, 63
	v_readlane_b32 s76, v254, 0
	v_readlane_b32 s77, v254, 1
	v_readlane_b32 s69, v253, 57
	v_readlane_b32 s70, v253, 58
	v_readlane_b32 s71, v253, 59
	v_readlane_b32 s72, v253, 60
	v_readlane_b32 s73, v253, 61
	v_readlane_b32 s78, v254, 2
	v_readlane_b32 s79, v254, 3
	v_readlane_b32 s80, v254, 4
	v_readlane_b32 s81, v254, 5
	v_readlane_b32 s82, v254, 6
	v_readlane_b32 s83, v254, 7
	v_lshl_add_u64 v[62:63], s[74:75], 0, v[64:65]
	v_lshl_add_u64 v[64:65], s[76:77], 0, v[64:65]
	s_mov_b64 s[2:3], 0

.LBB0_463:
	s_waitcnt lgkmcnt(0)
	s_barrier
	global_load_dwordx4 v[8:11], v[76:77], off
	global_load_dwordx4 v[16:19], v[78:79], off
	global_load_dwordx4 v[12:15], v[78:79], off offset:2048
	global_load_dwordx4 v[4:7], v[80:81], off
	global_load_dwordx4 v[0:3], v[82:83], off
	v_xor_b32_e32 v64, s26, v128
	s_xor_b64 s[24:25], s[0:1], -1
	v_lshl_or_b32 v175, v64, 7, v130
	s_mov_b64 s[40:41], -1
	s_mov_b32 s27, 0
	s_waitcnt vmcnt(3)
	v_pk_fma_f32 v[60:61], v[60:61], v[18:19], v[10:11]
	v_pk_fma_f32 v[62:63], v[62:63], v[16:17], v[8:9]
	s_waitcnt vmcnt(2)
	v_pk_fma_f32 v[60:61], v[56:57], v[14:15], v[60:61]
	v_pk_fma_f32 v[62:63], v[58:59], v[12:13], v[62:63]
	s_waitcnt vmcnt(1)
	v_pk_fma_f32 v[60:61], v[52:53], v[6:7], v[60:61]
	v_pk_fma_f32 v[62:63], v[54:55], v[4:5], v[62:63]
	s_waitcnt vmcnt(0)
	v_pk_fma_f32 v[60:61], v[48:49], v[2:3], v[60:61]
	v_pk_fma_f32 v[62:63], v[50:51], v[0:1], v[62:63]
	v_pk_fma_f32 v[56:57], v[56:57], v[18:19], v[10:11]
	v_pk_fma_f32 v[58:59], v[58:59], v[16:17], v[8:9]
	v_pk_fma_f32 v[56:57], v[52:53], v[14:15], v[56:57]
	v_pk_fma_f32 v[58:59], v[54:55], v[12:13], v[58:59]
	v_pk_fma_f32 v[56:57], v[48:49], v[6:7], v[56:57]
	v_pk_fma_f32 v[58:59], v[50:51], v[4:5], v[58:59]
	v_pk_fma_f32 v[56:57], v[40:41], v[2:3], v[56:57]
	v_pk_fma_f32 v[58:59], v[44:45], v[0:1], v[58:59]
	v_cvt_pk_bf16_f32 v61, v60, v61
	v_cvt_pk_bf16_f32 v60, v62, v63
	v_pk_fma_f32 v[52:53], v[52:53], v[18:19], v[10:11]
	v_pk_fma_f32 v[54:55], v[54:55], v[16:17], v[8:9]
	v_pk_fma_f32 v[52:53], v[48:49], v[14:15], v[52:53]
	v_pk_fma_f32 v[54:55], v[50:51], v[12:13], v[54:55]
	v_pk_fma_f32 v[52:53], v[40:41], v[6:7], v[52:53]
	v_pk_fma_f32 v[54:55], v[44:45], v[4:5], v[54:55]
	v_cvt_pk_bf16_f32 v57, v56, v57
	v_cvt_pk_bf16_f32 v56, v58, v59
	v_pk_fma_f32 v[52:53], v[32:33], v[2:3], v[52:53]
	v_pk_fma_f32 v[54:55], v[36:37], v[0:1], v[54:55]
	ds_write2_b64 v228, v[60:61], v[56:57] offset1:16
	v_pk_fma_f32 v[48:49], v[48:49], v[18:19], v[10:11]
	v_pk_fma_f32 v[50:51], v[50:51], v[16:17], v[8:9]
	v_pk_fma_f32 v[48:49], v[40:41], v[14:15], v[48:49]
	v_pk_fma_f32 v[50:51], v[44:45], v[12:13], v[50:51]
	v_pk_fma_f32 v[48:49], v[32:33], v[6:7], v[48:49]
	v_pk_fma_f32 v[50:51], v[36:37], v[4:5], v[50:51]
	v_cvt_pk_bf16_f32 v53, v52, v53
	v_cvt_pk_bf16_f32 v52, v54, v55
	v_pk_fma_f32 v[48:49], v[24:25], v[2:3], v[48:49]
	v_pk_fma_f32 v[50:51], v[28:29], v[0:1], v[50:51]
	ds_write_b64 v229, v[52:53]
	v_pk_fma_f32 v[40:41], v[40:41], v[18:19], v[10:11]
	v_pk_fma_f32 v[44:45], v[44:45], v[16:17], v[8:9]
	v_pk_fma_f32 v[40:41], v[32:33], v[14:15], v[40:41]
	v_pk_fma_f32 v[44:45], v[36:37], v[12:13], v[44:45]
	v_pk_fma_f32 v[40:41], v[24:25], v[6:7], v[40:41]
	v_pk_fma_f32 v[44:45], v[28:29], v[4:5], v[44:45]
	v_cvt_pk_bf16_f32 v49, v48, v49
	v_cvt_pk_bf16_f32 v48, v50, v51
	v_pk_fma_f32 v[40:41], v[20:21], v[2:3], v[40:41]
	v_pk_fma_f32 v[44:45], v[22:23], v[0:1], v[44:45]
	ds_write_b64 v230, v[48:49]
	v_pk_fma_f32 v[32:33], v[32:33], v[18:19], v[10:11]
	v_pk_fma_f32 v[36:37], v[36:37], v[16:17], v[8:9]
	v_pk_fma_f32 v[32:33], v[24:25], v[14:15], v[32:33]
	v_pk_fma_f32 v[36:37], v[28:29], v[12:13], v[36:37]
	v_pk_fma_f32 v[32:33], v[20:21], v[6:7], v[32:33]
	v_pk_fma_f32 v[36:37], v[22:23], v[4:5], v[36:37]
	v_cvt_pk_bf16_f32 v41, v40, v41
	v_cvt_pk_bf16_f32 v40, v44, v45
	v_pk_fma_f32 v[32:33], v[26:27], v[2:3], v[32:33]
	v_pk_fma_f32 v[36:37], v[30:31], v[0:1], v[36:37]
	ds_write_b64 v231, v[40:41]
	v_pk_fma_f32 v[24:25], v[24:25], v[18:19], v[10:11]
	v_pk_fma_f32 v[28:29], v[28:29], v[16:17], v[8:9]
	v_pk_fma_f32 v[10:11], v[20:21], v[18:19], v[10:11]
	v_pk_fma_f32 v[8:9], v[22:23], v[16:17], v[8:9]
	v_pk_fma_f32 v[24:25], v[20:21], v[14:15], v[24:25]
	v_pk_fma_f32 v[28:29], v[22:23], v[12:13], v[28:29]
	v_pk_fma_f32 v[10:11], v[26:27], v[14:15], v[10:11]
	v_pk_fma_f32 v[8:9], v[30:31], v[12:13], v[8:9]
	v_pk_fma_f32 v[24:25], v[26:27], v[6:7], v[24:25]
	v_pk_fma_f32 v[28:29], v[30:31], v[4:5], v[28:29]
	v_pk_fma_f32 v[6:7], v[34:35], v[6:7], v[10:11]
	v_pk_fma_f32 v[4:5], v[38:39], v[4:5], v[8:9]
	v_cvt_pk_bf16_f32 v33, v32, v33
	v_cvt_pk_bf16_f32 v32, v36, v37
	v_pk_fma_f32 v[24:25], v[34:35], v[2:3], v[24:25]
	v_pk_fma_f32 v[28:29], v[38:39], v[0:1], v[28:29]
	v_pk_fma_f32 v[2:3], v[42:43], v[2:3], v[6:7]
	v_pk_fma_f32 v[0:1], v[46:47], v[0:1], v[4:5]
	ds_write_b64 v232, v[32:33]
	v_and_b32_sdwa v5, v0, v170 dst_sel:DWORD dst_unused:UNUSED_PAD src0_sel:WORD_1 src1_sel:DWORD
	v_add3_u32 v0, v0, v5, s56
	v_and_b32_sdwa v5, v1, v170 dst_sel:DWORD dst_unused:UNUSED_PAD src0_sel:WORD_1 src1_sel:DWORD
	v_add3_u32 v1, v1, v5, s56
	v_and_b32_e32 v4, 0xffff0000, v1
	v_cvt_pk_bf16_f32 v25, v24, v25
	v_cvt_pk_bf16_f32 v24, v28, v29
	v_cvt_pk_bf16_f32 v1, v2, v3
	v_or_b32_sdwa v0, v4, v0 dst_sel:DWORD dst_unused:UNUSED_PAD src0_sel:DWORD src1_sel:WORD_1
	ds_write_b64 v233, v[24:25]
	ds_write_b64 v234, v[0:1]
	global_load_dwordx4 v[40:43], v[140:141], off offset:3072
	global_load_dwordx4 v[36:39], v[142:143], off offset:3072
	global_load_dwordx4 v[32:35], v[144:145], off offset:3072
	global_load_dwordx4 v[28:31], v[146:147], off offset:3072
	global_load_dwordx4 v[24:27], v[148:149], off offset:3072
	global_load_dwordx4 v[20:23], v[150:151], off offset:3072
	global_load_dwordx4 v[16:19], v[152:153], off offset:3072
	global_load_dwordx4 v[12:15], v[154:155], off offset:3072
	global_load_dwordx4 v[8:11], v[156:157], off offset:3072
	global_load_dwordx4 v[4:7], v[158:159], off offset:3072
	global_load_dwordx4 v[0:3], v[160:161], off offset:3072
	s_waitcnt lgkmcnt(0)
	s_barrier
	s_branch .LBB0_465

.LBB0_515:
	s_or_b64 exec, exec, s[28:29]
	s_waitcnt vmcnt(0)
	v_and_b32_sdwa v65, v60, v170 dst_sel:DWORD dst_unused:UNUSED_PAD src0_sel:WORD_1 src1_sel:DWORD
	v_add3_u32 v60, v60, v65, s56
	v_and_b32_sdwa v65, v61, v170 dst_sel:DWORD dst_unused:UNUSED_PAD src0_sel:WORD_1 src1_sel:DWORD
	v_add3_u32 v61, v61, v65, s56
	v_and_b32_e32 v64, 0xffff0000, v61
	v_cvt_pk_bf16_f32 v61, v62, v63
	v_or_b32_sdwa v60, v64, v60 dst_sel:DWORD dst_unused:UNUSED_PAD src0_sel:DWORD src1_sel:WORD_1
	ds_write_b64 v143, v[60:61]
	v_and_b32_sdwa v61, v56, v170 dst_sel:DWORD dst_unused:UNUSED_PAD src0_sel:WORD_1 src1_sel:DWORD
	v_add3_u32 v56, v56, v61, s56
	v_and_b32_sdwa v61, v57, v170 dst_sel:DWORD dst_unused:UNUSED_PAD src0_sel:WORD_1 src1_sel:DWORD
	v_add3_u32 v57, v57, v61, s56
	v_and_b32_e32 v60, 0xffff0000, v57
	v_cvt_pk_bf16_f32 v57, v58, v59
	v_or_b32_sdwa v56, v60, v56 dst_sel:DWORD dst_unused:UNUSED_PAD src0_sel:DWORD src1_sel:WORD_1
	ds_write_b64 v144, v[56:57]
	v_bfe_u32 v56, v52, 16, 1
	v_add3_u32 v52, v52, v56, s56
	ds_write_b16_d16_hi v145, v52 offset:4096
	v_bfe_u32 v52, v48, 16, 1
	v_add3_u32 v48, v48, v52, s56
	ds_write_b16_d16_hi v145, v48 offset:4352
	v_bfe_u32 v48, v53, 16, 1
	v_add3_u32 v48, v53, v48, s56
	ds_write_b16_d16_hi v145, v48 offset:4160
	v_bfe_u32 v48, v49, 16, 1
	v_add3_u32 v48, v49, v48, s56
	ds_write_b16_d16_hi v145, v48 offset:4416
	v_bfe_u32 v48, v54, 16, 1
	v_add3_u32 v48, v54, v48, s56
	ds_write_b16_d16_hi v145, v48 offset:4224
	v_bfe_u32 v48, v50, 16, 1
	v_add3_u32 v48, v50, v48, s56
	ds_write_b16_d16_hi v145, v48 offset:4480
	v_bfe_u32 v48, v55, 16, 1
	v_add3_u32 v48, v55, v48, s56
	ds_write_b16_d16_hi v145, v48 offset:4288
	v_bfe_u32 v48, v51, 16, 1
	v_add3_u32 v48, v51, v48, s56
	s_add_i32 s27, s26, 1
	ds_write_b16_d16_hi v145, v48 offset:4544
	v_mov_b32_e32 v48, s26
	v_mov_b32_e32 v49, s27
	v_cmp_lt_i32_e64 s[36:37], s27, v124
	s_waitcnt lgkmcnt(0)
	s_barrier
	v_cndmask_b32_e64 v48, v48, v49, s[36:37]
	v_sub_u32_e32 v50, v48, v121
	v_lshl_add_u32 v49, v48, 5, v120
	v_lshlrev_b32_e32 v50, 5, v50
	v_cmp_lt_i32_e64 s[38:39], v48, v121
	v_cmp_ge_i32_e64 s[36:37], v48, v121
	s_nop 0
	v_cndmask_b32_e64 v48, v50, v49, s[38:39]
	v_add_u32_e32 v52, v48, v125
	s_and_saveexec_b64 s[28:29], s[36:37]
	s_xor_b64 s[28:29], exec, s[28:29]
	s_cbranch_execz .LBB0_517
	v_ashrrev_i32_e32 v53, 31, v52
	v_lshl_add_u64 v[48:49], v[52:53], 0, v[110:111]
	v_lshlrev_b64 v[48:49], 9, v[48:49]
	v_readlane_b32 s68, v253, 56
	v_lshl_or_b32 v48, v108, 2, v48
	v_readlane_b32 s74, v253, 62
	v_readlane_b32 s75, v253, 63
	v_readlane_b32 s76, v254, 0
	v_readlane_b32 s77, v254, 1
	v_readlane_b32 s69, v253, 57
	v_readlane_b32 s70, v253, 58
	v_readlane_b32 s71, v253, 59
	v_readlane_b32 s72, v253, 60
	v_readlane_b32 s73, v253, 61
	v_readlane_b32 s78, v254, 2
	v_readlane_b32 s79, v254, 3
	v_readlane_b32 s80, v254, 4
	v_readlane_b32 s81, v254, 5
	v_readlane_b32 s82, v254, 6
	v_readlane_b32 s83, v254, 7
	v_lshl_add_u64 v[50:51], s[74:75], 0, v[48:49]
	v_lshl_add_u64 v[48:49], s[76:77], 0, v[48:49]

.LBB0_539:
	s_sub_i32 s1, 7, s24
	v_mov_b32_e32 v0, s1
	v_mov_b32_e32 v1, s24
	v_cndmask_b32_e64 v124, v0, v1, s[38:39]
	s_waitcnt lgkmcnt(0)
	s_barrier
	global_load_dwordx4 v[8:11], v[70:71], off
	global_load_dwordx4 v[16:19], v[72:73], off
	global_load_dwordx4 v[12:15], v[72:73], off offset:2048
	global_load_dwordx4 v[4:7], v[76:77], off
	global_load_dwordx4 v[0:3], v[78:79], off
	s_mov_b32 s0, s24
	s_add_i32 s24, s24, 1
	s_cmp_lg_u32 s0, 7
	s_cselect_b32 s0, s24, 7
	s_sub_i32 s1, 7, s0
	v_lshl_add_u32 v124, v124, 7, v97
	s_mov_b64 s[2:3], -1
	s_mov_b32 s25, 0
	s_waitcnt vmcnt(3)
	v_pk_fma_f32 v[38:39], v[90:91], v[18:19], v[10:11]
	v_pk_fma_f32 v[40:41], v[92:93], v[16:17], v[8:9]
	s_waitcnt vmcnt(2)
	v_pk_fma_f32 v[38:39], v[62:63], v[14:15], v[38:39]
	v_pk_fma_f32 v[40:41], v[64:65], v[12:13], v[40:41]
	s_waitcnt vmcnt(1)
	v_pk_fma_f32 v[38:39], v[58:59], v[6:7], v[38:39]
	v_pk_fma_f32 v[40:41], v[60:61], v[4:5], v[40:41]
	s_waitcnt vmcnt(0)
	v_pk_fma_f32 v[38:39], v[54:55], v[2:3], v[38:39]
	v_pk_fma_f32 v[40:41], v[56:57], v[0:1], v[40:41]
	v_cvt_pk_bf16_f32 v39, v38, v39
	v_cvt_pk_bf16_f32 v38, v40, v41
	v_pk_fma_f32 v[40:41], v[62:63], v[18:19], v[10:11]
	v_pk_fma_f32 v[42:43], v[64:65], v[16:17], v[8:9]
	v_pk_fma_f32 v[40:41], v[58:59], v[14:15], v[40:41]
	v_pk_fma_f32 v[42:43], v[60:61], v[12:13], v[42:43]
	v_pk_fma_f32 v[40:41], v[54:55], v[6:7], v[40:41]
	v_pk_fma_f32 v[42:43], v[56:57], v[4:5], v[42:43]
	v_pk_fma_f32 v[40:41], v[50:51], v[2:3], v[40:41]
	v_pk_fma_f32 v[42:43], v[52:53], v[0:1], v[42:43]
	v_cvt_pk_bf16_f32 v41, v40, v41
	v_cvt_pk_bf16_f32 v40, v42, v43
	ds_write2_b64 v115, v[38:39], v[40:41] offset1:16
	v_pk_fma_f32 v[38:39], v[58:59], v[18:19], v[10:11]
	v_pk_fma_f32 v[40:41], v[60:61], v[16:17], v[8:9]
	v_pk_fma_f32 v[38:39], v[54:55], v[14:15], v[38:39]
	v_pk_fma_f32 v[40:41], v[56:57], v[12:13], v[40:41]
	v_pk_fma_f32 v[38:39], v[50:51], v[6:7], v[38:39]
	v_pk_fma_f32 v[40:41], v[52:53], v[4:5], v[40:41]
	v_pk_fma_f32 v[38:39], v[46:47], v[2:3], v[38:39]
	v_pk_fma_f32 v[40:41], v[48:49], v[0:1], v[40:41]
	v_cvt_pk_bf16_f32 v39, v38, v39
	v_cvt_pk_bf16_f32 v38, v40, v41
	ds_write_b64 v116, v[38:39]
	v_pk_fma_f32 v[38:39], v[54:55], v[18:19], v[10:11]
	v_pk_fma_f32 v[40:41], v[56:57], v[16:17], v[8:9]
	v_pk_fma_f32 v[38:39], v[50:51], v[14:15], v[38:39]
	v_pk_fma_f32 v[40:41], v[52:53], v[12:13], v[40:41]
	v_pk_fma_f32 v[38:39], v[46:47], v[6:7], v[38:39]
	v_pk_fma_f32 v[40:41], v[48:49], v[4:5], v[40:41]
	v_pk_fma_f32 v[38:39], v[26:27], v[2:3], v[38:39]
	v_pk_fma_f32 v[40:41], v[44:45], v[0:1], v[40:41]
	v_cvt_pk_bf16_f32 v39, v38, v39
	v_cvt_pk_bf16_f32 v38, v40, v41
	ds_write_b64 v117, v[38:39]
	v_pk_fma_f32 v[38:39], v[50:51], v[18:19], v[10:11]
	v_pk_fma_f32 v[40:41], v[52:53], v[16:17], v[8:9]
	v_pk_fma_f32 v[38:39], v[46:47], v[14:15], v[38:39]
	v_pk_fma_f32 v[40:41], v[48:49], v[12:13], v[40:41]
	v_pk_fma_f32 v[38:39], v[26:27], v[6:7], v[38:39]
	v_pk_fma_f32 v[40:41], v[44:45], v[4:5], v[40:41]
	v_pk_fma_f32 v[38:39], v[20:21], v[2:3], v[38:39]
	v_pk_fma_f32 v[40:41], v[22:23], v[0:1], v[40:41]
	v_cvt_pk_bf16_f32 v39, v38, v39
	v_cvt_pk_bf16_f32 v38, v40, v41
	ds_write_b64 v118, v[38:39]
	v_pk_fma_f32 v[38:39], v[46:47], v[18:19], v[10:11]
	v_pk_fma_f32 v[40:41], v[48:49], v[16:17], v[8:9]
	v_pk_fma_f32 v[38:39], v[26:27], v[14:15], v[38:39]
	v_pk_fma_f32 v[40:41], v[44:45], v[12:13], v[40:41]
	v_pk_fma_f32 v[38:39], v[20:21], v[6:7], v[38:39]
	v_pk_fma_f32 v[40:41], v[22:23], v[4:5], v[40:41]
	v_pk_fma_f32 v[38:39], v[24:25], v[2:3], v[38:39]
	v_pk_fma_f32 v[40:41], v[28:29], v[0:1], v[40:41]
	v_cvt_pk_bf16_f32 v39, v38, v39
	v_cvt_pk_bf16_f32 v38, v40, v41
	ds_write_b64 v119, v[38:39]
	v_pk_fma_f32 v[26:27], v[26:27], v[18:19], v[10:11]
	v_pk_fma_f32 v[38:39], v[44:45], v[16:17], v[8:9]
	v_pk_fma_f32 v[10:11], v[20:21], v[18:19], v[10:11]
	v_pk_fma_f32 v[8:9], v[22:23], v[16:17], v[8:9]
	v_pk_fma_f32 v[26:27], v[20:21], v[14:15], v[26:27]
	v_pk_fma_f32 v[38:39], v[22:23], v[12:13], v[38:39]
	v_pk_fma_f32 v[10:11], v[24:25], v[14:15], v[10:11]
	v_pk_fma_f32 v[8:9], v[28:29], v[12:13], v[8:9]
	v_pk_fma_f32 v[26:27], v[24:25], v[6:7], v[26:27]
	v_pk_fma_f32 v[38:39], v[28:29], v[4:5], v[38:39]
	v_pk_fma_f32 v[6:7], v[30:31], v[6:7], v[10:11]
	v_pk_fma_f32 v[4:5], v[32:33], v[4:5], v[8:9]
	v_pk_fma_f32 v[26:27], v[30:31], v[2:3], v[26:27]
	v_pk_fma_f32 v[38:39], v[32:33], v[0:1], v[38:39]
	v_pk_fma_f32 v[2:3], v[34:35], v[2:3], v[6:7]
	v_pk_fma_f32 v[0:1], v[36:37], v[0:1], v[4:5]
	v_and_b32_sdwa v5, v0, v170 dst_sel:DWORD dst_unused:UNUSED_PAD src0_sel:WORD_1 src1_sel:DWORD
	v_add3_u32 v0, v0, v5, s56
	v_and_b32_sdwa v5, v1, v170 dst_sel:DWORD dst_unused:UNUSED_PAD src0_sel:WORD_1 src1_sel:DWORD
	v_add3_u32 v1, v1, v5, s56
	v_and_b32_e32 v4, 0xffff0000, v1
	v_cvt_pk_bf16_f32 v27, v26, v27
	v_cvt_pk_bf16_f32 v26, v38, v39
	v_cvt_pk_bf16_f32 v1, v2, v3
	v_or_b32_sdwa v0, v4, v0 dst_sel:DWORD dst_unused:UNUSED_PAD src0_sel:DWORD src1_sel:WORD_1
	ds_write_b64 v120, v[26:27]
	ds_write_b64 v121, v[0:1]
	v_mov_b32_e32 v0, s1
	v_mov_b32_e32 v1, s0
	v_cndmask_b32_e64 v0, v0, v1, s[38:39]
	v_lshl_add_u32 v122, v0, 7, v98
	v_min_i32_e32 v0, 0x401, v122
	v_or_b32_e32 v4, 1, v122
	v_add_u32_e32 v0, -2, v0
	v_cmp_lt_i32_e32 vcc, 1, v122
	v_min_i32_e32 v5, 0x401, v4
	v_or_b32_e32 v8, 2, v122
	v_or_b32_e32 v12, 3, v122
	v_or_b32_e32 v16, 4, v122
	v_or_b32_e32 v20, 5, v122
	v_or_b32_e32 v24, 6, v122
	v_or_b32_e32 v28, 7, v122
	v_cndmask_b32_e32 v0, 0, v0, vcc
	v_add_u32_e32 v5, -2, v5
	v_cmp_lt_i32_e32 vcc, 1, v4
	v_min_i32_e32 v8, 0x401, v8
	v_min_i32_e32 v12, 0x401, v12
	v_min_i32_e32 v16, 0x401, v16
	v_min_i32_e32 v20, 0x401, v20
	v_min_i32_e32 v24, 0x401, v24
	v_min_i32_e32 v28, 0x401, v28
	v_add_u32_e32 v123, 8, v122
	v_cndmask_b32_e32 v4, 0, v5, vcc
	v_cmp_gt_i32_e32 vcc, 0, v122
	v_add_u32_e32 v8, -2, v8
	v_add_u32_e32 v12, -2, v12
	v_add_u32_e32 v16, -2, v16
	v_add_u32_e32 v20, -2, v20
	v_add_u32_e32 v24, -2, v24
	v_add_u32_e32 v28, -2, v28
	v_min_i32_e32 v32, 0x401, v123
	v_cndmask_b32_e64 v8, v8, 0, vcc
	v_cndmask_b32_e64 v12, v12, 0, vcc
	v_cndmask_b32_e64 v16, v16, 0, vcc
	v_cndmask_b32_e64 v20, v20, 0, vcc
	v_cndmask_b32_e64 v24, v24, 0, vcc
	v_cndmask_b32_e64 v28, v28, 0, vcc
	v_add_u32_e32 v32, -2, v32
	v_cmp_lt_i32_e32 vcc, 1, v123
	v_min_i32_e32 v36, 0x3f8, v122
	v_or_b32_e32 v36, 7, v36
	v_cndmask_b32_e32 v32, 0, v32, vcc
	v_cmp_lt_i32_e32 vcc, -8, v122
	v_add_u32_e32 v0, v0, v97
	v_add_u32_e32 v4, v4, v97
	v_cndmask_b32_e32 v36, 0, v36, vcc
	v_add_u32_e32 v36, v36, v97
	v_ashrrev_i32_e32 v37, 31, v36
	v_lshlrev_b64 v[36:37], 13, v[36:37]
	v_lshl_add_u64 v[36:37], v[88:89], 0, v[36:37]
	global_load_dwordx4 v[40:43], v[36:37], off offset:3072
	v_min_i32_e32 v36, 0x3f7, v122
	v_add_u32_e32 v36, 8, v36
	v_cmp_lt_i32_e32 vcc, -9, v122
	v_add_u32_e32 v8, v8, v97
	v_add_u32_e32 v12, v12, v97
	v_cndmask_b32_e32 v36, 0, v36, vcc
	v_add_u32_e32 v16, v16, v97
	v_add_u32_e32 v20, v20, v97
	v_add_u32_e32 v24, v24, v97
	v_add_u32_e32 v28, v28, v97
	v_add_u32_e32 v32, v32, v97
	v_add_u32_e32 v36, v36, v97
	v_ashrrev_i32_e32 v1, 31, v0
	v_ashrrev_i32_e32 v5, 31, v4
	v_ashrrev_i32_e32 v9, 31, v8
	v_ashrrev_i32_e32 v13, 31, v12
	v_ashrrev_i32_e32 v17, 31, v16
	v_ashrrev_i32_e32 v21, 31, v20
	v_ashrrev_i32_e32 v25, 31, v24
	v_ashrrev_i32_e32 v29, 31, v28
	v_ashrrev_i32_e32 v33, 31, v32
	v_ashrrev_i32_e32 v37, 31, v36
	v_lshlrev_b64 v[0:1], 13, v[0:1]
	v_lshlrev_b64 v[4:5], 13, v[4:5]
	v_lshlrev_b64 v[8:9], 13, v[8:9]
	v_lshlrev_b64 v[12:13], 13, v[12:13]
	v_lshlrev_b64 v[16:17], 13, v[16:17]
	v_lshlrev_b64 v[20:21], 13, v[20:21]
	v_lshlrev_b64 v[24:25], 13, v[24:25]
	v_lshlrev_b64 v[28:29], 13, v[28:29]
	v_lshlrev_b64 v[32:33], 13, v[32:33]
	v_lshlrev_b64 v[36:37], 13, v[36:37]
	v_lshl_add_u64 v[0:1], v[88:89], 0, v[0:1]
	v_lshl_add_u64 v[4:5], v[88:89], 0, v[4:5]
	v_lshl_add_u64 v[8:9], v[88:89], 0, v[8:9]
	v_lshl_add_u64 v[12:13], v[88:89], 0, v[12:13]
	v_lshl_add_u64 v[16:17], v[88:89], 0, v[16:17]
	v_lshl_add_u64 v[20:21], v[88:89], 0, v[20:21]
	v_lshl_add_u64 v[24:25], v[88:89], 0, v[24:25]
	v_lshl_add_u64 v[28:29], v[88:89], 0, v[28:29]
	v_lshl_add_u64 v[32:33], v[88:89], 0, v[32:33]
	v_lshl_add_u64 v[36:37], v[88:89], 0, v[36:37]
	global_load_dwordx4 v[0:3], v[0:1], off offset:3072
	s_nop 0
	global_load_dwordx4 v[4:7], v[4:5], off offset:3072
	s_nop 0
	global_load_dwordx4 v[8:11], v[8:9], off offset:3072
	s_nop 0
	global_load_dwordx4 v[12:15], v[12:13], off offset:3072
	s_nop 0
	global_load_dwordx4 v[16:19], v[16:17], off offset:3072
	s_nop 0
	global_load_dwordx4 v[20:23], v[20:21], off offset:3072
	s_nop 0
	global_load_dwordx4 v[24:27], v[24:25], off offset:3072
	s_nop 0
	global_load_dwordx4 v[28:31], v[28:29], off offset:3072
	s_nop 0
	global_load_dwordx4 v[32:35], v[32:33], off offset:3072
	s_nop 0
	global_load_dwordx4 v[36:39], v[36:37], off offset:3072
	s_waitcnt lgkmcnt(0)
	s_barrier
	s_branch .LBB0_541

.Ltail582:
	s_add_i32 s0, s1, 2
	v_add_u32_e32 v111, v104, v105
	ds_read_b128 v[136:139], v111 offset:16384
	ds_read_b128 v[140:143], v111 offset:18432
	ds_read_b128 v[144:147], v111 offset:20480
	ds_read_b128 v[148:151], v111 offset:22528
	v_add_u32_e32 v110, v103, v105
	ds_read_b128 v[116:119], v110
	s_add_i32 s1, s1, 4
	ds_read_b128 v[120:123], v110 offset:2048
	s_min_u32 s1, s1, 63
	v_add_u32_e32 v113, v104, v114
	s_lshl_b32 s92, s1, 7
	ds_read_b128 v[124:127], v110 offset:4096
	v_add_u32_e32 v112, v103, v114
	ds_read_b128 v[194:197], v113 offset:16384
	ds_read_b128 v[198:201], v113 offset:18432
	ds_read_b128 v[202:205], v113 offset:20480
	ds_read_b128 v[206:209], v113 offset:22528
	v_lshl_add_u64 v[164:165], v[98:99], 0, s[92:93]
	ds_read_b128 v[132:135], v110 offset:6144
	ds_read_b128 v[152:155], v112
	ds_read_b128 v[156:159], v112 offset:2048
	ds_read_b128 v[160:163], v112 offset:4096
	ds_read_b128 v[190:193], v112 offset:6144
	s_waitcnt lgkmcnt(11)
	v_mfma_f32_16x16x32_bf16 v[92:95], v[136:139], v[116:119], v[92:95]
	v_mfma_f32_16x16x32_bf16 v[88:91], v[140:143], v[116:119], v[88:91]
	v_mfma_f32_16x16x32_bf16 v[52:55], v[144:147], v[116:119], v[52:55]
	v_mfma_f32_16x16x32_bf16 v[48:51], v[148:151], v[116:119], v[48:51]
	s_waitcnt vmcnt(7)
	ds_write_b128 v109, v[56:59] offset:32768
	v_add_co_u32_e32 v56, vcc, s7, v164
	s_waitcnt lgkmcnt(11)
	v_mfma_f32_16x16x32_bf16 v[44:47], v[136:139], v[120:123], v[44:47]
	v_addc_co_u32_e32 v57, vcc, 0, v165, vcc
	v_mfma_f32_16x16x32_bf16 v[40:43], v[140:143], v[120:123], v[40:43]
	v_mfma_f32_16x16x32_bf16 v[36:39], v[144:147], v[120:123], v[36:39]
	v_mfma_f32_16x16x32_bf16 v[32:35], v[148:151], v[120:123], v[32:35]
	v_add_co_u32_e32 v56, vcc, s52, v164
	s_waitcnt vmcnt(6)
	ds_write_b128 v109, v[60:63] offset:36864
	s_nop 0
	v_addc_co_u32_e32 v57, vcc, 0, v165, vcc
	s_waitcnt lgkmcnt(11)
	v_mfma_f32_16x16x32_bf16 v[28:31], v[136:139], v[124:127], v[28:31]
	v_mfma_f32_16x16x32_bf16 v[24:27], v[140:143], v[124:127], v[24:27]
	v_mfma_f32_16x16x32_bf16 v[20:23], v[144:147], v[124:127], v[20:23]
	v_mfma_f32_16x16x32_bf16 v[16:19], v[148:151], v[124:127], v[16:19]
	v_add_co_u32_e32 v56, vcc, s34, v164
	s_waitcnt vmcnt(5)
	ds_write_b128 v109, v[64:67] offset:40960
	s_nop 0
	v_addc_co_u32_e32 v57, vcc, 0, v165, vcc
	v_lshl_add_u64 v[64:65], v[100:101], 0, s[92:93]
	v_add_co_u32_e32 v66, vcc, s7, v64
	s_waitcnt lgkmcnt(7)
	v_mfma_f32_16x16x32_bf16 v[12:15], v[136:139], v[132:135], v[12:15]
	v_addc_co_u32_e32 v67, vcc, 0, v65, vcc
	v_mfma_f32_16x16x32_bf16 v[8:11], v[140:143], v[132:135], v[8:11]
	v_mfma_f32_16x16x32_bf16 v[4:7], v[144:147], v[132:135], v[4:7]
	v_mfma_f32_16x16x32_bf16 v[0:3], v[148:151], v[132:135], v[0:3]
	s_waitcnt vmcnt(4)
	ds_write_b128 v109, v[72:75] offset:45056
	s_waitcnt lgkmcnt(7)
	v_mfma_f32_16x16x32_bf16 v[56:59], v[194:197], v[152:155], v[92:95]
	v_mfma_f32_16x16x32_bf16 v[60:63], v[198:201], v[152:155], v[88:91]
	v_mfma_f32_16x16x32_bf16 v[52:55], v[202:205], v[152:155], v[52:55]
	v_mfma_f32_16x16x32_bf16 v[48:51], v[206:209], v[152:155], v[48:51]
	s_waitcnt vmcnt(3)
	ds_write_b128 v109, v[68:71] offset:49152
	s_waitcnt lgkmcnt(7)
	v_mfma_f32_16x16x32_bf16 v[44:47], v[194:197], v[156:159], v[44:47]
	v_mfma_f32_16x16x32_bf16 v[40:43], v[198:201], v[156:159], v[40:43]
	v_mfma_f32_16x16x32_bf16 v[36:39], v[202:205], v[156:159], v[36:39]
	v_mfma_f32_16x16x32_bf16 v[32:35], v[206:209], v[156:159], v[32:35]
	v_add_co_u32_e32 v66, vcc, s52, v64
	s_waitcnt vmcnt(2)
	ds_write_b128 v109, v[76:79] offset:53248
	v_addc_co_u32_e32 v67, vcc, 0, v65, vcc
	v_add_co_u32_e32 v64, vcc, s34, v64
	s_waitcnt lgkmcnt(7)
	v_mfma_f32_16x16x32_bf16 v[28:31], v[194:197], v[160:163], v[28:31]
	v_addc_co_u32_e32 v65, vcc, 0, v65, vcc
	v_mfma_f32_16x16x32_bf16 v[24:27], v[198:201], v[160:163], v[24:27]
	v_mfma_f32_16x16x32_bf16 v[20:23], v[202:205], v[160:163], v[20:23]
	v_mfma_f32_16x16x32_bf16 v[16:19], v[206:209], v[160:163], v[16:19]
	s_waitcnt vmcnt(1)
	ds_write_b128 v109, v[80:83] offset:57344
	s_waitcnt lgkmcnt(7)
	v_mfma_f32_16x16x32_bf16 v[12:15], v[194:197], v[190:193], v[12:15]
	v_mfma_f32_16x16x32_bf16 v[8:11], v[198:201], v[190:193], v[8:11]
	v_mfma_f32_16x16x32_bf16 v[4:7], v[202:205], v[190:193], v[4:7]
	v_mfma_f32_16x16x32_bf16 v[0:3], v[206:209], v[190:193], v[0:3]
	s_waitcnt vmcnt(0)
	ds_write_b128 v109, v[84:87] offset:61440
	s_waitcnt lgkmcnt(0)
	s_barrier
	ds_read_b128 v[84:87], v111 offset:51200
	ds_read_b128 v[80:83], v111 offset:49152
	ds_read_b128 v[88:91], v111 offset:53248
	ds_read_b128 v[92:95], v111 offset:55296
	ds_read_b128 v[64:67], v110 offset:32768
	s_min_u32 s1, s0, 60
	s_lshl_b32 s92, s1, 7
	ds_read_b128 v[68:71], v110 offset:34816
	v_lshl_add_u64 v[164:165], v[98:99], 0, s[92:93]
	ds_read_b128 v[72:75], v110 offset:36864
	ds_read_b128 v[76:79], v110 offset:38912
	ds_read_b128 v[152:155], v112 offset:32768
	ds_read_b128 v[156:159], v112 offset:34816
	ds_read_b128 v[160:163], v112 offset:36864
	ds_read_b128 v[190:193], v112 offset:38912
	ds_read_b128 v[194:197], v113 offset:49152
	ds_read_b128 v[198:201], v113 offset:51200
	ds_read_b128 v[202:205], v113 offset:53248
	ds_read_b128 v[206:209], v113 offset:55296
	s_waitcnt lgkmcnt(11)
	v_mfma_f32_16x16x32_bf16 v[214:217], v[84:87], v[64:67], v[60:63]
	v_mfma_f32_16x16x32_bf16 v[210:213], v[80:83], v[64:67], v[56:59]
	s_nop 1
	v_add_co_u32_e32 v60, vcc, s7, v164
	s_nop 1
	v_addc_co_u32_e32 v61, vcc, 0, v165, vcc
	v_mfma_f32_16x16x32_bf16 v[52:55], v[88:91], v[64:67], v[52:55]
	v_mfma_f32_16x16x32_bf16 v[48:51], v[92:95], v[64:67], v[48:51]
	v_add_co_u32_e32 v64, vcc, s52, v164
	s_nop 0
	v_addc_co_u32_e32 v65, vcc, 0, v165, vcc
	s_waitcnt lgkmcnt(10)
	v_mfma_f32_16x16x32_bf16 v[44:47], v[80:83], v[68:71], v[44:47]
	v_mfma_f32_16x16x32_bf16 v[40:43], v[84:87], v[68:71], v[40:43]
	v_mfma_f32_16x16x32_bf16 v[36:39], v[88:91], v[68:71], v[36:39]
	v_mfma_f32_16x16x32_bf16 v[32:35], v[92:95], v[68:71], v[32:35]
	v_add_co_u32_e32 v68, vcc, s34, v164
	s_waitcnt lgkmcnt(9)
	v_mfma_f32_16x16x32_bf16 v[28:31], v[80:83], v[72:75], v[28:31]
	v_addc_co_u32_e32 v69, vcc, 0, v165, vcc
	v_mfma_f32_16x16x32_bf16 v[24:27], v[84:87], v[72:75], v[24:27]
	v_mfma_f32_16x16x32_bf16 v[20:23], v[88:91], v[72:75], v[20:23]
	v_mfma_f32_16x16x32_bf16 v[16:19], v[92:95], v[72:75], v[16:19]
	s_waitcnt lgkmcnt(8)
	v_mfma_f32_16x16x32_bf16 v[8:11], v[84:87], v[76:79], v[8:11]
	v_lshl_add_u64 v[84:85], v[100:101], 0, s[92:93]
	v_mfma_f32_16x16x32_bf16 v[12:15], v[80:83], v[76:79], v[12:15]
	v_mfma_f32_16x16x32_bf16 v[4:7], v[88:91], v[76:79], v[4:7]
	v_mfma_f32_16x16x32_bf16 v[0:3], v[92:95], v[76:79], v[0:3]
	v_add_co_u32_e32 v76, vcc, s7, v84
	s_nop 0
	v_addc_co_u32_e32 v77, vcc, 0, v85, vcc
	v_add_co_u32_e32 v80, vcc, s52, v84
	v_addc_co_u32_e32 v81, vcc, 0, v85, vcc
	s_waitcnt lgkmcnt(3)
	v_mfma_f32_16x16x32_bf16 v[92:95], v[194:197], v[152:155], v[210:213]
	s_waitcnt lgkmcnt(2)
	v_mfma_f32_16x16x32_bf16 v[88:91], v[198:201], v[152:155], v[214:217]
	s_waitcnt lgkmcnt(1)
	v_mfma_f32_16x16x32_bf16 v[52:55], v[202:205], v[152:155], v[52:55]
	s_waitcnt lgkmcnt(0)
	v_mfma_f32_16x16x32_bf16 v[48:51], v[206:209], v[152:155], v[48:51]
	v_add_co_u32_e32 v84, vcc, s34, v84
	v_addc_co_u32_e32 v85, vcc, 0, v85, vcc
	v_mfma_f32_16x16x32_bf16 v[44:47], v[194:197], v[156:159], v[44:47]
	v_mfma_f32_16x16x32_bf16 v[40:43], v[198:201], v[156:159], v[40:43]
	v_mfma_f32_16x16x32_bf16 v[36:39], v[202:205], v[156:159], v[36:39]
	v_mfma_f32_16x16x32_bf16 v[32:35], v[206:209], v[156:159], v[32:35]
	v_mfma_f32_16x16x32_bf16 v[28:31], v[194:197], v[160:163], v[28:31]
	v_mfma_f32_16x16x32_bf16 v[24:27], v[198:201], v[160:163], v[24:27]
	v_mfma_f32_16x16x32_bf16 v[20:23], v[202:205], v[160:163], v[20:23]
	v_mfma_f32_16x16x32_bf16 v[16:19], v[206:209], v[160:163], v[16:19]
	v_mfma_f32_16x16x32_bf16 v[12:15], v[194:197], v[190:193], v[12:15]
	v_mfma_f32_16x16x32_bf16 v[8:11], v[198:201], v[190:193], v[8:11]
	v_mfma_f32_16x16x32_bf16 v[4:7], v[202:205], v[190:193], v[4:7]
	v_mfma_f32_16x16x32_bf16 v[0:3], v[206:209], v[190:193], v[0:3]
	s_mov_b32 s1, s0
	s_waitcnt lgkmcnt(0)
	s_barrier
	s_or_b32 s0, s69, 1
	s_mul_i32 s1, s69, 0x12000
	v_readlane_b32 s26, v250, 25
	v_readlane_b32 s27, v250, 26
	s_add_u32 s1, s26, s1
	s_addc_u32 s24, s27, 0
	s_add_u32 s38, s1, 0x5000
	v_readlane_b32 s1, v251, 5
	v_lshlrev_b32_e32 v114, 6, v102
	v_lshlrev_b32_e32 v115, 2, v97
	s_waitcnt vmcnt(5)
	v_add_u32_e32 v64, s1, v108
	v_readlane_b32 s1, v251, 6
	v_add_u32_e32 v56, 0xffffe000, v64
	v_or_b32_e32 v62, v64, v107
	v_or_b32_e32 v65, s1, v114
	v_lshrrev_b32_e32 v56, 10, v56
	s_movk_i32 s1, 0x1800
	v_mad_u32_u24 v56, v56, s1, s1
	v_cmp_lt_i32_e32 vcc, s13, v62
	v_or_b32_e32 v58, v65, v115
	s_addc_u32 s39, s24, 0
	v_cndmask_b32_e32 v56, 0, v56, vcc
	v_ashrrev_i32_e32 v57, 31, v56
	s_waitcnt vmcnt(4)
	v_lshlrev_b64 v[74:75], 2, v[56:57]
	v_ashrrev_i32_e32 v59, 31, v58
	v_ashrrev_i32_e32 v63, 31, v62
	v_lshl_add_u64 v[56:57], s[38:39], 0, v[74:75]
	v_lshlrev_b64 v[60:61], 2, v[58:59]
	v_readlane_b32 s16, v250, 15
	s_waitcnt vmcnt(1)
	v_lshl_add_u64 v[82:83], v[56:57], 0, v[60:61]
	v_lshlrev_b64 v[56:57], 12, v[62:63]
	v_readlane_b32 s17, v250, 16
	v_readlane_b32 s68, v250, 41
	s_mul_i32 s24, s0, 0x12000
	v_lshl_add_u64 v[56:57], s[16:17], 0, v[56:57]
	s_waitcnt vmcnt(0)
	v_lshl_add_u64 v[84:85], v[56:57], 0, v[60:61]
	global_load_dwordx4 v[116:119], v[82:83], off
	global_load_dwordx4 v[120:123], v[82:83], off offset:64
	global_load_dwordx4 v[124:127], v[82:83], off offset:128
	global_load_dwordx4 v[132:135], v[82:83], off offset:192
	global_load_dwordx4 v[190:193], v[84:85], off
	global_load_dwordx4 v[194:197], v[84:85], off offset:64
	global_load_dwordx4 v[198:201], v[84:85], off offset:128
	global_load_dwordx4 v[202:205], v[84:85], off offset:192
	v_add_co_u32_e32 v164, vcc, 0x10000, v84
	s_nop 1
	v_addc_co_u32_e32 v165, vcc, 0, v85, vcc
	v_add_co_u32_e32 v222, vcc, 0x20000, v84
	s_nop 1
	v_addc_co_u32_e32 v223, vcc, 0, v85, vcc
	v_add_co_u32_e32 v224, vcc, 0x30000, v84
	s_nop 1
	v_addc_co_u32_e32 v225, vcc, 0, v85, vcc
	global_load_dwordx4 v[206:209], v[164:165], off
	global_load_dwordx4 v[210:213], v[164:165], off offset:64
	global_load_dwordx4 v[214:217], v[164:165], off offset:128
	global_load_dwordx4 v[218:221], v[164:165], off offset:192
	s_lshl_b32 s0, s0, 12
	v_readlane_b32 s70, v250, 43
	v_readlane_b32 s71, v250, 44
	s_add_u32 s0, s70, s0
	s_addc_u32 s1, s71, 0
	s_add_u32 s24, s26, s24
	s_addc_u32 s25, s27, 0
	s_add_u32 s40, s24, 0x1000
	s_addc_u32 s41, s25, 0
	v_lshl_add_u64 v[74:75], s[40:41], 0, v[74:75]
	v_lshl_add_u64 v[56:57], s[0:1], 0, v[60:61]
	v_lshl_add_u64 v[86:87], v[74:75], 0, v[60:61]
	v_readlane_b32 s16, v250, 21
	v_lshlrev_b64 v[78:79], 11, v[62:63]
	v_readlane_b32 s17, v250, 22
	v_readlane_b32 s69, v250, 42
	v_readlane_b32 s69, v254, 49
	v_lshl_add_u64 v[78:79], s[16:17], 0, v[78:79]
	s_mul_i32 s24, s69, 0x140000
	s_add_u32 s24, s86, s24
	s_mov_b32 s16, 0xa000
	s_addc_u32 s25, s87, 0
	s_add_u32 s26, s24, 0xafba000
	s_addc_u32 s27, s25, 0
	v_cmp_eq_u32_e64 s[36:37], 0, v97
	v_readlane_b32 s72, v250, 45
	v_readlane_b32 s73, v250, 46
	v_readlane_b32 s74, v250, 47
	v_readlane_b32 s75, v250, 48
	v_readlane_b32 s76, v250, 49
	v_readlane_b32 s77, v250, 50
	v_readlane_b32 s78, v250, 51
	v_readlane_b32 s79, v250, 52
	v_readlane_b32 s80, v250, 53
	v_readlane_b32 s81, v250, 54
	v_readlane_b32 s82, v250, 55
	v_readlane_b32 s83, v250, 56
	s_waitcnt vmcnt(4)
	v_pk_fma_f32 v[68:69], v[94:95], v[118:119], v[192:193]
	v_pk_fma_f32 v[66:67], v[92:93], v[116:117], v[190:191]
	global_store_dwordx4 v[84:85], v[66:69], off
	global_load_dwordx4 v[136:139], v[56:57], off
	global_load_dwordx4 v[140:143], v[56:57], off offset:64
	global_load_dwordx4 v[144:147], v[56:57], off offset:128
	global_load_dwordx4 v[148:151], v[56:57], off offset:192
	global_load_dwordx4 v[152:155], v[86:87], off
	global_load_dwordx4 v[156:159], v[86:87], off offset:64
	global_load_dwordx4 v[160:163], v[86:87], off offset:128
	global_load_dwordx4 v[180:183], v[86:87], off offset:192
	v_lshl_add_u64 v[92:93], v[58:59], 1, v[78:79]
	s_waitcnt vmcnt(0)
	v_pk_mul_f32 v[72:73], v[68:69], v[138:139]
	v_pk_mul_f32 v[70:71], v[66:67], v[136:137]
	s_waitcnt vmcnt(0)
	v_pk_add_f32 v[76:77], v[154:155], 1.0 op_sel_hi:[1,0]
	v_pk_add_f32 v[74:75], v[152:153], 1.0 op_sel_hi:[1,0]
	v_pk_mul_f32 v[72:73], v[72:73], v[76:77]
	v_pk_mul_f32 v[70:71], v[70:71], v[74:75]
	v_and_b32_sdwa v77, v71, v170 dst_sel:DWORD dst_unused:UNUSED_PAD src0_sel:WORD_1 src1_sel:DWORD
	v_and_b32_sdwa v75, v70, v170 dst_sel:DWORD dst_unused:UNUSED_PAD src0_sel:WORD_1 src1_sel:DWORD
	v_add3_u32 v71, v71, v77, s56
	v_add3_u32 v70, v70, v75, s56
	v_and_b32_e32 v74, 0xffff0000, v71
	v_cvt_pk_bf16_f32 v71, v72, v73
	v_or_b32_sdwa v70, v74, v70 dst_sel:DWORD dst_unused:UNUSED_PAD src0_sel:DWORD src1_sel:WORD_1
	global_store_dwordx2 v[92:93], v[70:71], off
	s_nop 0
	s_waitcnt vmcnt(0)
	v_pk_fma_f32 v[72:73], v[90:91], v[122:123], v[196:197]
	v_pk_fma_f32 v[70:71], v[88:89], v[120:121], v[194:195]
	global_store_dwordx4 v[84:85], v[70:73], off offset:64
	v_pk_mul_f32 v[76:77], v[72:73], v[142:143]
	v_pk_mul_f32 v[74:75], v[70:71], v[140:141]
	v_pk_add_f32 v[80:81], v[158:159], 1.0 op_sel_hi:[1,0]
	v_pk_add_f32 v[78:79], v[156:157], 1.0 op_sel_hi:[1,0]
	v_pk_mul_f32 v[76:77], v[76:77], v[80:81]
	v_pk_mul_f32 v[74:75], v[74:75], v[78:79]
	v_and_b32_sdwa v81, v75, v170 dst_sel:DWORD dst_unused:UNUSED_PAD src0_sel:WORD_1 src1_sel:DWORD
	v_and_b32_sdwa v79, v74, v170 dst_sel:DWORD dst_unused:UNUSED_PAD src0_sel:WORD_1 src1_sel:DWORD
	v_add3_u32 v75, v75, v81, s56
	v_add3_u32 v74, v74, v79, s56
	v_and_b32_e32 v78, 0xffff0000, v75
	v_cvt_pk_bf16_f32 v75, v76, v77
	v_or_b32_sdwa v74, v78, v74 dst_sel:DWORD dst_unused:UNUSED_PAD src0_sel:DWORD src1_sel:WORD_1
	global_store_dwordx2 v[92:93], v[74:75], off offset:32
	s_nop 0
	v_pk_fma_f32 v[54:55], v[54:55], v[126:127], v[200:201]
	v_pk_fma_f32 v[52:53], v[52:53], v[124:125], v[198:199]
	global_store_dwordx4 v[84:85], v[52:55], off offset:128
	v_pk_mul_f32 v[76:77], v[54:55], v[146:147]
	v_pk_mul_f32 v[74:75], v[52:53], v[144:145]
	v_pk_add_f32 v[80:81], v[162:163], 1.0 op_sel_hi:[1,0]
	v_pk_add_f32 v[78:79], v[160:161], 1.0 op_sel_hi:[1,0]
	v_pk_mul_f32 v[76:77], v[76:77], v[80:81]
	v_pk_mul_f32 v[74:75], v[74:75], v[78:79]
	v_and_b32_sdwa v81, v75, v170 dst_sel:DWORD dst_unused:UNUSED_PAD src0_sel:WORD_1 src1_sel:DWORD
	v_and_b32_sdwa v79, v74, v170 dst_sel:DWORD dst_unused:UNUSED_PAD src0_sel:WORD_1 src1_sel:DWORD
	v_add3_u32 v75, v75, v81, s56
	v_add3_u32 v74, v74, v79, s56
	v_and_b32_e32 v78, 0xffff0000, v75
	v_cvt_pk_bf16_f32 v75, v76, v77
	v_or_b32_sdwa v74, v78, v74 dst_sel:DWORD dst_unused:UNUSED_PAD src0_sel:DWORD src1_sel:WORD_1
	global_store_dwordx2 v[92:93], v[74:75], off offset:64
	s_nop 0
	v_pk_fma_f32 v[76:77], v[50:51], v[134:135], v[204:205]
	v_pk_fma_f32 v[74:75], v[48:49], v[132:133], v[202:203]
	global_store_dwordx4 v[84:85], v[74:77], off offset:192
	s_nop 0
	v_mul_f32_e32 v50, v67, v67
	v_mul_f32_e32 v51, v71, v71
	v_fmac_f32_e32 v50, v66, v66
	v_fmac_f32_e32 v51, v70, v70
	v_fmac_f32_e32 v50, v68, v68
	v_fmac_f32_e32 v51, v72, v72
	v_fmac_f32_e32 v50, v69, v69
	v_fmac_f32_e32 v51, v73, v73
	v_add_f32_e32 v50, v50, v51
	v_mul_f32_e32 v51, v53, v53
	v_fmac_f32_e32 v51, v52, v52
	v_fmac_f32_e32 v51, v54, v54
	v_fmac_f32_e32 v51, v55, v55
	v_add_f32_e32 v50, v50, v51
	v_mul_f32_e32 v51, v75, v75
	v_xor_b32_e32 v48, 16, v176
	v_fmac_f32_e32 v51, v74, v74
	v_cmp_lt_i32_e32 vcc, v48, v177
	v_fmac_f32_e32 v51, v76, v76
	v_fmac_f32_e32 v51, v77, v77
	v_cndmask_b32_e32 v48, v176, v48, vcc
	v_lshlrev_b32_e32 v105, 2, v48
	v_add_f32_e32 v50, v50, v51
	ds_bpermute_b32 v51, v105, v50
	v_xor_b32_e32 v49, 32, v176
	v_cmp_lt_i32_e32 vcc, v49, v177
	v_lshrrev_b32_e32 v48, 6, v65
	v_mul_lo_u32 v48, v48, s16
	v_cndmask_b32_e32 v49, v176, v49, vcc
	v_lshlrev_b32_e32 v104, 2, v49
	s_waitcnt lgkmcnt(0)
	v_add_f32_e32 v50, v50, v51
	ds_bpermute_b32 v51, v104, v50
	v_ashrrev_i32_e32 v49, 31, v48
	v_lshl_add_u64 v[48:49], s[26:27], 0, v[48:49]
	v_lshl_add_u64 v[48:49], v[62:63], 2, v[48:49]
	v_pk_mul_f32 v[52:53], v[76:77], v[150:151]
	v_pk_mul_f32 v[54:55], v[74:75], v[148:149]
	v_pk_add_f32 v[66:67], v[182:183], 1.0 op_sel_hi:[1,0]
	v_pk_add_f32 v[68:69], v[180:181], 1.0 op_sel_hi:[1,0]
	v_pk_mul_f32 v[52:53], v[52:53], v[66:67]
	v_pk_mul_f32 v[54:55], v[54:55], v[68:69]
	v_cvt_pk_bf16_f32 v53, v52, v53
	v_cvt_pk_bf16_f32 v52, v54, v55
	global_store_dwordx2 v[92:93], v[52:53], off offset:96
	s_and_saveexec_b64 s[24:25], s[36:37]
	s_cbranch_execz .LBB0_585
	s_waitcnt lgkmcnt(0)
	v_add_f32_e32 v50, v50, v51
	global_store_dword v[48:49], v50, off
.LBB0_585:
	s_or_b64 exec, exec, s[24:25]
	v_add_u32_e32 v50, 0xffffe010, v64
	v_or_b32_e32 v54, 16, v62
	v_lshrrev_b32_e32 v50, 10, v50
	s_movk_i32 s5, 0x1800
	s_movk_i32 s13, 0x1fff
	v_mad_u32_u24 v50, v50, s5, s5
	v_cmp_lt_i32_e32 vcc, s13, v54
	v_ashrrev_i32_e32 v55, 31, v54
	v_readlane_b32 s16, v250, 15
	v_cndmask_b32_e32 v50, 0, v50, vcc
	s_waitcnt lgkmcnt(0)
	v_ashrrev_i32_e32 v51, 31, v50
	v_lshlrev_b64 v[70:71], 2, v[50:51]
	v_lshl_add_u64 v[50:51], s[38:39], 0, v[70:71]
	v_lshl_add_u64 v[72:73], v[50:51], 0, v[60:61]
	v_lshlrev_b64 v[50:51], 12, v[54:55]
	v_readlane_b32 s17, v250, 16
	v_lshl_add_u64 v[70:71], s[40:41], 0, v[70:71]
	v_lshl_add_u64 v[70:71], v[70:71], 0, v[60:61]
	v_lshl_add_u64 v[50:51], s[16:17], 0, v[50:51]
	v_lshl_add_u64 v[74:75], v[50:51], 0, v[60:61]
	v_readlane_b32 s16, v250, 21
	v_lshlrev_b64 v[54:55], 11, v[54:55]
	v_readlane_b32 s17, v250, 22
	global_load_dwordx4 v[190:193], v[222:223], off
	global_load_dwordx4 v[194:197], v[222:223], off offset:64
	global_load_dwordx4 v[198:201], v[222:223], off offset:128
	global_load_dwordx4 v[202:205], v[222:223], off offset:192
	s_waitcnt vmcnt(20)
	v_pk_fma_f32 v[46:47], v[46:47], v[118:119], v[208:209]
	v_pk_fma_f32 v[44:45], v[44:45], v[116:117], v[206:207]
	global_store_dwordx4 v[74:75], v[44:47], off
	v_lshl_add_u64 v[54:55], s[16:17], 0, v[54:55]
	v_lshl_add_u64 v[54:55], v[58:59], 1, v[54:55]
	v_pk_mul_f32 v[52:53], v[46:47], v[138:139]
	v_pk_mul_f32 v[50:51], v[44:45], v[136:137]
	v_pk_add_f32 v[68:69], v[154:155], 1.0 op_sel_hi:[1,0]
	v_pk_add_f32 v[66:67], v[152:153], 1.0 op_sel_hi:[1,0]
	v_pk_mul_f32 v[52:53], v[52:53], v[68:69]
	v_pk_mul_f32 v[50:51], v[50:51], v[66:67]
	v_and_b32_sdwa v67, v51, v170 dst_sel:DWORD dst_unused:UNUSED_PAD src0_sel:WORD_1 src1_sel:DWORD
	v_and_b32_sdwa v65, v50, v170 dst_sel:DWORD dst_unused:UNUSED_PAD src0_sel:WORD_1 src1_sel:DWORD
	v_add3_u32 v51, v51, v67, s56
	v_add3_u32 v50, v50, v65, s56
	v_and_b32_e32 v63, 0xffff0000, v51
	v_cvt_pk_bf16_f32 v51, v52, v53
	v_or_b32_sdwa v50, v63, v50 dst_sel:DWORD dst_unused:UNUSED_PAD src0_sel:DWORD src1_sel:WORD_1
	global_store_dwordx2 v[54:55], v[50:51], off
	s_nop 0
	v_pk_fma_f32 v[42:43], v[42:43], v[122:123], v[212:213]
	v_pk_fma_f32 v[40:41], v[40:41], v[120:121], v[210:211]
	global_store_dwordx4 v[74:75], v[40:43], off offset:64
	v_pk_mul_f32 v[52:53], v[42:43], v[142:143]
	v_pk_mul_f32 v[50:51], v[40:41], v[140:141]
	v_pk_add_f32 v[68:69], v[158:159], 1.0 op_sel_hi:[1,0]
	v_pk_add_f32 v[66:67], v[156:157], 1.0 op_sel_hi:[1,0]
	v_pk_mul_f32 v[52:53], v[52:53], v[68:69]
	v_pk_mul_f32 v[50:51], v[50:51], v[66:67]
	v_and_b32_sdwa v67, v51, v170 dst_sel:DWORD dst_unused:UNUSED_PAD src0_sel:WORD_1 src1_sel:DWORD
	v_and_b32_sdwa v65, v50, v170 dst_sel:DWORD dst_unused:UNUSED_PAD src0_sel:WORD_1 src1_sel:DWORD
	v_add3_u32 v51, v51, v67, s56
	v_add3_u32 v50, v50, v65, s56
	v_and_b32_e32 v63, 0xffff0000, v51
	v_cvt_pk_bf16_f32 v51, v52, v53
	v_or_b32_sdwa v50, v63, v50 dst_sel:DWORD dst_unused:UNUSED_PAD src0_sel:DWORD src1_sel:WORD_1
	global_store_dwordx2 v[54:55], v[50:51], off offset:32
	s_nop 0
	v_pk_fma_f32 v[38:39], v[38:39], v[126:127], v[216:217]
	v_pk_fma_f32 v[36:37], v[36:37], v[124:125], v[214:215]
	global_store_dwordx4 v[74:75], v[36:39], off offset:128
	v_pk_mul_f32 v[52:53], v[38:39], v[146:147]
	v_pk_mul_f32 v[50:51], v[36:37], v[144:145]
	v_pk_add_f32 v[68:69], v[162:163], 1.0 op_sel_hi:[1,0]
	v_pk_add_f32 v[66:67], v[160:161], 1.0 op_sel_hi:[1,0]
	v_pk_mul_f32 v[52:53], v[52:53], v[68:69]
	v_pk_mul_f32 v[50:51], v[50:51], v[66:67]
	v_and_b32_sdwa v67, v51, v170 dst_sel:DWORD dst_unused:UNUSED_PAD src0_sel:WORD_1 src1_sel:DWORD
	v_and_b32_sdwa v65, v50, v170 dst_sel:DWORD dst_unused:UNUSED_PAD src0_sel:WORD_1 src1_sel:DWORD
	v_add3_u32 v51, v51, v67, s56
	v_add3_u32 v50, v50, v65, s56
	v_and_b32_e32 v63, 0xffff0000, v51
	v_cvt_pk_bf16_f32 v51, v52, v53
	v_or_b32_sdwa v50, v63, v50 dst_sel:DWORD dst_unused:UNUSED_PAD src0_sel:DWORD src1_sel:WORD_1
	global_store_dwordx2 v[54:55], v[50:51], off offset:64
	s_nop 0
	v_pk_fma_f32 v[52:53], v[34:35], v[134:135], v[220:221]
	v_pk_fma_f32 v[50:51], v[32:33], v[132:133], v[218:219]
	global_store_dwordx4 v[74:75], v[50:53], off offset:192
	s_nop 0
	v_mul_f32_e32 v32, v45, v45
	v_mul_f32_e32 v33, v41, v41
	v_fmac_f32_e32 v32, v44, v44
	v_fmac_f32_e32 v33, v40, v40
	v_fmac_f32_e32 v32, v46, v46
	v_fmac_f32_e32 v33, v42, v42
	v_fmac_f32_e32 v32, v47, v47
	v_fmac_f32_e32 v33, v43, v43
	v_add_f32_e32 v32, v32, v33
	v_mul_f32_e32 v33, v37, v37
	v_fmac_f32_e32 v33, v36, v36
	v_fmac_f32_e32 v33, v38, v38
	v_fmac_f32_e32 v33, v39, v39
	v_add_f32_e32 v32, v32, v33
	v_mul_f32_e32 v33, v51, v51
	v_fmac_f32_e32 v33, v50, v50
	v_fmac_f32_e32 v33, v52, v52
	v_fmac_f32_e32 v33, v53, v53
	v_add_f32_e32 v32, v32, v33
	ds_bpermute_b32 v33, v105, v32
	s_waitcnt lgkmcnt(0)
	v_add_f32_e32 v32, v32, v33
	ds_bpermute_b32 v33, v104, v32
	v_pk_mul_f32 v[34:35], v[52:53], v[150:151]
	v_pk_mul_f32 v[36:37], v[50:51], v[148:149]
	v_pk_add_f32 v[38:39], v[182:183], 1.0 op_sel_hi:[1,0]
	v_pk_add_f32 v[40:41], v[180:181], 1.0 op_sel_hi:[1,0]
	v_pk_mul_f32 v[34:35], v[34:35], v[38:39]
	v_pk_mul_f32 v[36:37], v[36:37], v[40:41]
	v_cvt_pk_bf16_f32 v35, v34, v35
	v_cvt_pk_bf16_f32 v34, v36, v37
	global_store_dwordx2 v[54:55], v[34:35], off offset:96
	s_and_saveexec_b64 s[24:25], s[36:37]
	s_cbranch_execz .LBB0_587
	s_waitcnt lgkmcnt(0)
	v_add_f32_e32 v32, v32, v33
	global_store_dword v[48:49], v32, off offset:64
.LBB0_587:
	s_or_b64 exec, exec, s[24:25]
	v_add_u32_e32 v32, 0xffffe020, v64
	v_or_b32_e32 v40, 32, v62
	v_lshrrev_b32_e32 v32, 10, v32
	v_mad_u32_u24 v32, v32, s5, s5
	v_cmp_lt_i32_e32 vcc, s13, v40
	v_ashrrev_i32_e32 v41, 31, v40
	v_readlane_b32 s16, v250, 15
	v_cndmask_b32_e32 v32, 0, v32, vcc
	s_waitcnt lgkmcnt(0)
	v_ashrrev_i32_e32 v33, 31, v32
	v_lshlrev_b64 v[42:43], 2, v[32:33]
	v_lshl_add_u64 v[32:33], s[38:39], 0, v[42:43]
	v_lshl_add_u64 v[44:45], v[32:33], 0, v[60:61]
	v_lshlrev_b64 v[32:33], 12, v[40:41]
	v_readlane_b32 s17, v250, 16
	v_lshl_add_u64 v[42:43], s[40:41], 0, v[42:43]
	v_lshl_add_u64 v[42:43], v[42:43], 0, v[60:61]
	v_lshl_add_u64 v[32:33], s[16:17], 0, v[32:33]
	v_lshl_add_u64 v[46:47], v[32:33], 0, v[60:61]
	v_readlane_b32 s16, v250, 21
	v_lshlrev_b64 v[40:41], 11, v[40:41]
	v_readlane_b32 s17, v250, 22
	global_load_dwordx4 v[206:209], v[224:225], off
	global_load_dwordx4 v[210:213], v[224:225], off offset:64
	global_load_dwordx4 v[214:217], v[224:225], off offset:128
	global_load_dwordx4 v[218:221], v[224:225], off offset:192
	s_waitcnt vmcnt(12)
	v_pk_fma_f32 v[30:31], v[30:31], v[118:119], v[192:193]
	v_pk_fma_f32 v[28:29], v[28:29], v[116:117], v[190:191]
	global_store_dwordx4 v[46:47], v[28:31], off
	v_lshl_add_u64 v[40:41], s[16:17], 0, v[40:41]
	v_lshl_add_u64 v[50:51], v[58:59], 1, v[40:41]
	v_pk_mul_f32 v[34:35], v[30:31], v[138:139]
	v_pk_mul_f32 v[32:33], v[28:29], v[136:137]
	v_pk_add_f32 v[38:39], v[154:155], 1.0 op_sel_hi:[1,0]
	v_pk_add_f32 v[36:37], v[152:153], 1.0 op_sel_hi:[1,0]
	v_pk_mul_f32 v[34:35], v[34:35], v[38:39]
	v_pk_mul_f32 v[32:33], v[32:33], v[36:37]
	v_and_b32_sdwa v39, v33, v170 dst_sel:DWORD dst_unused:UNUSED_PAD src0_sel:WORD_1 src1_sel:DWORD
	v_and_b32_sdwa v37, v32, v170 dst_sel:DWORD dst_unused:UNUSED_PAD src0_sel:WORD_1 src1_sel:DWORD
	v_add3_u32 v33, v33, v39, s56
	v_add3_u32 v32, v32, v37, s56
	v_and_b32_e32 v36, 0xffff0000, v33
	v_cvt_pk_bf16_f32 v33, v34, v35
	v_or_b32_sdwa v32, v36, v32 dst_sel:DWORD dst_unused:UNUSED_PAD src0_sel:DWORD src1_sel:WORD_1
	global_store_dwordx2 v[50:51], v[32:33], off
	s_nop 0
	v_pk_fma_f32 v[26:27], v[26:27], v[122:123], v[196:197]
	v_pk_fma_f32 v[24:25], v[24:25], v[120:121], v[194:195]
	global_store_dwordx4 v[46:47], v[24:27], off offset:64
	v_pk_mul_f32 v[34:35], v[26:27], v[142:143]
	v_pk_mul_f32 v[32:33], v[24:25], v[140:141]
	v_pk_add_f32 v[38:39], v[158:159], 1.0 op_sel_hi:[1,0]
	v_pk_add_f32 v[36:37], v[156:157], 1.0 op_sel_hi:[1,0]
	v_pk_mul_f32 v[34:35], v[34:35], v[38:39]
	v_pk_mul_f32 v[32:33], v[32:33], v[36:37]
	v_and_b32_sdwa v39, v33, v170 dst_sel:DWORD dst_unused:UNUSED_PAD src0_sel:WORD_1 src1_sel:DWORD
	v_and_b32_sdwa v37, v32, v170 dst_sel:DWORD dst_unused:UNUSED_PAD src0_sel:WORD_1 src1_sel:DWORD
	v_add3_u32 v33, v33, v39, s56
	v_add3_u32 v32, v32, v37, s56
	v_and_b32_e32 v36, 0xffff0000, v33
	v_cvt_pk_bf16_f32 v33, v34, v35
	v_or_b32_sdwa v32, v36, v32 dst_sel:DWORD dst_unused:UNUSED_PAD src0_sel:DWORD src1_sel:WORD_1
	global_store_dwordx2 v[50:51], v[32:33], off offset:32
	s_nop 0
	v_pk_fma_f32 v[22:23], v[22:23], v[126:127], v[200:201]
	v_pk_fma_f32 v[20:21], v[20:21], v[124:125], v[198:199]
	global_store_dwordx4 v[46:47], v[20:23], off offset:128
	v_pk_mul_f32 v[34:35], v[22:23], v[146:147]
	v_pk_mul_f32 v[32:33], v[20:21], v[144:145]
	v_pk_add_f32 v[38:39], v[162:163], 1.0 op_sel_hi:[1,0]
	v_pk_add_f32 v[36:37], v[160:161], 1.0 op_sel_hi:[1,0]
	v_pk_mul_f32 v[34:35], v[34:35], v[38:39]
	v_pk_mul_f32 v[32:33], v[32:33], v[36:37]
	v_and_b32_sdwa v39, v33, v170 dst_sel:DWORD dst_unused:UNUSED_PAD src0_sel:WORD_1 src1_sel:DWORD
	v_and_b32_sdwa v37, v32, v170 dst_sel:DWORD dst_unused:UNUSED_PAD src0_sel:WORD_1 src1_sel:DWORD
	v_add3_u32 v33, v33, v39, s56
	v_add3_u32 v32, v32, v37, s56
	v_and_b32_e32 v36, 0xffff0000, v33
	v_cvt_pk_bf16_f32 v33, v34, v35
	v_or_b32_sdwa v32, v36, v32 dst_sel:DWORD dst_unused:UNUSED_PAD src0_sel:DWORD src1_sel:WORD_1
	global_store_dwordx2 v[50:51], v[32:33], off offset:64
	s_nop 0
	v_pk_fma_f32 v[34:35], v[18:19], v[134:135], v[204:205]
	v_pk_fma_f32 v[32:33], v[16:17], v[132:133], v[202:203]
	global_store_dwordx4 v[46:47], v[32:35], off offset:192
	s_nop 0
	v_mul_f32_e32 v16, v29, v29
	v_mul_f32_e32 v17, v25, v25
	v_fmac_f32_e32 v16, v28, v28
	v_fmac_f32_e32 v17, v24, v24
	v_fmac_f32_e32 v16, v30, v30
	v_fmac_f32_e32 v17, v26, v26
	v_fmac_f32_e32 v16, v31, v31
	v_fmac_f32_e32 v17, v27, v27
	v_add_f32_e32 v16, v16, v17
	v_mul_f32_e32 v17, v21, v21
	v_fmac_f32_e32 v17, v20, v20
	v_fmac_f32_e32 v17, v22, v22
	v_fmac_f32_e32 v17, v23, v23
	v_add_f32_e32 v16, v16, v17
	v_mul_f32_e32 v17, v33, v33
	v_fmac_f32_e32 v17, v32, v32
	v_fmac_f32_e32 v17, v34, v34
	v_fmac_f32_e32 v17, v35, v35
	v_add_f32_e32 v16, v16, v17
	ds_bpermute_b32 v17, v105, v16
	s_waitcnt lgkmcnt(0)
	v_add_f32_e32 v16, v16, v17
	ds_bpermute_b32 v17, v104, v16
	v_pk_mul_f32 v[18:19], v[34:35], v[150:151]
	v_pk_mul_f32 v[20:21], v[32:33], v[148:149]
	v_pk_add_f32 v[22:23], v[182:183], 1.0 op_sel_hi:[1,0]
	v_pk_add_f32 v[24:25], v[180:181], 1.0 op_sel_hi:[1,0]
	v_pk_mul_f32 v[18:19], v[18:19], v[22:23]
	v_pk_mul_f32 v[20:21], v[20:21], v[24:25]
	v_cvt_pk_bf16_f32 v19, v18, v19
	v_cvt_pk_bf16_f32 v18, v20, v21
	global_store_dwordx2 v[50:51], v[18:19], off offset:96
	s_and_saveexec_b64 s[24:25], s[36:37]
	s_movk_i32 s8, 0x400
	s_mov_b32 s5, 0xffff0000
	s_mov_b32 s9, 0x12000
	s_movk_i32 s89, 0xff
	s_cbranch_execz .LBB0_589
	s_waitcnt lgkmcnt(0)
	v_add_f32_e32 v16, v16, v17
	global_store_dword v[48:49], v16, off offset:128
.LBB0_589:
	s_or_b64 exec, exec, s[24:25]
	v_add_u32_e32 v16, 0xffffe030, v64
	v_or_b32_e32 v24, 48, v62
	v_lshrrev_b32_e32 v16, 10, v16
	s_movk_i32 s16, 0x1800
	v_mad_u32_u24 v16, v16, s16, s16
	v_cmp_lt_i32_e32 vcc, s13, v24
	v_ashrrev_i32_e32 v25, 31, v24
	v_readlane_b32 s16, v250, 15
	v_cndmask_b32_e32 v16, 0, v16, vcc
	s_waitcnt lgkmcnt(0)
	v_ashrrev_i32_e32 v17, 31, v16
	v_lshlrev_b64 v[26:27], 2, v[16:17]
	v_lshl_add_u64 v[16:17], s[38:39], 0, v[26:27]
	v_lshl_add_u64 v[28:29], v[16:17], 0, v[60:61]
	v_lshlrev_b64 v[16:17], 12, v[24:25]
	v_readlane_b32 s17, v250, 16
	v_lshl_add_u64 v[26:27], s[40:41], 0, v[26:27]
	v_lshl_add_u64 v[26:27], v[26:27], 0, v[60:61]
	v_lshl_add_u64 v[16:17], s[16:17], 0, v[16:17]
	v_lshl_add_u64 v[30:31], v[16:17], 0, v[60:61]
	v_readlane_b32 s16, v250, 21
	v_lshlrev_b64 v[24:25], 11, v[24:25]
	v_readlane_b32 s17, v250, 22
	s_waitcnt vmcnt(8)
	v_pk_fma_f32 v[14:15], v[14:15], v[118:119], v[208:209]
	v_pk_fma_f32 v[12:13], v[12:13], v[116:117], v[206:207]
	global_store_dwordx4 v[30:31], v[12:15], off
	v_lshl_add_u64 v[24:25], s[16:17], 0, v[24:25]
	v_lshl_add_u64 v[32:33], v[58:59], 1, v[24:25]
	v_pk_mul_f32 v[18:19], v[14:15], v[138:139]
	v_pk_mul_f32 v[16:17], v[12:13], v[136:137]
	v_pk_add_f32 v[22:23], v[154:155], 1.0 op_sel_hi:[1,0]
	v_pk_add_f32 v[20:21], v[152:153], 1.0 op_sel_hi:[1,0]
	v_pk_mul_f32 v[18:19], v[18:19], v[22:23]
	v_pk_mul_f32 v[16:17], v[16:17], v[20:21]
	v_and_b32_sdwa v23, v17, v170 dst_sel:DWORD dst_unused:UNUSED_PAD src0_sel:WORD_1 src1_sel:DWORD
	v_and_b32_sdwa v21, v16, v170 dst_sel:DWORD dst_unused:UNUSED_PAD src0_sel:WORD_1 src1_sel:DWORD
	v_add3_u32 v17, v17, v23, s56
	v_add3_u32 v16, v16, v21, s56
	v_and_b32_e32 v20, 0xffff0000, v17
	v_cvt_pk_bf16_f32 v17, v18, v19
	v_or_b32_sdwa v16, v20, v16 dst_sel:DWORD dst_unused:UNUSED_PAD src0_sel:DWORD src1_sel:WORD_1
	global_store_dwordx2 v[32:33], v[16:17], off
	s_nop 0
	v_pk_fma_f32 v[10:11], v[10:11], v[122:123], v[212:213]
	v_pk_fma_f32 v[8:9], v[8:9], v[120:121], v[210:211]
	global_store_dwordx4 v[30:31], v[8:11], off offset:64
	v_pk_mul_f32 v[18:19], v[10:11], v[142:143]
	v_pk_mul_f32 v[16:17], v[8:9], v[140:141]
	v_pk_add_f32 v[22:23], v[158:159], 1.0 op_sel_hi:[1,0]
	v_pk_add_f32 v[20:21], v[156:157], 1.0 op_sel_hi:[1,0]
	v_pk_mul_f32 v[18:19], v[18:19], v[22:23]
	v_pk_mul_f32 v[16:17], v[16:17], v[20:21]
	v_and_b32_sdwa v23, v17, v170 dst_sel:DWORD dst_unused:UNUSED_PAD src0_sel:WORD_1 src1_sel:DWORD
	v_and_b32_sdwa v21, v16, v170 dst_sel:DWORD dst_unused:UNUSED_PAD src0_sel:WORD_1 src1_sel:DWORD
	v_add3_u32 v17, v17, v23, s56
	v_add3_u32 v16, v16, v21, s56
	v_and_b32_e32 v20, 0xffff0000, v17
	v_cvt_pk_bf16_f32 v17, v18, v19
	v_or_b32_sdwa v16, v20, v16 dst_sel:DWORD dst_unused:UNUSED_PAD src0_sel:DWORD src1_sel:WORD_1
	global_store_dwordx2 v[32:33], v[16:17], off offset:32
	s_nop 0
	v_pk_fma_f32 v[6:7], v[6:7], v[126:127], v[216:217]
	v_pk_fma_f32 v[4:5], v[4:5], v[124:125], v[214:215]
	global_store_dwordx4 v[30:31], v[4:7], off offset:128
	v_pk_mul_f32 v[18:19], v[6:7], v[146:147]
	v_pk_mul_f32 v[16:17], v[4:5], v[144:145]
	v_pk_add_f32 v[22:23], v[162:163], 1.0 op_sel_hi:[1,0]
	v_pk_add_f32 v[20:21], v[160:161], 1.0 op_sel_hi:[1,0]
	v_pk_mul_f32 v[18:19], v[18:19], v[22:23]
	v_pk_mul_f32 v[16:17], v[16:17], v[20:21]
	v_and_b32_sdwa v23, v17, v170 dst_sel:DWORD dst_unused:UNUSED_PAD src0_sel:WORD_1 src1_sel:DWORD
	v_and_b32_sdwa v21, v16, v170 dst_sel:DWORD dst_unused:UNUSED_PAD src0_sel:WORD_1 src1_sel:DWORD
	v_add3_u32 v17, v17, v23, s56
	v_add3_u32 v16, v16, v21, s56
	v_and_b32_e32 v20, 0xffff0000, v17
	v_cvt_pk_bf16_f32 v17, v18, v19
	v_or_b32_sdwa v16, v20, v16 dst_sel:DWORD dst_unused:UNUSED_PAD src0_sel:DWORD src1_sel:WORD_1
	global_store_dwordx2 v[32:33], v[16:17], off offset:64
	s_nop 0
	v_pk_fma_f32 v[18:19], v[2:3], v[134:135], v[220:221]
	v_pk_fma_f32 v[16:17], v[0:1], v[132:133], v[218:219]
	global_store_dwordx4 v[30:31], v[16:19], off offset:192
	s_nop 0
	v_mul_f32_e32 v0, v13, v13
	v_mul_f32_e32 v1, v9, v9
	v_fmac_f32_e32 v0, v12, v12
	v_fmac_f32_e32 v1, v8, v8
	v_fmac_f32_e32 v0, v14, v14
	v_fmac_f32_e32 v1, v10, v10
	v_fmac_f32_e32 v0, v15, v15
	v_fmac_f32_e32 v1, v11, v11
	v_add_f32_e32 v0, v0, v1
	v_mul_f32_e32 v1, v5, v5
	v_fmac_f32_e32 v1, v4, v4
	v_fmac_f32_e32 v1, v6, v6
	v_fmac_f32_e32 v1, v7, v7
	v_add_f32_e32 v0, v0, v1
	v_mul_f32_e32 v1, v17, v17
	v_fmac_f32_e32 v1, v16, v16
	v_fmac_f32_e32 v1, v18, v18
	v_fmac_f32_e32 v1, v19, v19
	v_add_f32_e32 v0, v0, v1
	ds_bpermute_b32 v1, v105, v0
	s_waitcnt lgkmcnt(0)
	v_add_f32_e32 v0, v0, v1
	ds_bpermute_b32 v1, v104, v0
	v_pk_mul_f32 v[2:3], v[18:19], v[150:151]
	v_pk_mul_f32 v[4:5], v[16:17], v[148:149]
	v_pk_add_f32 v[6:7], v[182:183], 1.0 op_sel_hi:[1,0]
	v_pk_add_f32 v[8:9], v[180:181], 1.0 op_sel_hi:[1,0]
	v_pk_mul_f32 v[2:3], v[2:3], v[6:7]
	v_pk_mul_f32 v[4:5], v[4:5], v[8:9]
	v_cvt_pk_bf16_f32 v3, v2, v3
	v_cvt_pk_bf16_f32 v2, v4, v5
	global_store_dwordx2 v[32:33], v[2:3], off offset:96
	s_and_saveexec_b64 s[24:25], s[36:37]
	s_cbranch_execz .LBB0_591
	s_waitcnt lgkmcnt(0)
	v_add_f32_e32 v0, v0, v1
	global_store_dword v[48:49], v0, off offset:192

.Ltail596:
	s_add_i32 s29, s42, 2
	ds_read_b128 v[136:139], v111 offset:16384
	ds_read_b128 v[140:143], v111 offset:18432
	ds_read_b128 v[144:147], v111 offset:20480
	ds_read_b128 v[148:151], v111 offset:22528
	ds_read_b128 v[116:119], v110
	s_add_i32 s42, s42, 4
	ds_read_b128 v[120:123], v110 offset:2048
	s_min_u32 s42, s42, 63
	s_lshl_b32 s92, s42, 7
	ds_read_b128 v[124:127], v110 offset:4096
	ds_read_b128 v[194:197], v113 offset:16384
	ds_read_b128 v[198:201], v113 offset:18432
	ds_read_b128 v[202:205], v113 offset:20480
	ds_read_b128 v[206:209], v113 offset:22528
	v_lshl_add_u64 v[164:165], v[100:101], 0, s[92:93]
	ds_read_b128 v[132:135], v110 offset:6144
	ds_read_b128 v[152:155], v112
	ds_read_b128 v[156:159], v112 offset:2048
	ds_read_b128 v[160:163], v112 offset:4096
	ds_read_b128 v[190:193], v112 offset:6144
	s_waitcnt lgkmcnt(11)
	v_mfma_f32_16x16x32_bf16 v[92:95], v[136:139], v[116:119], v[92:95]
	v_mfma_f32_16x16x32_bf16 v[88:91], v[140:143], v[116:119], v[88:91]
	v_mfma_f32_16x16x32_bf16 v[56:59], v[144:147], v[116:119], v[56:59]
	v_mfma_f32_16x16x32_bf16 v[48:51], v[148:151], v[116:119], v[48:51]
	s_waitcnt vmcnt(7)
	ds_write_b128 v109, v[52:55] offset:32768
	v_add_co_u32_e32 v52, vcc, s7, v164
	s_waitcnt lgkmcnt(11)
	v_mfma_f32_16x16x32_bf16 v[44:47], v[136:139], v[120:123], v[44:47]
	v_addc_co_u32_e32 v53, vcc, 0, v165, vcc
	v_mfma_f32_16x16x32_bf16 v[40:43], v[140:143], v[120:123], v[40:43]
	v_mfma_f32_16x16x32_bf16 v[36:39], v[144:147], v[120:123], v[36:39]
	v_mfma_f32_16x16x32_bf16 v[32:35], v[148:151], v[120:123], v[32:35]
	v_add_co_u32_e32 v52, vcc, s52, v164
	s_waitcnt vmcnt(6)
	ds_write_b128 v109, v[60:63] offset:36864
	s_nop 0
	v_addc_co_u32_e32 v53, vcc, 0, v165, vcc
	s_waitcnt lgkmcnt(11)
	v_mfma_f32_16x16x32_bf16 v[28:31], v[136:139], v[124:127], v[28:31]
	v_mfma_f32_16x16x32_bf16 v[24:27], v[140:143], v[124:127], v[24:27]
	v_mfma_f32_16x16x32_bf16 v[20:23], v[144:147], v[124:127], v[20:23]
	v_mfma_f32_16x16x32_bf16 v[16:19], v[148:151], v[124:127], v[16:19]
	v_add_co_u32_e32 v52, vcc, s34, v164
	s_waitcnt vmcnt(5)
	ds_write_b128 v109, v[64:67] offset:40960
	s_nop 0
	v_addc_co_u32_e32 v53, vcc, 0, v165, vcc
	v_lshl_add_u64 v[64:65], v[102:103], 0, s[92:93]
	v_add_co_u32_e32 v66, vcc, s7, v64
	s_waitcnt lgkmcnt(7)
	v_mfma_f32_16x16x32_bf16 v[12:15], v[136:139], v[132:135], v[12:15]
	v_addc_co_u32_e32 v67, vcc, 0, v65, vcc
	v_mfma_f32_16x16x32_bf16 v[8:11], v[140:143], v[132:135], v[8:11]
	v_mfma_f32_16x16x32_bf16 v[4:7], v[144:147], v[132:135], v[4:7]
	v_mfma_f32_16x16x32_bf16 v[0:3], v[148:151], v[132:135], v[0:3]
	s_waitcnt vmcnt(4)
	ds_write_b128 v109, v[72:75] offset:45056
	s_waitcnt lgkmcnt(7)
	v_mfma_f32_16x16x32_bf16 v[52:55], v[194:197], v[152:155], v[92:95]
	v_mfma_f32_16x16x32_bf16 v[60:63], v[198:201], v[152:155], v[88:91]
	v_mfma_f32_16x16x32_bf16 v[56:59], v[202:205], v[152:155], v[56:59]
	v_mfma_f32_16x16x32_bf16 v[48:51], v[206:209], v[152:155], v[48:51]
	s_waitcnt vmcnt(3)
	ds_write_b128 v109, v[68:71] offset:49152
	s_waitcnt lgkmcnt(7)
	v_mfma_f32_16x16x32_bf16 v[44:47], v[194:197], v[156:159], v[44:47]
	v_mfma_f32_16x16x32_bf16 v[40:43], v[198:201], v[156:159], v[40:43]
	v_mfma_f32_16x16x32_bf16 v[36:39], v[202:205], v[156:159], v[36:39]
	v_mfma_f32_16x16x32_bf16 v[32:35], v[206:209], v[156:159], v[32:35]
	v_add_co_u32_e32 v66, vcc, s52, v64
	s_waitcnt vmcnt(2)
	ds_write_b128 v109, v[76:79] offset:53248
	v_addc_co_u32_e32 v67, vcc, 0, v65, vcc
	v_add_co_u32_e32 v64, vcc, s34, v64
	s_waitcnt lgkmcnt(7)
	v_mfma_f32_16x16x32_bf16 v[28:31], v[194:197], v[160:163], v[28:31]
	v_addc_co_u32_e32 v65, vcc, 0, v65, vcc
	v_mfma_f32_16x16x32_bf16 v[24:27], v[198:201], v[160:163], v[24:27]
	v_mfma_f32_16x16x32_bf16 v[20:23], v[202:205], v[160:163], v[20:23]
	v_mfma_f32_16x16x32_bf16 v[16:19], v[206:209], v[160:163], v[16:19]
	s_waitcnt vmcnt(1)
	ds_write_b128 v109, v[80:83] offset:57344
	s_waitcnt lgkmcnt(7)
	v_mfma_f32_16x16x32_bf16 v[12:15], v[194:197], v[190:193], v[12:15]
	v_mfma_f32_16x16x32_bf16 v[8:11], v[198:201], v[190:193], v[8:11]
	v_mfma_f32_16x16x32_bf16 v[4:7], v[202:205], v[190:193], v[4:7]
	v_mfma_f32_16x16x32_bf16 v[0:3], v[206:209], v[190:193], v[0:3]
	s_waitcnt vmcnt(0)
	ds_write_b128 v109, v[84:87] offset:61440
	s_waitcnt lgkmcnt(0)
	s_barrier
	ds_read_b128 v[84:87], v111 offset:51200
	ds_read_b128 v[80:83], v111 offset:49152
	ds_read_b128 v[88:91], v111 offset:53248
	ds_read_b128 v[92:95], v111 offset:55296
	ds_read_b128 v[64:67], v110 offset:32768
	s_min_u32 s42, s29, 60
	s_lshl_b32 s92, s42, 7
	ds_read_b128 v[68:71], v110 offset:34816
	v_lshl_add_u64 v[164:165], v[100:101], 0, s[92:93]
	ds_read_b128 v[72:75], v110 offset:36864
	ds_read_b128 v[76:79], v110 offset:38912
	ds_read_b128 v[152:155], v112 offset:32768
	ds_read_b128 v[156:159], v112 offset:34816
	ds_read_b128 v[160:163], v112 offset:36864
	ds_read_b128 v[190:193], v112 offset:38912
	ds_read_b128 v[194:197], v113 offset:49152
	ds_read_b128 v[198:201], v113 offset:51200
	ds_read_b128 v[202:205], v113 offset:53248
	ds_read_b128 v[206:209], v113 offset:55296
	s_waitcnt lgkmcnt(11)
	v_mfma_f32_16x16x32_bf16 v[214:217], v[84:87], v[64:67], v[60:63]
	v_mfma_f32_16x16x32_bf16 v[210:213], v[80:83], v[64:67], v[52:55]
	s_nop 1
	v_add_co_u32_e32 v60, vcc, s7, v164
	s_nop 1
	v_addc_co_u32_e32 v61, vcc, 0, v165, vcc
	v_mfma_f32_16x16x32_bf16 v[56:59], v[88:91], v[64:67], v[56:59]
	v_mfma_f32_16x16x32_bf16 v[48:51], v[92:95], v[64:67], v[48:51]
	v_add_co_u32_e32 v64, vcc, s52, v164
	s_nop 0
	v_addc_co_u32_e32 v65, vcc, 0, v165, vcc
	s_waitcnt lgkmcnt(10)
	v_mfma_f32_16x16x32_bf16 v[44:47], v[80:83], v[68:71], v[44:47]
	v_mfma_f32_16x16x32_bf16 v[40:43], v[84:87], v[68:71], v[40:43]
	v_mfma_f32_16x16x32_bf16 v[36:39], v[88:91], v[68:71], v[36:39]
	v_mfma_f32_16x16x32_bf16 v[32:35], v[92:95], v[68:71], v[32:35]
	v_add_co_u32_e32 v68, vcc, s34, v164
	s_waitcnt lgkmcnt(9)
	v_mfma_f32_16x16x32_bf16 v[28:31], v[80:83], v[72:75], v[28:31]
	v_addc_co_u32_e32 v69, vcc, 0, v165, vcc
	v_mfma_f32_16x16x32_bf16 v[24:27], v[84:87], v[72:75], v[24:27]
	v_mfma_f32_16x16x32_bf16 v[20:23], v[88:91], v[72:75], v[20:23]
	v_mfma_f32_16x16x32_bf16 v[16:19], v[92:95], v[72:75], v[16:19]
	s_waitcnt lgkmcnt(8)
	v_mfma_f32_16x16x32_bf16 v[8:11], v[84:87], v[76:79], v[8:11]
	v_lshl_add_u64 v[84:85], v[102:103], 0, s[92:93]
	v_mfma_f32_16x16x32_bf16 v[12:15], v[80:83], v[76:79], v[12:15]
	v_mfma_f32_16x16x32_bf16 v[4:7], v[88:91], v[76:79], v[4:7]
	v_mfma_f32_16x16x32_bf16 v[0:3], v[92:95], v[76:79], v[0:3]
	v_add_co_u32_e32 v76, vcc, s7, v84
	s_nop 0
	v_addc_co_u32_e32 v77, vcc, 0, v85, vcc
	v_add_co_u32_e32 v80, vcc, s52, v84
	v_addc_co_u32_e32 v81, vcc, 0, v85, vcc
	s_waitcnt lgkmcnt(3)
	v_mfma_f32_16x16x32_bf16 v[92:95], v[194:197], v[152:155], v[210:213]
	s_waitcnt lgkmcnt(2)
	v_mfma_f32_16x16x32_bf16 v[88:91], v[198:201], v[152:155], v[214:217]
	s_waitcnt lgkmcnt(1)
	v_mfma_f32_16x16x32_bf16 v[56:59], v[202:205], v[152:155], v[56:59]
	s_waitcnt lgkmcnt(0)
	v_mfma_f32_16x16x32_bf16 v[48:51], v[206:209], v[152:155], v[48:51]
	v_add_co_u32_e32 v84, vcc, s34, v84
	v_addc_co_u32_e32 v85, vcc, 0, v85, vcc
	v_mfma_f32_16x16x32_bf16 v[44:47], v[194:197], v[156:159], v[44:47]
	v_mfma_f32_16x16x32_bf16 v[40:43], v[198:201], v[156:159], v[40:43]
	v_mfma_f32_16x16x32_bf16 v[36:39], v[202:205], v[156:159], v[36:39]
	v_mfma_f32_16x16x32_bf16 v[32:35], v[206:209], v[156:159], v[32:35]
	v_mfma_f32_16x16x32_bf16 v[28:31], v[194:197], v[160:163], v[28:31]
	v_mfma_f32_16x16x32_bf16 v[24:27], v[198:201], v[160:163], v[24:27]
	v_mfma_f32_16x16x32_bf16 v[20:23], v[202:205], v[160:163], v[20:23]
	v_mfma_f32_16x16x32_bf16 v[16:19], v[206:209], v[160:163], v[16:19]
	v_mfma_f32_16x16x32_bf16 v[12:15], v[194:197], v[190:193], v[12:15]
	v_mfma_f32_16x16x32_bf16 v[8:11], v[198:201], v[190:193], v[8:11]
	v_mfma_f32_16x16x32_bf16 v[4:7], v[202:205], v[190:193], v[4:7]
	v_mfma_f32_16x16x32_bf16 v[0:3], v[206:209], v[190:193], v[0:3]
	s_mov_b32 s42, s29
	s_waitcnt lgkmcnt(0)
	s_barrier
	s_waitcnt vmcnt(5)
	v_add_u32_e32 v64, s24, v108
	v_add_u32_e32 v52, 0xffffe000, v64
	v_or_b32_e32 v62, v64, v107
	v_lshrrev_b32_e32 v52, 10, v52
	s_movk_i32 s16, 0x1800
	v_mad_u32_u24 v52, v52, s16, s16
	v_cmp_lt_i32_e32 vcc, s13, v62
	v_or_b32_e32 v65, s25, v114
	v_or_b32_e32 v54, v65, v115
	v_cndmask_b32_e32 v52, 0, v52, vcc
	v_ashrrev_i32_e32 v53, 31, v52
	s_waitcnt vmcnt(4)
	v_lshlrev_b64 v[74:75], 2, v[52:53]
	v_ashrrev_i32_e32 v55, 31, v54
	v_ashrrev_i32_e32 v63, 31, v62
	v_lshl_add_u64 v[52:53], s[38:39], 0, v[74:75]
	v_lshlrev_b64 v[60:61], 2, v[54:55]
	v_readlane_b32 s16, v250, 15
	s_waitcnt vmcnt(1)
	v_lshl_add_u64 v[82:83], v[52:53], 0, v[60:61]
	v_lshlrev_b64 v[52:53], 12, v[62:63]
	v_readlane_b32 s17, v250, 16
	v_lshl_add_u64 v[74:75], s[40:41], 0, v[74:75]
	s_waitcnt vmcnt(0)
	v_lshl_add_u64 v[86:87], v[74:75], 0, v[60:61]
	v_lshl_add_u64 v[52:53], s[16:17], 0, v[52:53]
	v_lshl_add_u64 v[84:85], v[52:53], 0, v[60:61]
	global_load_dwordx4 v[66:69], v[82:83], off
	global_load_dwordx4 v[70:73], v[84:85], off
	v_lshl_add_u64 v[52:53], s[0:1], 0, v[60:61]
	v_readlane_b32 s16, v250, 21
	v_lshlrev_b64 v[78:79], 11, v[62:63]
	v_readlane_b32 s17, v250, 22
	s_waitcnt vmcnt(0)
	v_pk_fma_f32 v[68:69], v[94:95], v[68:69], v[72:73]
	v_pk_fma_f32 v[66:67], v[92:93], v[66:67], v[70:71]
	global_store_dwordx4 v[84:85], v[66:69], off
	global_load_dwordx4 v[70:73], v[52:53], off
	global_load_dwordx4 v[74:77], v[86:87], off
	v_lshl_add_u64 v[78:79], s[16:17], 0, v[78:79]
	v_lshl_add_u64 v[92:93], v[54:55], 1, v[78:79]
	s_mov_b32 s16, 0xa000
	s_waitcnt vmcnt(1)
	v_pk_mul_f32 v[72:73], v[68:69], v[72:73]
	v_pk_mul_f32 v[70:71], v[66:67], v[70:71]
	s_waitcnt vmcnt(0)
	v_pk_add_f32 v[76:77], v[76:77], 1.0 op_sel_hi:[1,0]
	v_pk_add_f32 v[74:75], v[74:75], 1.0 op_sel_hi:[1,0]
	v_pk_mul_f32 v[72:73], v[72:73], v[76:77]
	v_pk_mul_f32 v[70:71], v[70:71], v[74:75]
	v_and_b32_sdwa v77, v71, v170 dst_sel:DWORD dst_unused:UNUSED_PAD src0_sel:WORD_1 src1_sel:DWORD
	v_and_b32_sdwa v75, v70, v170 dst_sel:DWORD dst_unused:UNUSED_PAD src0_sel:WORD_1 src1_sel:DWORD
	v_add3_u32 v71, v71, v77, s56
	v_add3_u32 v70, v70, v75, s56
	v_and_b32_e32 v74, 0xffff0000, v71
	v_cvt_pk_bf16_f32 v71, v72, v73
	v_or_b32_sdwa v70, v74, v70 dst_sel:DWORD dst_unused:UNUSED_PAD src0_sel:DWORD src1_sel:WORD_1
	global_store_dwordx2 v[92:93], v[70:71], off
	global_load_dwordx4 v[70:73], v[82:83], off offset:64
	s_nop 0
	global_load_dwordx4 v[74:77], v[84:85], off offset:64
	s_waitcnt vmcnt(0)
	v_pk_fma_f32 v[72:73], v[90:91], v[72:73], v[76:77]
	v_pk_fma_f32 v[70:71], v[88:89], v[70:71], v[74:75]
	global_store_dwordx4 v[84:85], v[70:73], off offset:64
	global_load_dwordx4 v[74:77], v[52:53], off offset:64
	global_load_dwordx4 v[78:81], v[86:87], off offset:64
	s_waitcnt vmcnt(1)
	v_pk_mul_f32 v[76:77], v[72:73], v[76:77]
	v_pk_mul_f32 v[74:75], v[70:71], v[74:75]
	s_waitcnt vmcnt(0)
	v_pk_add_f32 v[80:81], v[80:81], 1.0 op_sel_hi:[1,0]
	v_pk_add_f32 v[78:79], v[78:79], 1.0 op_sel_hi:[1,0]
	v_pk_mul_f32 v[76:77], v[76:77], v[80:81]
	v_pk_mul_f32 v[74:75], v[74:75], v[78:79]
	v_and_b32_sdwa v81, v75, v170 dst_sel:DWORD dst_unused:UNUSED_PAD src0_sel:WORD_1 src1_sel:DWORD
	v_and_b32_sdwa v79, v74, v170 dst_sel:DWORD dst_unused:UNUSED_PAD src0_sel:WORD_1 src1_sel:DWORD
	v_add3_u32 v75, v75, v81, s56
	v_add3_u32 v74, v74, v79, s56
	v_and_b32_e32 v78, 0xffff0000, v75
	v_cvt_pk_bf16_f32 v75, v76, v77
	v_or_b32_sdwa v74, v78, v74 dst_sel:DWORD dst_unused:UNUSED_PAD src0_sel:DWORD src1_sel:WORD_1
	global_store_dwordx2 v[92:93], v[74:75], off offset:32
	global_load_dwordx4 v[74:77], v[82:83], off offset:128
	s_nop 0
	global_load_dwordx4 v[78:81], v[84:85], off offset:128
	s_waitcnt vmcnt(0)
	v_pk_fma_f32 v[58:59], v[58:59], v[76:77], v[80:81]
	v_pk_fma_f32 v[56:57], v[56:57], v[74:75], v[78:79]
	global_store_dwordx4 v[84:85], v[56:59], off offset:128
	global_load_dwordx4 v[74:77], v[52:53], off offset:128
	global_load_dwordx4 v[78:81], v[86:87], off offset:128
	s_waitcnt vmcnt(1)
	v_pk_mul_f32 v[76:77], v[58:59], v[76:77]
	v_pk_mul_f32 v[74:75], v[56:57], v[74:75]
	s_waitcnt vmcnt(0)
	v_pk_add_f32 v[80:81], v[80:81], 1.0 op_sel_hi:[1,0]
	v_pk_add_f32 v[78:79], v[78:79], 1.0 op_sel_hi:[1,0]
	v_pk_mul_f32 v[76:77], v[76:77], v[80:81]
	v_pk_mul_f32 v[74:75], v[74:75], v[78:79]
	v_and_b32_sdwa v81, v75, v170 dst_sel:DWORD dst_unused:UNUSED_PAD src0_sel:WORD_1 src1_sel:DWORD
	v_and_b32_sdwa v79, v74, v170 dst_sel:DWORD dst_unused:UNUSED_PAD src0_sel:WORD_1 src1_sel:DWORD
	v_add3_u32 v75, v75, v81, s56
	v_add3_u32 v74, v74, v79, s56
	v_and_b32_e32 v78, 0xffff0000, v75
	v_cvt_pk_bf16_f32 v75, v76, v77
	v_or_b32_sdwa v74, v78, v74 dst_sel:DWORD dst_unused:UNUSED_PAD src0_sel:DWORD src1_sel:WORD_1
	global_store_dwordx2 v[92:93], v[74:75], off offset:64
	global_load_dwordx4 v[74:77], v[82:83], off offset:192
	s_nop 0
	global_load_dwordx4 v[78:81], v[84:85], off offset:192
	s_waitcnt vmcnt(0)
	v_pk_fma_f32 v[76:77], v[50:51], v[76:77], v[80:81]
	v_pk_fma_f32 v[74:75], v[48:49], v[74:75], v[78:79]
	global_store_dwordx4 v[84:85], v[74:77], off offset:192
	global_load_dwordx4 v[78:81], v[52:53], off offset:192
	s_nop 0
	global_load_dwordx4 v[82:85], v[86:87], off offset:192
	v_mul_f32_e32 v48, v67, v67
	v_mul_f32_e32 v49, v71, v71
	v_fmac_f32_e32 v48, v66, v66
	v_fmac_f32_e32 v49, v70, v70
	v_fmac_f32_e32 v48, v68, v68
	v_fmac_f32_e32 v49, v72, v72
	v_fmac_f32_e32 v48, v69, v69
	v_fmac_f32_e32 v49, v73, v73
	v_add_f32_e32 v48, v48, v49
	v_mul_f32_e32 v49, v57, v57
	v_fmac_f32_e32 v49, v56, v56
	v_fmac_f32_e32 v49, v58, v58
	v_fmac_f32_e32 v49, v59, v59
	v_add_f32_e32 v48, v48, v49
	v_mul_f32_e32 v49, v75, v75
	v_fmac_f32_e32 v49, v74, v74
	v_fmac_f32_e32 v49, v76, v76
	v_fmac_f32_e32 v49, v77, v77
	v_add_f32_e32 v50, v48, v49
	ds_bpermute_b32 v51, v105, v50
	v_lshrrev_b32_e32 v48, 6, v65
	v_mul_lo_u32 v48, v48, s16
	v_ashrrev_i32_e32 v49, 31, v48
	v_lshl_add_u64 v[48:49], s[26:27], 0, v[48:49]
	s_waitcnt lgkmcnt(0)
	v_add_f32_e32 v50, v50, v51
	ds_bpermute_b32 v51, v104, v50
	v_lshl_add_u64 v[48:49], v[62:63], 2, v[48:49]
	s_waitcnt vmcnt(1)
	v_pk_mul_f32 v[56:57], v[76:77], v[80:81]
	v_pk_mul_f32 v[58:59], v[74:75], v[78:79]
	s_waitcnt vmcnt(0)
	v_pk_add_f32 v[66:67], v[84:85], 1.0 op_sel_hi:[1,0]
	v_pk_add_f32 v[68:69], v[82:83], 1.0 op_sel_hi:[1,0]
	v_pk_mul_f32 v[56:57], v[56:57], v[66:67]
	v_pk_mul_f32 v[58:59], v[58:59], v[68:69]
	v_cvt_pk_bf16_f32 v57, v56, v57
	v_cvt_pk_bf16_f32 v56, v58, v59
	global_store_dwordx2 v[92:93], v[56:57], off offset:96
	s_and_saveexec_b64 s[24:25], s[36:37]
	s_cbranch_execz .LBB0_599
	s_waitcnt lgkmcnt(0)
	v_add_f32_e32 v50, v50, v51
	global_store_dword v[48:49], v50, off
.LBB0_599:
	s_or_b64 exec, exec, s[24:25]
	s_waitcnt lgkmcnt(0)
	v_add_u32_e32 v51, 0xffffe010, v64
	v_or_b32_e32 v50, 16, v62
	v_lshrrev_b32_e32 v51, 10, v51
	s_movk_i32 s16, 0x1800
	v_mad_u32_u24 v51, v51, s16, s16
	v_cmp_lt_i32_e32 vcc, s13, v50
	v_readlane_b32 s16, v250, 15
	v_readlane_b32 s17, v250, 16
	v_cndmask_b32_e32 v56, 0, v51, vcc
	v_ashrrev_i32_e32 v57, 31, v56
	v_lshlrev_b64 v[70:71], 2, v[56:57]
	v_ashrrev_i32_e32 v51, 31, v50
	v_lshl_add_u64 v[56:57], s[38:39], 0, v[70:71]
	v_lshl_add_u64 v[72:73], v[56:57], 0, v[60:61]
	v_lshlrev_b64 v[56:57], 12, v[50:51]
	v_lshl_add_u64 v[56:57], s[16:17], 0, v[56:57]
	v_lshl_add_u64 v[74:75], v[56:57], 0, v[60:61]
	global_load_dwordx4 v[56:59], v[72:73], off
	global_load_dwordx4 v[66:69], v[74:75], off
	v_lshl_add_u64 v[70:71], s[40:41], 0, v[70:71]
	v_lshl_add_u64 v[70:71], v[70:71], 0, v[60:61]
	v_readlane_b32 s16, v250, 21
	v_lshlrev_b64 v[50:51], 11, v[50:51]
	v_readlane_b32 s17, v250, 22
	s_waitcnt vmcnt(0)
	v_pk_fma_f32 v[46:47], v[46:47], v[58:59], v[68:69]
	v_pk_fma_f32 v[44:45], v[44:45], v[56:57], v[66:67]
	global_store_dwordx4 v[74:75], v[44:47], off
	global_load_dwordx4 v[56:59], v[52:53], off
	global_load_dwordx4 v[66:69], v[70:71], off
	v_lshl_add_u64 v[50:51], s[16:17], 0, v[50:51]
	v_lshl_add_u64 v[50:51], v[54:55], 1, v[50:51]
	s_waitcnt vmcnt(1)
	v_pk_mul_f32 v[58:59], v[46:47], v[58:59]
	v_pk_mul_f32 v[56:57], v[44:45], v[56:57]
	s_waitcnt vmcnt(0)
	v_pk_add_f32 v[68:69], v[68:69], 1.0 op_sel_hi:[1,0]
	v_pk_add_f32 v[66:67], v[66:67], 1.0 op_sel_hi:[1,0]
	v_pk_mul_f32 v[58:59], v[58:59], v[68:69]
	v_pk_mul_f32 v[56:57], v[56:57], v[66:67]
	v_and_b32_sdwa v67, v57, v170 dst_sel:DWORD dst_unused:UNUSED_PAD src0_sel:WORD_1 src1_sel:DWORD
	v_and_b32_sdwa v65, v56, v170 dst_sel:DWORD dst_unused:UNUSED_PAD src0_sel:WORD_1 src1_sel:DWORD
	v_add3_u32 v57, v57, v67, s56
	v_add3_u32 v56, v56, v65, s56
	v_and_b32_e32 v63, 0xffff0000, v57
	v_cvt_pk_bf16_f32 v57, v58, v59
	v_or_b32_sdwa v56, v63, v56 dst_sel:DWORD dst_unused:UNUSED_PAD src0_sel:DWORD src1_sel:WORD_1
	global_store_dwordx2 v[50:51], v[56:57], off
	global_load_dwordx4 v[56:59], v[72:73], off offset:64
	s_nop 0
	global_load_dwordx4 v[66:69], v[74:75], off offset:64
	s_waitcnt vmcnt(0)
	v_pk_fma_f32 v[42:43], v[42:43], v[58:59], v[68:69]
	v_pk_fma_f32 v[40:41], v[40:41], v[56:57], v[66:67]
	global_store_dwordx4 v[74:75], v[40:43], off offset:64
	global_load_dwordx4 v[56:59], v[52:53], off offset:64
	global_load_dwordx4 v[66:69], v[70:71], off offset:64
	s_waitcnt vmcnt(1)
	v_pk_mul_f32 v[58:59], v[42:43], v[58:59]
	v_pk_mul_f32 v[56:57], v[40:41], v[56:57]
	s_waitcnt vmcnt(0)
	v_pk_add_f32 v[68:69], v[68:69], 1.0 op_sel_hi:[1,0]
	v_pk_add_f32 v[66:67], v[66:67], 1.0 op_sel_hi:[1,0]
	v_pk_mul_f32 v[58:59], v[58:59], v[68:69]
	v_pk_mul_f32 v[56:57], v[56:57], v[66:67]
	v_and_b32_sdwa v67, v57, v170 dst_sel:DWORD dst_unused:UNUSED_PAD src0_sel:WORD_1 src1_sel:DWORD
	v_and_b32_sdwa v65, v56, v170 dst_sel:DWORD dst_unused:UNUSED_PAD src0_sel:WORD_1 src1_sel:DWORD
	v_add3_u32 v57, v57, v67, s56
	v_add3_u32 v56, v56, v65, s56
	v_and_b32_e32 v63, 0xffff0000, v57
	v_cvt_pk_bf16_f32 v57, v58, v59
	v_or_b32_sdwa v56, v63, v56 dst_sel:DWORD dst_unused:UNUSED_PAD src0_sel:DWORD src1_sel:WORD_1
	global_store_dwordx2 v[50:51], v[56:57], off offset:32
	global_load_dwordx4 v[56:59], v[72:73], off offset:128
	s_nop 0
	global_load_dwordx4 v[66:69], v[74:75], off offset:128
	s_waitcnt vmcnt(0)
	v_pk_fma_f32 v[38:39], v[38:39], v[58:59], v[68:69]
	v_pk_fma_f32 v[36:37], v[36:37], v[56:57], v[66:67]
	global_store_dwordx4 v[74:75], v[36:39], off offset:128
	global_load_dwordx4 v[56:59], v[52:53], off offset:128
	global_load_dwordx4 v[66:69], v[70:71], off offset:128
	s_waitcnt vmcnt(1)
	v_pk_mul_f32 v[58:59], v[38:39], v[58:59]
	v_pk_mul_f32 v[56:57], v[36:37], v[56:57]
	s_waitcnt vmcnt(0)
	v_pk_add_f32 v[68:69], v[68:69], 1.0 op_sel_hi:[1,0]
	v_pk_add_f32 v[66:67], v[66:67], 1.0 op_sel_hi:[1,0]
	v_pk_mul_f32 v[58:59], v[58:59], v[68:69]
	v_pk_mul_f32 v[56:57], v[56:57], v[66:67]
	v_and_b32_sdwa v67, v57, v170 dst_sel:DWORD dst_unused:UNUSED_PAD src0_sel:WORD_1 src1_sel:DWORD
	v_and_b32_sdwa v65, v56, v170 dst_sel:DWORD dst_unused:UNUSED_PAD src0_sel:WORD_1 src1_sel:DWORD
	v_add3_u32 v57, v57, v67, s56
	v_add3_u32 v56, v56, v65, s56
	v_and_b32_e32 v63, 0xffff0000, v57
	v_cvt_pk_bf16_f32 v57, v58, v59
	v_or_b32_sdwa v56, v63, v56 dst_sel:DWORD dst_unused:UNUSED_PAD src0_sel:DWORD src1_sel:WORD_1
	global_store_dwordx2 v[50:51], v[56:57], off offset:64
	global_load_dwordx4 v[56:59], v[72:73], off offset:192
	s_nop 0
	global_load_dwordx4 v[66:69], v[74:75], off offset:192
	s_waitcnt vmcnt(0)
	v_pk_fma_f32 v[58:59], v[34:35], v[58:59], v[68:69]
	v_pk_fma_f32 v[56:57], v[32:33], v[56:57], v[66:67]
	global_store_dwordx4 v[74:75], v[56:59], off offset:192
	global_load_dwordx4 v[66:69], v[52:53], off offset:192
	s_nop 0
	global_load_dwordx4 v[70:73], v[70:71], off offset:192
	v_mul_f32_e32 v32, v45, v45
	v_mul_f32_e32 v33, v41, v41
	v_fmac_f32_e32 v32, v44, v44
	v_fmac_f32_e32 v33, v40, v40
	v_fmac_f32_e32 v32, v46, v46
	v_fmac_f32_e32 v33, v42, v42
	v_fmac_f32_e32 v32, v47, v47
	v_fmac_f32_e32 v33, v43, v43
	v_add_f32_e32 v32, v32, v33
	v_mul_f32_e32 v33, v37, v37
	v_fmac_f32_e32 v33, v36, v36
	v_fmac_f32_e32 v33, v38, v38
	v_fmac_f32_e32 v33, v39, v39
	v_add_f32_e32 v32, v32, v33
	v_mul_f32_e32 v33, v57, v57
	v_fmac_f32_e32 v33, v56, v56
	v_fmac_f32_e32 v33, v58, v58
	v_fmac_f32_e32 v33, v59, v59
	v_add_f32_e32 v32, v32, v33
	ds_bpermute_b32 v33, v105, v32
	s_waitcnt lgkmcnt(0)
	v_add_f32_e32 v32, v32, v33
	ds_bpermute_b32 v33, v104, v32
	s_waitcnt vmcnt(1)
	v_pk_mul_f32 v[34:35], v[58:59], v[68:69]
	v_pk_mul_f32 v[36:37], v[56:57], v[66:67]
	s_waitcnt vmcnt(0)
	v_pk_add_f32 v[38:39], v[72:73], 1.0 op_sel_hi:[1,0]
	v_pk_add_f32 v[40:41], v[70:71], 1.0 op_sel_hi:[1,0]
	v_pk_mul_f32 v[34:35], v[34:35], v[38:39]
	v_pk_mul_f32 v[36:37], v[36:37], v[40:41]
	v_cvt_pk_bf16_f32 v35, v34, v35
	v_cvt_pk_bf16_f32 v34, v36, v37
	global_store_dwordx2 v[50:51], v[34:35], off offset:96
	s_and_saveexec_b64 s[24:25], s[36:37]
	s_cbranch_execz .LBB0_601
	s_waitcnt lgkmcnt(0)
	v_add_f32_e32 v32, v32, v33
	global_store_dword v[48:49], v32, off offset:64
.LBB0_601:
	s_or_b64 exec, exec, s[24:25]
	v_add_u32_e32 v32, 0xffffe020, v64
	v_or_b32_e32 v40, 32, v62
	v_lshrrev_b32_e32 v32, 10, v32
	s_movk_i32 s16, 0x1800
	v_mad_u32_u24 v32, v32, s16, s16
	v_cmp_lt_i32_e32 vcc, s13, v40
	v_ashrrev_i32_e32 v41, 31, v40
	v_readlane_b32 s16, v250, 15
	v_cndmask_b32_e32 v32, 0, v32, vcc
	s_waitcnt lgkmcnt(0)
	v_ashrrev_i32_e32 v33, 31, v32
	v_lshlrev_b64 v[42:43], 2, v[32:33]
	v_lshl_add_u64 v[32:33], s[38:39], 0, v[42:43]
	v_lshl_add_u64 v[44:45], v[32:33], 0, v[60:61]
	v_lshlrev_b64 v[32:33], 12, v[40:41]
	v_readlane_b32 s17, v250, 16
	v_lshl_add_u64 v[42:43], s[40:41], 0, v[42:43]
	v_lshl_add_u64 v[42:43], v[42:43], 0, v[60:61]
	v_lshl_add_u64 v[32:33], s[16:17], 0, v[32:33]
	v_lshl_add_u64 v[46:47], v[32:33], 0, v[60:61]
	global_load_dwordx4 v[32:35], v[44:45], off
	global_load_dwordx4 v[36:39], v[46:47], off
	v_readlane_b32 s16, v250, 21
	v_lshlrev_b64 v[40:41], 11, v[40:41]
	v_readlane_b32 s17, v250, 22
	s_waitcnt vmcnt(0)
	v_pk_fma_f32 v[30:31], v[30:31], v[34:35], v[38:39]
	v_pk_fma_f32 v[28:29], v[28:29], v[32:33], v[36:37]
	global_store_dwordx4 v[46:47], v[28:31], off
	global_load_dwordx4 v[32:35], v[52:53], off
	global_load_dwordx4 v[36:39], v[42:43], off
	v_lshl_add_u64 v[40:41], s[16:17], 0, v[40:41]
	v_lshl_add_u64 v[50:51], v[54:55], 1, v[40:41]
	s_waitcnt vmcnt(1)
	v_pk_mul_f32 v[34:35], v[30:31], v[34:35]
	v_pk_mul_f32 v[32:33], v[28:29], v[32:33]
	s_waitcnt vmcnt(0)
	v_pk_add_f32 v[38:39], v[38:39], 1.0 op_sel_hi:[1,0]
	v_pk_add_f32 v[36:37], v[36:37], 1.0 op_sel_hi:[1,0]
	v_pk_mul_f32 v[34:35], v[34:35], v[38:39]
	v_pk_mul_f32 v[32:33], v[32:33], v[36:37]
	v_and_b32_sdwa v39, v33, v170 dst_sel:DWORD dst_unused:UNUSED_PAD src0_sel:WORD_1 src1_sel:DWORD
	v_and_b32_sdwa v37, v32, v170 dst_sel:DWORD dst_unused:UNUSED_PAD src0_sel:WORD_1 src1_sel:DWORD
	v_add3_u32 v33, v33, v39, s56
	v_add3_u32 v32, v32, v37, s56
	v_and_b32_e32 v36, 0xffff0000, v33
	v_cvt_pk_bf16_f32 v33, v34, v35
	v_or_b32_sdwa v32, v36, v32 dst_sel:DWORD dst_unused:UNUSED_PAD src0_sel:DWORD src1_sel:WORD_1
	global_store_dwordx2 v[50:51], v[32:33], off
	global_load_dwordx4 v[32:35], v[44:45], off offset:64
	s_nop 0
	global_load_dwordx4 v[36:39], v[46:47], off offset:64
	s_waitcnt vmcnt(0)
	v_pk_fma_f32 v[26:27], v[26:27], v[34:35], v[38:39]
	v_pk_fma_f32 v[24:25], v[24:25], v[32:33], v[36:37]
	global_store_dwordx4 v[46:47], v[24:27], off offset:64
	global_load_dwordx4 v[32:35], v[52:53], off offset:64
	global_load_dwordx4 v[36:39], v[42:43], off offset:64
	s_waitcnt vmcnt(1)
	v_pk_mul_f32 v[34:35], v[26:27], v[34:35]
	v_pk_mul_f32 v[32:33], v[24:25], v[32:33]
	s_waitcnt vmcnt(0)
	v_pk_add_f32 v[38:39], v[38:39], 1.0 op_sel_hi:[1,0]
	v_pk_add_f32 v[36:37], v[36:37], 1.0 op_sel_hi:[1,0]
	v_pk_mul_f32 v[34:35], v[34:35], v[38:39]
	v_pk_mul_f32 v[32:33], v[32:33], v[36:37]
	v_and_b32_sdwa v39, v33, v170 dst_sel:DWORD dst_unused:UNUSED_PAD src0_sel:WORD_1 src1_sel:DWORD
	v_and_b32_sdwa v37, v32, v170 dst_sel:DWORD dst_unused:UNUSED_PAD src0_sel:WORD_1 src1_sel:DWORD
	v_add3_u32 v33, v33, v39, s56
	v_add3_u32 v32, v32, v37, s56
	v_and_b32_e32 v36, 0xffff0000, v33
	v_cvt_pk_bf16_f32 v33, v34, v35
	v_or_b32_sdwa v32, v36, v32 dst_sel:DWORD dst_unused:UNUSED_PAD src0_sel:DWORD src1_sel:WORD_1
	global_store_dwordx2 v[50:51], v[32:33], off offset:32
	global_load_dwordx4 v[32:35], v[44:45], off offset:128
	s_nop 0
	global_load_dwordx4 v[36:39], v[46:47], off offset:128
	s_waitcnt vmcnt(0)
	v_pk_fma_f32 v[22:23], v[22:23], v[34:35], v[38:39]
	v_pk_fma_f32 v[20:21], v[20:21], v[32:33], v[36:37]
	global_store_dwordx4 v[46:47], v[20:23], off offset:128
	global_load_dwordx4 v[32:35], v[52:53], off offset:128
	global_load_dwordx4 v[36:39], v[42:43], off offset:128
	s_waitcnt vmcnt(1)
	v_pk_mul_f32 v[34:35], v[22:23], v[34:35]
	v_pk_mul_f32 v[32:33], v[20:21], v[32:33]
	s_waitcnt vmcnt(0)
	v_pk_add_f32 v[38:39], v[38:39], 1.0 op_sel_hi:[1,0]
	v_pk_add_f32 v[36:37], v[36:37], 1.0 op_sel_hi:[1,0]
	v_pk_mul_f32 v[34:35], v[34:35], v[38:39]
	v_pk_mul_f32 v[32:33], v[32:33], v[36:37]
	v_and_b32_sdwa v39, v33, v170 dst_sel:DWORD dst_unused:UNUSED_PAD src0_sel:WORD_1 src1_sel:DWORD
	v_and_b32_sdwa v37, v32, v170 dst_sel:DWORD dst_unused:UNUSED_PAD src0_sel:WORD_1 src1_sel:DWORD
	v_add3_u32 v33, v33, v39, s56
	v_add3_u32 v32, v32, v37, s56
	v_and_b32_e32 v36, 0xffff0000, v33
	v_cvt_pk_bf16_f32 v33, v34, v35
	v_or_b32_sdwa v32, v36, v32 dst_sel:DWORD dst_unused:UNUSED_PAD src0_sel:DWORD src1_sel:WORD_1
	global_store_dwordx2 v[50:51], v[32:33], off offset:64
	global_load_dwordx4 v[32:35], v[44:45], off offset:192
	s_nop 0
	global_load_dwordx4 v[36:39], v[46:47], off offset:192
	s_waitcnt vmcnt(0)
	v_pk_fma_f32 v[34:35], v[18:19], v[34:35], v[38:39]
	v_pk_fma_f32 v[32:33], v[16:17], v[32:33], v[36:37]
	global_store_dwordx4 v[46:47], v[32:35], off offset:192
	global_load_dwordx4 v[36:39], v[52:53], off offset:192
	s_nop 0
	global_load_dwordx4 v[40:43], v[42:43], off offset:192
	v_mul_f32_e32 v16, v29, v29
	v_mul_f32_e32 v17, v25, v25
	v_fmac_f32_e32 v16, v28, v28
	v_fmac_f32_e32 v17, v24, v24
	v_fmac_f32_e32 v16, v30, v30
	v_fmac_f32_e32 v17, v26, v26
	v_fmac_f32_e32 v16, v31, v31
	v_fmac_f32_e32 v17, v27, v27
	v_add_f32_e32 v16, v16, v17
	v_mul_f32_e32 v17, v21, v21
	v_fmac_f32_e32 v17, v20, v20
	v_fmac_f32_e32 v17, v22, v22
	v_fmac_f32_e32 v17, v23, v23
	v_add_f32_e32 v16, v16, v17
	v_mul_f32_e32 v17, v33, v33
	v_fmac_f32_e32 v17, v32, v32
	v_fmac_f32_e32 v17, v34, v34
	v_fmac_f32_e32 v17, v35, v35
	v_add_f32_e32 v16, v16, v17
	ds_bpermute_b32 v17, v105, v16
	s_waitcnt lgkmcnt(0)
	v_add_f32_e32 v16, v16, v17
	ds_bpermute_b32 v17, v104, v16
	s_waitcnt vmcnt(1)
	v_pk_mul_f32 v[18:19], v[34:35], v[38:39]
	v_pk_mul_f32 v[20:21], v[32:33], v[36:37]
	s_waitcnt vmcnt(0)
	v_pk_add_f32 v[22:23], v[42:43], 1.0 op_sel_hi:[1,0]
	v_pk_add_f32 v[24:25], v[40:41], 1.0 op_sel_hi:[1,0]
	v_pk_mul_f32 v[18:19], v[18:19], v[22:23]
	v_pk_mul_f32 v[20:21], v[20:21], v[24:25]
	v_cvt_pk_bf16_f32 v19, v18, v19
	v_cvt_pk_bf16_f32 v18, v20, v21
	global_store_dwordx2 v[50:51], v[18:19], off offset:96
	s_and_saveexec_b64 s[24:25], s[36:37]
	s_movk_i32 s89, 0xff
	s_cbranch_execz .LBB0_603
	s_waitcnt lgkmcnt(0)
	v_add_f32_e32 v16, v16, v17
	global_store_dword v[48:49], v16, off offset:128
.LBB0_603:
	s_or_b64 exec, exec, s[24:25]
	v_add_u32_e32 v16, 0xffffe030, v64
	v_or_b32_e32 v24, 48, v62
	v_lshrrev_b32_e32 v16, 10, v16
	s_movk_i32 s16, 0x1800
	v_mad_u32_u24 v16, v16, s16, s16
	v_cmp_lt_i32_e32 vcc, s13, v24
	v_ashrrev_i32_e32 v25, 31, v24
	v_readlane_b32 s16, v250, 15
	v_cndmask_b32_e32 v16, 0, v16, vcc
	s_waitcnt lgkmcnt(0)
	v_ashrrev_i32_e32 v17, 31, v16
	v_lshlrev_b64 v[26:27], 2, v[16:17]
	v_lshl_add_u64 v[16:17], s[38:39], 0, v[26:27]
	v_lshl_add_u64 v[28:29], v[16:17], 0, v[60:61]
	v_lshlrev_b64 v[16:17], 12, v[24:25]
	v_readlane_b32 s17, v250, 16
	v_lshl_add_u64 v[26:27], s[40:41], 0, v[26:27]
	v_lshl_add_u64 v[26:27], v[26:27], 0, v[60:61]
	v_lshl_add_u64 v[16:17], s[16:17], 0, v[16:17]
	v_lshl_add_u64 v[30:31], v[16:17], 0, v[60:61]
	global_load_dwordx4 v[16:19], v[28:29], off
	global_load_dwordx4 v[20:23], v[30:31], off
	v_readlane_b32 s16, v250, 21
	v_lshlrev_b64 v[24:25], 11, v[24:25]
	v_readlane_b32 s17, v250, 22
	s_waitcnt vmcnt(0)
	v_pk_fma_f32 v[14:15], v[14:15], v[18:19], v[22:23]
	v_pk_fma_f32 v[12:13], v[12:13], v[16:17], v[20:21]
	global_store_dwordx4 v[30:31], v[12:15], off
	global_load_dwordx4 v[16:19], v[52:53], off
	global_load_dwordx4 v[20:23], v[26:27], off
	v_lshl_add_u64 v[24:25], s[16:17], 0, v[24:25]
	v_lshl_add_u64 v[32:33], v[54:55], 1, v[24:25]
	s_waitcnt vmcnt(1)
	v_pk_mul_f32 v[18:19], v[14:15], v[18:19]
	v_pk_mul_f32 v[16:17], v[12:13], v[16:17]
	s_waitcnt vmcnt(0)
	v_pk_add_f32 v[22:23], v[22:23], 1.0 op_sel_hi:[1,0]
	v_pk_add_f32 v[20:21], v[20:21], 1.0 op_sel_hi:[1,0]
	v_pk_mul_f32 v[18:19], v[18:19], v[22:23]
	v_pk_mul_f32 v[16:17], v[16:17], v[20:21]
	v_and_b32_sdwa v23, v17, v170 dst_sel:DWORD dst_unused:UNUSED_PAD src0_sel:WORD_1 src1_sel:DWORD
	v_and_b32_sdwa v21, v16, v170 dst_sel:DWORD dst_unused:UNUSED_PAD src0_sel:WORD_1 src1_sel:DWORD
	v_add3_u32 v17, v17, v23, s56
	v_add3_u32 v16, v16, v21, s56
	v_and_b32_e32 v20, 0xffff0000, v17
	v_cvt_pk_bf16_f32 v17, v18, v19
	v_or_b32_sdwa v16, v20, v16 dst_sel:DWORD dst_unused:UNUSED_PAD src0_sel:DWORD src1_sel:WORD_1
	global_store_dwordx2 v[32:33], v[16:17], off
	global_load_dwordx4 v[16:19], v[28:29], off offset:64
	s_nop 0
	global_load_dwordx4 v[20:23], v[30:31], off offset:64
	s_waitcnt vmcnt(0)
	v_pk_fma_f32 v[10:11], v[10:11], v[18:19], v[22:23]
	v_pk_fma_f32 v[8:9], v[8:9], v[16:17], v[20:21]
	global_store_dwordx4 v[30:31], v[8:11], off offset:64
	global_load_dwordx4 v[16:19], v[52:53], off offset:64
	global_load_dwordx4 v[20:23], v[26:27], off offset:64
	s_waitcnt vmcnt(1)
	v_pk_mul_f32 v[18:19], v[10:11], v[18:19]
	v_pk_mul_f32 v[16:17], v[8:9], v[16:17]
	s_waitcnt vmcnt(0)
	v_pk_add_f32 v[22:23], v[22:23], 1.0 op_sel_hi:[1,0]
	v_pk_add_f32 v[20:21], v[20:21], 1.0 op_sel_hi:[1,0]
	v_pk_mul_f32 v[18:19], v[18:19], v[22:23]
	v_pk_mul_f32 v[16:17], v[16:17], v[20:21]
	v_and_b32_sdwa v23, v17, v170 dst_sel:DWORD dst_unused:UNUSED_PAD src0_sel:WORD_1 src1_sel:DWORD
	v_and_b32_sdwa v21, v16, v170 dst_sel:DWORD dst_unused:UNUSED_PAD src0_sel:WORD_1 src1_sel:DWORD
	v_add3_u32 v17, v17, v23, s56
	v_add3_u32 v16, v16, v21, s56
	v_and_b32_e32 v20, 0xffff0000, v17
	v_cvt_pk_bf16_f32 v17, v18, v19
	v_or_b32_sdwa v16, v20, v16 dst_sel:DWORD dst_unused:UNUSED_PAD src0_sel:DWORD src1_sel:WORD_1
	global_store_dwordx2 v[32:33], v[16:17], off offset:32
	global_load_dwordx4 v[16:19], v[28:29], off offset:128
	s_nop 0
	global_load_dwordx4 v[20:23], v[30:31], off offset:128
	s_waitcnt vmcnt(0)
	v_pk_fma_f32 v[6:7], v[6:7], v[18:19], v[22:23]
	v_pk_fma_f32 v[4:5], v[4:5], v[16:17], v[20:21]
	global_store_dwordx4 v[30:31], v[4:7], off offset:128
	global_load_dwordx4 v[16:19], v[52:53], off offset:128
	global_load_dwordx4 v[20:23], v[26:27], off offset:128
	s_waitcnt vmcnt(1)
	v_pk_mul_f32 v[18:19], v[6:7], v[18:19]
	v_pk_mul_f32 v[16:17], v[4:5], v[16:17]
	s_waitcnt vmcnt(0)
	v_pk_add_f32 v[22:23], v[22:23], 1.0 op_sel_hi:[1,0]
	v_pk_add_f32 v[20:21], v[20:21], 1.0 op_sel_hi:[1,0]
	v_pk_mul_f32 v[18:19], v[18:19], v[22:23]
	v_pk_mul_f32 v[16:17], v[16:17], v[20:21]
	v_and_b32_sdwa v23, v17, v170 dst_sel:DWORD dst_unused:UNUSED_PAD src0_sel:WORD_1 src1_sel:DWORD
	v_and_b32_sdwa v21, v16, v170 dst_sel:DWORD dst_unused:UNUSED_PAD src0_sel:WORD_1 src1_sel:DWORD
	v_add3_u32 v17, v17, v23, s56
	v_add3_u32 v16, v16, v21, s56
	v_and_b32_e32 v20, 0xffff0000, v17
	v_cvt_pk_bf16_f32 v17, v18, v19
	v_or_b32_sdwa v16, v20, v16 dst_sel:DWORD dst_unused:UNUSED_PAD src0_sel:DWORD src1_sel:WORD_1
	global_store_dwordx2 v[32:33], v[16:17], off offset:64
	global_load_dwordx4 v[16:19], v[28:29], off offset:192
	s_nop 0
	global_load_dwordx4 v[20:23], v[30:31], off offset:192
	s_waitcnt vmcnt(0)
	v_pk_fma_f32 v[18:19], v[2:3], v[18:19], v[22:23]
	v_pk_fma_f32 v[16:17], v[0:1], v[16:17], v[20:21]
	global_store_dwordx4 v[30:31], v[16:19], off offset:192
	global_load_dwordx4 v[20:23], v[52:53], off offset:192
	s_nop 0
	global_load_dwordx4 v[24:27], v[26:27], off offset:192
	v_mul_f32_e32 v0, v13, v13
	v_mul_f32_e32 v1, v9, v9
	v_fmac_f32_e32 v0, v12, v12
	v_fmac_f32_e32 v1, v8, v8
	v_fmac_f32_e32 v0, v14, v14
	v_fmac_f32_e32 v1, v10, v10
	v_fmac_f32_e32 v0, v15, v15
	v_fmac_f32_e32 v1, v11, v11
	v_add_f32_e32 v0, v0, v1
	v_mul_f32_e32 v1, v5, v5
	v_fmac_f32_e32 v1, v4, v4
	v_fmac_f32_e32 v1, v6, v6
	v_fmac_f32_e32 v1, v7, v7
	v_add_f32_e32 v0, v0, v1
	v_mul_f32_e32 v1, v17, v17
	v_fmac_f32_e32 v1, v16, v16
	v_fmac_f32_e32 v1, v18, v18
	v_fmac_f32_e32 v1, v19, v19
	v_add_f32_e32 v0, v0, v1
	ds_bpermute_b32 v1, v105, v0
	s_waitcnt lgkmcnt(0)
	v_add_f32_e32 v0, v0, v1
	ds_bpermute_b32 v1, v104, v0
	s_waitcnt vmcnt(1)
	v_pk_mul_f32 v[2:3], v[18:19], v[22:23]
	v_pk_mul_f32 v[4:5], v[16:17], v[20:21]
	s_waitcnt vmcnt(0)
	v_pk_add_f32 v[6:7], v[26:27], 1.0 op_sel_hi:[1,0]
	v_pk_add_f32 v[8:9], v[24:25], 1.0 op_sel_hi:[1,0]
	v_pk_mul_f32 v[2:3], v[2:3], v[6:7]
	v_pk_mul_f32 v[4:5], v[4:5], v[8:9]
	v_cvt_pk_bf16_f32 v3, v2, v3
	v_cvt_pk_bf16_f32 v2, v4, v5
	global_store_dwordx2 v[32:33], v[2:3], off offset:96
	s_and_saveexec_b64 s[24:25], s[36:37]
	s_cbranch_execz .LBB0_594
	s_waitcnt lgkmcnt(0)
	v_add_f32_e32 v0, v0, v1
	global_store_dword v[48:49], v0, off offset:192
	s_branch .LBB0_594

.LBB0_612:
	s_or_b64 exec, exec, s[2:3]
	v_add_u32_e32 v13, 0xffffe010, v18
	s_waitcnt lgkmcnt(0)
	v_lshl_add_u64 v[14:15], s[0:1], 0, v[128:129]
	v_or_b32_e32 v12, 16, v12
	v_lshrrev_b32_e32 v13, 10, v13
	s_movk_i32 s0, 0x1800
	v_mad_u32_u24 v13, v13, s0, s0
	v_cmp_lt_i32_e64 s[0:1], s13, v12
	s_nop 1
	v_cndmask_b32_e64 v18, 0, v13, s[0:1]
	v_ashrrev_i32_e32 v19, 31, v18
	v_lshlrev_b64 v[34:35], 2, v[18:19]
	v_ashrrev_i32_e32 v13, 31, v12
	v_lshl_add_u64 v[18:19], s[38:39], 0, v[34:35]
	v_readlane_b32 s0, v250, 15
	v_lshl_add_u64 v[20:21], v[18:19], 0, v[128:129]
	v_lshlrev_b64 v[18:19], 12, v[12:13]
	v_readlane_b32 s1, v250, 16
	s_nop 0
	v_lshl_add_u64 v[18:19], s[0:1], 0, v[18:19]
	v_lshl_add_u64 v[18:19], v[18:19], 0, v[128:129]
	v_readlane_b32 s0, v250, 21
	v_readlane_b32 s1, v250, 22
	s_waitcnt vmcnt(16)
	v_pk_fma_f32 v[28:29], v[38:39], v[74:75], v[212:213]
	v_pk_fma_f32 v[26:27], v[36:37], v[72:73], v[210:211]
	v_lshl_add_u64 v[22:23], s[40:41], 0, v[34:35]
	global_store_dwordx4 v[18:19], v[26:29], off
	v_lshl_add_u64 v[22:23], v[22:23], 0, v[128:129]
	v_mul_f32_e32 v38, v27, v27
	v_fmac_f32_e32 v38, v26, v26
	v_fmac_f32_e32 v38, v28, v28
	v_fmac_f32_e32 v38, v29, v29
	v_pk_mul_f32 v[24:25], v[28:29], v[142:143]
	v_pk_add_f32 v[28:29], v[158:159], 1.0 op_sel_hi:[1,0]
	v_pk_mul_f32 v[26:27], v[26:27], v[140:141]
	v_pk_add_f32 v[30:31], v[156:157], 1.0 op_sel_hi:[1,0]
	v_pk_mul_f32 v[24:25], v[24:25], v[28:29]
	v_lshlrev_b64 v[28:29], 11, v[12:13]
	v_pk_mul_f32 v[26:27], v[26:27], v[30:31]
	v_lshl_add_u64 v[28:29], s[0:1], 0, v[28:29]
	v_lshl_add_u64 v[16:17], v[28:29], 0, v[16:17]
	v_cvt_pk_bf16_f32 v25, v24, v25
	v_cvt_pk_bf16_f32 v24, v26, v27
	global_store_dwordx2 v[16:17], v[24:25], off
	s_nop 0
	v_pk_fma_f32 v[8:9], v[8:9], v[80:81], v[214:215]
	s_nop 0
	v_mul_f32_e32 v24, v9, v9
	v_pk_fma_f32 v[10:11], v[10:11], v[82:83], v[216:217]
	v_fmac_f32_e32 v24, v8, v8
	v_fmac_f32_e32 v24, v10, v10
	global_store_dwordx4 v[18:19], v[8:11], off offset:64
	v_fmac_f32_e32 v24, v11, v11
	v_add_f32_e32 v32, v38, v24
	v_pk_mul_f32 v[10:11], v[10:11], v[146:147]
	v_pk_mul_f32 v[8:9], v[8:9], v[144:145]
	v_pk_add_f32 v[24:25], v[162:163], 1.0 op_sel_hi:[1,0]
	v_pk_add_f32 v[26:27], v[160:161], 1.0 op_sel_hi:[1,0]
	v_pk_mul_f32 v[10:11], v[10:11], v[24:25]
	v_pk_mul_f32 v[8:9], v[8:9], v[26:27]
	v_and_b32_sdwa v25, v8, v170 dst_sel:DWORD dst_unused:UNUSED_PAD src0_sel:WORD_1 src1_sel:DWORD
	v_add3_u32 v8, v8, v25, s56
	v_and_b32_sdwa v25, v9, v170 dst_sel:DWORD dst_unused:UNUSED_PAD src0_sel:WORD_1 src1_sel:DWORD
	v_add3_u32 v9, v9, v25, s56
	v_and_b32_e32 v24, 0xffff0000, v9
	v_cvt_pk_bf16_f32 v9, v10, v11
	v_or_b32_sdwa v8, v24, v8 dst_sel:DWORD dst_unused:UNUSED_PAD src0_sel:DWORD src1_sel:WORD_1
	global_store_dwordx2 v[16:17], v[8:9], off offset:32
	s_nop 0
	v_pk_fma_f32 v[4:5], v[4:5], v[88:89], v[218:219]
	s_nop 0
	v_mul_f32_e32 v8, v5, v5
	v_pk_fma_f32 v[6:7], v[6:7], v[90:91], v[220:221]
	v_fmac_f32_e32 v8, v4, v4
	v_fmac_f32_e32 v8, v6, v6
	global_store_dwordx4 v[18:19], v[4:7], off offset:128
	v_fmac_f32_e32 v8, v7, v7
	v_add_f32_e32 v28, v32, v8
	v_pk_mul_f32 v[6:7], v[6:7], v[150:151]
	v_pk_mul_f32 v[4:5], v[4:5], v[148:149]
	v_pk_add_f32 v[8:9], v[182:183], 1.0 op_sel_hi:[1,0]
	v_pk_add_f32 v[10:11], v[180:181], 1.0 op_sel_hi:[1,0]
	v_pk_mul_f32 v[6:7], v[6:7], v[8:9]
	v_pk_mul_f32 v[4:5], v[4:5], v[10:11]
	v_and_b32_sdwa v9, v4, v170 dst_sel:DWORD dst_unused:UNUSED_PAD src0_sel:WORD_1 src1_sel:DWORD
	v_add3_u32 v4, v4, v9, s56
	v_and_b32_sdwa v9, v5, v170 dst_sel:DWORD dst_unused:UNUSED_PAD src0_sel:WORD_1 src1_sel:DWORD
	v_add3_u32 v5, v5, v9, s56
	v_and_b32_e32 v8, 0xffff0000, v5
	v_cvt_pk_bf16_f32 v5, v6, v7
	v_or_b32_sdwa v4, v8, v4 dst_sel:DWORD dst_unused:UNUSED_PAD src0_sel:DWORD src1_sel:WORD_1
	global_store_dwordx2 v[16:17], v[4:5], off offset:64
	s_nop 0
	v_pk_fma_f32 v[0:1], v[0:1], v[136:137], v[222:223]
	s_nop 0
	v_mul_f32_e32 v4, v1, v1
	v_pk_fma_f32 v[2:3], v[2:3], v[138:139], v[224:225]
	v_fmac_f32_e32 v4, v0, v0
	v_fmac_f32_e32 v4, v2, v2
	global_store_dwordx4 v[18:19], v[0:3], off offset:192
	v_fmac_f32_e32 v4, v3, v3
	v_add_f32_e32 v18, v28, v4
	v_pk_mul_f32 v[2:3], v[2:3], v[154:155]
	v_pk_mul_f32 v[0:1], v[0:1], v[152:153]
	v_pk_add_f32 v[4:5], v[192:193], 1.0 op_sel_hi:[1,0]
	v_pk_add_f32 v[6:7], v[190:191], 1.0 op_sel_hi:[1,0]
	v_pk_mul_f32 v[2:3], v[2:3], v[4:5]
	v_pk_mul_f32 v[0:1], v[0:1], v[6:7]
	v_and_b32_sdwa v5, v0, v170 dst_sel:DWORD dst_unused:UNUSED_PAD src0_sel:WORD_1 src1_sel:DWORD
	v_add3_u32 v0, v0, v5, s56
	v_and_b32_sdwa v5, v1, v170 dst_sel:DWORD dst_unused:UNUSED_PAD src0_sel:WORD_1 src1_sel:DWORD
	v_add3_u32 v1, v1, v5, s56
	v_and_b32_e32 v4, 0xffff0000, v1
	v_cvt_pk_bf16_f32 v1, v2, v3
	v_or_b32_sdwa v0, v4, v0 dst_sel:DWORD dst_unused:UNUSED_PAD src0_sel:DWORD src1_sel:WORD_1
	global_store_dwordx2 v[16:17], v[0:1], off offset:96
	ds_bpermute_b32 v0, v105, v18
	s_waitcnt lgkmcnt(0)
	v_add_f32_e32 v0, v18, v0
	ds_bpermute_b32 v1, v104, v0
	s_and_saveexec_b64 s[0:1], vcc
	s_movk_i32 s89, 0xff
	s_cbranch_execz .LBB0_614
	v_readlane_b32 s2, v253, 20
	s_add_u32 s2, s26, s2
	s_addc_u32 s3, s27, 0
	v_lshl_add_u64 v[2:3], v[12:13], 2, s[2:3]
	s_waitcnt lgkmcnt(0)
	v_add_f32_e32 v0, v0, v1
	global_store_dword v[2:3], v0, off
